# LayerNorm GEMM epilogues: packed f32 VALU ops split into scalar ops (identical arithmetic)
# baseline (speedup 1.0000x reference)
;     __device__ __forceinline__ void fused(f32x4 (&acc)[2][2][4][2], const Unit& u, int wr, int wc, int fr, int fq, PG8_LAS unsigned char* lds, int wid, int lane) const {
;     ...
;         const int col0 = u.pn * BM + wc * 32 + 4 * fq; const int b = (u.pm * BM) >> 13; const size_t mo = (size_t)b * 9216;
; #pragma unroll
;         for (int bj = 0; bj < 2; ++bj)
; #pragma unroll
;             for (int n = 0; n < 2; ++n) { const f32x4 gv = (*(const f32x4*)(gate + mo + col0 + bj * HALF + n * 16) + 1.0f) * coef;
; #pragma unroll
;                 for (int ai = 0; ai < 2; ++ai)
; #pragma unroll
;                     for (int m = 0; m < 4; ++m) acc[ai][bj][m][n] = acc[ai][bj][m][n] * gv; }
; #pragma unroll
;         for (int ai = 0; ai < 2; ++ai)
; #pragma unroll
;             for (int m = 0; m < 4; ++m) { const size_t off = (size_t)(u.pm * BM + ai * HALF + wr * 64 + m * 16 + fr) * 1024 + col0;
; #pragma unroll
;                 for (int bj = 0; bj < 2; ++bj)
; #pragma unroll
;                     for (int n = 0; n < 2; ++n) { const f32x4 xv = *(const f32x4*)(xin + off + bj * HALF + n * 16); acc[ai][bj][m][n] = xv * ALPHA_ + acc[ai][bj][m][n]; }
;                 asm volatile("" : "+v"(acc[ai][0][m][0]), "+v"(acc[ai][0][m][1]), "+v"(acc[ai][1][m][0]), "+v"(acc[ai][1][m][1]));
;                 if (m & 1) asm volatile("" ::: "memory"); }
.LBB0_392:
	s_lshl_b32 s6, s21, 5
	s_lshl_b32 s7, s14, 8
	s_or_b32 s6, s7, s6
	v_lshrrev_b32_e32 v4, 2, v149
	v_and_or_b32 v154, v4, 12, s6
	s_ashr_i32 s6, s50, 5
	s_mul_hi_i32 s7, s6, 0x2400
	s_mulk_i32 s6, 0x2400
	s_lshl_b64 s[16:17], s[6:7], 2
	v_ashrrev_i32_e32 v155, 31, v154
	s_add_u32 s6, s12, s16
	s_addc_u32 s7, s13, s17
	v_lshlrev_b64 v[136:137], 2, v[154:155]
	v_lshl_add_u64 v[156:157], s[6:7], 0, v[136:137]
	s_mov_b64 s[6:7], 0x2000
	s_lshl_b32 s20, s50, 8
	v_lshl_add_u64 v[164:165], v[156:157], 0, s[6:7]
	s_add_i32 s6, s20, s60
	v_or_b32_e32 v172, s6, v151
	s_movk_i32 s8, 0x2000
	v_ashrrev_i32_e32 v173, 31, v172
	v_add_co_u32_e32 v4, vcc, s8, v156
	v_lshlrev_b64 v[168:169], 12, v[172:173]
	s_nop 0
	v_addc_co_u32_e32 v5, vcc, 0, v157, vcc
	s_waitcnt vmcnt(0) lgkmcnt(0)
	v_lshl_add_u64 v[168:169], v[138:139], 0, v[168:169]
	s_barrier
	global_load_dwordx4 v[4:7], v[4:5], off
	s_nop 0
	global_load_dwordx4 v[156:159], v[164:165], off offset:64
	global_load_dwordx4 v[160:163], v[164:165], off offset:512
	s_nop 0
	global_load_dwordx4 v[164:167], v[164:165], off offset:576
	v_lshl_add_u64 v[168:169], v[168:169], 0, v[136:137]
	global_load_dwordx4 v[174:177], v[168:169], off
	global_load_dwordx4 v[182:185], v[168:169], off offset:64
	global_load_dwordx4 v[186:189], v[168:169], off offset:512
	global_load_dwordx4 v[190:193], v[168:169], off offset:576
	v_or_b32_e32 v168, 16, v172
	v_ashrrev_i32_e32 v169, 31, v168
	v_lshlrev_b64 v[168:169], 12, v[168:169]
	v_lshl_add_u64 v[168:169], v[138:139], 0, v[168:169]
	s_mov_b32 s6, 0x3f9837f0
	v_lshl_add_u64 v[194:195], v[168:169], 0, v[136:137]
	s_waitcnt vmcnt(0) lgkmcnt(0)
	v_add_f32_e64 v168, v158, 1.0
	v_add_f32_e64 v169, v159, 1.0
	v_add_f32_e64 v6, v6, 1.0
	v_add_f32_e64 v7, v7, 1.0
	v_add_f32_e64 v4, v4, 1.0
	v_add_f32_e64 v5, v5, 1.0
	v_add_f32_e64 v170, v156, 1.0
	v_add_f32_e64 v171, v157, 1.0
	v_add_f32_e64 v196, v162, 1.0
	v_add_f32_e64 v197, v163, 1.0
	v_add_f32_e64 v198, v160, 1.0
	v_add_f32_e64 v199, v161, 1.0
	v_add_f32_e64 v200, v166, 1.0
	v_add_f32_e64 v201, v167, 1.0
	v_add_f32_e64 v202, v164, 1.0
	v_add_f32_e64 v203, v165, 1.0
	v_mul_f32_e64 v156, v6, 0.5
	v_mul_f32_e64 v157, v7, 0.5
	v_mul_f32_e64 v158, v4, 0.5
	v_mul_f32_e64 v159, v5, 0.5
	v_mul_f32_e64 v160, v168, 0.5
	v_mul_f32_e64 v161, v169, 0.5
	v_mul_f32_e64 v162, v170, 0.5
	v_mul_f32_e64 v163, v171, 0.5
	v_mul_f32_e64 v164, v196, 0.5
	v_mul_f32_e64 v165, v197, 0.5
	v_mul_f32_e64 v166, v198, 0.5
	v_mul_f32_e64 v167, v199, 0.5
	v_mul_f32_e64 v168, v200, 0.5
	v_mul_f32_e64 v169, v201, 0.5
	v_mul_f32_e64 v170, v202, 0.5
	v_mul_f32_e64 v171, v203, 0.5
	v_mul_f32_e64 v4, v176, s6
	v_mul_f32_e64 v5, v177, s6
	v_mul_f32_e64 v6, v174, s6
	v_mul_f32_e64 v7, v175, s6
	v_mul_f32_e64 v174, v184, s6
	v_mul_f32_e64 v175, v185, s6
	v_mul_f32_e64 v176, v182, s6
	v_mul_f32_e64 v177, v183, s6
	v_mul_f32_e64 v182, v188, s6
	v_mul_f32_e64 v183, v189, s6
	v_mul_f32_e64 v184, v186, s6
	v_mul_f32_e64 v185, v187, s6
	v_mul_f32_e64 v186, v192, s6
	v_mul_f32_e64 v187, v193, s6
	v_mul_f32_e64 v188, v190, s6
	v_mul_f32_e64 v189, v191, s6
	v_fma_f32 v94, v94, v156, v4
	v_fma_f32 v95, v95, v157, v5
	v_fma_f32 v92, v92, v158, v6
	v_fma_f32 v93, v93, v159, v7
	v_fma_f32 v62, v62, v160, v174
	v_fma_f32 v63, v63, v161, v175
	v_fma_f32 v60, v60, v162, v176
	v_fma_f32 v61, v61, v163, v177
	v_fma_f32 v30, v30, v164, v182
	v_fma_f32 v31, v31, v165, v183
	v_fma_f32 v28, v28, v166, v184
	v_fma_f32 v29, v29, v167, v185
	v_fma_f32 v6, v134, v168, v186
	v_fma_f32 v7, v135, v169, v187
	v_fma_f32 v4, v132, v170, v188
	v_fma_f32 v5, v133, v171, v189
	v_or_b32_e32 v190, 32, v172
	global_load_dwordx4 v[132:135], v[194:195], off
	global_load_dwordx4 v[174:177], v[194:195], off offset:64
	global_load_dwordx4 v[182:185], v[194:195], off offset:512
	global_load_dwordx4 v[186:189], v[194:195], off offset:576
	v_ashrrev_i32_e32 v191, 31, v190
	v_lshlrev_b64 v[190:191], 12, v[190:191]
	v_lshl_add_u64 v[190:191], v[138:139], 0, v[190:191]
	v_lshl_add_u64 v[190:191], v[190:191], 0, v[136:137]
	v_mov_b32_e32 v194, v92
	v_mov_b32_e32 v195, v95
	v_mov_b32_e32 v196, v61
	v_mov_b32_e32 v197, v62
	v_add_f32_e32 v199, v30, v31
	v_mov_b32_e32 v198, v5
	v_mov_b32_e32 v200, v7
	s_waitcnt vmcnt(0) lgkmcnt(0)
	v_mul_f32_e64 v134, v134, s6
	v_mul_f32_e64 v135, v135, s6
	v_mul_f32_e64 v132, v132, s6
	v_mul_f32_e64 v133, v133, s6
	v_mul_f32_e64 v176, v176, s6
	v_mul_f32_e64 v177, v177, s6
	v_mul_f32_e64 v174, v174, s6
	v_mul_f32_e64 v175, v175, s6
	v_mul_f32_e64 v184, v184, s6
	v_mul_f32_e64 v185, v185, s6
	v_mul_f32_e64 v182, v182, s6
	v_mul_f32_e64 v183, v183, s6
	v_mul_f32_e64 v188, v188, s6
	v_mul_f32_e64 v189, v189, s6
	v_mul_f32_e64 v186, v186, s6
	v_mul_f32_e64 v187, v187, s6
	v_fma_f32 v102, v102, v156, v134
	v_fma_f32 v103, v103, v157, v135
	v_fma_f32 v100, v100, v158, v132
	v_fma_f32 v101, v101, v159, v133
	v_fma_f32 v70, v70, v160, v176
	v_fma_f32 v71, v71, v161, v177
	v_fma_f32 v68, v68, v162, v174
	v_fma_f32 v69, v69, v163, v175
	v_fma_f32 v38, v38, v164, v184
	v_fma_f32 v39, v39, v165, v185
	v_fma_f32 v36, v36, v166, v182
	v_fma_f32 v37, v37, v167, v183
	v_fma_f32 v10, v10, v168, v188
	v_fma_f32 v11, v11, v169, v189
	v_fma_f32 v8, v8, v170, v186
	v_fma_f32 v9, v9, v171, v187
	s_nop 0
	global_load_dwordx4 v[132:135], v[190:191], off
	global_load_dwordx4 v[174:177], v[190:191], off offset:64
	global_load_dwordx4 v[182:185], v[190:191], off offset:512
	global_load_dwordx4 v[186:189], v[190:191], off offset:576
	v_or_b32_e32 v190, 48, v172
	v_ashrrev_i32_e32 v191, 31, v190
	v_lshlrev_b64 v[190:191], 12, v[190:191]
	v_lshl_add_u64 v[190:191], v[138:139], 0, v[190:191]
	v_lshl_add_u64 v[190:191], v[190:191], 0, v[136:137]
	s_waitcnt vmcnt(0) lgkmcnt(0)
;     __device__ __forceinline__ bool run(const f32x4 (&v)[2][2][4][2], const Unit& u, int wr, int wc, int fr, int fq, PG8_LAS unsigned char* lds, int wid, int lane) const {
;     ...
;                     for (int n = 0; n < 2; ++n) { const f32x4 x = v[ai][bj][m][n]; s += (x[0] + x[1]) + (x[2] + x[3]); }
;                 s += __shfl_xor(s, 16); s += __shfl_xor(s, 32);
;     __device__ __forceinline__ void fused(f32x4 (&acc)[2][2][4][2], const Unit& u, int wr, int wc, int fr, int fq, PG8_LAS unsigned char* lds, int wid, int lane) const {
;     ...
;         for (int ai = 0; ai < 2; ++ai)
; #pragma unroll
;             for (int m = 0; m < 4; ++m) { const size_t off = (size_t)(u.pm * BM + ai * HALF + wr * 64 + m * 16 + fr) * 1024 + col0;
; #pragma unroll
;                 for (int bj = 0; bj < 2; ++bj)
; #pragma unroll
;                     for (int n = 0; n < 2; ++n) { const f32x4 xv = *(const f32x4*)(xin + off + bj * HALF + n * 16); acc[ai][bj][m][n] = xv * ALPHA_ + acc[ai][bj][m][n]; }
;                 asm volatile("" : "+v"(acc[ai][0][m][0]), "+v"(acc[ai][0][m][1]), "+v"(acc[ai][1][m][0]), "+v"(acc[ai][1][m][1]));
;                 if (m & 1) asm volatile("" ::: "memory"); }
	v_mul_f32_e64 v134, v134, s6
	v_mul_f32_e64 v135, v135, s6
	v_mul_f32_e64 v132, v132, s6
	v_mul_f32_e64 v133, v133, s6
	v_mul_f32_e64 v176, v176, s6
	v_mul_f32_e64 v177, v177, s6
	v_mul_f32_e64 v174, v174, s6
	v_mul_f32_e64 v175, v175, s6
	v_mul_f32_e64 v184, v184, s6
	v_mul_f32_e64 v185, v185, s6
	v_mul_f32_e64 v182, v182, s6
	v_mul_f32_e64 v183, v183, s6
	v_mul_f32_e64 v188, v188, s6
	v_mul_f32_e64 v189, v189, s6
	v_mul_f32_e64 v186, v186, s6
	v_mul_f32_e64 v187, v187, s6
	v_fma_f32 v110, v110, v156, v134
	v_fma_f32 v111, v111, v157, v135
	v_fma_f32 v108, v108, v158, v132
	v_fma_f32 v109, v109, v159, v133
	v_fma_f32 v74, v74, v160, v176
	v_fma_f32 v75, v75, v161, v177
	v_fma_f32 v72, v72, v162, v174
	v_fma_f32 v73, v73, v163, v175
	v_fma_f32 v42, v42, v164, v184
	v_fma_f32 v43, v43, v165, v185
	v_fma_f32 v40, v40, v166, v182
	v_fma_f32 v41, v41, v167, v183
	v_fma_f32 v14, v14, v168, v188
	v_fma_f32 v15, v15, v169, v189
	v_fma_f32 v12, v12, v170, v186
	v_fma_f32 v13, v13, v171, v187
	s_nop 0
	global_load_dwordx4 v[132:135], v[190:191], off
	global_load_dwordx4 v[174:177], v[190:191], off offset:64
	global_load_dwordx4 v[182:185], v[190:191], off offset:512
	global_load_dwordx4 v[186:189], v[190:191], off offset:576
	v_add_u32_e32 v190, 0x80, v172
	v_ashrrev_i32_e32 v191, 31, v190
	v_lshlrev_b64 v[190:191], 12, v[190:191]
	v_lshl_add_u64 v[190:191], v[138:139], 0, v[190:191]
	v_lshl_add_u64 v[190:191], v[190:191], 0, v[136:137]
	s_waitcnt vmcnt(0) lgkmcnt(0)
	v_mul_f32_e64 v134, v134, s6
	v_mul_f32_e64 v135, v135, s6
	v_mul_f32_e64 v132, v132, s6
	v_mul_f32_e64 v133, v133, s6
	v_mul_f32_e64 v176, v176, s6
	v_mul_f32_e64 v177, v177, s6
	v_mul_f32_e64 v174, v174, s6
	v_mul_f32_e64 v175, v175, s6
	v_mul_f32_e64 v184, v184, s6
	v_mul_f32_e64 v185, v185, s6
	v_mul_f32_e64 v182, v182, s6
	v_mul_f32_e64 v183, v183, s6
	v_mul_f32_e64 v188, v188, s6
	v_mul_f32_e64 v189, v189, s6
	v_mul_f32_e64 v186, v186, s6
	v_mul_f32_e64 v187, v187, s6
	v_fma_f32 v114, v114, v156, v134
	v_fma_f32 v115, v115, v157, v135
	v_fma_f32 v112, v112, v158, v132
	v_fma_f32 v113, v113, v159, v133
	v_fma_f32 v82, v82, v160, v176
	v_fma_f32 v83, v83, v161, v177
	v_fma_f32 v80, v80, v162, v174
	v_fma_f32 v81, v81, v163, v175
	v_fma_f32 v50, v50, v164, v184
	v_fma_f32 v51, v51, v165, v185
	v_fma_f32 v48, v48, v166, v182
	v_fma_f32 v49, v49, v167, v183
	v_fma_f32 v18, v18, v168, v188
	v_fma_f32 v19, v19, v169, v189
	v_fma_f32 v16, v16, v170, v186
	v_fma_f32 v17, v17, v171, v187
	s_nop 0
	global_load_dwordx4 v[132:135], v[190:191], off
	global_load_dwordx4 v[174:177], v[190:191], off offset:64
	global_load_dwordx4 v[182:185], v[190:191], off offset:512
	global_load_dwordx4 v[186:189], v[190:191], off offset:576
	v_add_u32_e32 v190, 0x90, v172
	v_ashrrev_i32_e32 v191, 31, v190
	v_lshlrev_b64 v[190:191], 12, v[190:191]
	v_lshl_add_u64 v[190:191], v[138:139], 0, v[190:191]
	v_lshl_add_u64 v[190:191], v[190:191], 0, v[136:137]
	s_waitcnt vmcnt(0) lgkmcnt(0)
	v_mul_f32_e64 v134, v134, s6
	v_mul_f32_e64 v135, v135, s6
	v_mul_f32_e64 v132, v132, s6
	v_mul_f32_e64 v133, v133, s6
	v_mul_f32_e64 v176, v176, s6
	v_mul_f32_e64 v177, v177, s6
	v_mul_f32_e64 v174, v174, s6
	v_mul_f32_e64 v175, v175, s6
	v_mul_f32_e64 v184, v184, s6
	v_mul_f32_e64 v185, v185, s6
	v_mul_f32_e64 v182, v182, s6
	v_mul_f32_e64 v183, v183, s6
	v_mul_f32_e64 v188, v188, s6
	v_mul_f32_e64 v189, v189, s6
	v_mul_f32_e64 v186, v186, s6
	v_mul_f32_e64 v187, v187, s6
	v_fma_f32 v118, v118, v156, v134
	v_fma_f32 v119, v119, v157, v135
	v_fma_f32 v116, v116, v158, v132
	v_fma_f32 v117, v117, v159, v133
	v_fma_f32 v86, v86, v160, v176
	v_fma_f32 v87, v87, v161, v177
	v_fma_f32 v84, v84, v162, v174
	v_fma_f32 v85, v85, v163, v175
	v_fma_f32 v54, v54, v164, v184
	v_fma_f32 v55, v55, v165, v185
	v_fma_f32 v52, v52, v166, v182
	v_fma_f32 v53, v53, v167, v183
	v_fma_f32 v22, v22, v168, v188
	v_fma_f32 v23, v23, v169, v189
	v_fma_f32 v20, v20, v170, v186
	v_fma_f32 v21, v21, v171, v187
	s_nop 0
	global_load_dwordx4 v[132:135], v[190:191], off
	global_load_dwordx4 v[174:177], v[190:191], off offset:64
	global_load_dwordx4 v[182:185], v[190:191], off offset:512
	global_load_dwordx4 v[186:189], v[190:191], off offset:576
	v_add_u32_e32 v190, 0xa0, v172
	v_ashrrev_i32_e32 v191, 31, v190
	v_lshlrev_b64 v[190:191], 12, v[190:191]
	v_lshl_add_u64 v[190:191], v[138:139], 0, v[190:191]
	v_lshl_add_u64 v[190:191], v[190:191], 0, v[136:137]
	s_waitcnt vmcnt(0) lgkmcnt(0)
	v_mul_f32_e64 v134, v134, s6
	v_mul_f32_e64 v135, v135, s6
	v_mul_f32_e64 v132, v132, s6
	v_mul_f32_e64 v133, v133, s6
	v_mul_f32_e64 v176, v176, s6
	v_mul_f32_e64 v177, v177, s6
	v_mul_f32_e64 v174, v174, s6
	v_mul_f32_e64 v175, v175, s6
	v_mul_f32_e64 v184, v184, s6
	v_mul_f32_e64 v185, v185, s6
	v_mul_f32_e64 v182, v182, s6
	v_mul_f32_e64 v183, v183, s6
	v_mul_f32_e64 v188, v188, s6
	v_mul_f32_e64 v189, v189, s6
	v_mul_f32_e64 v186, v186, s6
	v_mul_f32_e64 v187, v187, s6
	v_fma_f32 v122, v122, v156, v134
	v_fma_f32 v123, v123, v157, v135
	v_fma_f32 v120, v120, v158, v132
	v_fma_f32 v121, v121, v159, v133
	v_fma_f32 v90, v90, v160, v176
	v_fma_f32 v91, v91, v161, v177
	v_fma_f32 v88, v88, v162, v174
	v_fma_f32 v89, v89, v163, v175
	v_fma_f32 v58, v58, v164, v184
	v_fma_f32 v59, v59, v165, v185
	v_fma_f32 v56, v56, v166, v182
	v_fma_f32 v57, v57, v167, v183
	v_fma_f32 v26, v26, v168, v188
	v_fma_f32 v27, v27, v169, v189
	v_fma_f32 v24, v24, v170, v186
	v_fma_f32 v25, v25, v171, v187
	v_mbcnt_hi_u32_b32 v133, -1, v145
	global_load_dwordx4 v[174:177], v[190:191], off
	global_load_dwordx4 v[182:185], v[190:191], off offset:64
	global_load_dwordx4 v[186:189], v[190:191], off offset:512
	s_nop 0
	global_load_dwordx4 v[190:193], v[190:191], off offset:576
	v_and_b32_e32 v134, 64, v133
	v_add_u32_e32 v181, 64, v134
	v_add_u32_e32 v134, 0xb0, v172
	v_ashrrev_i32_e32 v135, 31, v134
	v_lshlrev_b64 v[134:135], 12, v[134:135]
	v_lshl_add_u64 v[134:135], v[138:139], 0, v[134:135]
	v_lshl_add_u64 v[134:135], v[134:135], 0, v[136:137]
	v_mov_b32_e32 v138, v93
	v_mov_b32_e32 v139, v94
	v_add_f32_e64 v138, v138, v194
	v_add_f32_e64 v139, v139, v195
	v_xor_b32_e32 v132, 16, v133
	v_add_f32_e32 v194, v138, v139
	v_add_f32_e32 v201, 0, v194
	v_cmp_lt_i32_e32 vcc, v132, v181
	s_waitcnt vmcnt(0) lgkmcnt(0)
;     __device__ __forceinline__ bool run(const f32x4 (&v)[2][2][4][2], const Unit& u, int wr, int wc, int fr, int fq, PG8_LAS unsigned char* lds, int wid, int lane) const {
;     ...
;                 float s = 0.f;
; #pragma unroll
;                 for (int bj = 0; bj < 2; ++bj)
; #pragma unroll
;                     for (int n = 0; n < 2; ++n) { const f32x4 x = v[ai][bj][m][n]; s += (x[0] + x[1]) + (x[2] + x[3]); }
;                 s += __shfl_xor(s, 16); s += __shfl_xor(s, 32);
;                 const float mw = s * (1.0f / 64.0f); float q = 0.f;
; #pragma unroll
;                 for (int bj = 0; bj < 2; ++bj)
; #pragma unroll
;                     for (int n = 0; n < 2; ++n) { const f32x4 d = v[ai][bj][m][n] - mw; q += (d[0] * d[0] + d[1] * d[1]) + (d[2] * d[2] + d[3] * d[3]); }
;                 q += __shfl_xor(q, 16); q += __shfl_xor(q, 32);
;                 if (fq == 0) P[(ai * HALF + wr * 64 + m * 16 + fr) * 4 + wc] = (f32x2v){mw, q};
;     __device__ __forceinline__ void fused(f32x4 (&acc)[2][2][4][2], const Unit& u, int wr, int wc, int fr, int fq, PG8_LAS unsigned char* lds, int wid, int lane) const {
;     ...
;                     for (int n = 0; n < 2; ++n) { const f32x4 xv = *(const f32x4*)(xin + off + bj * HALF + n * 16); acc[ai][bj][m][n] = xv * ALPHA_ + acc[ai][bj][m][n]; }
;                 asm volatile("" : "+v"(acc[ai][0][m][0]), "+v"(acc[ai][0][m][1]), "+v"(acc[ai][1][m][0]), "+v"(acc[ai][1][m][1]));
;                 if (m & 1) asm volatile("" ::: "memory"); }
	v_mul_f32_e64 v172, v176, s6
	v_mul_f32_e64 v173, v177, s6
	v_mul_f32_e64 v174, v174, s6
	v_mul_f32_e64 v175, v175, s6
	v_mul_f32_e64 v176, v184, s6
	v_mul_f32_e64 v177, v185, s6
	v_mul_f32_e64 v182, v182, s6
	v_mul_f32_e64 v183, v183, s6
	v_mul_f32_e64 v184, v188, s6
	v_mul_f32_e64 v185, v189, s6
	v_mul_f32_e64 v186, v186, s6
	v_mul_f32_e64 v187, v187, s6
	v_mul_f32_e64 v188, v192, s6
	v_mul_f32_e64 v189, v193, s6
	v_mul_f32_e64 v190, v190, s6
	v_mul_f32_e64 v191, v191, s6
	v_fma_f32 v130, v130, v156, v172
	v_fma_f32 v131, v131, v157, v173
	v_fma_f32 v128, v128, v158, v174
	v_fma_f32 v129, v129, v159, v175
	v_fma_f32 v98, v98, v160, v176
	v_fma_f32 v99, v99, v161, v177
	v_fma_f32 v96, v96, v162, v182
	v_fma_f32 v97, v97, v163, v183
	v_fma_f32 v66, v66, v164, v184
	v_fma_f32 v67, v67, v165, v185
	v_fma_f32 v64, v64, v166, v186
	v_fma_f32 v65, v65, v167, v187
	v_fma_f32 v34, v34, v168, v188
	v_fma_f32 v35, v35, v169, v189
	v_fma_f32 v32, v32, v170, v190
	v_fma_f32 v33, v33, v171, v191
	v_mov_b32_e32 v176, v60
	global_load_dwordx4 v[172:175], v[134:135], off
	global_load_dwordx4 v[182:185], v[134:135], off offset:64
	global_load_dwordx4 v[186:189], v[134:135], off offset:512
	global_load_dwordx4 v[190:193], v[134:135], off offset:576
	v_mov_b32_e32 v177, v63
	v_add_f32_e64 v176, v196, v176
	v_add_f32_e64 v177, v197, v177
	v_add_f32_e32 v135, v28, v29
	v_add_f32_e64 v138, v176, v176
	v_add_f32_e64 v139, v176, v177
	v_mov_b32_e32 v134, v4
	v_mov_b32_e32 v138, v6
	v_add_f32_e64 v134, v134, v198
	v_add_f32_e64 v135, v135, v199
	v_add_f32_e64 v138, v138, v200
	v_add_f32_e64 v139, v139, v201
	v_cndmask_b32_e32 v132, v133, v132, vcc
	v_add_f32_e64 v134, v134, v138
	v_add_f32_e64 v135, v135, v139
	v_lshlrev_b32_e32 v132, 2, v132
	v_add_f32_e32 v134, v134, v135
	ds_bpermute_b32 v135, v132, v134
	v_xor_b32_e32 v138, 32, v133
	v_cmp_lt_i32_e32 vcc, v138, v181
	s_waitcnt lgkmcnt(0)
	v_add_f32_e32 v134, v134, v135
	v_cndmask_b32_e32 v133, v133, v138, vcc
	v_lshlrev_b32_e32 v133, 2, v133
	ds_bpermute_b32 v135, v133, v134
	s_waitcnt lgkmcnt(0)
	v_add_f32_e32 v135, v134, v135
	v_fmamk_f32 v138, v135, 0xbc800000, v95
	v_fmamk_f32 v176, v135, 0xbc800000, v93
	v_fmamk_f32 v181, v135, 0xbc800000, v63
	v_fmamk_f32 v195, v135, 0xbc800000, v61
	v_fmamk_f32 v134, v135, 0xbc800000, v94
	v_fmamk_f32 v139, v135, 0xbc800000, v92
	v_fmamk_f32 v177, v135, 0xbc800000, v62
	v_fmamk_f32 v194, v135, 0xbc800000, v60
	v_fmamk_f32 v197, v135, 0xbc800000, v31
	v_fmamk_f32 v199, v135, 0xbc800000, v29
	v_mul_f32_e32 v176, v176, v176
	v_mul_f32_e32 v138, v138, v138
	v_mul_f32_e32 v195, v195, v195
	v_mul_f32_e32 v181, v181, v181
	v_fmamk_f32 v196, v135, 0xbc800000, v30
	v_fmamk_f32 v198, v135, 0xbc800000, v28
	v_fmamk_f32 v201, v135, 0xbc800000, v7
	v_fmamk_f32 v203, v135, 0xbc800000, v5
	v_mul_f32_e32 v199, v199, v199
	v_mul_f32_e32 v197, v197, v197
	v_fmac_f32_e32 v176, v139, v139
	v_fmac_f32_e32 v138, v134, v134
	v_fmac_f32_e32 v195, v194, v194
	v_fmac_f32_e32 v181, v177, v177
	v_fmamk_f32 v200, v135, 0xbc800000, v6
	v_fmamk_f32 v202, v135, 0xbc800000, v4
	v_mul_f32_e32 v203, v203, v203
	v_mul_f32_e32 v201, v201, v201
	v_fmac_f32_e32 v199, v198, v198
	v_fmac_f32_e32 v197, v196, v196
	v_add_f32_e32 v134, v176, v138
	v_add_f32_e32 v138, v195, v181
	v_fmac_f32_e32 v203, v202, v202
	v_fmac_f32_e32 v201, v200, v200
	v_add_f32_e32 v139, v199, v197
	v_add_f32_e32 v134, v134, v138
	v_add_f32_e32 v176, v203, v201
	v_add_f32_e32 v134, v139, v134
	v_add_f32_e32 v138, v176, v134
	ds_bpermute_b32 v139, v132, v138
	v_and_b32_e32 v134, 63, v149
	v_cmp_gt_u32_e32 vcc, 16, v134
	s_waitcnt lgkmcnt(0)
	v_add_f32_e32 v138, v138, v139
	ds_bpermute_b32 v139, v133, v138
	s_waitcnt vmcnt(0)
	v_mul_f32_e64 v174, v174, s6
	v_mul_f32_e64 v175, v175, s6
	v_mul_f32_e64 v172, v172, s6
	v_mul_f32_e64 v173, v173, s6
	v_mul_f32_e64 v176, v184, s6
	v_mul_f32_e64 v177, v185, s6
	v_mul_f32_e64 v182, v182, s6
	v_mul_f32_e64 v183, v183, s6
	v_mul_f32_e64 v184, v188, s6
	v_mul_f32_e64 v185, v189, s6
	v_mul_f32_e64 v186, v186, s6
	v_mul_f32_e64 v187, v187, s6
	v_mul_f32_e64 v188, v192, s6
	v_mul_f32_e64 v189, v193, s6
	v_mul_f32_e64 v190, v190, s6
	v_mul_f32_e64 v191, v191, s6
	v_fma_f32 v126, v126, v156, v174
	v_fma_f32 v127, v127, v157, v175
	v_fma_f32 v124, v124, v158, v172
	v_fma_f32 v125, v125, v159, v173
	v_fma_f32 v106, v106, v160, v176
	v_fma_f32 v107, v107, v161, v177
	v_fma_f32 v104, v104, v162, v182
	v_fma_f32 v105, v105, v163, v183
	v_fma_f32 v78, v78, v164, v184
	v_fma_f32 v79, v79, v165, v185
	v_fma_f32 v76, v76, v166, v186
	v_fma_f32 v77, v77, v167, v187
	v_fma_f32 v46, v46, v168, v188
	v_fma_f32 v47, v47, v169, v189
	v_fma_f32 v44, v44, v170, v190
	v_fma_f32 v45, v45, v171, v191
	s_lshl_b32 s6, s21, 3
	s_add_i32 s8, s6, 0
	s_and_saveexec_b64 s[6:7], vcc
	s_cbranch_execz .LBB0_394
	s_lshl_b32 s9, s51, 11
	s_add_i32 s9, s8, s9
	v_mul_f32_e32 v156, 0x3c800000, v135
	v_lshl_add_u32 v135, v151, 5, s9
	s_waitcnt lgkmcnt(0)
	v_add_f32_e32 v157, v138, v139
	ds_write_b64 v135, v[156:157]
;     __device__ __forceinline__ bool run(const f32x4 (&v)[2][2][4][2], const Unit& u, int wr, int wc, int fr, int fq, PG8_LAS unsigned char* lds, int wid, int lane) const {
;     ...
;                 float s = 0.f;
; #pragma unroll
;                 for (int bj = 0; bj < 2; ++bj)
; #pragma unroll
;                     for (int n = 0; n < 2; ++n) { const f32x4 x = v[ai][bj][m][n]; s += (x[0] + x[1]) + (x[2] + x[3]); }
;                 s += __shfl_xor(s, 16); s += __shfl_xor(s, 32);
;                 const float mw = s * (1.0f / 64.0f); float q = 0.f;
; #pragma unroll
;                 for (int bj = 0; bj < 2; ++bj)
; #pragma unroll
;                     for (int n = 0; n < 2; ++n) { const f32x4 d = v[ai][bj][m][n] - mw; q += (d[0] * d[0] + d[1] * d[1]) + (d[2] * d[2] + d[3] * d[3]); }
;                 q += __shfl_xor(q, 16); q += __shfl_xor(q, 32);
;                 if (fq == 0) P[(ai * HALF + wr * 64 + m * 16 + fr) * 4 + wc] = (f32x2v){mw, q};
.LBB0_394:
	s_or_b64 exec, exec, s[6:7]
	v_mov_b32_e32 v138, v101
	s_waitcnt lgkmcnt(0)
	v_mov_b32_e32 v139, v102
	v_mov_b32_e32 v156, v100
	v_mov_b32_e32 v157, v103
	v_add_f32_e64 v138, v138, v156
	v_add_f32_e64 v139, v139, v157
	v_mov_b32_e32 v156, v69
	v_mov_b32_e32 v157, v70
	v_mov_b32_e32 v158, v68
	v_mov_b32_e32 v159, v71
	v_add_f32_e64 v156, v156, v158
	v_add_f32_e64 v157, v157, v159
	v_add_f32_e32 v135, v138, v139
	v_add_f32_e64 v157, v156, v157
	v_add_f32_e64 v156, v156, v156
	v_add_f32_e32 v139, 0, v135
	v_add_f32_e32 v159, v36, v37
	v_add_f32_e32 v161, v38, v39
	v_mov_b32_e32 v158, v8
	v_mov_b32_e32 v160, v9
	v_mov_b32_e32 v156, v10
	v_mov_b32_e32 v138, v11
	v_add_f32_e64 v158, v158, v160
	v_add_f32_e64 v159, v159, v161
	v_add_f32_e64 v138, v156, v138
	v_add_f32_e64 v139, v157, v139
	s_nop 0
	v_add_f32_e64 v138, v158, v138
	v_add_f32_e64 v139, v159, v139
	s_nop 0
	v_add_f32_e32 v135, v138, v139
	ds_bpermute_b32 v138, v132, v135
	s_waitcnt lgkmcnt(0)
	v_add_f32_e32 v135, v135, v138
	ds_bpermute_b32 v138, v133, v135
	s_waitcnt lgkmcnt(0)
	v_add_f32_e32 v135, v135, v138
	v_fmamk_f32 v139, v135, 0xbc800000, v103
	v_fmamk_f32 v157, v135, 0xbc800000, v101
	v_fmamk_f32 v138, v135, 0xbc800000, v102
	v_fmamk_f32 v156, v135, 0xbc800000, v100
	v_mul_f32_e32 v157, v157, v157
	v_mul_f32_e32 v139, v139, v139
	v_fmac_f32_e32 v157, v156, v156
	v_fmac_f32_e32 v139, v138, v138
	v_fmamk_f32 v156, v135, 0xbc800000, v71
	v_fmamk_f32 v158, v135, 0xbc800000, v69
	v_add_f32_e32 v138, v157, v139
	v_fmamk_f32 v139, v135, 0xbc800000, v70
	v_fmamk_f32 v157, v135, 0xbc800000, v68
	v_mul_f32_e32 v158, v158, v158
	v_mul_f32_e32 v156, v156, v156
	v_fmac_f32_e32 v158, v157, v157
	v_fmac_f32_e32 v156, v139, v139
	v_add_f32_e32 v139, v158, v156
	v_fmamk_f32 v156, v135, 0xbc800000, v39
	v_fmamk_f32 v158, v135, 0xbc800000, v37
	v_add_f32_e32 v138, v138, v139
	v_fmamk_f32 v139, v135, 0xbc800000, v38
	v_fmamk_f32 v157, v135, 0xbc800000, v36
	v_mul_f32_e32 v158, v158, v158
	v_mul_f32_e32 v156, v156, v156
	v_fmac_f32_e32 v158, v157, v157
	v_fmac_f32_e32 v156, v139, v139
	v_add_f32_e32 v139, v158, v156
	v_fmamk_f32 v156, v135, 0xbc800000, v11
	v_fmamk_f32 v158, v135, 0xbc800000, v9
	v_add_f32_e32 v138, v139, v138
	v_fmamk_f32 v139, v135, 0xbc800000, v10
	v_fmamk_f32 v157, v135, 0xbc800000, v8
	v_mul_f32_e32 v158, v158, v158
	v_mul_f32_e32 v156, v156, v156
	v_fmac_f32_e32 v158, v157, v157
	v_fmac_f32_e32 v156, v139, v139
	v_add_f32_e32 v139, v158, v156
	v_add_f32_e32 v138, v139, v138
	ds_bpermute_b32 v139, v132, v138
	s_waitcnt lgkmcnt(0)
	v_add_f32_e32 v138, v138, v139
	ds_bpermute_b32 v139, v133, v138
	s_and_saveexec_b64 s[6:7], vcc
	s_cbranch_execz .LBB0_396
	s_lshl_b32 s9, s51, 11
	s_add_i32 s9, s8, s9
	v_mul_f32_e32 v156, 0x3c800000, v135
	v_lshl_add_u32 v135, v151, 5, s9
	s_waitcnt lgkmcnt(0)
	v_add_f32_e32 v157, v138, v139
	ds_write_b64 v135, v[156:157] offset:512
.LBB0_396:
	s_or_b64 exec, exec, s[6:7]
	v_mov_b32_e32 v138, v109
	s_waitcnt lgkmcnt(0)
	v_mov_b32_e32 v139, v110
	v_mov_b32_e32 v156, v108
	v_mov_b32_e32 v157, v111
	v_add_f32_e64 v138, v138, v156
	v_add_f32_e64 v139, v139, v157
	v_mov_b32_e32 v156, v73
	v_mov_b32_e32 v157, v74
	v_mov_b32_e32 v158, v72
	v_mov_b32_e32 v159, v75
	v_add_f32_e64 v156, v156, v158
	v_add_f32_e64 v157, v157, v159
	v_add_f32_e32 v135, v138, v139
	v_add_f32_e64 v157, v156, v157
	v_add_f32_e64 v156, v156, v156
	v_add_f32_e32 v139, 0, v135
	v_add_f32_e32 v159, v40, v41
	v_add_f32_e32 v161, v42, v43
	v_mov_b32_e32 v158, v12
	v_mov_b32_e32 v160, v13
	v_mov_b32_e32 v156, v14
	v_mov_b32_e32 v138, v15
	v_add_f32_e64 v158, v158, v160
	v_add_f32_e64 v159, v159, v161
	v_add_f32_e64 v138, v156, v138
	v_add_f32_e64 v139, v157, v139
	s_nop 0
	v_add_f32_e64 v138, v158, v138
	v_add_f32_e64 v139, v159, v139
	s_nop 0
	v_add_f32_e32 v135, v138, v139
	ds_bpermute_b32 v138, v132, v135
	s_waitcnt lgkmcnt(0)
	v_add_f32_e32 v135, v135, v138
	ds_bpermute_b32 v138, v133, v135
	s_waitcnt lgkmcnt(0)
	v_add_f32_e32 v135, v135, v138
	v_fmamk_f32 v139, v135, 0xbc800000, v111
	v_fmamk_f32 v157, v135, 0xbc800000, v109
	v_fmamk_f32 v138, v135, 0xbc800000, v110
	v_fmamk_f32 v156, v135, 0xbc800000, v108
	v_mul_f32_e32 v157, v157, v157
	v_mul_f32_e32 v139, v139, v139
	v_fmac_f32_e32 v157, v156, v156
	v_fmac_f32_e32 v139, v138, v138
	v_fmamk_f32 v156, v135, 0xbc800000, v75
	v_fmamk_f32 v158, v135, 0xbc800000, v73
	v_add_f32_e32 v138, v157, v139
	v_fmamk_f32 v139, v135, 0xbc800000, v74
	v_fmamk_f32 v157, v135, 0xbc800000, v72
	v_mul_f32_e32 v158, v158, v158
	v_mul_f32_e32 v156, v156, v156
	v_fmac_f32_e32 v158, v157, v157
	v_fmac_f32_e32 v156, v139, v139
	v_add_f32_e32 v139, v158, v156
	v_fmamk_f32 v156, v135, 0xbc800000, v43
	v_fmamk_f32 v158, v135, 0xbc800000, v41
	v_add_f32_e32 v138, v138, v139
	v_fmamk_f32 v139, v135, 0xbc800000, v42
	v_fmamk_f32 v157, v135, 0xbc800000, v40
	v_mul_f32_e32 v158, v158, v158
	v_mul_f32_e32 v156, v156, v156
	v_fmac_f32_e32 v158, v157, v157
	v_fmac_f32_e32 v156, v139, v139
	v_add_f32_e32 v139, v158, v156
	v_fmamk_f32 v156, v135, 0xbc800000, v15
	v_fmamk_f32 v158, v135, 0xbc800000, v13
	v_add_f32_e32 v138, v139, v138
	v_fmamk_f32 v139, v135, 0xbc800000, v14
	v_fmamk_f32 v157, v135, 0xbc800000, v12
	v_mul_f32_e32 v158, v158, v158
	v_mul_f32_e32 v156, v156, v156
	v_fmac_f32_e32 v158, v157, v157
	v_fmac_f32_e32 v156, v139, v139
	v_add_f32_e32 v139, v158, v156
	v_add_f32_e32 v138, v139, v138
	ds_bpermute_b32 v139, v132, v138
	s_waitcnt lgkmcnt(0)
	v_add_f32_e32 v138, v138, v139
	ds_bpermute_b32 v139, v133, v138
	s_and_saveexec_b64 s[6:7], vcc
	s_cbranch_execz .LBB0_398
	s_lshl_b32 s9, s51, 11
	s_add_i32 s9, s8, s9
	v_mul_f32_e32 v156, 0x3c800000, v135
	v_lshl_add_u32 v135, v151, 5, s9
	s_waitcnt lgkmcnt(0)
	v_add_f32_e32 v157, v138, v139
	ds_write_b64 v135, v[156:157] offset:1024
;     __device__ __forceinline__ bool run(const f32x4 (&v)[2][2][4][2], const Unit& u, int wr, int wc, int fr, int fq, PG8_LAS unsigned char* lds, int wid, int lane) const {
;     ...
;                 float s = 0.f;
; #pragma unroll
;                 for (int bj = 0; bj < 2; ++bj)
; #pragma unroll
;                     for (int n = 0; n < 2; ++n) { const f32x4 x = v[ai][bj][m][n]; s += (x[0] + x[1]) + (x[2] + x[3]); }
;                 s += __shfl_xor(s, 16); s += __shfl_xor(s, 32);
;                 const float mw = s * (1.0f / 64.0f); float q = 0.f;
; #pragma unroll
;                 for (int bj = 0; bj < 2; ++bj)
; #pragma unroll
;                     for (int n = 0; n < 2; ++n) { const f32x4 d = v[ai][bj][m][n] - mw; q += (d[0] * d[0] + d[1] * d[1]) + (d[2] * d[2] + d[3] * d[3]); }
;                 q += __shfl_xor(q, 16); q += __shfl_xor(q, 32);
;                 if (fq == 0) P[(ai * HALF + wr * 64 + m * 16 + fr) * 4 + wc] = (f32x2v){mw, q};
.LBB0_398:
	s_or_b64 exec, exec, s[6:7]
	v_mov_b32_e32 v138, v113
	s_waitcnt lgkmcnt(0)
	v_mov_b32_e32 v139, v114
	v_mov_b32_e32 v156, v112
	v_mov_b32_e32 v157, v115
	v_add_f32_e64 v138, v138, v156
	v_add_f32_e64 v139, v139, v157
	v_mov_b32_e32 v156, v81
	v_mov_b32_e32 v157, v82
	v_mov_b32_e32 v158, v80
	v_mov_b32_e32 v159, v83
	v_add_f32_e64 v156, v156, v158
	v_add_f32_e64 v157, v157, v159
	v_add_f32_e32 v135, v138, v139
	v_add_f32_e64 v157, v156, v157
	v_add_f32_e64 v156, v156, v156
	v_add_f32_e32 v139, 0, v135
	v_add_f32_e32 v159, v48, v49
	v_add_f32_e32 v161, v50, v51
	v_mov_b32_e32 v158, v16
	v_mov_b32_e32 v160, v17
	v_mov_b32_e32 v156, v18
	v_mov_b32_e32 v138, v19
	v_add_f32_e64 v158, v158, v160
	v_add_f32_e64 v159, v159, v161
	v_add_f32_e64 v138, v156, v138
	v_add_f32_e64 v139, v157, v139
	s_nop 0
	v_add_f32_e64 v138, v158, v138
	v_add_f32_e64 v139, v159, v139
	s_nop 0
	v_add_f32_e32 v135, v138, v139
	ds_bpermute_b32 v138, v132, v135
	s_waitcnt lgkmcnt(0)
	v_add_f32_e32 v135, v135, v138
	ds_bpermute_b32 v138, v133, v135
	s_waitcnt lgkmcnt(0)
	v_add_f32_e32 v135, v135, v138
	v_fmamk_f32 v139, v135, 0xbc800000, v115
	v_fmamk_f32 v157, v135, 0xbc800000, v113
	v_fmamk_f32 v138, v135, 0xbc800000, v114
	v_fmamk_f32 v156, v135, 0xbc800000, v112
	v_mul_f32_e32 v157, v157, v157
	v_mul_f32_e32 v139, v139, v139
	v_fmac_f32_e32 v157, v156, v156
	v_fmac_f32_e32 v139, v138, v138
	v_fmamk_f32 v156, v135, 0xbc800000, v83
	v_fmamk_f32 v158, v135, 0xbc800000, v81
	v_add_f32_e32 v138, v157, v139
	v_fmamk_f32 v139, v135, 0xbc800000, v82
	v_fmamk_f32 v157, v135, 0xbc800000, v80
	v_mul_f32_e32 v158, v158, v158
	v_mul_f32_e32 v156, v156, v156
	v_fmac_f32_e32 v158, v157, v157
	v_fmac_f32_e32 v156, v139, v139
	v_add_f32_e32 v139, v158, v156
	v_fmamk_f32 v156, v135, 0xbc800000, v51
	v_fmamk_f32 v158, v135, 0xbc800000, v49
	v_add_f32_e32 v138, v138, v139
	v_fmamk_f32 v139, v135, 0xbc800000, v50
	v_fmamk_f32 v157, v135, 0xbc800000, v48
	v_mul_f32_e32 v158, v158, v158
	v_mul_f32_e32 v156, v156, v156
	v_fmac_f32_e32 v158, v157, v157
	v_fmac_f32_e32 v156, v139, v139
	v_add_f32_e32 v139, v158, v156
	v_fmamk_f32 v156, v135, 0xbc800000, v19
	v_fmamk_f32 v158, v135, 0xbc800000, v17
	v_add_f32_e32 v138, v139, v138
	v_fmamk_f32 v139, v135, 0xbc800000, v18
	v_fmamk_f32 v157, v135, 0xbc800000, v16
	v_mul_f32_e32 v158, v158, v158
	v_mul_f32_e32 v156, v156, v156
	v_fmac_f32_e32 v158, v157, v157
	v_fmac_f32_e32 v156, v139, v139
	v_add_f32_e32 v139, v158, v156
	v_add_f32_e32 v138, v139, v138
	ds_bpermute_b32 v139, v132, v138
	s_waitcnt lgkmcnt(0)
	v_add_f32_e32 v138, v138, v139
	ds_bpermute_b32 v139, v133, v138
	s_and_saveexec_b64 s[6:7], vcc
	s_cbranch_execz .LBB0_400
	s_lshl_b32 s9, s51, 11
	s_add_i32 s9, s8, s9
	v_mul_f32_e32 v156, 0x3c800000, v135
	v_lshl_add_u32 v135, v151, 5, s9
	s_waitcnt lgkmcnt(0)
	v_add_f32_e32 v157, v138, v139
	ds_write_b64 v135, v[156:157] offset:1536
.LBB0_400:
	s_or_b64 exec, exec, s[6:7]
	v_mov_b32_e32 v138, v117
	s_waitcnt lgkmcnt(0)
	v_mov_b32_e32 v139, v118
	v_mov_b32_e32 v156, v116
	v_mov_b32_e32 v157, v119
	v_add_f32_e64 v138, v138, v156
	v_add_f32_e64 v139, v139, v157
	v_mov_b32_e32 v156, v85
	v_mov_b32_e32 v157, v86
	v_mov_b32_e32 v158, v84
	v_mov_b32_e32 v159, v87
	v_add_f32_e64 v156, v156, v158
	v_add_f32_e64 v157, v157, v159
	v_add_f32_e32 v135, v138, v139
	v_add_f32_e64 v157, v156, v157
	v_add_f32_e64 v156, v156, v156
	v_add_f32_e32 v139, 0, v135
	v_add_f32_e32 v159, v52, v53
	v_add_f32_e32 v161, v54, v55
	v_mov_b32_e32 v158, v20
	v_mov_b32_e32 v160, v21
	v_mov_b32_e32 v156, v22
	v_mov_b32_e32 v138, v23
	v_add_f32_e64 v158, v158, v160
	v_add_f32_e64 v159, v159, v161
	v_add_f32_e64 v138, v156, v138
	v_add_f32_e64 v139, v157, v139
	s_nop 0
	v_add_f32_e64 v138, v158, v138
	v_add_f32_e64 v139, v159, v139
	s_nop 0
	v_add_f32_e32 v135, v138, v139
	ds_bpermute_b32 v138, v132, v135
	s_waitcnt lgkmcnt(0)
	v_add_f32_e32 v135, v135, v138
	ds_bpermute_b32 v138, v133, v135
	s_waitcnt lgkmcnt(0)
	v_add_f32_e32 v135, v135, v138
	v_fmamk_f32 v139, v135, 0xbc800000, v119
	v_fmamk_f32 v157, v135, 0xbc800000, v117
	v_fmamk_f32 v138, v135, 0xbc800000, v118
	v_fmamk_f32 v156, v135, 0xbc800000, v116
	v_mul_f32_e32 v157, v157, v157
	v_mul_f32_e32 v139, v139, v139
	v_fmac_f32_e32 v157, v156, v156
	v_fmac_f32_e32 v139, v138, v138
	v_fmamk_f32 v156, v135, 0xbc800000, v87
	v_fmamk_f32 v158, v135, 0xbc800000, v85
	v_add_f32_e32 v138, v157, v139
	v_fmamk_f32 v139, v135, 0xbc800000, v86
	v_fmamk_f32 v157, v135, 0xbc800000, v84
	v_mul_f32_e32 v158, v158, v158
	v_mul_f32_e32 v156, v156, v156
	v_fmac_f32_e32 v158, v157, v157
	v_fmac_f32_e32 v156, v139, v139
	v_add_f32_e32 v139, v158, v156
	v_fmamk_f32 v156, v135, 0xbc800000, v55
	v_fmamk_f32 v158, v135, 0xbc800000, v53
	v_add_f32_e32 v138, v138, v139
	v_fmamk_f32 v139, v135, 0xbc800000, v54
	v_fmamk_f32 v157, v135, 0xbc800000, v52
	v_mul_f32_e32 v158, v158, v158
	v_mul_f32_e32 v156, v156, v156
	v_fmac_f32_e32 v158, v157, v157
	v_fmac_f32_e32 v156, v139, v139
	v_add_f32_e32 v139, v158, v156
	v_fmamk_f32 v156, v135, 0xbc800000, v23
	v_fmamk_f32 v158, v135, 0xbc800000, v21
	v_add_f32_e32 v138, v139, v138
	v_fmamk_f32 v139, v135, 0xbc800000, v22
	v_fmamk_f32 v157, v135, 0xbc800000, v20
	v_mul_f32_e32 v158, v158, v158
	v_mul_f32_e32 v156, v156, v156
	v_fmac_f32_e32 v158, v157, v157
	v_fmac_f32_e32 v156, v139, v139
	v_add_f32_e32 v139, v158, v156
	v_add_f32_e32 v138, v139, v138
	ds_bpermute_b32 v139, v132, v138
	s_waitcnt lgkmcnt(0)
	v_add_f32_e32 v138, v138, v139
	ds_bpermute_b32 v139, v133, v138
	s_and_saveexec_b64 s[6:7], vcc
	s_cbranch_execz .LBB0_402
	s_lshl_b32 s9, s51, 11
	s_add_i32 s9, s8, s9
	v_mul_f32_e32 v156, 0x3c800000, v135
	v_lshl_add_u32 v135, v151, 5, s9
	s_waitcnt lgkmcnt(0)
	v_add_f32_e32 v157, v138, v139
	ds_write_b64 v135, v[156:157] offset:4096
;     __device__ __forceinline__ bool run(const f32x4 (&v)[2][2][4][2], const Unit& u, int wr, int wc, int fr, int fq, PG8_LAS unsigned char* lds, int wid, int lane) const {
;     ...
;                 float s = 0.f;
; #pragma unroll
;                 for (int bj = 0; bj < 2; ++bj)
; #pragma unroll
;                     for (int n = 0; n < 2; ++n) { const f32x4 x = v[ai][bj][m][n]; s += (x[0] + x[1]) + (x[2] + x[3]); }
;                 s += __shfl_xor(s, 16); s += __shfl_xor(s, 32);
;                 const float mw = s * (1.0f / 64.0f); float q = 0.f;
; #pragma unroll
;                 for (int bj = 0; bj < 2; ++bj)
; #pragma unroll
;                     for (int n = 0; n < 2; ++n) { const f32x4 d = v[ai][bj][m][n] - mw; q += (d[0] * d[0] + d[1] * d[1]) + (d[2] * d[2] + d[3] * d[3]); }
;                 q += __shfl_xor(q, 16); q += __shfl_xor(q, 32);
;                 if (fq == 0) P[(ai * HALF + wr * 64 + m * 16 + fr) * 4 + wc] = (f32x2v){mw, q};
.LBB0_402:
	s_or_b64 exec, exec, s[6:7]
	v_mov_b32_e32 v138, v121
	s_waitcnt lgkmcnt(0)
	v_mov_b32_e32 v139, v122
	v_mov_b32_e32 v156, v120
	v_mov_b32_e32 v157, v123
	v_add_f32_e64 v138, v138, v156
	v_add_f32_e64 v139, v139, v157
	v_mov_b32_e32 v156, v89
	v_mov_b32_e32 v157, v90
	v_mov_b32_e32 v158, v88
	v_mov_b32_e32 v159, v91
	v_add_f32_e64 v156, v156, v158
	v_add_f32_e64 v157, v157, v159
	v_add_f32_e32 v135, v138, v139
	v_add_f32_e64 v157, v156, v157
	v_add_f32_e64 v156, v156, v156
	v_add_f32_e32 v139, 0, v135
	v_add_f32_e32 v159, v56, v57
	v_add_f32_e32 v161, v58, v59
	v_mov_b32_e32 v158, v24
	v_mov_b32_e32 v160, v25
	v_mov_b32_e32 v156, v26
	v_mov_b32_e32 v138, v27
	v_add_f32_e64 v158, v158, v160
	v_add_f32_e64 v159, v159, v161
	v_add_f32_e64 v138, v156, v138
	v_add_f32_e64 v139, v157, v139
	s_nop 0
	v_add_f32_e64 v138, v158, v138
	v_add_f32_e64 v139, v159, v139
	s_nop 0
	v_add_f32_e32 v135, v138, v139
	ds_bpermute_b32 v138, v132, v135
	s_waitcnt lgkmcnt(0)
	v_add_f32_e32 v135, v135, v138
	ds_bpermute_b32 v138, v133, v135
	s_waitcnt lgkmcnt(0)
	v_add_f32_e32 v135, v135, v138
	v_fmamk_f32 v139, v135, 0xbc800000, v123
	v_fmamk_f32 v157, v135, 0xbc800000, v121
	v_fmamk_f32 v138, v135, 0xbc800000, v122
	v_fmamk_f32 v156, v135, 0xbc800000, v120
	v_mul_f32_e32 v157, v157, v157
	v_mul_f32_e32 v139, v139, v139
	v_fmac_f32_e32 v157, v156, v156
	v_fmac_f32_e32 v139, v138, v138
	v_fmamk_f32 v156, v135, 0xbc800000, v91
	v_fmamk_f32 v158, v135, 0xbc800000, v89
	v_add_f32_e32 v138, v157, v139
	v_fmamk_f32 v139, v135, 0xbc800000, v90
	v_fmamk_f32 v157, v135, 0xbc800000, v88
	v_mul_f32_e32 v158, v158, v158
	v_mul_f32_e32 v156, v156, v156
	v_fmac_f32_e32 v158, v157, v157
	v_fmac_f32_e32 v156, v139, v139
	v_add_f32_e32 v139, v158, v156
	v_fmamk_f32 v156, v135, 0xbc800000, v59
	v_fmamk_f32 v158, v135, 0xbc800000, v57
	v_add_f32_e32 v138, v138, v139
	v_fmamk_f32 v139, v135, 0xbc800000, v58
	v_fmamk_f32 v157, v135, 0xbc800000, v56
	v_mul_f32_e32 v158, v158, v158
	v_mul_f32_e32 v156, v156, v156
	v_fmac_f32_e32 v158, v157, v157
	v_fmac_f32_e32 v156, v139, v139
	v_add_f32_e32 v139, v158, v156
	v_fmamk_f32 v156, v135, 0xbc800000, v27
	v_fmamk_f32 v158, v135, 0xbc800000, v25
	v_add_f32_e32 v138, v139, v138
	v_fmamk_f32 v139, v135, 0xbc800000, v26
	v_fmamk_f32 v157, v135, 0xbc800000, v24
	v_mul_f32_e32 v158, v158, v158
	v_mul_f32_e32 v156, v156, v156
	v_fmac_f32_e32 v158, v157, v157
	v_fmac_f32_e32 v156, v139, v139
	v_add_f32_e32 v139, v158, v156
	v_add_f32_e32 v138, v139, v138
	ds_bpermute_b32 v139, v132, v138
	s_waitcnt lgkmcnt(0)
	v_add_f32_e32 v138, v138, v139
	ds_bpermute_b32 v139, v133, v138
	s_and_saveexec_b64 s[6:7], vcc
	s_cbranch_execz .LBB0_404
	s_lshl_b32 s9, s51, 11
	s_add_i32 s9, s8, s9
	v_mul_f32_e32 v156, 0x3c800000, v135
	v_lshl_add_u32 v135, v151, 5, s9
	s_waitcnt lgkmcnt(0)
	v_add_f32_e32 v157, v138, v139
	ds_write_b64 v135, v[156:157] offset:4608
.LBB0_404:
	s_or_b64 exec, exec, s[6:7]
	v_mov_b32_e32 v138, v129
	s_waitcnt lgkmcnt(0)
	v_mov_b32_e32 v139, v130
	v_mov_b32_e32 v156, v128
	v_mov_b32_e32 v157, v131
	v_add_f32_e64 v138, v138, v156
	v_add_f32_e64 v139, v139, v157
	v_mov_b32_e32 v156, v97
	v_mov_b32_e32 v157, v98
	v_mov_b32_e32 v158, v96
	v_mov_b32_e32 v159, v99
	v_add_f32_e64 v156, v156, v158
	v_add_f32_e64 v157, v157, v159
	v_add_f32_e32 v135, v138, v139
	v_add_f32_e64 v157, v156, v157
	v_add_f32_e64 v156, v156, v156
	v_add_f32_e32 v139, 0, v135
	v_add_f32_e32 v159, v64, v65
	v_add_f32_e32 v161, v66, v67
	v_mov_b32_e32 v158, v32
	v_mov_b32_e32 v160, v33
	v_mov_b32_e32 v156, v34
	v_mov_b32_e32 v138, v35
	v_add_f32_e64 v158, v158, v160
	v_add_f32_e64 v159, v159, v161
	v_add_f32_e64 v138, v156, v138
	v_add_f32_e64 v139, v157, v139
	s_nop 0
	v_add_f32_e64 v138, v158, v138
	v_add_f32_e64 v139, v159, v139
	s_nop 0
	v_add_f32_e32 v135, v138, v139
	ds_bpermute_b32 v138, v132, v135
	s_waitcnt lgkmcnt(0)
	v_add_f32_e32 v135, v135, v138
	ds_bpermute_b32 v138, v133, v135
	s_waitcnt lgkmcnt(0)
	v_add_f32_e32 v135, v135, v138
	v_fmamk_f32 v139, v135, 0xbc800000, v131
	v_fmamk_f32 v157, v135, 0xbc800000, v129
	v_fmamk_f32 v138, v135, 0xbc800000, v130
	v_fmamk_f32 v156, v135, 0xbc800000, v128
	v_mul_f32_e32 v157, v157, v157
	v_mul_f32_e32 v139, v139, v139
	v_fmac_f32_e32 v157, v156, v156
	v_fmac_f32_e32 v139, v138, v138
	v_fmamk_f32 v156, v135, 0xbc800000, v99
	v_fmamk_f32 v158, v135, 0xbc800000, v97
	v_add_f32_e32 v138, v157, v139
	v_fmamk_f32 v139, v135, 0xbc800000, v98
	v_fmamk_f32 v157, v135, 0xbc800000, v96
	v_mul_f32_e32 v158, v158, v158
	v_mul_f32_e32 v156, v156, v156
	v_fmac_f32_e32 v158, v157, v157
	v_fmac_f32_e32 v156, v139, v139
	v_add_f32_e32 v139, v158, v156
	v_fmamk_f32 v156, v135, 0xbc800000, v67
	v_fmamk_f32 v158, v135, 0xbc800000, v65
	v_add_f32_e32 v138, v138, v139
	v_fmamk_f32 v139, v135, 0xbc800000, v66
	v_fmamk_f32 v157, v135, 0xbc800000, v64
	v_mul_f32_e32 v158, v158, v158
	v_mul_f32_e32 v156, v156, v156
	v_fmac_f32_e32 v158, v157, v157
	v_fmac_f32_e32 v156, v139, v139
	v_add_f32_e32 v139, v158, v156
	v_fmamk_f32 v156, v135, 0xbc800000, v35
	v_fmamk_f32 v158, v135, 0xbc800000, v33
	v_add_f32_e32 v138, v139, v138
	v_fmamk_f32 v139, v135, 0xbc800000, v34
	v_fmamk_f32 v157, v135, 0xbc800000, v32
	v_mul_f32_e32 v158, v158, v158
	v_mul_f32_e32 v156, v156, v156
	v_fmac_f32_e32 v158, v157, v157
	v_fmac_f32_e32 v156, v139, v139
	v_add_f32_e32 v139, v158, v156
	v_add_f32_e32 v138, v139, v138
	ds_bpermute_b32 v139, v132, v138
	s_waitcnt lgkmcnt(0)
	v_add_f32_e32 v138, v138, v139
	ds_bpermute_b32 v139, v133, v138
	s_and_saveexec_b64 s[6:7], vcc
	s_cbranch_execz .LBB0_406
	s_lshl_b32 s9, s51, 11
	s_add_i32 s9, s8, s9
	v_mul_f32_e32 v156, 0x3c800000, v135
	v_lshl_add_u32 v135, v151, 5, s9
	s_waitcnt lgkmcnt(0)
	v_add_f32_e32 v157, v138, v139
	ds_write_b64 v135, v[156:157] offset:5120
;     __device__ __forceinline__ bool run(const f32x4 (&v)[2][2][4][2], const Unit& u, int wr, int wc, int fr, int fq, PG8_LAS unsigned char* lds, int wid, int lane) const {
;     ...
;                 float s = 0.f;
; #pragma unroll
;                 for (int bj = 0; bj < 2; ++bj)
; #pragma unroll
;                     for (int n = 0; n < 2; ++n) { const f32x4 x = v[ai][bj][m][n]; s += (x[0] + x[1]) + (x[2] + x[3]); }
;                 s += __shfl_xor(s, 16); s += __shfl_xor(s, 32);
;                 const float mw = s * (1.0f / 64.0f); float q = 0.f;
; #pragma unroll
;                 for (int bj = 0; bj < 2; ++bj)
; #pragma unroll
;                     for (int n = 0; n < 2; ++n) { const f32x4 d = v[ai][bj][m][n] - mw; q += (d[0] * d[0] + d[1] * d[1]) + (d[2] * d[2] + d[3] * d[3]); }
;                 q += __shfl_xor(q, 16); q += __shfl_xor(q, 32);
;                 if (fq == 0) P[(ai * HALF + wr * 64 + m * 16 + fr) * 4 + wc] = (f32x2v){mw, q};
;     ...
;         const int row = wid * 32 + (lane & 31);
;         if (lane < 32) {
;             const f32x2v a = P[row * 4 + 0], b = P[row * 4 + 1], c = P[row * 4 + 2], d = P[row * 4 + 3];
;             const float mt = (a.x + b.x + c.x + d.x) * 0.25f;
;             const float da = a.x - mt, db = b.x - mt, dc = c.x - mt, dd = d.x - mt;
;             const float m2 = (a.y + b.y) + (c.y + d.y) + 64.0f * ((da * da + db * db) + (dc * dc + dd * dd));
;             unsigned long long* slot = (unsigned long long*)xbuf + ((size_t)(u.pm * BM + row) * 4 + u.pn);
;             __hip_atomic_store(slot, ((unsigned long long)__float_as_uint(m2) << 32) | __float_as_uint(mt), __ATOMIC_RELAXED, __HIP_MEMORY_SCOPE_AGENT);
.LBB0_406:
	s_or_b64 exec, exec, s[6:7]
	v_mov_b32_e32 v138, v125
	s_waitcnt lgkmcnt(0)
	v_mov_b32_e32 v139, v126
	v_mov_b32_e32 v156, v124
	v_mov_b32_e32 v157, v127
	v_add_f32_e64 v138, v138, v156
	v_add_f32_e64 v139, v139, v157
	v_mov_b32_e32 v156, v105
	v_mov_b32_e32 v157, v106
	v_mov_b32_e32 v158, v104
	v_mov_b32_e32 v159, v107
	v_add_f32_e64 v156, v156, v158
	v_add_f32_e64 v157, v157, v159
	v_add_f32_e32 v135, v138, v139
	v_add_f32_e64 v157, v156, v157
	v_add_f32_e64 v156, v156, v156
	v_add_f32_e32 v139, 0, v135
	v_add_f32_e32 v159, v76, v77
	v_add_f32_e32 v161, v78, v79
	v_mov_b32_e32 v158, v44
	v_mov_b32_e32 v160, v45
	v_mov_b32_e32 v156, v46
	v_mov_b32_e32 v138, v47
	v_add_f32_e64 v158, v158, v160
	v_add_f32_e64 v159, v159, v161
	v_add_f32_e64 v138, v156, v138
	v_add_f32_e64 v139, v157, v139
	s_nop 0
	v_add_f32_e64 v138, v158, v138
	v_add_f32_e64 v139, v159, v139
	s_nop 0
	v_add_f32_e32 v135, v138, v139
	ds_bpermute_b32 v138, v132, v135
	s_waitcnt lgkmcnt(0)
	v_add_f32_e32 v135, v135, v138
	ds_bpermute_b32 v138, v133, v135
	s_waitcnt lgkmcnt(0)
	v_add_f32_e32 v135, v135, v138
	v_fmamk_f32 v139, v135, 0xbc800000, v127
	v_fmamk_f32 v157, v135, 0xbc800000, v125
	v_fmamk_f32 v138, v135, 0xbc800000, v126
	v_fmamk_f32 v156, v135, 0xbc800000, v124
	v_mul_f32_e32 v157, v157, v157
	v_mul_f32_e32 v139, v139, v139
	v_fmac_f32_e32 v157, v156, v156
	v_fmac_f32_e32 v139, v138, v138
	v_fmamk_f32 v156, v135, 0xbc800000, v107
	v_fmamk_f32 v158, v135, 0xbc800000, v105
	v_add_f32_e32 v138, v157, v139
	v_fmamk_f32 v139, v135, 0xbc800000, v106
	v_fmamk_f32 v157, v135, 0xbc800000, v104
	v_mul_f32_e32 v158, v158, v158
	v_mul_f32_e32 v156, v156, v156
	v_fmac_f32_e32 v158, v157, v157
	v_fmac_f32_e32 v156, v139, v139
	v_add_f32_e32 v139, v158, v156
	v_fmamk_f32 v156, v135, 0xbc800000, v79
	v_fmamk_f32 v158, v135, 0xbc800000, v77
	v_add_f32_e32 v138, v138, v139
	v_fmamk_f32 v139, v135, 0xbc800000, v78
	v_fmamk_f32 v157, v135, 0xbc800000, v76
	v_mul_f32_e32 v158, v158, v158
	v_mul_f32_e32 v156, v156, v156
	v_fmac_f32_e32 v158, v157, v157
	v_fmac_f32_e32 v156, v139, v139
	v_add_f32_e32 v139, v158, v156
	v_fmamk_f32 v156, v135, 0xbc800000, v47
	v_fmamk_f32 v158, v135, 0xbc800000, v45
	v_add_f32_e32 v138, v139, v138
	v_fmamk_f32 v139, v135, 0xbc800000, v46
	v_fmamk_f32 v157, v135, 0xbc800000, v44
	v_mul_f32_e32 v158, v158, v158
	v_mul_f32_e32 v156, v156, v156
	v_fmac_f32_e32 v158, v157, v157
	v_fmac_f32_e32 v156, v139, v139
	v_add_f32_e32 v139, v158, v156
	v_add_f32_e32 v138, v139, v138
	ds_bpermute_b32 v132, v132, v138
	s_waitcnt lgkmcnt(0)
	v_add_f32_e32 v132, v138, v132
	ds_bpermute_b32 v133, v133, v132
	s_and_saveexec_b64 s[6:7], vcc
	s_cbranch_execz .LBB0_408
	s_lshl_b32 s9, s51, 11
	s_add_i32 s8, s8, s9
	v_mul_f32_e32 v138, 0x3c800000, v135
	v_lshl_add_u32 v135, v151, 5, s8
	s_waitcnt lgkmcnt(0)
	v_add_f32_e32 v139, v132, v133
	ds_write_b64 v135, v[138:139] offset:5632
.LBB0_408:
	s_or_b64 exec, exec, s[6:7]
	v_and_b32_e32 v132, 31, v149
	s_waitcnt lgkmcnt(0)
	s_barrier
	v_lshl_or_b32 v149, s15, 5, v132
	s_add_u32 s18, s12, 0x3780000
	v_add_u32_e32 v132, s20, v149
	s_addc_u32 s19, s13, 0
	v_cmp_gt_u32_e64 s[6:7], 32, v134
	s_waitcnt lgkmcnt(0)
	v_ashrrev_i32_e32 v133, 31, v132
	s_and_saveexec_b64 s[8:9], s[6:7]
	s_cbranch_execz .LBB0_410
	v_lshl_add_u32 v135, v149, 5, 0
	ds_read_b128 v[156:159], v135
	ds_read_b128 v[160:163], v135 offset:16
	s_ashr_i32 s15, s14, 31
	s_waitcnt lgkmcnt(1)
	v_add_f32_e32 v135, v156, v158
	s_waitcnt lgkmcnt(0)
	v_add_f32_e32 v135, v135, v160
	v_add_f32_e32 v135, v135, v162
	v_fmamk_f32 v139, v135, 0xbe800000, v156
	v_fmac_f32_e32 v158, 0xbe800000, v135
	v_fmamk_f32 v151, v135, 0xbe800000, v160
	v_fmac_f32_e32 v162, 0xbe800000, v135
	v_mul_f32_e32 v165, v139, v139
	v_mul_f32_e32 v167, v158, v158
	v_mul_f32_e32 v169, v151, v151
	v_mul_f32_e32 v171, v162, v162
	v_mov_b32_e32 v164, v157
	v_mov_b32_e32 v166, v159
	v_mov_b32_e32 v168, v161
	v_mov_b32_e32 v170, v163
	v_add_f32_e64 v156, v164, v166
	v_add_f32_e64 v157, v165, v167
	v_add_f32_e64 v158, v168, v170
	v_add_f32_e64 v159, v169, v171
	v_mul_f32_e32 v138, 0x3e800000, v135
	v_add_f32_e64 v156, v156, v158
	v_add_f32_e64 v157, v157, v159
	s_nop 0
	v_fmamk_f32 v139, v157, 0x42800000, v156
	v_lshlrev_b64 v[156:157], 5, v[132:133]
	v_lshl_add_u64 v[156:157], s[18:19], 0, v[156:157]
	v_lshl_add_u64 v[156:157], s[14:15], 3, v[156:157]
	global_store_dwordx2 v[156:157], v[138:139], off sc1

; __device__ __forceinline__ unsigned cvt_pk_bf16(float lo, float hi) { unsigned r; asm volatile("v_cvt_pk_bf16_f32 %0, %1, %2" : "=v"(r) : "v"(lo), "v"(hi)); return r; }
;     __device__ __forceinline__ void fused(f32x4 (&acc)[2][2][4][2], const Unit& u, int wr, int wc, int fr, int fq, PG8_LAS unsigned char* lds, int wid, int lane) const {
;     ...
; #pragma unroll
;         for (int bj = 0; bj < 2; ++bj)
; #pragma unroll
;             for (int n = 0; n < 2; ++n) {
;                 const int col = col0 + bj * HALF + n * 16;
;                 const f32x4 lg = *(const f32x4*)(lng + col), lb = *(const f32x4*)(lnb + col);
;                 f32x4 sc1 = (f32x4){1.f, 1.f, 1.f, 1.f}, sh = (f32x4){0.f, 0.f, 0.f, 0.f};
;                 if (DO_U) { sc1 = *(const f32x4*)(msc + mo + col) + 1.0f; sh = *(const f32x4*)(msh + mo + col); }
; #pragma unroll
;                 for (int ai = 0; ai < 2; ++ai)
; #pragma unroll
;                     for (int m = 0; m < 4; ++m) { const int r = ai * HALF + wr * 64 + m * 16 + fr; const f32x2v sr = S[r]; const size_t off = (size_t)(u.pm * BM + r) * 1024 + col;
;                         f32x4 y = (acc[ai][bj][m][n] - sr.x) * sr.y * lg + lb; if (bad) y = (f32x4){qnan, qnan, qnan, qnan};
;                         *(f32x4*)(out + off) = y;
;                         if (DO_U) { const f32x4 uu = y * sc1 + sh; u32x2v w; w.x = cvt_pk_bf16(uu[0], uu[1]); w.y = cvt_pk_bf16(uu[2], uu[3]); *(u32x2v*)(U + off) = w; } }
.LBB0_431:
	s_or_b64 exec, exec, s[8:9]
	s_add_u32 s6, s12, 0x3a00000
	s_addc_u32 s7, s13, 0
	s_add_u32 s8, s12, s16
	s_addc_u32 s9, s13, s17
	v_lshl_add_u64 v[174:175], s[8:9], 0, v[136:137]
	s_movk_i32 s8, 0x4000
	v_lshl_add_u64 v[156:157], v[0:1], 0, v[136:137]
	v_lshl_add_u64 v[158:159], v[2:3], 0, v[136:137]
	v_add_co_u32_e32 v136, vcc, s8, v174
	s_waitcnt lgkmcnt(0)
	s_barrier
	s_nop 0
	v_addc_co_u32_e32 v137, vcc, 0, v175, vcc
	s_movk_i32 s8, 0x3000
	global_load_dwordx4 v[132:135], v[156:157], off
	global_load_dwordx4 v[0:3], v[158:159], off
	global_load_dwordx4 v[160:163], v[136:137], off
	v_add_co_u32_e32 v136, vcc, s8, v174
	v_lshl_add_u32 v149, v147, 3, 0
	s_nop 0
	v_addc_co_u32_e32 v137, vcc, 0, v175, vcc
	global_load_dwordx4 v[136:139], v[136:137], off
	ds_read_b64 v[164:165], v149 offset:8192
	v_add_u32_e32 v176, s20, v147
	v_ashrrev_i32_e32 v177, 31, v176
	v_lshlrev_b64 v[170:171], 10, v[176:177]
	v_mov_b32_e32 v147, 0x7fc00000
	s_waitcnt lgkmcnt(0)
	v_sub_f32_e32 v93, v93, v164
	v_sub_f32_e32 v92, v92, v164
	v_sub_f32_e32 v95, v95, v164
	v_sub_f32_e32 v94, v94, v164
	v_mul_f32_e64 v92, v165, v92
	v_mul_f32_e64 v93, v165, v93
	v_lshl_add_u64 v[182:183], v[170:171], 0, v[154:155]
	v_mul_f32_e64 v94, v165, v94
	v_mul_f32_e64 v95, v165, v95
	v_cmp_eq_u32_e32 vcc, 0, v151
	v_lshl_add_u64 v[166:167], v[182:183], 2, v[152:153]
	v_lshl_add_u64 v[188:189], v[182:183], 1, s[6:7]
	v_add_u32_e32 v168, 16, v176
	v_ashrrev_i32_e32 v169, 31, v168
	v_lshlrev_b64 v[168:169], 10, v[168:169]
	v_lshl_add_u64 v[164:165], v[168:169], 0, v[154:155]
	v_add_u32_e32 v172, 32, v176
	v_ashrrev_i32_e32 v173, 31, v172
	v_add_u32_e32 v186, 48, v176
	v_ashrrev_i32_e32 v187, 31, v186
	s_mov_b64 s[8:9], 0x4000
	s_waitcnt vmcnt(0)
	v_fma_f32 v92, v132, v92, v0
	v_fma_f32 v93, v133, v93, v1
	v_fma_f32 v94, v134, v94, v2
	v_fma_f32 v95, v135, v95, v3
	v_cndmask_b32_e32 v183, v147, v93, vcc
	v_cndmask_b32_e32 v182, v147, v92, vcc
	v_add_f32_e64 v92, v160, 1.0
	v_add_f32_e64 v93, v161, 1.0
	v_cndmask_b32_e32 v185, v147, v95, vcc
	v_cndmask_b32_e32 v184, v147, v94, vcc
	v_add_f32_e64 v94, v162, 1.0
	v_add_f32_e64 v95, v163, 1.0
	v_fma_f32 v162, v92, v182, v136
	v_fma_f32 v163, v93, v183, v137
	global_store_dwordx4 v[166:167], v[182:185], off sc0 sc1
	v_fma_f32 v160, v94, v184, v138
	v_fma_f32 v161, v95, v185, v139
	v_cvt_pk_bf16_f32 v162, v162, v163
	s_nop 0
	v_cvt_pk_bf16_f32 v163, v160, v161
	global_store_dwordx2 v[188:189], v[162:163], off
	ds_read_b64 v[160:161], v149 offset:8320
	v_lshl_add_u64 v[162:163], v[164:165], 2, v[152:153]
	v_lshl_add_u64 v[164:165], v[164:165], 1, s[6:7]
	s_waitcnt lgkmcnt(0)
	v_sub_f32_e32 v103, v103, v160
	v_sub_f32_e32 v102, v102, v160
	v_sub_f32_e32 v101, v101, v160
	v_sub_f32_e32 v100, v100, v160
	v_mul_f32_e64 v100, v161, v100
	v_mul_f32_e64 v101, v161, v101
	v_mul_f32_e64 v102, v161, v102
	v_mul_f32_e64 v103, v161, v103
	v_fma_f32 v100, v132, v100, v0
	v_fma_f32 v101, v133, v101, v1
	v_fma_f32 v102, v134, v102, v2
	v_fma_f32 v103, v135, v103, v3
	v_cndmask_b32_e32 v101, v147, v101, vcc
	v_cndmask_b32_e32 v103, v147, v103, vcc
	v_cndmask_b32_e32 v102, v147, v102, vcc
	v_cndmask_b32_e32 v100, v147, v100, vcc
	global_store_dwordx4 v[162:163], v[100:103], off sc0 sc1
	s_nop 1
	v_fma_f32 v100, v92, v100, v136
	v_fma_f32 v101, v93, v101, v137
	v_fma_f32 v102, v94, v102, v138
	v_fma_f32 v103, v95, v103, v139
	v_cvt_pk_bf16_f32 v100, v100, v101
	s_nop 0
	v_cvt_pk_bf16_f32 v101, v102, v103
	global_store_dwordx2 v[164:165], v[100:101], off
	ds_read_b64 v[100:101], v149 offset:8448
	v_lshlrev_b64 v[164:165], 10, v[172:173]
	v_lshl_add_u64 v[102:103], v[164:165], 0, v[154:155]
	v_lshl_add_u64 v[160:161], v[102:103], 2, v[152:153]
	v_lshl_add_u64 v[172:173], v[102:103], 1, s[6:7]
	s_waitcnt lgkmcnt(0)
	v_sub_f32_e32 v103, v111, v100
	v_sub_f32_e32 v102, v110, v100
	v_sub_f32_e32 v109, v109, v100
	v_sub_f32_e32 v108, v108, v100
	v_mul_f32_e64 v108, v101, v108
	v_mul_f32_e64 v109, v101, v109
	v_mul_f32_e64 v100, v101, v102
	v_mul_f32_e64 v101, v101, v103
	v_fma_f32 v108, v132, v108, v0
	v_fma_f32 v109, v133, v109, v1
	v_fma_f32 v100, v134, v100, v2
	v_fma_f32 v101, v135, v101, v3
	v_lshlrev_b64 v[110:111], 10, v[186:187]
	v_cndmask_b32_e32 v103, v147, v101, vcc
	v_cndmask_b32_e32 v102, v147, v100, vcc
	v_cndmask_b32_e32 v101, v147, v109, vcc
	v_cndmask_b32_e32 v100, v147, v108, vcc
	global_store_dwordx4 v[160:161], v[100:103], off sc0 sc1
	v_lshl_add_u64 v[182:183], v[110:111], 0, v[154:155]
	s_nop 0
	v_fma_f32 v100, v92, v100, v136
	v_fma_f32 v101, v93, v101, v137
	v_fma_f32 v102, v94, v102, v138
	v_fma_f32 v103, v95, v103, v139
	v_cvt_pk_bf16_f32 v100, v100, v101
	s_nop 0
	v_cvt_pk_bf16_f32 v101, v102, v103
	global_store_dwordx2 v[172:173], v[100:101], off
	ds_read_b64 v[100:101], v149 offset:8576
	v_lshl_add_u64 v[172:173], v[174:175], 0, s[8:9]
	s_mov_b64 s[8:9], 0x3000
	s_waitcnt lgkmcnt(0)
	v_sub_f32_e32 v103, v115, v100
	v_sub_f32_e32 v102, v114, v100
	v_sub_f32_e32 v109, v113, v100
	v_sub_f32_e32 v108, v112, v100
	v_mul_f32_e64 v108, v101, v108
	v_mul_f32_e64 v109, v101, v109
	v_mul_f32_e64 v100, v101, v102
	v_mul_f32_e64 v101, v101, v103
	v_fma_f32 v108, v132, v108, v0
	v_fma_f32 v109, v133, v109, v1
	v_fma_f32 v100, v134, v100, v2
	v_fma_f32 v101, v135, v101, v3
	s_nop 0
	v_cndmask_b32_e32 v103, v147, v101, vcc
	v_cndmask_b32_e32 v102, v147, v100, vcc
	v_cndmask_b32_e32 v101, v147, v109, vcc
	v_cndmask_b32_e32 v100, v147, v108, vcc
	v_lshl_add_u64 v[108:109], v[182:183], 2, v[152:153]
	global_store_dwordx4 v[108:109], v[100:103], off sc0 sc1
	s_nop 1
	v_fma_f32 v102, v94, v102, v138
	v_fma_f32 v103, v95, v103, v139
	v_fma_f32 v100, v92, v100, v136
	v_fma_f32 v101, v93, v101, v137
	s_nop 0
	v_cvt_pk_bf16_f32 v100, v100, v101
	v_cvt_pk_bf16_f32 v101, v102, v103
	v_lshl_add_u64 v[102:103], v[182:183], 1, s[6:7]
	global_store_dwordx2 v[102:103], v[100:101], off
	ds_read_b64 v[100:101], v149 offset:9216
	v_add_u32_e32 v102, 0x80, v176
	v_ashrrev_i32_e32 v103, 31, v102
	v_lshlrev_b64 v[114:115], 10, v[102:103]
	v_lshl_add_u64 v[182:183], v[114:115], 0, v[154:155]
	s_waitcnt lgkmcnt(0)
; __device__ __forceinline__ unsigned cvt_pk_bf16(float lo, float hi) { unsigned r; asm volatile("v_cvt_pk_bf16_f32 %0, %1, %2" : "=v"(r) : "v"(lo), "v"(hi)); return r; }
;     __device__ __forceinline__ void fused(f32x4 (&acc)[2][2][4][2], const Unit& u, int wr, int wc, int fr, int fq, PG8_LAS unsigned char* lds, int wid, int lane) const {
;     ...
; #pragma unroll
;         for (int bj = 0; bj < 2; ++bj)
; #pragma unroll
;             for (int n = 0; n < 2; ++n) {
;                 const int col = col0 + bj * HALF + n * 16;
;                 const f32x4 lg = *(const f32x4*)(lng + col), lb = *(const f32x4*)(lnb + col);
;                 f32x4 sc1 = (f32x4){1.f, 1.f, 1.f, 1.f}, sh = (f32x4){0.f, 0.f, 0.f, 0.f};
;                 if (DO_U) { sc1 = *(const f32x4*)(msc + mo + col) + 1.0f; sh = *(const f32x4*)(msh + mo + col); }
; #pragma unroll
;                 for (int ai = 0; ai < 2; ++ai)
; #pragma unroll
;                     for (int m = 0; m < 4; ++m) { const int r = ai * HALF + wr * 64 + m * 16 + fr; const f32x2v sr = S[r]; const size_t off = (size_t)(u.pm * BM + r) * 1024 + col;
;                         f32x4 y = (acc[ai][bj][m][n] - sr.x) * sr.y * lg + lb; if (bad) y = (f32x4){qnan, qnan, qnan, qnan};
;                         *(f32x4*)(out + off) = y;
;                         if (DO_U) { const f32x4 uu = y * sc1 + sh; u32x2v w; w.x = cvt_pk_bf16(uu[0], uu[1]); w.y = cvt_pk_bf16(uu[2], uu[3]); *(u32x2v*)(U + off) = w; } }
	v_sub_f32_e32 v103, v119, v100
	v_sub_f32_e32 v102, v118, v100
	v_sub_f32_e32 v113, v117, v100
	v_sub_f32_e32 v112, v116, v100
	v_mul_f32_e64 v112, v101, v112
	v_mul_f32_e64 v113, v101, v113
	v_mul_f32_e64 v100, v101, v102
	v_mul_f32_e64 v101, v101, v103
	v_fma_f32 v112, v132, v112, v0
	v_fma_f32 v113, v133, v113, v1
	v_fma_f32 v100, v134, v100, v2
	v_fma_f32 v101, v135, v101, v3
	s_nop 0
	v_cndmask_b32_e32 v103, v147, v101, vcc
	v_cndmask_b32_e32 v102, v147, v100, vcc
	v_cndmask_b32_e32 v101, v147, v113, vcc
	v_cndmask_b32_e32 v100, v147, v112, vcc
	v_lshl_add_u64 v[112:113], v[182:183], 2, v[152:153]
	global_store_dwordx4 v[112:113], v[100:103], off sc0 sc1
	s_nop 1
	v_fma_f32 v102, v94, v102, v138
	v_fma_f32 v103, v95, v103, v139
	v_fma_f32 v100, v92, v100, v136
	v_fma_f32 v101, v93, v101, v137
	s_nop 0
	v_cvt_pk_bf16_f32 v100, v100, v101
	v_cvt_pk_bf16_f32 v101, v102, v103
	v_lshl_add_u64 v[102:103], v[182:183], 1, s[6:7]
	global_store_dwordx2 v[102:103], v[100:101], off
	ds_read_b64 v[100:101], v149 offset:9344
	v_add_u32_e32 v102, 0x90, v176
	v_ashrrev_i32_e32 v103, 31, v102
	v_lshlrev_b64 v[118:119], 10, v[102:103]
	v_lshl_add_u64 v[182:183], v[118:119], 0, v[154:155]
	s_waitcnt lgkmcnt(0)
	v_sub_f32_e32 v103, v123, v100
	v_sub_f32_e32 v102, v122, v100
	v_sub_f32_e32 v117, v121, v100
	v_sub_f32_e32 v116, v120, v100
	v_mul_f32_e64 v116, v101, v116
	v_mul_f32_e64 v117, v101, v117
	v_mul_f32_e64 v100, v101, v102
	v_mul_f32_e64 v101, v101, v103
	v_fma_f32 v116, v132, v116, v0
	v_fma_f32 v117, v133, v117, v1
	v_fma_f32 v100, v134, v100, v2
	v_fma_f32 v101, v135, v101, v3
	s_nop 0
	v_cndmask_b32_e32 v103, v147, v101, vcc
	v_cndmask_b32_e32 v102, v147, v100, vcc
	v_cndmask_b32_e32 v101, v147, v117, vcc
	v_cndmask_b32_e32 v100, v147, v116, vcc
	v_lshl_add_u64 v[116:117], v[182:183], 2, v[152:153]
	global_store_dwordx4 v[116:117], v[100:103], off sc0 sc1
	s_nop 1
	v_fma_f32 v102, v94, v102, v138
	v_fma_f32 v103, v95, v103, v139
	v_fma_f32 v100, v92, v100, v136
	v_fma_f32 v101, v93, v101, v137
	s_nop 0
	v_cvt_pk_bf16_f32 v100, v100, v101
	v_cvt_pk_bf16_f32 v101, v102, v103
	v_lshl_add_u64 v[102:103], v[182:183], 1, s[6:7]
	global_store_dwordx2 v[102:103], v[100:101], off
	ds_read_b64 v[100:101], v149 offset:9472
	v_add_u32_e32 v102, 0xa0, v176
	v_ashrrev_i32_e32 v103, 31, v102
	v_lshlrev_b64 v[122:123], 10, v[102:103]
	v_lshl_add_u64 v[182:183], v[122:123], 0, v[154:155]
	s_waitcnt lgkmcnt(0)
	v_sub_f32_e32 v103, v131, v100
	v_sub_f32_e32 v102, v130, v100
	v_sub_f32_e32 v121, v129, v100
	v_sub_f32_e32 v120, v128, v100
	v_mul_f32_e64 v120, v101, v120
	v_mul_f32_e64 v121, v101, v121
	v_mul_f32_e64 v100, v101, v102
	v_mul_f32_e64 v101, v101, v103
	v_fma_f32 v120, v132, v120, v0
	v_fma_f32 v121, v133, v121, v1
	v_fma_f32 v100, v134, v100, v2
	v_fma_f32 v101, v135, v101, v3
	v_or_b32_e32 v130, 16, v154
	v_cndmask_b32_e32 v103, v147, v101, vcc
	v_cndmask_b32_e32 v102, v147, v100, vcc
	v_cndmask_b32_e32 v101, v147, v121, vcc
	v_cndmask_b32_e32 v100, v147, v120, vcc
	v_lshl_add_u64 v[120:121], v[182:183], 2, v[152:153]
	global_store_dwordx4 v[120:121], v[100:103], off sc0 sc1
	v_ashrrev_i32_e32 v131, 31, v130
	s_nop 0
	v_fma_f32 v102, v94, v102, v138
	v_fma_f32 v103, v95, v103, v139
	v_fma_f32 v100, v92, v100, v136
	v_fma_f32 v101, v93, v101, v137
	s_nop 0
	v_cvt_pk_bf16_f32 v100, v100, v101
	v_cvt_pk_bf16_f32 v101, v102, v103
	v_lshl_add_u64 v[102:103], v[182:183], 1, s[6:7]
	global_store_dwordx2 v[102:103], v[100:101], off
	ds_read_b64 v[100:101], v149 offset:9600
	v_add_u32_e32 v102, 0xb0, v176
	v_ashrrev_i32_e32 v103, 31, v102
	v_lshlrev_b64 v[128:129], 10, v[102:103]
	v_lshl_add_u64 v[102:103], v[128:129], 0, v[154:155]
	s_waitcnt lgkmcnt(0)
	v_sub_f32_e32 v127, v127, v100
	v_sub_f32_e32 v126, v126, v100
	v_sub_f32_e32 v125, v125, v100
	v_sub_f32_e32 v124, v124, v100
	v_mul_f32_e64 v124, v101, v124
	v_mul_f32_e64 v125, v101, v125
	v_mul_f32_e64 v100, v101, v126
	v_mul_f32_e64 v101, v101, v127
	v_fma_f32 v0, v132, v124, v0
	v_fma_f32 v1, v133, v125, v1
	v_fma_f32 v2, v134, v100, v2
	v_fma_f32 v3, v135, v101, v3
	v_cndmask_b32_e32 v1, v147, v1, vcc
	v_cndmask_b32_e32 v3, v147, v3, vcc
	v_cndmask_b32_e32 v2, v147, v2, vcc
	v_cndmask_b32_e32 v0, v147, v0, vcc
	v_lshl_add_u64 v[124:125], v[102:103], 2, v[152:153]
	global_store_dwordx4 v[124:125], v[0:3], off sc0 sc1
	v_lshl_add_u64 v[126:127], v[174:175], 0, s[8:9]
	s_nop 0
	v_fma_f32 v2, v94, v2, v138
	v_fma_f32 v3, v95, v3, v139
	v_fma_f32 v0, v92, v0, v136
	v_fma_f32 v1, v93, v1, v137
	v_lshl_add_u64 v[138:139], v[170:171], 0, v[130:131]
	v_cvt_pk_bf16_f32 v0, v0, v1
	v_cvt_pk_bf16_f32 v1, v2, v3
	v_lshl_add_u64 v[2:3], v[102:103], 1, s[6:7]
	global_store_dwordx2 v[2:3], v[0:1], off
	global_load_dwordx4 v[132:135], v[172:173], off offset:64
	global_load_dwordx4 v[92:95], v[156:157], off offset:64
	global_load_dwordx4 v[100:103], v[158:159], off offset:64
	ds_read_b64 v[136:137], v149 offset:8192
	global_load_dwordx4 v[0:3], v[126:127], off offset:64
	s_waitcnt lgkmcnt(0)
	v_sub_f32_e32 v63, v63, v136
	v_sub_f32_e32 v62, v62, v136
	v_sub_f32_e32 v61, v61, v136
	v_sub_f32_e32 v60, v60, v136
	v_mul_f32_e64 v152, v137, v60
	v_mul_f32_e64 v153, v137, v61
	v_mul_f32_e64 v136, v137, v62
	v_mul_f32_e64 v137, v137, v63
	s_waitcnt vmcnt(0)
; __device__ __forceinline__ unsigned cvt_pk_bf16(float lo, float hi) { unsigned r; asm volatile("v_cvt_pk_bf16_f32 %0, %1, %2" : "=v"(r) : "v"(lo), "v"(hi)); return r; }
;     __device__ __forceinline__ void fused(f32x4 (&acc)[2][2][4][2], const Unit& u, int wr, int wc, int fr, int fq, PG8_LAS unsigned char* lds, int wid, int lane) const {
;     ...
; #pragma unroll
;         for (int bj = 0; bj < 2; ++bj)
; #pragma unroll
;             for (int n = 0; n < 2; ++n) {
;                 const int col = col0 + bj * HALF + n * 16;
;                 const f32x4 lg = *(const f32x4*)(lng + col), lb = *(const f32x4*)(lnb + col);
;                 f32x4 sc1 = (f32x4){1.f, 1.f, 1.f, 1.f}, sh = (f32x4){0.f, 0.f, 0.f, 0.f};
;                 if (DO_U) { sc1 = *(const f32x4*)(msc + mo + col) + 1.0f; sh = *(const f32x4*)(msh + mo + col); }
; #pragma unroll
;                 for (int ai = 0; ai < 2; ++ai)
; #pragma unroll
;                     for (int m = 0; m < 4; ++m) { const int r = ai * HALF + wr * 64 + m * 16 + fr; const f32x2v sr = S[r]; const size_t off = (size_t)(u.pm * BM + r) * 1024 + col;
;                         f32x4 y = (acc[ai][bj][m][n] - sr.x) * sr.y * lg + lb; if (bad) y = (f32x4){qnan, qnan, qnan, qnan};
;                         *(f32x4*)(out + off) = y;
;                         if (DO_U) { const f32x4 uu = y * sc1 + sh; u32x2v w; w.x = cvt_pk_bf16(uu[0], uu[1]); w.y = cvt_pk_bf16(uu[2], uu[3]); *(u32x2v*)(U + off) = w; } }
	v_add_f32_e64 v60, v132, 1.0
	v_add_f32_e64 v61, v133, 1.0
	v_add_f32_e64 v62, v134, 1.0
	v_add_f32_e64 v63, v135, 1.0
	v_fma_f32 v132, v94, v136, v102
	v_fma_f32 v133, v95, v137, v103
	v_fma_f32 v136, v92, v152, v100
	v_fma_f32 v137, v93, v153, v101
	v_cndmask_b32_e32 v135, v147, v133, vcc
	v_cndmask_b32_e32 v134, v147, v132, vcc
	v_cndmask_b32_e32 v133, v147, v137, vcc
	v_cndmask_b32_e32 v132, v147, v136, vcc
	global_store_dwordx4 v[166:167], v[132:135], off offset:64 sc0 sc1
	s_nop 1
	v_fma_f32 v134, v62, v134, v2
	v_fma_f32 v135, v63, v135, v3
	v_fma_f32 v132, v60, v132, v0
	v_fma_f32 v133, v61, v133, v1
	s_nop 0
	v_cvt_pk_bf16_f32 v132, v132, v133
	v_cvt_pk_bf16_f32 v133, v134, v135
	v_lshl_add_u64 v[134:135], v[138:139], 1, s[6:7]
	global_store_dwordx2 v[134:135], v[132:133], off
	ds_read_b64 v[132:133], v149 offset:8320
	v_lshl_add_u64 v[134:135], v[168:169], 0, v[130:131]
	s_waitcnt lgkmcnt(0)
	v_sub_f32_e32 v71, v71, v132
	v_sub_f32_e32 v70, v70, v132
	v_sub_f32_e32 v69, v69, v132
	v_sub_f32_e32 v68, v68, v132
	v_mul_f32_e64 v68, v133, v68
	v_mul_f32_e64 v69, v133, v69
	v_mul_f32_e64 v70, v133, v70
	v_mul_f32_e64 v71, v133, v71
	v_fma_f32 v68, v92, v68, v100
	v_fma_f32 v69, v93, v69, v101
	v_fma_f32 v70, v94, v70, v102
	v_fma_f32 v71, v95, v71, v103
	v_cndmask_b32_e32 v69, v147, v69, vcc
	v_cndmask_b32_e32 v71, v147, v71, vcc
	v_cndmask_b32_e32 v70, v147, v70, vcc
	v_cndmask_b32_e32 v68, v147, v68, vcc
	global_store_dwordx4 v[162:163], v[68:71], off offset:64 sc0 sc1
	v_lshl_add_u64 v[132:133], v[164:165], 0, v[130:131]
	s_nop 0
	v_fma_f32 v70, v62, v70, v2
	v_fma_f32 v71, v63, v71, v3
	v_fma_f32 v68, v60, v68, v0
	v_fma_f32 v69, v61, v69, v1
	s_nop 0
	v_cvt_pk_bf16_f32 v68, v68, v69
	v_cvt_pk_bf16_f32 v69, v70, v71
	v_lshl_add_u64 v[70:71], v[134:135], 1, s[6:7]
	global_store_dwordx2 v[70:71], v[68:69], off
	ds_read_b64 v[68:69], v149 offset:8448
	s_waitcnt lgkmcnt(0)
	v_sub_f32_e32 v71, v75, v68
	v_sub_f32_e32 v70, v74, v68
	v_sub_f32_e32 v73, v73, v68
	v_sub_f32_e32 v72, v72, v68
	v_mul_f32_e64 v72, v69, v72
	v_mul_f32_e64 v73, v69, v73
	v_mul_f32_e64 v68, v69, v70
	v_mul_f32_e64 v69, v69, v71
	v_fma_f32 v72, v92, v72, v100
	v_fma_f32 v73, v93, v73, v101
	v_fma_f32 v68, v94, v68, v102
	v_fma_f32 v69, v95, v69, v103
	s_nop 0
	v_cndmask_b32_e32 v71, v147, v69, vcc
	v_cndmask_b32_e32 v70, v147, v68, vcc
	v_cndmask_b32_e32 v69, v147, v73, vcc
	v_cndmask_b32_e32 v68, v147, v72, vcc
	global_store_dwordx4 v[160:161], v[68:71], off offset:64 sc0 sc1
	v_lshl_add_u64 v[72:73], v[110:111], 0, v[130:131]
	s_nop 0
	v_fma_f32 v70, v62, v70, v2
	v_fma_f32 v71, v63, v71, v3
	v_fma_f32 v68, v60, v68, v0
	v_fma_f32 v69, v61, v69, v1
	s_nop 0
	v_cvt_pk_bf16_f32 v68, v68, v69
	v_cvt_pk_bf16_f32 v69, v70, v71
	v_lshl_add_u64 v[70:71], v[132:133], 1, s[6:7]
	global_store_dwordx2 v[70:71], v[68:69], off
	ds_read_b64 v[68:69], v149 offset:8576
	s_waitcnt lgkmcnt(0)
	v_sub_f32_e32 v71, v83, v68
	v_sub_f32_e32 v70, v82, v68
	v_sub_f32_e32 v75, v81, v68
	v_sub_f32_e32 v74, v80, v68
	v_mul_f32_e64 v74, v69, v74
	v_mul_f32_e64 v75, v69, v75
	v_mul_f32_e64 v68, v69, v70
	v_mul_f32_e64 v69, v69, v71
	v_fma_f32 v74, v92, v74, v100
	v_fma_f32 v75, v93, v75, v101
	v_fma_f32 v68, v94, v68, v102
	v_fma_f32 v69, v95, v69, v103
	s_nop 0
	v_cndmask_b32_e32 v71, v147, v69, vcc
	v_cndmask_b32_e32 v70, v147, v68, vcc
	v_cndmask_b32_e32 v69, v147, v75, vcc
	v_cndmask_b32_e32 v68, v147, v74, vcc
	global_store_dwordx4 v[108:109], v[68:71], off offset:64 sc0 sc1
	s_nop 1
	v_fma_f32 v70, v62, v70, v2
	v_fma_f32 v71, v63, v71, v3
	v_fma_f32 v68, v60, v68, v0
	v_fma_f32 v69, v61, v69, v1
	s_nop 0
	v_cvt_pk_bf16_f32 v68, v68, v69
	v_cvt_pk_bf16_f32 v69, v70, v71
	v_lshl_add_u64 v[70:71], v[72:73], 1, s[6:7]
	global_store_dwordx2 v[70:71], v[68:69], off
	ds_read_b64 v[68:69], v149 offset:9216
	v_lshl_add_u64 v[72:73], v[114:115], 0, v[130:131]
	s_waitcnt lgkmcnt(0)
	v_sub_f32_e32 v71, v87, v68
	v_sub_f32_e32 v70, v86, v68
	v_sub_f32_e32 v75, v85, v68
	v_sub_f32_e32 v74, v84, v68
	v_mul_f32_e64 v74, v69, v74
	v_mul_f32_e64 v75, v69, v75
	v_mul_f32_e64 v68, v69, v70
	v_mul_f32_e64 v69, v69, v71
	v_fma_f32 v74, v92, v74, v100
	v_fma_f32 v75, v93, v75, v101
	v_fma_f32 v68, v94, v68, v102
	v_fma_f32 v69, v95, v69, v103
	s_nop 0
	v_cndmask_b32_e32 v71, v147, v69, vcc
	v_cndmask_b32_e32 v70, v147, v68, vcc
	v_cndmask_b32_e32 v69, v147, v75, vcc
	v_cndmask_b32_e32 v68, v147, v74, vcc
	global_store_dwordx4 v[112:113], v[68:71], off offset:64 sc0 sc1
	s_nop 1
	v_fma_f32 v70, v62, v70, v2
	v_fma_f32 v71, v63, v71, v3
	v_fma_f32 v68, v60, v68, v0
	v_fma_f32 v69, v61, v69, v1
	s_nop 0
	v_cvt_pk_bf16_f32 v68, v68, v69
	v_cvt_pk_bf16_f32 v69, v70, v71
	v_lshl_add_u64 v[70:71], v[72:73], 1, s[6:7]
	global_store_dwordx2 v[70:71], v[68:69], off
	ds_read_b64 v[68:69], v149 offset:9344
	v_lshl_add_u64 v[72:73], v[118:119], 0, v[130:131]
	s_waitcnt lgkmcnt(0)
	v_sub_f32_e32 v71, v91, v68
	v_sub_f32_e32 v70, v90, v68
	v_sub_f32_e32 v75, v89, v68
	v_sub_f32_e32 v74, v88, v68
	v_mul_f32_e64 v74, v69, v74
	v_mul_f32_e64 v75, v69, v75
	v_mul_f32_e64 v68, v69, v70
	v_mul_f32_e64 v69, v69, v71
	v_fma_f32 v74, v92, v74, v100
	v_fma_f32 v75, v93, v75, v101
	v_fma_f32 v68, v94, v68, v102
	v_fma_f32 v69, v95, v69, v103
	s_nop 0
	v_cndmask_b32_e32 v71, v147, v69, vcc
	v_cndmask_b32_e32 v70, v147, v68, vcc
	v_cndmask_b32_e32 v69, v147, v75, vcc
	v_cndmask_b32_e32 v68, v147, v74, vcc
	global_store_dwordx4 v[116:117], v[68:71], off offset:64 sc0 sc1
	s_nop 1
	v_fma_f32 v70, v62, v70, v2
	v_fma_f32 v71, v63, v71, v3
	v_fma_f32 v68, v60, v68, v0
	v_fma_f32 v69, v61, v69, v1
	s_nop 0
	v_cvt_pk_bf16_f32 v68, v68, v69
	v_cvt_pk_bf16_f32 v69, v70, v71
	v_lshl_add_u64 v[70:71], v[72:73], 1, s[6:7]
	global_store_dwordx2 v[70:71], v[68:69], off
	ds_read_b64 v[68:69], v149 offset:9472
	v_lshl_add_u64 v[72:73], v[122:123], 0, v[130:131]
	s_waitcnt lgkmcnt(0)
; __device__ __forceinline__ unsigned cvt_pk_bf16(float lo, float hi) { unsigned r; asm volatile("v_cvt_pk_bf16_f32 %0, %1, %2" : "=v"(r) : "v"(lo), "v"(hi)); return r; }
;     __device__ __forceinline__ void fused(f32x4 (&acc)[2][2][4][2], const Unit& u, int wr, int wc, int fr, int fq, PG8_LAS unsigned char* lds, int wid, int lane) const {
;     ...
; #pragma unroll
;         for (int bj = 0; bj < 2; ++bj)
; #pragma unroll
;             for (int n = 0; n < 2; ++n) {
;                 const int col = col0 + bj * HALF + n * 16;
;                 const f32x4 lg = *(const f32x4*)(lng + col), lb = *(const f32x4*)(lnb + col);
;                 f32x4 sc1 = (f32x4){1.f, 1.f, 1.f, 1.f}, sh = (f32x4){0.f, 0.f, 0.f, 0.f};
;                 if (DO_U) { sc1 = *(const f32x4*)(msc + mo + col) + 1.0f; sh = *(const f32x4*)(msh + mo + col); }
; #pragma unroll
;                 for (int ai = 0; ai < 2; ++ai)
; #pragma unroll
;                     for (int m = 0; m < 4; ++m) { const int r = ai * HALF + wr * 64 + m * 16 + fr; const f32x2v sr = S[r]; const size_t off = (size_t)(u.pm * BM + r) * 1024 + col;
;                         f32x4 y = (acc[ai][bj][m][n] - sr.x) * sr.y * lg + lb; if (bad) y = (f32x4){qnan, qnan, qnan, qnan};
;                         *(f32x4*)(out + off) = y;
;                         if (DO_U) { const f32x4 uu = y * sc1 + sh; u32x2v w; w.x = cvt_pk_bf16(uu[0], uu[1]); w.y = cvt_pk_bf16(uu[2], uu[3]); *(u32x2v*)(U + off) = w; } }
	v_sub_f32_e32 v71, v99, v68
	v_sub_f32_e32 v70, v98, v68
	v_sub_f32_e32 v75, v97, v68
	v_sub_f32_e32 v74, v96, v68
	v_mul_f32_e64 v74, v69, v74
	v_mul_f32_e64 v75, v69, v75
	v_mul_f32_e64 v68, v69, v70
	v_mul_f32_e64 v69, v69, v71
	v_fma_f32 v74, v92, v74, v100
	v_fma_f32 v75, v93, v75, v101
	v_fma_f32 v68, v94, v68, v102
	v_fma_f32 v69, v95, v69, v103
	s_nop 0
	v_cndmask_b32_e32 v71, v147, v69, vcc
	v_cndmask_b32_e32 v70, v147, v68, vcc
	v_cndmask_b32_e32 v69, v147, v75, vcc
	v_cndmask_b32_e32 v68, v147, v74, vcc
	global_store_dwordx4 v[120:121], v[68:71], off offset:64 sc0 sc1
	s_nop 1
	v_fma_f32 v70, v62, v70, v2
	v_fma_f32 v71, v63, v71, v3
	v_fma_f32 v68, v60, v68, v0
	v_fma_f32 v69, v61, v69, v1
	s_nop 0
	v_cvt_pk_bf16_f32 v68, v68, v69
	v_cvt_pk_bf16_f32 v69, v70, v71
	v_lshl_add_u64 v[70:71], v[72:73], 1, s[6:7]
	global_store_dwordx2 v[70:71], v[68:69], off
	ds_read_b64 v[68:69], v149 offset:9600
	v_lshl_add_u64 v[72:73], v[128:129], 0, v[130:131]
	s_waitcnt lgkmcnt(0)
	v_sub_f32_e32 v71, v107, v68
	v_sub_f32_e32 v70, v106, v68
	v_sub_f32_e32 v75, v105, v68
	v_sub_f32_e32 v74, v104, v68
	v_mul_f32_e64 v74, v69, v74
	v_mul_f32_e64 v75, v69, v75
	v_mul_f32_e64 v68, v69, v70
	v_mul_f32_e64 v69, v69, v71
	v_fma_f32 v74, v92, v74, v100
	v_fma_f32 v75, v93, v75, v101
	v_fma_f32 v68, v94, v68, v102
	v_fma_f32 v69, v95, v69, v103
	s_nop 0
	v_cndmask_b32_e32 v71, v147, v69, vcc
	v_cndmask_b32_e32 v70, v147, v68, vcc
	v_cndmask_b32_e32 v69, v147, v75, vcc
	v_cndmask_b32_e32 v68, v147, v74, vcc
	v_fma_f32 v2, v62, v70, v2
	v_fma_f32 v3, v63, v71, v3
	v_fma_f32 v0, v60, v68, v0
	v_fma_f32 v1, v61, v69, v1
	global_store_dwordx4 v[124:125], v[68:71], off offset:64 sc0 sc1
	v_cvt_pk_bf16_f32 v0, v0, v1
	v_cvt_pk_bf16_f32 v1, v2, v3
	v_lshl_add_u64 v[2:3], v[72:73], 1, s[6:7]
	global_store_dwordx2 v[2:3], v[0:1], off
	global_load_dwordx4 v[80:83], v[172:173], off offset:512
	global_load_dwordx4 v[60:63], v[156:157], off offset:512
	global_load_dwordx4 v[68:71], v[158:159], off offset:512
	s_nop 0
	global_load_dwordx4 v[0:3], v[126:127], off offset:512
	ds_read_b64 v[84:85], v149 offset:8192
	v_or_b32_e32 v74, 0x80, v154
	v_ashrrev_i32_e32 v75, 31, v74
	v_lshl_add_u64 v[86:87], v[170:171], 0, v[74:75]
	s_waitcnt lgkmcnt(0)
	v_sub_f32_e32 v89, v31, v84
	v_sub_f32_e32 v88, v30, v84
	v_sub_f32_e32 v29, v29, v84
	v_sub_f32_e32 v28, v28, v84
	v_mul_f32_e64 v28, v85, v28
	v_mul_f32_e64 v29, v85, v29
	s_waitcnt vmcnt(0)
	v_add_f32_e64 v30, v80, 1.0
	v_add_f32_e64 v31, v81, 1.0
	v_mul_f32_e64 v80, v85, v88
	v_mul_f32_e64 v81, v85, v89
	v_fma_f32 v28, v60, v28, v68
	v_fma_f32 v29, v61, v29, v69
	v_fma_f32 v80, v62, v80, v70
	v_fma_f32 v81, v63, v81, v71
	v_add_f32_e64 v72, v82, 1.0
	v_add_f32_e64 v73, v83, 1.0
	v_cndmask_b32_e32 v83, v147, v81, vcc
	v_cndmask_b32_e32 v82, v147, v80, vcc
	v_cndmask_b32_e32 v81, v147, v29, vcc
	v_cndmask_b32_e32 v80, v147, v28, vcc
	global_store_dwordx4 v[166:167], v[80:83], off offset:512 sc0 sc1
	v_fma_f32 v28, v72, v82, v2
	v_fma_f32 v29, v73, v83, v3
	s_nop 0
	v_fma_f32 v80, v30, v80, v0
	v_fma_f32 v81, v31, v81, v1
	s_nop 0
	v_cvt_pk_bf16_f32 v80, v80, v81
	v_cvt_pk_bf16_f32 v81, v28, v29
	v_lshl_add_u64 v[28:29], v[86:87], 1, s[6:7]
	global_store_dwordx2 v[28:29], v[80:81], off
	ds_read_b64 v[28:29], v149 offset:8320
	v_lshl_add_u64 v[80:81], v[168:169], 0, v[74:75]
	s_waitcnt lgkmcnt(0)
	v_sub_f32_e32 v39, v39, v28
	v_sub_f32_e32 v38, v38, v28
	v_sub_f32_e32 v37, v37, v28
	v_sub_f32_e32 v36, v36, v28
	v_mul_f32_e64 v36, v29, v36
	v_mul_f32_e64 v37, v29, v37
	v_mul_f32_e64 v28, v29, v38
	v_mul_f32_e64 v29, v29, v39
	v_fma_f32 v36, v60, v36, v68
	v_fma_f32 v37, v61, v37, v69
	v_fma_f32 v28, v62, v28, v70
	v_fma_f32 v29, v63, v29, v71
	v_cndmask_b32_e32 v37, v147, v37, vcc
	v_cndmask_b32_e32 v39, v147, v29, vcc
	v_cndmask_b32_e32 v38, v147, v28, vcc
	v_cndmask_b32_e32 v36, v147, v36, vcc
	global_store_dwordx4 v[162:163], v[36:39], off offset:512 sc0 sc1
	v_fma_f32 v28, v72, v38, v2
	v_fma_f32 v29, v73, v39, v3
	s_nop 0
	v_fma_f32 v36, v30, v36, v0
	v_fma_f32 v37, v31, v37, v1
	s_nop 0
	v_cvt_pk_bf16_f32 v36, v36, v37
	v_cvt_pk_bf16_f32 v37, v28, v29
	v_lshl_add_u64 v[28:29], v[80:81], 1, s[6:7]
	global_store_dwordx2 v[28:29], v[36:37], off
	ds_read_b64 v[28:29], v149 offset:8448
	v_lshl_add_u64 v[80:81], v[164:165], 0, v[74:75]
	s_waitcnt lgkmcnt(0)
	v_sub_f32_e32 v37, v43, v28
	v_sub_f32_e32 v36, v42, v28
	v_sub_f32_e32 v39, v41, v28
	v_sub_f32_e32 v38, v40, v28
	v_mul_f32_e64 v38, v29, v38
	v_mul_f32_e64 v39, v29, v39
	v_mul_f32_e64 v28, v29, v36
	v_mul_f32_e64 v29, v29, v37
	v_fma_f32 v36, v60, v38, v68
	v_fma_f32 v37, v61, v39, v69
	v_fma_f32 v28, v62, v28, v70
	v_fma_f32 v29, v63, v29, v71
	v_cndmask_b32_e32 v37, v147, v37, vcc
	v_cndmask_b32_e32 v39, v147, v29, vcc
	v_cndmask_b32_e32 v38, v147, v28, vcc
	v_cndmask_b32_e32 v36, v147, v36, vcc
	global_store_dwordx4 v[160:161], v[36:39], off offset:512 sc0 sc1
	v_fma_f32 v28, v72, v38, v2
	v_fma_f32 v29, v73, v39, v3
	v_lshl_add_u64 v[40:41], v[110:111], 0, v[74:75]
	v_fma_f32 v36, v30, v36, v0
	v_fma_f32 v37, v31, v37, v1
	s_nop 0
	v_cvt_pk_bf16_f32 v36, v36, v37
	v_cvt_pk_bf16_f32 v37, v28, v29
	v_lshl_add_u64 v[28:29], v[80:81], 1, s[6:7]
	global_store_dwordx2 v[28:29], v[36:37], off
	ds_read_b64 v[28:29], v149 offset:8576
	s_waitcnt lgkmcnt(0)
; __device__ __forceinline__ unsigned cvt_pk_bf16(float lo, float hi) { unsigned r; asm volatile("v_cvt_pk_bf16_f32 %0, %1, %2" : "=v"(r) : "v"(lo), "v"(hi)); return r; }
;     __device__ __forceinline__ void fused(f32x4 (&acc)[2][2][4][2], const Unit& u, int wr, int wc, int fr, int fq, PG8_LAS unsigned char* lds, int wid, int lane) const {
;     ...
; #pragma unroll
;         for (int bj = 0; bj < 2; ++bj)
; #pragma unroll
;             for (int n = 0; n < 2; ++n) {
;                 const int col = col0 + bj * HALF + n * 16;
;                 const f32x4 lg = *(const f32x4*)(lng + col), lb = *(const f32x4*)(lnb + col);
;                 f32x4 sc1 = (f32x4){1.f, 1.f, 1.f, 1.f}, sh = (f32x4){0.f, 0.f, 0.f, 0.f};
;                 if (DO_U) { sc1 = *(const f32x4*)(msc + mo + col) + 1.0f; sh = *(const f32x4*)(msh + mo + col); }
; #pragma unroll
;                 for (int ai = 0; ai < 2; ++ai)
; #pragma unroll
;                     for (int m = 0; m < 4; ++m) { const int r = ai * HALF + wr * 64 + m * 16 + fr; const f32x2v sr = S[r]; const size_t off = (size_t)(u.pm * BM + r) * 1024 + col;
;                         f32x4 y = (acc[ai][bj][m][n] - sr.x) * sr.y * lg + lb; if (bad) y = (f32x4){qnan, qnan, qnan, qnan};
;                         *(f32x4*)(out + off) = y;
;                         if (DO_U) { const f32x4 uu = y * sc1 + sh; u32x2v w; w.x = cvt_pk_bf16(uu[0], uu[1]); w.y = cvt_pk_bf16(uu[2], uu[3]); *(u32x2v*)(U + off) = w; } }
	v_sub_f32_e32 v37, v51, v28
	v_sub_f32_e32 v36, v50, v28
	v_sub_f32_e32 v39, v49, v28
	v_sub_f32_e32 v38, v48, v28
	v_mul_f32_e64 v38, v29, v38
	v_mul_f32_e64 v39, v29, v39
	v_mul_f32_e64 v28, v29, v36
	v_mul_f32_e64 v29, v29, v37
	v_fma_f32 v36, v60, v38, v68
	v_fma_f32 v37, v61, v39, v69
	v_fma_f32 v28, v62, v28, v70
	v_fma_f32 v29, v63, v29, v71
	v_cndmask_b32_e32 v37, v147, v37, vcc
	v_cndmask_b32_e32 v39, v147, v29, vcc
	v_cndmask_b32_e32 v38, v147, v28, vcc
	v_cndmask_b32_e32 v36, v147, v36, vcc
	global_store_dwordx4 v[108:109], v[36:39], off offset:512 sc0 sc1
	v_fma_f32 v28, v72, v38, v2
	v_fma_f32 v29, v73, v39, v3
	v_or_b32_e32 v48, 0x90, v154
	v_fma_f32 v36, v30, v36, v0
	v_fma_f32 v37, v31, v37, v1
	v_ashrrev_i32_e32 v49, 31, v48
	v_cvt_pk_bf16_f32 v36, v36, v37
	v_cvt_pk_bf16_f32 v37, v28, v29
	v_lshl_add_u64 v[28:29], v[40:41], 1, s[6:7]
	global_store_dwordx2 v[28:29], v[36:37], off
	ds_read_b64 v[28:29], v149 offset:9216
	v_lshl_add_u64 v[40:41], v[114:115], 0, v[74:75]
	s_waitcnt lgkmcnt(0)
	v_sub_f32_e32 v37, v55, v28
	v_sub_f32_e32 v36, v54, v28
	v_sub_f32_e32 v39, v53, v28
	v_sub_f32_e32 v38, v52, v28
	v_mul_f32_e64 v38, v29, v38
	v_mul_f32_e64 v39, v29, v39
	v_mul_f32_e64 v28, v29, v36
	v_mul_f32_e64 v29, v29, v37
	v_fma_f32 v36, v60, v38, v68
	v_fma_f32 v37, v61, v39, v69
	v_fma_f32 v28, v62, v28, v70
	v_fma_f32 v29, v63, v29, v71
	v_cndmask_b32_e32 v37, v147, v37, vcc
	v_cndmask_b32_e32 v39, v147, v29, vcc
	v_cndmask_b32_e32 v38, v147, v28, vcc
	v_cndmask_b32_e32 v36, v147, v36, vcc
	global_store_dwordx4 v[112:113], v[36:39], off offset:512 sc0 sc1
	v_fma_f32 v28, v72, v38, v2
	v_fma_f32 v29, v73, v39, v3
	v_lshl_add_u64 v[52:53], v[170:171], 0, v[48:49]
	v_fma_f32 v36, v30, v36, v0
	v_fma_f32 v37, v31, v37, v1
	s_nop 0
	v_cvt_pk_bf16_f32 v36, v36, v37
	v_cvt_pk_bf16_f32 v37, v28, v29
	v_lshl_add_u64 v[28:29], v[40:41], 1, s[6:7]
	global_store_dwordx2 v[28:29], v[36:37], off
	ds_read_b64 v[28:29], v149 offset:9344
	v_lshl_add_u64 v[40:41], v[118:119], 0, v[74:75]
	s_waitcnt lgkmcnt(0)
	v_sub_f32_e32 v37, v59, v28
	v_sub_f32_e32 v36, v58, v28
	v_sub_f32_e32 v39, v57, v28
	v_sub_f32_e32 v38, v56, v28
	v_mul_f32_e64 v38, v29, v38
	v_mul_f32_e64 v39, v29, v39
	v_mul_f32_e64 v28, v29, v36
	v_mul_f32_e64 v29, v29, v37
	v_fma_f32 v36, v60, v38, v68
	v_fma_f32 v37, v61, v39, v69
	v_fma_f32 v28, v62, v28, v70
	v_fma_f32 v29, v63, v29, v71
	v_cndmask_b32_e32 v37, v147, v37, vcc
	v_cndmask_b32_e32 v39, v147, v29, vcc
	v_cndmask_b32_e32 v38, v147, v28, vcc
	v_cndmask_b32_e32 v36, v147, v36, vcc
	global_store_dwordx4 v[116:117], v[36:39], off offset:512 sc0 sc1
	v_fma_f32 v28, v72, v38, v2
	v_fma_f32 v29, v73, v39, v3
	s_nop 0
	v_fma_f32 v36, v30, v36, v0
	v_fma_f32 v37, v31, v37, v1
	s_nop 0
	v_cvt_pk_bf16_f32 v36, v36, v37
	v_cvt_pk_bf16_f32 v37, v28, v29
	v_lshl_add_u64 v[28:29], v[40:41], 1, s[6:7]
	global_store_dwordx2 v[28:29], v[36:37], off
	ds_read_b64 v[28:29], v149 offset:9472
	v_lshl_add_u64 v[40:41], v[122:123], 0, v[74:75]
	s_waitcnt lgkmcnt(0)
	v_sub_f32_e32 v37, v67, v28
	v_sub_f32_e32 v36, v66, v28
	v_sub_f32_e32 v39, v65, v28
	v_sub_f32_e32 v38, v64, v28
	v_mul_f32_e64 v38, v29, v38
	v_mul_f32_e64 v39, v29, v39
	v_mul_f32_e64 v28, v29, v36
	v_mul_f32_e64 v29, v29, v37
	v_fma_f32 v36, v60, v38, v68
	v_fma_f32 v37, v61, v39, v69
	v_fma_f32 v28, v62, v28, v70
	v_fma_f32 v29, v63, v29, v71
	v_cndmask_b32_e32 v37, v147, v37, vcc
	v_cndmask_b32_e32 v39, v147, v29, vcc
	v_cndmask_b32_e32 v38, v147, v28, vcc
	v_cndmask_b32_e32 v36, v147, v36, vcc
	global_store_dwordx4 v[120:121], v[36:39], off offset:512 sc0 sc1
	v_fma_f32 v28, v72, v38, v2
	v_fma_f32 v29, v73, v39, v3
	s_nop 0
	v_fma_f32 v36, v30, v36, v0
	v_fma_f32 v37, v31, v37, v1
	s_nop 0
	v_cvt_pk_bf16_f32 v36, v36, v37
	v_cvt_pk_bf16_f32 v37, v28, v29
	v_lshl_add_u64 v[28:29], v[40:41], 1, s[6:7]
	global_store_dwordx2 v[28:29], v[36:37], off
	ds_read_b64 v[28:29], v149 offset:9600
	v_lshl_add_u64 v[40:41], v[128:129], 0, v[74:75]
	s_waitcnt lgkmcnt(0)
	v_sub_f32_e32 v37, v79, v28
	v_sub_f32_e32 v36, v78, v28
	v_sub_f32_e32 v39, v77, v28
	v_sub_f32_e32 v38, v76, v28
	v_mul_f32_e64 v38, v29, v38
	v_mul_f32_e64 v39, v29, v39
	v_mul_f32_e64 v28, v29, v36
	v_mul_f32_e64 v29, v29, v37
	v_fma_f32 v36, v60, v38, v68
	v_fma_f32 v37, v61, v39, v69
	v_fma_f32 v28, v62, v28, v70
	v_fma_f32 v29, v63, v29, v71
	v_cndmask_b32_e32 v37, v147, v37, vcc
	v_cndmask_b32_e32 v39, v147, v29, vcc
	v_cndmask_b32_e32 v38, v147, v28, vcc
	v_cndmask_b32_e32 v36, v147, v36, vcc
	v_fma_f32 v2, v72, v38, v2
	v_fma_f32 v3, v73, v39, v3
	v_fma_f32 v0, v30, v36, v0
	v_fma_f32 v1, v31, v37, v1
	global_store_dwordx4 v[124:125], v[36:39], off offset:512 sc0 sc1
	v_cvt_pk_bf16_f32 v0, v0, v1
	v_cvt_pk_bf16_f32 v1, v2, v3
	v_lshl_add_u64 v[2:3], v[40:41], 1, s[6:7]
	global_store_dwordx2 v[2:3], v[0:1], off
	global_load_dwordx4 v[40:43], v[172:173], off offset:576
	global_load_dwordx4 v[28:31], v[156:157], off offset:576
	global_load_dwordx4 v[36:39], v[158:159], off offset:576
	s_nop 0
	global_load_dwordx4 v[0:3], v[126:127], off offset:576
	ds_read_b64 v[50:51], v149 offset:8192
	s_waitcnt lgkmcnt(0)
	v_sub_f32_e32 v7, v7, v50
	v_sub_f32_e32 v6, v6, v50
	v_sub_f32_e32 v5, v5, v50
	v_sub_f32_e32 v4, v4, v50
	v_mul_f32_e64 v4, v51, v4
	v_mul_f32_e64 v5, v51, v5
	v_mul_f32_e64 v6, v51, v6
	v_mul_f32_e64 v7, v51, v7
	v_lshl_add_u64 v[50:51], v[168:169], 0, v[48:49]
	s_waitcnt vmcnt(0)
; __device__ __forceinline__ unsigned cvt_pk_bf16(float lo, float hi) { unsigned r; asm volatile("v_cvt_pk_bf16_f32 %0, %1, %2" : "=v"(r) : "v"(lo), "v"(hi)); return r; }
;     __device__ __forceinline__ void fused(f32x4 (&acc)[2][2][4][2], const Unit& u, int wr, int wc, int fr, int fq, PG8_LAS unsigned char* lds, int wid, int lane) const {
;     ...
; #pragma unroll
;         for (int bj = 0; bj < 2; ++bj)
; #pragma unroll
;             for (int n = 0; n < 2; ++n) {
;                 const int col = col0 + bj * HALF + n * 16;
;                 const f32x4 lg = *(const f32x4*)(lng + col), lb = *(const f32x4*)(lnb + col);
;                 f32x4 sc1 = (f32x4){1.f, 1.f, 1.f, 1.f}, sh = (f32x4){0.f, 0.f, 0.f, 0.f};
;                 if (DO_U) { sc1 = *(const f32x4*)(msc + mo + col) + 1.0f; sh = *(const f32x4*)(msh + mo + col); }
; #pragma unroll
;                 for (int ai = 0; ai < 2; ++ai)
; #pragma unroll
;                     for (int m = 0; m < 4; ++m) { const int r = ai * HALF + wr * 64 + m * 16 + fr; const f32x2v sr = S[r]; const size_t off = (size_t)(u.pm * BM + r) * 1024 + col;
;                         f32x4 y = (acc[ai][bj][m][n] - sr.x) * sr.y * lg + lb; if (bad) y = (f32x4){qnan, qnan, qnan, qnan};
;                         *(f32x4*)(out + off) = y;
;                         if (DO_U) { const f32x4 uu = y * sc1 + sh; u32x2v w; w.x = cvt_pk_bf16(uu[0], uu[1]); w.y = cvt_pk_bf16(uu[2], uu[3]); *(u32x2v*)(U + off) = w; } }
	v_add_f32_e64 v42, v42, 1.0
	v_add_f32_e64 v43, v43, 1.0
	v_add_f32_e64 v40, v40, 1.0
	v_add_f32_e64 v41, v41, 1.0
	v_fma_f32 v6, v30, v6, v38
	v_fma_f32 v7, v31, v7, v39
	v_fma_f32 v4, v28, v4, v36
	v_fma_f32 v5, v29, v5, v37
	v_cndmask_b32_e32 v7, v147, v7, vcc
	v_cndmask_b32_e32 v6, v147, v6, vcc
	v_cndmask_b32_e32 v5, v147, v5, vcc
	v_cndmask_b32_e32 v4, v147, v4, vcc
	global_store_dwordx4 v[166:167], v[4:7], off offset:576 sc0 sc1
	s_nop 1
	v_fma_f32 v6, v42, v6, v2
	v_fma_f32 v7, v43, v7, v3
	v_fma_f32 v4, v40, v4, v0
	v_fma_f32 v5, v41, v5, v1
	s_nop 0
	v_cvt_pk_bf16_f32 v4, v4, v5
	v_cvt_pk_bf16_f32 v5, v6, v7
	v_lshl_add_u64 v[6:7], v[52:53], 1, s[6:7]
	global_store_dwordx2 v[6:7], v[4:5], off
	ds_read_b64 v[4:5], v149 offset:8320
	s_waitcnt lgkmcnt(0)
	v_sub_f32_e32 v7, v11, v4
	v_sub_f32_e32 v6, v10, v4
	v_sub_f32_e32 v9, v9, v4
	v_sub_f32_e32 v8, v8, v4
	v_mul_f32_e64 v8, v5, v8
	v_mul_f32_e64 v9, v5, v9
	v_mul_f32_e64 v4, v5, v6
	v_mul_f32_e64 v5, v5, v7
	v_fma_f32 v8, v28, v8, v36
	v_fma_f32 v9, v29, v9, v37
	v_fma_f32 v4, v30, v4, v38
	v_fma_f32 v5, v31, v5, v39
	s_nop 0
	v_cndmask_b32_e32 v7, v147, v5, vcc
	v_cndmask_b32_e32 v6, v147, v4, vcc
	v_cndmask_b32_e32 v5, v147, v9, vcc
	v_cndmask_b32_e32 v4, v147, v8, vcc
	global_store_dwordx4 v[162:163], v[4:7], off offset:576 sc0 sc1
	v_lshl_add_u64 v[8:9], v[164:165], 0, v[48:49]
	s_nop 0
	v_fma_f32 v6, v42, v6, v2
	v_fma_f32 v7, v43, v7, v3
	v_fma_f32 v4, v40, v4, v0
	v_fma_f32 v5, v41, v5, v1
	s_nop 0
	v_cvt_pk_bf16_f32 v4, v4, v5
	v_cvt_pk_bf16_f32 v5, v6, v7
	v_lshl_add_u64 v[6:7], v[50:51], 1, s[6:7]
	global_store_dwordx2 v[6:7], v[4:5], off
	ds_read_b64 v[4:5], v149 offset:8448
	s_waitcnt lgkmcnt(0)
	v_sub_f32_e32 v7, v15, v4
	v_sub_f32_e32 v6, v14, v4
	v_sub_f32_e32 v11, v13, v4
	v_sub_f32_e32 v10, v12, v4
	v_mul_f32_e64 v10, v5, v10
	v_mul_f32_e64 v11, v5, v11
	v_mul_f32_e64 v4, v5, v6
	v_mul_f32_e64 v5, v5, v7
	v_fma_f32 v10, v28, v10, v36
	v_fma_f32 v11, v29, v11, v37
	v_fma_f32 v4, v30, v4, v38
	v_fma_f32 v5, v31, v5, v39
	s_nop 0
	v_cndmask_b32_e32 v7, v147, v5, vcc
	v_cndmask_b32_e32 v6, v147, v4, vcc
	v_cndmask_b32_e32 v5, v147, v11, vcc
	v_cndmask_b32_e32 v4, v147, v10, vcc
	global_store_dwordx4 v[160:161], v[4:7], off offset:576 sc0 sc1
	s_nop 1
	v_fma_f32 v6, v42, v6, v2
	v_fma_f32 v7, v43, v7, v3
	v_fma_f32 v4, v40, v4, v0
	v_fma_f32 v5, v41, v5, v1
	s_nop 0
	v_cvt_pk_bf16_f32 v4, v4, v5
	v_cvt_pk_bf16_f32 v5, v6, v7
	v_lshl_add_u64 v[6:7], v[8:9], 1, s[6:7]
	global_store_dwordx2 v[6:7], v[4:5], off
	ds_read_b64 v[4:5], v149 offset:8576
	v_lshl_add_u64 v[8:9], v[110:111], 0, v[48:49]
	s_waitcnt lgkmcnt(0)
	v_sub_f32_e32 v7, v19, v4
	v_sub_f32_e32 v6, v18, v4
	v_sub_f32_e32 v11, v17, v4
	v_sub_f32_e32 v10, v16, v4
	v_mul_f32_e64 v10, v5, v10
	v_mul_f32_e64 v11, v5, v11
	v_mul_f32_e64 v4, v5, v6
	v_mul_f32_e64 v5, v5, v7
	v_fma_f32 v10, v28, v10, v36
	v_fma_f32 v11, v29, v11, v37
	v_fma_f32 v4, v30, v4, v38
	v_fma_f32 v5, v31, v5, v39
	s_nop 0
	v_cndmask_b32_e32 v7, v147, v5, vcc
	v_cndmask_b32_e32 v6, v147, v4, vcc
	v_cndmask_b32_e32 v5, v147, v11, vcc
	v_cndmask_b32_e32 v4, v147, v10, vcc
	global_store_dwordx4 v[108:109], v[4:7], off offset:576 sc0 sc1
	s_nop 1
	v_fma_f32 v6, v42, v6, v2
	v_fma_f32 v7, v43, v7, v3
	v_fma_f32 v4, v40, v4, v0
	v_fma_f32 v5, v41, v5, v1
	s_nop 0
	v_cvt_pk_bf16_f32 v4, v4, v5
	v_cvt_pk_bf16_f32 v5, v6, v7
	v_lshl_add_u64 v[6:7], v[8:9], 1, s[6:7]
	global_store_dwordx2 v[6:7], v[4:5], off
	ds_read_b64 v[4:5], v149 offset:9216
	v_lshl_add_u64 v[8:9], v[114:115], 0, v[48:49]
	s_waitcnt lgkmcnt(0)
; __device__ __forceinline__ unsigned cvt_pk_bf16(float lo, float hi) { unsigned r; asm volatile("v_cvt_pk_bf16_f32 %0, %1, %2" : "=v"(r) : "v"(lo), "v"(hi)); return r; }
;     __device__ __forceinline__ void fused(f32x4 (&acc)[2][2][4][2], const Unit& u, int wr, int wc, int fr, int fq, PG8_LAS unsigned char* lds, int wid, int lane) const {
;     ...
; #pragma unroll
;         for (int bj = 0; bj < 2; ++bj)
; #pragma unroll
;             for (int n = 0; n < 2; ++n) {
;                 const int col = col0 + bj * HALF + n * 16;
;                 const f32x4 lg = *(const f32x4*)(lng + col), lb = *(const f32x4*)(lnb + col);
;                 f32x4 sc1 = (f32x4){1.f, 1.f, 1.f, 1.f}, sh = (f32x4){0.f, 0.f, 0.f, 0.f};
;                 if (DO_U) { sc1 = *(const f32x4*)(msc + mo + col) + 1.0f; sh = *(const f32x4*)(msh + mo + col); }
; #pragma unroll
;                 for (int ai = 0; ai < 2; ++ai)
; #pragma unroll
;                     for (int m = 0; m < 4; ++m) { const int r = ai * HALF + wr * 64 + m * 16 + fr; const f32x2v sr = S[r]; const size_t off = (size_t)(u.pm * BM + r) * 1024 + col;
;                         f32x4 y = (acc[ai][bj][m][n] - sr.x) * sr.y * lg + lb; if (bad) y = (f32x4){qnan, qnan, qnan, qnan};
;                         *(f32x4*)(out + off) = y;
;                         if (DO_U) { const f32x4 uu = y * sc1 + sh; u32x2v w; w.x = cvt_pk_bf16(uu[0], uu[1]); w.y = cvt_pk_bf16(uu[2], uu[3]); *(u32x2v*)(U + off) = w; } }
	v_sub_f32_e32 v7, v23, v4
	v_sub_f32_e32 v6, v22, v4
	v_sub_f32_e32 v11, v21, v4
	v_sub_f32_e32 v10, v20, v4
	v_mul_f32_e64 v10, v5, v10
	v_mul_f32_e64 v11, v5, v11
	v_mul_f32_e64 v4, v5, v6
	v_mul_f32_e64 v5, v5, v7
	v_fma_f32 v10, v28, v10, v36
	v_fma_f32 v11, v29, v11, v37
	v_fma_f32 v4, v30, v4, v38
	v_fma_f32 v5, v31, v5, v39
	s_nop 0
	v_cndmask_b32_e32 v7, v147, v5, vcc
	v_cndmask_b32_e32 v6, v147, v4, vcc
	v_cndmask_b32_e32 v5, v147, v11, vcc
	v_cndmask_b32_e32 v4, v147, v10, vcc
	global_store_dwordx4 v[112:113], v[4:7], off offset:576 sc0 sc1
	s_nop 1
	v_fma_f32 v6, v42, v6, v2
	v_fma_f32 v7, v43, v7, v3
	v_fma_f32 v4, v40, v4, v0
	v_fma_f32 v5, v41, v5, v1
	s_nop 0
	v_cvt_pk_bf16_f32 v4, v4, v5
	v_cvt_pk_bf16_f32 v5, v6, v7
	v_lshl_add_u64 v[6:7], v[8:9], 1, s[6:7]
	global_store_dwordx2 v[6:7], v[4:5], off
	ds_read_b64 v[4:5], v149 offset:9344
	v_lshl_add_u64 v[8:9], v[118:119], 0, v[48:49]
	s_waitcnt lgkmcnt(0)
	v_sub_f32_e32 v7, v27, v4
	v_sub_f32_e32 v6, v26, v4
	v_sub_f32_e32 v11, v25, v4
	v_sub_f32_e32 v10, v24, v4
	v_mul_f32_e64 v10, v5, v10
	v_mul_f32_e64 v11, v5, v11
	v_mul_f32_e64 v4, v5, v6
	v_mul_f32_e64 v5, v5, v7
	v_fma_f32 v10, v28, v10, v36
	v_fma_f32 v11, v29, v11, v37
	v_fma_f32 v4, v30, v4, v38
	v_fma_f32 v5, v31, v5, v39
	s_nop 0
	v_cndmask_b32_e32 v7, v147, v5, vcc
	v_cndmask_b32_e32 v6, v147, v4, vcc
	v_cndmask_b32_e32 v5, v147, v11, vcc
	v_cndmask_b32_e32 v4, v147, v10, vcc
	global_store_dwordx4 v[116:117], v[4:7], off offset:576 sc0 sc1
	s_nop 1
	v_fma_f32 v6, v42, v6, v2
	v_fma_f32 v7, v43, v7, v3
	v_fma_f32 v4, v40, v4, v0
	v_fma_f32 v5, v41, v5, v1
	s_nop 0
	v_cvt_pk_bf16_f32 v4, v4, v5
	v_cvt_pk_bf16_f32 v5, v6, v7
	v_lshl_add_u64 v[6:7], v[8:9], 1, s[6:7]
	global_store_dwordx2 v[6:7], v[4:5], off
	ds_read_b64 v[4:5], v149 offset:9472
	v_lshl_add_u64 v[8:9], v[122:123], 0, v[48:49]
	s_waitcnt lgkmcnt(0)
	v_sub_f32_e32 v7, v35, v4
	v_sub_f32_e32 v6, v34, v4
	v_sub_f32_e32 v11, v33, v4
	v_sub_f32_e32 v10, v32, v4
	v_mul_f32_e64 v10, v5, v10
	v_mul_f32_e64 v11, v5, v11
	v_mul_f32_e64 v4, v5, v6
	v_mul_f32_e64 v5, v5, v7
	v_fma_f32 v10, v28, v10, v36
	v_fma_f32 v11, v29, v11, v37
	v_fma_f32 v4, v30, v4, v38
	v_fma_f32 v5, v31, v5, v39
	s_nop 0
	v_cndmask_b32_e32 v7, v147, v5, vcc
	v_cndmask_b32_e32 v6, v147, v4, vcc
	v_cndmask_b32_e32 v5, v147, v11, vcc
	v_cndmask_b32_e32 v4, v147, v10, vcc
	global_store_dwordx4 v[120:121], v[4:7], off offset:576 sc0 sc1
	s_nop 1
	v_fma_f32 v6, v42, v6, v2
	v_fma_f32 v7, v43, v7, v3
	v_fma_f32 v4, v40, v4, v0
	v_fma_f32 v5, v41, v5, v1
	s_nop 0
	v_cvt_pk_bf16_f32 v4, v4, v5
	v_cvt_pk_bf16_f32 v5, v6, v7
	v_lshl_add_u64 v[6:7], v[8:9], 1, s[6:7]
	global_store_dwordx2 v[6:7], v[4:5], off
	ds_read_b64 v[4:5], v149 offset:9600
	v_lshl_add_u64 v[8:9], v[128:129], 0, v[48:49]
	s_waitcnt lgkmcnt(0)
	v_sub_f32_e32 v7, v47, v4
	v_sub_f32_e32 v6, v46, v4
	v_sub_f32_e32 v11, v45, v4
	v_sub_f32_e32 v10, v44, v4
	v_mul_f32_e64 v10, v5, v10
	v_mul_f32_e64 v11, v5, v11
	v_mul_f32_e64 v4, v5, v6
	v_mul_f32_e64 v5, v5, v7
	v_fma_f32 v10, v28, v10, v36
	v_fma_f32 v11, v29, v11, v37
	v_fma_f32 v4, v30, v4, v38
	v_fma_f32 v5, v31, v5, v39
	s_nop 0
	v_cndmask_b32_e32 v7, v147, v5, vcc
	v_cndmask_b32_e32 v6, v147, v4, vcc
	v_cndmask_b32_e32 v5, v147, v11, vcc
	v_cndmask_b32_e32 v4, v147, v10, vcc
	v_fma_f32 v2, v42, v6, v2
	v_fma_f32 v3, v43, v7, v3
	v_fma_f32 v0, v40, v4, v0
	v_fma_f32 v1, v41, v5, v1
	global_store_dwordx4 v[124:125], v[4:7], off offset:576 sc0 sc1
	v_cvt_pk_bf16_f32 v0, v0, v1
	v_cvt_pk_bf16_f32 v1, v2, v3
	v_lshl_add_u64 v[2:3], v[8:9], 1, s[6:7]
	global_store_dwordx2 v[2:3], v[0:1], off

;     __device__ __forceinline__ void fused(f32x4 (&acc)[2][2][4][2], const Unit& u, int wr, int wc, int fr, int fq, PG8_LAS unsigned char* lds, int wid, int lane) const {
;     ...
;         const int col0 = u.pn * BM + wc * 32 + 4 * fq; const int b = (u.pm * BM) >> 13; const size_t mo = (size_t)b * 9216;
; #pragma unroll
;         for (int bj = 0; bj < 2; ++bj)
; #pragma unroll
;             for (int n = 0; n < 2; ++n) { const f32x4 gv = (*(const f32x4*)(gate + mo + col0 + bj * HALF + n * 16) + 1.0f) * coef;
; #pragma unroll
;                 for (int ai = 0; ai < 2; ++ai)
; #pragma unroll
;                     for (int m = 0; m < 4; ++m) acc[ai][bj][m][n] = acc[ai][bj][m][n] * gv; }
; #pragma unroll
;         for (int ai = 0; ai < 2; ++ai)
; #pragma unroll
;             for (int m = 0; m < 4; ++m) { const size_t off = (size_t)(u.pm * BM + ai * HALF + wr * 64 + m * 16 + fr) * 1024 + col0;
; #pragma unroll
;                 for (int bj = 0; bj < 2; ++bj)
; #pragma unroll
;                     for (int n = 0; n < 2; ++n) { const f32x4 xv = *(const f32x4*)(xin + off + bj * HALF + n * 16); acc[ai][bj][m][n] = xv * ALPHA_ + acc[ai][bj][m][n]; }
;                 asm volatile("" : "+v"(acc[ai][0][m][0]), "+v"(acc[ai][0][m][1]), "+v"(acc[ai][1][m][0]), "+v"(acc[ai][1][m][1]));
;                 if (m & 1) asm volatile("" ::: "memory"); }
.LBB0_1300:
	s_lshl_b32 s6, s21, 5
	s_lshl_b32 s7, s14, 8
	s_or_b32 s6, s7, s6
	v_lshrrev_b32_e32 v4, 2, v177
	v_and_or_b32 v140, v4, 12, s6
	s_ashr_i32 s6, s46, 5
	s_mul_hi_i32 s7, s6, 0x2400
	s_mulk_i32 s6, 0x2400
	s_lshl_b64 s[16:17], s[6:7], 2
	v_ashrrev_i32_e32 v141, 31, v140
	s_add_u32 s6, s12, s16
	s_addc_u32 s7, s13, s17
	v_lshlrev_b64 v[136:137], 2, v[140:141]
	v_lshl_add_u64 v[4:5], s[6:7], 0, v[136:137]
	s_mov_b64 s[6:7], 0x5000
	v_lshl_add_u64 v[142:143], v[4:5], 0, s[6:7]
	s_movk_i32 s6, 0x5000
	s_lshl_b32 s20, s46, 8
	v_add_co_u32_e32 v146, vcc, s6, v4
	s_add_i32 s6, s20, s57
	v_or_b32_e32 v158, s6, v178
	v_ashrrev_i32_e32 v159, 31, v158
	s_barrier
	v_addc_co_u32_e32 v147, vcc, 0, v5, vcc
	global_load_dwordx4 v[4:7], v[142:143], off offset:64
	global_load_dwordx4 v[148:151], v[142:143], off offset:512
	global_load_dwordx4 v[152:155], v[146:147], off
	global_load_dwordx4 v[180:183], v[142:143], off offset:576
	v_lshlrev_b64 v[142:143], 12, v[158:159]
	s_waitcnt vmcnt(0) lgkmcnt(0)
	v_lshl_add_u64 v[142:143], v[138:139], 0, v[142:143]
	v_lshl_add_u64 v[142:143], v[142:143], 0, v[136:137]
	global_load_dwordx4 v[184:187], v[142:143], off
	global_load_dwordx4 v[188:191], v[142:143], off offset:64
	global_load_dwordx4 v[192:195], v[142:143], off offset:512
	global_load_dwordx4 v[196:199], v[142:143], off offset:576
	v_or_b32_e32 v146, 16, v158
	v_ashrrev_i32_e32 v147, 31, v146
	s_mov_b32 s6, 0x3f9837f0
	v_lshlrev_b64 v[146:147], 12, v[146:147]
	v_lshl_add_u64 v[146:147], v[138:139], 0, v[146:147]
	v_lshl_add_u64 v[146:147], v[146:147], 0, v[136:137]
	v_add_f32_e64 v164, v6, 1.0
	v_add_f32_e64 v165, v7, 1.0
	v_add_f32_e64 v166, v4, 1.0
	v_add_f32_e64 v167, v5, 1.0
	v_add_f32_e64 v160, v154, 1.0
	v_add_f32_e64 v161, v155, 1.0
	v_add_f32_e64 v162, v152, 1.0
	v_add_f32_e64 v163, v153, 1.0
	v_add_f32_e64 v168, v150, 1.0
	v_add_f32_e64 v169, v151, 1.0
	v_add_f32_e64 v170, v148, 1.0
	v_add_f32_e64 v171, v149, 1.0
	v_add_f32_e64 v172, v182, 1.0
	v_add_f32_e64 v173, v183, 1.0
	v_add_f32_e64 v174, v180, 1.0
	v_add_f32_e64 v175, v181, 1.0
	s_waitcnt vmcnt(0) lgkmcnt(0)
	v_mul_f32_e64 v4, v186, s6
	v_mul_f32_e64 v5, v187, s6
	v_mul_f32_e64 v6, v184, s6
	v_mul_f32_e64 v7, v185, s6
	v_mul_f32_e64 v148, v190, s6
	v_mul_f32_e64 v149, v191, s6
	v_mul_f32_e64 v150, v188, s6
	v_mul_f32_e64 v151, v189, s6
	v_mul_f32_e64 v152, v194, s6
	v_mul_f32_e64 v153, v195, s6
	v_mul_f32_e64 v154, v192, s6
	v_mul_f32_e64 v155, v193, s6
	v_mul_f32_e64 v156, v198, s6
	v_mul_f32_e64 v157, v199, s6
	v_mul_f32_e64 v180, v196, s6
	v_mul_f32_e64 v181, v197, s6
	v_fma_f32 v94, v94, v160, v4
	v_fma_f32 v95, v95, v161, v5
	v_fma_f32 v92, v92, v162, v6
	v_fma_f32 v93, v93, v163, v7
	v_fma_f32 v66, v66, v164, v148
	v_fma_f32 v67, v67, v165, v149
	v_fma_f32 v64, v64, v166, v150
	v_fma_f32 v65, v65, v167, v151
	v_fma_f32 v34, v34, v168, v152
	v_fma_f32 v35, v35, v169, v153
	v_fma_f32 v32, v32, v170, v154
	v_fma_f32 v33, v33, v171, v155
	v_fma_f32 v6, v134, v172, v156
	v_fma_f32 v7, v135, v173, v157
	v_fma_f32 v4, v132, v174, v180
	v_fma_f32 v5, v133, v175, v181
	v_or_b32_e32 v148, 32, v158
	global_load_dwordx4 v[132:135], v[146:147], off
	global_load_dwordx4 v[150:153], v[146:147], off offset:64
	global_load_dwordx4 v[154:157], v[146:147], off offset:512
	global_load_dwordx4 v[180:183], v[146:147], off offset:576
	v_ashrrev_i32_e32 v149, 31, v148
	v_lshlrev_b64 v[148:149], 12, v[148:149]
	v_lshl_add_u64 v[148:149], v[138:139], 0, v[148:149]
	v_lshl_add_u64 v[148:149], v[148:149], 0, v[136:137]
	v_mov_b32_e32 v196, v65
	v_mov_b32_e32 v197, v66
	v_mov_b32_e32 v198, v64
	v_mov_b32_e32 v199, v67
	v_add_f32_e32 v201, v32, v33
	v_add_f32_e32 v203, v34, v35
	v_mov_b32_e32 v200, v4
	v_mov_b32_e32 v202, v5
	v_mov_b32_e32 v204, v7
	s_waitcnt vmcnt(0) lgkmcnt(0)
	v_mul_f32_e64 v134, v134, s6
	v_mul_f32_e64 v135, v135, s6
	v_mul_f32_e64 v132, v132, s6
	v_mul_f32_e64 v133, v133, s6
	v_mul_f32_e64 v152, v152, s6
	v_mul_f32_e64 v153, v153, s6
	v_mul_f32_e64 v150, v150, s6
	v_mul_f32_e64 v151, v151, s6
	v_mul_f32_e64 v156, v156, s6
	v_mul_f32_e64 v157, v157, s6
	v_mul_f32_e64 v154, v154, s6
	v_mul_f32_e64 v155, v155, s6
	v_mul_f32_e64 v182, v182, s6
	v_mul_f32_e64 v183, v183, s6
	v_mul_f32_e64 v180, v180, s6
	v_mul_f32_e64 v181, v181, s6
	v_fma_f32 v102, v102, v160, v134
	v_fma_f32 v103, v103, v161, v135
	v_fma_f32 v100, v100, v162, v132
	v_fma_f32 v101, v101, v163, v133
	v_fma_f32 v70, v70, v164, v152
	v_fma_f32 v71, v71, v165, v153
	v_fma_f32 v68, v68, v166, v150
	v_fma_f32 v69, v69, v167, v151
	v_fma_f32 v38, v38, v168, v156
	v_fma_f32 v39, v39, v169, v157
	v_fma_f32 v36, v36, v170, v154
	v_fma_f32 v37, v37, v171, v155
	v_fma_f32 v10, v10, v172, v182
	v_fma_f32 v11, v11, v173, v183
	v_fma_f32 v8, v8, v174, v180
	v_fma_f32 v9, v9, v175, v181
	v_or_b32_e32 v150, 48, v158
	global_load_dwordx4 v[132:135], v[148:149], off
	global_load_dwordx4 v[152:155], v[148:149], off offset:64
	global_load_dwordx4 v[180:183], v[148:149], off offset:512
	global_load_dwordx4 v[184:187], v[148:149], off offset:576
	v_ashrrev_i32_e32 v151, 31, v150
	v_lshlrev_b64 v[150:151], 12, v[150:151]
	v_lshl_add_u64 v[150:151], v[138:139], 0, v[150:151]
	v_lshl_add_u64 v[150:151], v[150:151], 0, v[136:137]
	s_waitcnt vmcnt(0) lgkmcnt(0)
;     __device__ __forceinline__ bool run(const f32x4 (&v)[2][2][4][2], const Unit& u, int wr, int wc, int fr, int fq, PG8_LAS unsigned char* lds, int wid, int lane) const {
;     ...
;                 float s = 0.f;
; #pragma unroll
;                 for (int bj = 0; bj < 2; ++bj)
; #pragma unroll
;                     for (int n = 0; n < 2; ++n) { const f32x4 x = v[ai][bj][m][n]; s += (x[0] + x[1]) + (x[2] + x[3]); }
;                 s += __shfl_xor(s, 16); s += __shfl_xor(s, 32);
;     __device__ __forceinline__ void fused(f32x4 (&acc)[2][2][4][2], const Unit& u, int wr, int wc, int fr, int fq, PG8_LAS unsigned char* lds, int wid, int lane) const {
;     ...
;         for (int bj = 0; bj < 2; ++bj)
; #pragma unroll
;             for (int n = 0; n < 2; ++n) { const f32x4 gv = (*(const f32x4*)(gate + mo + col0 + bj * HALF + n * 16) + 1.0f) * coef;
; #pragma unroll
;                 for (int ai = 0; ai < 2; ++ai)
; #pragma unroll
;                     for (int m = 0; m < 4; ++m) acc[ai][bj][m][n] = acc[ai][bj][m][n] * gv; }
; #pragma unroll
;         for (int ai = 0; ai < 2; ++ai)
; #pragma unroll
;             for (int m = 0; m < 4; ++m) { const size_t off = (size_t)(u.pm * BM + ai * HALF + wr * 64 + m * 16 + fr) * 1024 + col0;
; #pragma unroll
;                 for (int bj = 0; bj < 2; ++bj)
; #pragma unroll
;                     for (int n = 0; n < 2; ++n) { const f32x4 xv = *(const f32x4*)(xin + off + bj * HALF + n * 16); acc[ai][bj][m][n] = xv * ALPHA_ + acc[ai][bj][m][n]; }
;                 asm volatile("" : "+v"(acc[ai][0][m][0]), "+v"(acc[ai][0][m][1]), "+v"(acc[ai][1][m][0]), "+v"(acc[ai][1][m][1]));
;                 if (m & 1) asm volatile("" ::: "memory"); }
	v_mul_f32_e64 v134, v134, s6
	v_mul_f32_e64 v135, v135, s6
	v_mul_f32_e64 v132, v132, s6
	v_mul_f32_e64 v133, v133, s6
	v_mul_f32_e64 v154, v154, s6
	v_mul_f32_e64 v155, v155, s6
	v_mul_f32_e64 v152, v152, s6
	v_mul_f32_e64 v153, v153, s6
	v_mul_f32_e64 v156, v182, s6
	v_mul_f32_e64 v157, v183, s6
	v_mul_f32_e64 v180, v180, s6
	v_mul_f32_e64 v181, v181, s6
	v_mul_f32_e64 v182, v186, s6
	v_mul_f32_e64 v183, v187, s6
	v_mul_f32_e64 v184, v184, s6
	v_mul_f32_e64 v185, v185, s6
	v_fma_f32 v106, v106, v160, v134
	v_fma_f32 v107, v107, v161, v135
	v_fma_f32 v104, v104, v162, v132
	v_fma_f32 v105, v105, v163, v133
	v_fma_f32 v74, v74, v164, v154
	v_fma_f32 v75, v75, v165, v155
	v_fma_f32 v72, v72, v166, v152
	v_fma_f32 v73, v73, v167, v153
	v_fma_f32 v42, v42, v168, v156
	v_fma_f32 v43, v43, v169, v157
	v_fma_f32 v40, v40, v170, v180
	v_fma_f32 v41, v41, v171, v181
	v_fma_f32 v14, v14, v172, v182
	v_fma_f32 v15, v15, v173, v183
	v_fma_f32 v12, v12, v174, v184
	v_fma_f32 v13, v13, v175, v185
	v_add_u32_e32 v152, 0x80, v158
	global_load_dwordx4 v[132:135], v[150:151], off
	global_load_dwordx4 v[154:157], v[150:151], off offset:64
	global_load_dwordx4 v[180:183], v[150:151], off offset:512
	global_load_dwordx4 v[184:187], v[150:151], off offset:576
	v_ashrrev_i32_e32 v153, 31, v152
	v_lshlrev_b64 v[152:153], 12, v[152:153]
	v_lshl_add_u64 v[152:153], v[138:139], 0, v[152:153]
	v_lshl_add_u64 v[152:153], v[152:153], 0, v[136:137]
	s_waitcnt vmcnt(0) lgkmcnt(0)
	v_mul_f32_e64 v134, v134, s6
	v_mul_f32_e64 v135, v135, s6
	v_mul_f32_e64 v132, v132, s6
	v_mul_f32_e64 v133, v133, s6
	v_mul_f32_e64 v156, v156, s6
	v_mul_f32_e64 v157, v157, s6
	v_mul_f32_e64 v154, v154, s6
	v_mul_f32_e64 v155, v155, s6
	v_mul_f32_e64 v182, v182, s6
	v_mul_f32_e64 v183, v183, s6
	v_mul_f32_e64 v180, v180, s6
	v_mul_f32_e64 v181, v181, s6
	v_mul_f32_e64 v186, v186, s6
	v_mul_f32_e64 v187, v187, s6
	v_mul_f32_e64 v184, v184, s6
	v_mul_f32_e64 v185, v185, s6
	v_fma_f32 v114, v114, v160, v134
	v_fma_f32 v115, v115, v161, v135
	v_fma_f32 v112, v112, v162, v132
	v_fma_f32 v113, v113, v163, v133
	v_fma_f32 v82, v82, v164, v156
	v_fma_f32 v83, v83, v165, v157
	v_fma_f32 v80, v80, v166, v154
	v_fma_f32 v81, v81, v167, v155
	v_fma_f32 v50, v50, v168, v182
	v_fma_f32 v51, v51, v169, v183
	v_fma_f32 v48, v48, v170, v180
	v_fma_f32 v49, v49, v171, v181
	v_fma_f32 v18, v18, v172, v186
	v_fma_f32 v19, v19, v173, v187
	v_fma_f32 v16, v16, v174, v184
	v_fma_f32 v17, v17, v175, v185
	v_add_u32_e32 v154, 0x90, v158
	global_load_dwordx4 v[132:135], v[152:153], off
	global_load_dwordx4 v[180:183], v[152:153], off offset:64
	global_load_dwordx4 v[184:187], v[152:153], off offset:512
	global_load_dwordx4 v[188:191], v[152:153], off offset:576
	v_ashrrev_i32_e32 v155, 31, v154
	v_lshlrev_b64 v[154:155], 12, v[154:155]
	v_lshl_add_u64 v[154:155], v[138:139], 0, v[154:155]
	v_lshl_add_u64 v[154:155], v[154:155], 0, v[136:137]
	s_waitcnt vmcnt(0) lgkmcnt(0)
	v_mul_f32_e64 v134, v134, s6
	v_mul_f32_e64 v135, v135, s6
	v_mul_f32_e64 v132, v132, s6
	v_mul_f32_e64 v133, v133, s6
	v_mul_f32_e64 v156, v182, s6
	v_mul_f32_e64 v157, v183, s6
	v_mul_f32_e64 v180, v180, s6
	v_mul_f32_e64 v181, v181, s6
	v_mul_f32_e64 v182, v186, s6
	v_mul_f32_e64 v183, v187, s6
	v_mul_f32_e64 v184, v184, s6
	v_mul_f32_e64 v185, v185, s6
	v_mul_f32_e64 v186, v190, s6
	v_mul_f32_e64 v187, v191, s6
	v_mul_f32_e64 v188, v188, s6
	v_mul_f32_e64 v189, v189, s6
	v_fma_f32 v118, v118, v160, v134
	v_fma_f32 v119, v119, v161, v135
	v_fma_f32 v116, v116, v162, v132
	v_fma_f32 v117, v117, v163, v133
	v_fma_f32 v86, v86, v164, v156
	v_fma_f32 v87, v87, v165, v157
	v_fma_f32 v84, v84, v166, v180
	v_fma_f32 v85, v85, v167, v181
	v_fma_f32 v54, v54, v168, v182
	v_fma_f32 v55, v55, v169, v183
	v_fma_f32 v52, v52, v170, v184
	v_fma_f32 v53, v53, v171, v185
	v_fma_f32 v22, v22, v172, v186
	v_fma_f32 v23, v23, v173, v187
	v_fma_f32 v20, v20, v174, v188
	v_fma_f32 v21, v21, v175, v189
	v_add_u32_e32 v156, 0xa0, v158
	global_load_dwordx4 v[132:135], v[154:155], off
	global_load_dwordx4 v[180:183], v[154:155], off offset:64
	global_load_dwordx4 v[184:187], v[154:155], off offset:512
	global_load_dwordx4 v[188:191], v[154:155], off offset:576
	v_ashrrev_i32_e32 v157, 31, v156
	v_lshlrev_b64 v[156:157], 12, v[156:157]
	v_lshl_add_u64 v[156:157], v[138:139], 0, v[156:157]
	v_lshl_add_u64 v[156:157], v[156:157], 0, v[136:137]
	s_waitcnt vmcnt(0) lgkmcnt(0)
	v_mul_f32_e64 v134, v134, s6
	v_mul_f32_e64 v135, v135, s6
	v_mul_f32_e64 v132, v132, s6
	v_mul_f32_e64 v133, v133, s6
	v_mul_f32_e64 v182, v182, s6
	v_mul_f32_e64 v183, v183, s6
	v_mul_f32_e64 v180, v180, s6
	v_mul_f32_e64 v181, v181, s6
	v_mul_f32_e64 v186, v186, s6
	v_mul_f32_e64 v187, v187, s6
	v_mul_f32_e64 v184, v184, s6
	v_mul_f32_e64 v185, v185, s6
	v_mul_f32_e64 v190, v190, s6
	v_mul_f32_e64 v191, v191, s6
	v_mul_f32_e64 v188, v188, s6
	v_mul_f32_e64 v189, v189, s6
	v_fma_f32 v122, v122, v160, v134
	v_fma_f32 v123, v123, v161, v135
	v_fma_f32 v120, v120, v162, v132
	v_fma_f32 v121, v121, v163, v133
	v_fma_f32 v90, v90, v164, v182
	v_fma_f32 v91, v91, v165, v183
	v_fma_f32 v88, v88, v166, v180
	v_fma_f32 v89, v89, v167, v181
	v_fma_f32 v58, v58, v168, v186
	v_fma_f32 v59, v59, v169, v187
	v_fma_f32 v56, v56, v170, v184
	v_fma_f32 v57, v57, v171, v185
	v_fma_f32 v26, v26, v172, v190
	v_fma_f32 v27, v27, v173, v191
	v_fma_f32 v24, v24, v174, v188
	v_fma_f32 v25, v25, v175, v189
	v_mbcnt_hi_u32_b32 v133, -1, v145
	global_load_dwordx4 v[180:183], v[156:157], off
	global_load_dwordx4 v[184:187], v[156:157], off offset:64
	global_load_dwordx4 v[188:191], v[156:157], off offset:512
	global_load_dwordx4 v[192:195], v[156:157], off offset:576
	v_and_b32_e32 v134, 64, v133
	v_add_u32_e32 v179, 64, v134
	v_add_u32_e32 v134, 0xb0, v158
	v_ashrrev_i32_e32 v135, 31, v134
	v_lshlrev_b64 v[134:135], 12, v[134:135]
	v_lshl_add_u64 v[134:135], v[138:139], 0, v[134:135]
	v_lshl_add_u64 v[158:159], v[134:135], 0, v[136:137]
	v_mov_b32_e32 v134, v93
	v_mov_b32_e32 v135, v94
	v_mov_b32_e32 v138, v92
	v_mov_b32_e32 v139, v95
	v_add_f32_e64 v134, v134, v138
	v_add_f32_e64 v135, v135, v139
	v_add_f32_e64 v138, v196, v198
	v_add_f32_e64 v139, v197, v199
	v_add_f32_e32 v198, v134, v135
	v_add_f32_e64 v134, v138, v138
	v_add_f32_e64 v135, v138, v139
	v_xor_b32_e32 v132, 16, v133
	v_add_f32_e32 v205, 0, v198
	v_mov_b32_e32 v134, v6
	v_cmp_lt_i32_e32 vcc, v132, v179
	v_add_f32_e64 v196, v200, v202
	v_add_f32_e64 v197, v201, v203
	v_add_f32_e64 v134, v134, v204
	v_add_f32_e64 v135, v135, v205
	v_cndmask_b32_e32 v132, v133, v132, vcc
	v_add_f32_e64 v134, v196, v134
	v_add_f32_e64 v135, v197, v135
	v_lshlrev_b32_e32 v132, 2, v132
	v_add_f32_e32 v134, v134, v135
	ds_bpermute_b32 v135, v132, v134
	v_xor_b32_e32 v138, 32, v133
	v_cmp_lt_i32_e32 vcc, v138, v179
	s_waitcnt lgkmcnt(0)
;     __device__ __forceinline__ bool run(const f32x4 (&v)[2][2][4][2], const Unit& u, int wr, int wc, int fr, int fq, PG8_LAS unsigned char* lds, int wid, int lane) const {
;     ...
;                 const float mw = s * (1.0f / 64.0f); float q = 0.f;
; #pragma unroll
;                 for (int bj = 0; bj < 2; ++bj)
; #pragma unroll
;                     for (int n = 0; n < 2; ++n) { const f32x4 d = v[ai][bj][m][n] - mw; q += (d[0] * d[0] + d[1] * d[1]) + (d[2] * d[2] + d[3] * d[3]); }
;                 q += __shfl_xor(q, 16); q += __shfl_xor(q, 32);
;                 if (fq == 0) P[(ai * HALF + wr * 64 + m * 16 + fr) * 4 + wc] = (f32x2v){mw, q};
;     __device__ __forceinline__ void fused(f32x4 (&acc)[2][2][4][2], const Unit& u, int wr, int wc, int fr, int fq, PG8_LAS unsigned char* lds, int wid, int lane) const {
;     ...
;         for (int ai = 0; ai < 2; ++ai)
; #pragma unroll
;             for (int m = 0; m < 4; ++m) { const size_t off = (size_t)(u.pm * BM + ai * HALF + wr * 64 + m * 16 + fr) * 1024 + col0;
; #pragma unroll
;                 for (int bj = 0; bj < 2; ++bj)
; #pragma unroll
;                     for (int n = 0; n < 2; ++n) { const f32x4 xv = *(const f32x4*)(xin + off + bj * HALF + n * 16); acc[ai][bj][m][n] = xv * ALPHA_ + acc[ai][bj][m][n]; }
;                 asm volatile("" : "+v"(acc[ai][0][m][0]), "+v"(acc[ai][0][m][1]), "+v"(acc[ai][1][m][0]), "+v"(acc[ai][1][m][1]));
;                 if (m & 1) asm volatile("" ::: "memory"); }
	v_add_f32_e32 v134, v134, v135
	v_cndmask_b32_e32 v133, v133, v138, vcc
	v_lshlrev_b32_e32 v133, 2, v133
	ds_bpermute_b32 v135, v133, v134
	s_waitcnt lgkmcnt(0)
	v_add_f32_e32 v135, v134, v135
	v_fmamk_f32 v138, v135, 0xbc800000, v95
	v_fmamk_f32 v179, v135, 0xbc800000, v93
	v_fmamk_f32 v197, v135, 0xbc800000, v67
	v_fmamk_f32 v199, v135, 0xbc800000, v65
	v_fmamk_f32 v134, v135, 0xbc800000, v94
	v_fmamk_f32 v139, v135, 0xbc800000, v92
	v_fmamk_f32 v196, v135, 0xbc800000, v66
	v_fmamk_f32 v198, v135, 0xbc800000, v64
	v_fmamk_f32 v201, v135, 0xbc800000, v35
	v_fmamk_f32 v203, v135, 0xbc800000, v33
	v_mul_f32_e32 v179, v179, v179
	v_mul_f32_e32 v138, v138, v138
	v_mul_f32_e32 v199, v199, v199
	v_mul_f32_e32 v197, v197, v197
	v_fmamk_f32 v200, v135, 0xbc800000, v34
	v_fmamk_f32 v202, v135, 0xbc800000, v32
	v_fmamk_f32 v205, v135, 0xbc800000, v7
	v_fmamk_f32 v207, v135, 0xbc800000, v5
	v_mul_f32_e32 v203, v203, v203
	v_mul_f32_e32 v201, v201, v201
	v_fmac_f32_e32 v179, v139, v139
	v_fmac_f32_e32 v138, v134, v134
	v_fmac_f32_e32 v199, v198, v198
	v_fmac_f32_e32 v197, v196, v196
	v_fmamk_f32 v204, v135, 0xbc800000, v6
	v_fmamk_f32 v206, v135, 0xbc800000, v4
	v_mul_f32_e32 v207, v207, v207
	v_mul_f32_e32 v205, v205, v205
	v_fmac_f32_e32 v203, v202, v202
	v_fmac_f32_e32 v201, v200, v200
	v_add_f32_e32 v134, v179, v138
	v_add_f32_e32 v138, v199, v197
	v_fmac_f32_e32 v207, v206, v206
	v_fmac_f32_e32 v205, v204, v204
	v_add_f32_e32 v139, v203, v201
	v_add_f32_e32 v134, v134, v138
	v_add_f32_e32 v179, v207, v205
	s_waitcnt vmcnt(0)
	v_mul_f32_e64 v182, v182, s6
	v_mul_f32_e64 v183, v183, s6
	v_mul_f32_e64 v180, v180, s6
	v_mul_f32_e64 v181, v181, s6
	v_mul_f32_e64 v186, v186, s6
	v_mul_f32_e64 v187, v187, s6
	v_mul_f32_e64 v184, v184, s6
	v_mul_f32_e64 v185, v185, s6
	v_mul_f32_e64 v190, v190, s6
	v_mul_f32_e64 v191, v191, s6
	v_mul_f32_e64 v188, v188, s6
	v_mul_f32_e64 v189, v189, s6
	v_mul_f32_e64 v194, v194, s6
	v_mul_f32_e64 v195, v195, s6
	v_mul_f32_e64 v192, v192, s6
	v_mul_f32_e64 v193, v193, s6
	v_fma_f32 v126, v126, v160, v182
	v_fma_f32 v127, v127, v161, v183
	v_fma_f32 v124, v124, v162, v180
	v_fma_f32 v125, v125, v163, v181
	v_fma_f32 v98, v98, v164, v186
	v_fma_f32 v99, v99, v165, v187
	v_fma_f32 v96, v96, v166, v184
	v_fma_f32 v97, v97, v167, v185
	v_fma_f32 v62, v62, v168, v190
	v_fma_f32 v63, v63, v169, v191
	v_fma_f32 v60, v60, v170, v188
	v_fma_f32 v61, v61, v171, v189
	v_fma_f32 v30, v30, v172, v194
	v_fma_f32 v31, v31, v173, v195
	v_fma_f32 v28, v28, v174, v192
	v_fma_f32 v29, v29, v175, v193
	v_add_f32_e32 v134, v139, v134
	global_load_dwordx4 v[180:183], v[158:159], off
	global_load_dwordx4 v[184:187], v[158:159], off offset:64
	global_load_dwordx4 v[188:191], v[158:159], off offset:512
	global_load_dwordx4 v[192:195], v[158:159], off offset:576
	v_add_f32_e32 v138, v179, v134
	ds_bpermute_b32 v139, v132, v138
	v_and_b32_e32 v134, 63, v177
	v_cmp_gt_u32_e32 vcc, 16, v134
	s_waitcnt lgkmcnt(0)
	v_add_f32_e32 v138, v138, v139
	ds_bpermute_b32 v139, v133, v138
	s_waitcnt vmcnt(0)
	v_mul_f32_e64 v182, v182, s6
	v_mul_f32_e64 v183, v183, s6
	v_mul_f32_e64 v180, v180, s6
	v_mul_f32_e64 v181, v181, s6
	v_mul_f32_e64 v186, v186, s6
	v_mul_f32_e64 v187, v187, s6
	v_mul_f32_e64 v184, v184, s6
	v_mul_f32_e64 v185, v185, s6
	v_mul_f32_e64 v190, v190, s6
	v_mul_f32_e64 v191, v191, s6
	v_mul_f32_e64 v188, v188, s6
	v_mul_f32_e64 v189, v189, s6
	v_mul_f32_e64 v194, v194, s6
	v_mul_f32_e64 v195, v195, s6
	v_mul_f32_e64 v192, v192, s6
	v_mul_f32_e64 v193, v193, s6
	v_fma_f32 v130, v130, v160, v182
	v_fma_f32 v131, v131, v161, v183
	v_fma_f32 v128, v128, v162, v180
	v_fma_f32 v129, v129, v163, v181
	v_fma_f32 v110, v110, v164, v186
	v_fma_f32 v111, v111, v165, v187
	v_fma_f32 v108, v108, v166, v184
	v_fma_f32 v109, v109, v167, v185
	v_fma_f32 v78, v78, v168, v190
	v_fma_f32 v79, v79, v169, v191
	v_fma_f32 v76, v76, v170, v188
	v_fma_f32 v77, v77, v171, v189
	v_fma_f32 v46, v46, v172, v194
	v_fma_f32 v47, v47, v173, v195
	v_fma_f32 v44, v44, v174, v192
	v_fma_f32 v45, v45, v175, v193
	s_lshl_b32 s6, s21, 3
	s_add_i32 s8, s6, 0
	s_and_saveexec_b64 s[6:7], vcc
	s_cbranch_execz .LBB0_1302
	s_lshl_b32 s9, s47, 11
	s_add_i32 s9, s8, s9
	v_mul_f32_e32 v160, 0x3c800000, v135
	v_lshl_add_u32 v135, v178, 5, s9
	s_waitcnt lgkmcnt(0)
	v_add_f32_e32 v161, v138, v139
	ds_write_b64 v135, v[160:161]
;     __device__ __forceinline__ bool run(const f32x4 (&v)[2][2][4][2], const Unit& u, int wr, int wc, int fr, int fq, PG8_LAS unsigned char* lds, int wid, int lane) const {
;     ...
;                 float s = 0.f;
; #pragma unroll
;                 for (int bj = 0; bj < 2; ++bj)
; #pragma unroll
;                     for (int n = 0; n < 2; ++n) { const f32x4 x = v[ai][bj][m][n]; s += (x[0] + x[1]) + (x[2] + x[3]); }
;                 s += __shfl_xor(s, 16); s += __shfl_xor(s, 32);
;                 const float mw = s * (1.0f / 64.0f); float q = 0.f;
; #pragma unroll
;                 for (int bj = 0; bj < 2; ++bj)
; #pragma unroll
;                     for (int n = 0; n < 2; ++n) { const f32x4 d = v[ai][bj][m][n] - mw; q += (d[0] * d[0] + d[1] * d[1]) + (d[2] * d[2] + d[3] * d[3]); }
;                 q += __shfl_xor(q, 16); q += __shfl_xor(q, 32);
;                 if (fq == 0) P[(ai * HALF + wr * 64 + m * 16 + fr) * 4 + wc] = (f32x2v){mw, q};
.LBB0_1302:
	s_or_b64 exec, exec, s[6:7]
	v_mov_b32_e32 v138, v101
	s_waitcnt lgkmcnt(0)
	v_mov_b32_e32 v139, v102
	v_mov_b32_e32 v160, v100
	v_mov_b32_e32 v161, v103
	v_add_f32_e64 v138, v138, v160
	v_add_f32_e64 v139, v139, v161
	v_mov_b32_e32 v160, v69
	v_mov_b32_e32 v161, v70
	v_mov_b32_e32 v162, v68
	v_mov_b32_e32 v163, v71
	v_add_f32_e64 v160, v160, v162
	v_add_f32_e64 v161, v161, v163
	v_add_f32_e32 v135, v138, v139
	v_add_f32_e64 v161, v160, v161
	v_add_f32_e64 v160, v160, v160
	v_add_f32_e32 v139, 0, v135
	v_add_f32_e32 v163, v36, v37
	v_add_f32_e32 v165, v38, v39
	v_mov_b32_e32 v162, v8
	v_mov_b32_e32 v164, v9
	v_mov_b32_e32 v160, v10
	v_mov_b32_e32 v138, v11
	v_add_f32_e64 v162, v162, v164
	v_add_f32_e64 v163, v163, v165
	v_add_f32_e64 v138, v160, v138
	v_add_f32_e64 v139, v161, v139
	s_nop 0
	v_add_f32_e64 v138, v162, v138
	v_add_f32_e64 v139, v163, v139
	s_nop 0
	v_add_f32_e32 v135, v138, v139
	ds_bpermute_b32 v138, v132, v135
	s_waitcnt lgkmcnt(0)
	v_add_f32_e32 v135, v135, v138
	ds_bpermute_b32 v138, v133, v135
	s_waitcnt lgkmcnt(0)
	v_add_f32_e32 v135, v135, v138
	v_fmamk_f32 v139, v135, 0xbc800000, v103
	v_fmamk_f32 v161, v135, 0xbc800000, v101
	v_fmamk_f32 v138, v135, 0xbc800000, v102
	v_fmamk_f32 v160, v135, 0xbc800000, v100
	v_mul_f32_e32 v161, v161, v161
	v_mul_f32_e32 v139, v139, v139
	v_fmac_f32_e32 v161, v160, v160
	v_fmac_f32_e32 v139, v138, v138
	v_fmamk_f32 v160, v135, 0xbc800000, v71
	v_fmamk_f32 v162, v135, 0xbc800000, v69
	v_add_f32_e32 v138, v161, v139
	v_fmamk_f32 v139, v135, 0xbc800000, v70
	v_fmamk_f32 v161, v135, 0xbc800000, v68
	v_mul_f32_e32 v162, v162, v162
	v_mul_f32_e32 v160, v160, v160
	v_fmac_f32_e32 v162, v161, v161
	v_fmac_f32_e32 v160, v139, v139
	v_add_f32_e32 v139, v162, v160
	v_fmamk_f32 v160, v135, 0xbc800000, v39
	v_fmamk_f32 v162, v135, 0xbc800000, v37
	v_add_f32_e32 v138, v138, v139
	v_fmamk_f32 v139, v135, 0xbc800000, v38
	v_fmamk_f32 v161, v135, 0xbc800000, v36
	v_mul_f32_e32 v162, v162, v162
	v_mul_f32_e32 v160, v160, v160
	v_fmac_f32_e32 v162, v161, v161
	v_fmac_f32_e32 v160, v139, v139
	v_add_f32_e32 v139, v162, v160
	v_fmamk_f32 v160, v135, 0xbc800000, v11
	v_fmamk_f32 v162, v135, 0xbc800000, v9
	v_add_f32_e32 v138, v139, v138
	v_fmamk_f32 v139, v135, 0xbc800000, v10
	v_fmamk_f32 v161, v135, 0xbc800000, v8
	v_mul_f32_e32 v162, v162, v162
	v_mul_f32_e32 v160, v160, v160
	v_fmac_f32_e32 v162, v161, v161
	v_fmac_f32_e32 v160, v139, v139
	v_add_f32_e32 v139, v162, v160
	v_add_f32_e32 v138, v139, v138
	ds_bpermute_b32 v139, v132, v138
	s_waitcnt lgkmcnt(0)
	v_add_f32_e32 v138, v138, v139
	ds_bpermute_b32 v139, v133, v138
	s_and_saveexec_b64 s[6:7], vcc
	s_cbranch_execz .LBB0_1304
	s_lshl_b32 s9, s47, 11
	s_add_i32 s9, s8, s9
	v_mul_f32_e32 v160, 0x3c800000, v135
	v_lshl_add_u32 v135, v178, 5, s9
	s_waitcnt lgkmcnt(0)
	v_add_f32_e32 v161, v138, v139
	ds_write_b64 v135, v[160:161] offset:512
.LBB0_1304:
	s_or_b64 exec, exec, s[6:7]
	v_mov_b32_e32 v138, v105
	s_waitcnt lgkmcnt(0)
	v_mov_b32_e32 v139, v106
	v_mov_b32_e32 v160, v104
	v_mov_b32_e32 v161, v107
	v_add_f32_e64 v138, v138, v160
	v_add_f32_e64 v139, v139, v161
	v_mov_b32_e32 v160, v73
	v_mov_b32_e32 v161, v74
	v_mov_b32_e32 v162, v72
	v_mov_b32_e32 v163, v75
	v_add_f32_e64 v160, v160, v162
	v_add_f32_e64 v161, v161, v163
	v_add_f32_e32 v135, v138, v139
	v_add_f32_e64 v161, v160, v161
	v_add_f32_e64 v160, v160, v160
	v_add_f32_e32 v139, 0, v135
	v_add_f32_e32 v163, v40, v41
	v_add_f32_e32 v165, v42, v43
	v_mov_b32_e32 v162, v12
	v_mov_b32_e32 v164, v13
	v_mov_b32_e32 v160, v14
	v_mov_b32_e32 v138, v15
	v_add_f32_e64 v162, v162, v164
	v_add_f32_e64 v163, v163, v165
	v_add_f32_e64 v138, v160, v138
	v_add_f32_e64 v139, v161, v139
	s_nop 0
	v_add_f32_e64 v138, v162, v138
	v_add_f32_e64 v139, v163, v139
	s_nop 0
	v_add_f32_e32 v135, v138, v139
	ds_bpermute_b32 v138, v132, v135
	s_waitcnt lgkmcnt(0)
	v_add_f32_e32 v135, v135, v138
	ds_bpermute_b32 v138, v133, v135
	s_waitcnt lgkmcnt(0)
	v_add_f32_e32 v135, v135, v138
	v_fmamk_f32 v139, v135, 0xbc800000, v107
	v_fmamk_f32 v161, v135, 0xbc800000, v105
	v_fmamk_f32 v138, v135, 0xbc800000, v106
	v_fmamk_f32 v160, v135, 0xbc800000, v104
	v_mul_f32_e32 v161, v161, v161
	v_mul_f32_e32 v139, v139, v139
	v_fmac_f32_e32 v161, v160, v160
	v_fmac_f32_e32 v139, v138, v138
	v_fmamk_f32 v160, v135, 0xbc800000, v75
	v_fmamk_f32 v162, v135, 0xbc800000, v73
	v_add_f32_e32 v138, v161, v139
	v_fmamk_f32 v139, v135, 0xbc800000, v74
	v_fmamk_f32 v161, v135, 0xbc800000, v72
	v_mul_f32_e32 v162, v162, v162
	v_mul_f32_e32 v160, v160, v160
	v_fmac_f32_e32 v162, v161, v161
	v_fmac_f32_e32 v160, v139, v139
	v_add_f32_e32 v139, v162, v160
	v_fmamk_f32 v160, v135, 0xbc800000, v43
	v_fmamk_f32 v162, v135, 0xbc800000, v41
	v_add_f32_e32 v138, v138, v139
	v_fmamk_f32 v139, v135, 0xbc800000, v42
	v_fmamk_f32 v161, v135, 0xbc800000, v40
	v_mul_f32_e32 v162, v162, v162
	v_mul_f32_e32 v160, v160, v160
	v_fmac_f32_e32 v162, v161, v161
	v_fmac_f32_e32 v160, v139, v139
	v_add_f32_e32 v139, v162, v160
	v_fmamk_f32 v160, v135, 0xbc800000, v15
	v_fmamk_f32 v162, v135, 0xbc800000, v13
	v_add_f32_e32 v138, v139, v138
	v_fmamk_f32 v139, v135, 0xbc800000, v14
	v_fmamk_f32 v161, v135, 0xbc800000, v12
	v_mul_f32_e32 v162, v162, v162
	v_mul_f32_e32 v160, v160, v160
	v_fmac_f32_e32 v162, v161, v161
	v_fmac_f32_e32 v160, v139, v139
	v_add_f32_e32 v139, v162, v160
	v_add_f32_e32 v138, v139, v138
	ds_bpermute_b32 v139, v132, v138
	s_waitcnt lgkmcnt(0)
	v_add_f32_e32 v138, v138, v139
	ds_bpermute_b32 v139, v133, v138
	s_and_saveexec_b64 s[6:7], vcc
	s_cbranch_execz .LBB0_1306
	s_lshl_b32 s9, s47, 11
	s_add_i32 s9, s8, s9
	v_mul_f32_e32 v160, 0x3c800000, v135
	v_lshl_add_u32 v135, v178, 5, s9
	s_waitcnt lgkmcnt(0)
	v_add_f32_e32 v161, v138, v139
	ds_write_b64 v135, v[160:161] offset:1024
;     __device__ __forceinline__ bool run(const f32x4 (&v)[2][2][4][2], const Unit& u, int wr, int wc, int fr, int fq, PG8_LAS unsigned char* lds, int wid, int lane) const {
;     ...
;                 float s = 0.f;
; #pragma unroll
;                 for (int bj = 0; bj < 2; ++bj)
; #pragma unroll
;                     for (int n = 0; n < 2; ++n) { const f32x4 x = v[ai][bj][m][n]; s += (x[0] + x[1]) + (x[2] + x[3]); }
;                 s += __shfl_xor(s, 16); s += __shfl_xor(s, 32);
;                 const float mw = s * (1.0f / 64.0f); float q = 0.f;
; #pragma unroll
;                 for (int bj = 0; bj < 2; ++bj)
; #pragma unroll
;                     for (int n = 0; n < 2; ++n) { const f32x4 d = v[ai][bj][m][n] - mw; q += (d[0] * d[0] + d[1] * d[1]) + (d[2] * d[2] + d[3] * d[3]); }
;                 q += __shfl_xor(q, 16); q += __shfl_xor(q, 32);
;                 if (fq == 0) P[(ai * HALF + wr * 64 + m * 16 + fr) * 4 + wc] = (f32x2v){mw, q};
.LBB0_1306:
	s_or_b64 exec, exec, s[6:7]
	v_mov_b32_e32 v138, v113
	s_waitcnt lgkmcnt(0)
	v_mov_b32_e32 v139, v114
	v_mov_b32_e32 v160, v112
	v_mov_b32_e32 v161, v115
	v_add_f32_e64 v138, v138, v160
	v_add_f32_e64 v139, v139, v161
	v_mov_b32_e32 v160, v81
	v_mov_b32_e32 v161, v82
	v_mov_b32_e32 v162, v80
	v_mov_b32_e32 v163, v83
	v_add_f32_e64 v160, v160, v162
	v_add_f32_e64 v161, v161, v163
	v_add_f32_e32 v135, v138, v139
	v_add_f32_e64 v161, v160, v161
	v_add_f32_e64 v160, v160, v160
	v_add_f32_e32 v139, 0, v135
	v_add_f32_e32 v163, v48, v49
	v_add_f32_e32 v165, v50, v51
	v_mov_b32_e32 v162, v16
	v_mov_b32_e32 v164, v17
	v_mov_b32_e32 v160, v18
	v_mov_b32_e32 v138, v19
	v_add_f32_e64 v162, v162, v164
	v_add_f32_e64 v163, v163, v165
	v_add_f32_e64 v138, v160, v138
	v_add_f32_e64 v139, v161, v139
	s_nop 0
	v_add_f32_e64 v138, v162, v138
	v_add_f32_e64 v139, v163, v139
	s_nop 0
	v_add_f32_e32 v135, v138, v139
	ds_bpermute_b32 v138, v132, v135
	s_waitcnt lgkmcnt(0)
	v_add_f32_e32 v135, v135, v138
	ds_bpermute_b32 v138, v133, v135
	s_waitcnt lgkmcnt(0)
	v_add_f32_e32 v135, v135, v138
	v_fmamk_f32 v139, v135, 0xbc800000, v115
	v_fmamk_f32 v161, v135, 0xbc800000, v113
	v_fmamk_f32 v138, v135, 0xbc800000, v114
	v_fmamk_f32 v160, v135, 0xbc800000, v112
	v_mul_f32_e32 v161, v161, v161
	v_mul_f32_e32 v139, v139, v139
	v_fmac_f32_e32 v161, v160, v160
	v_fmac_f32_e32 v139, v138, v138
	v_fmamk_f32 v160, v135, 0xbc800000, v83
	v_fmamk_f32 v162, v135, 0xbc800000, v81
	v_add_f32_e32 v138, v161, v139
	v_fmamk_f32 v139, v135, 0xbc800000, v82
	v_fmamk_f32 v161, v135, 0xbc800000, v80
	v_mul_f32_e32 v162, v162, v162
	v_mul_f32_e32 v160, v160, v160
	v_fmac_f32_e32 v162, v161, v161
	v_fmac_f32_e32 v160, v139, v139
	v_add_f32_e32 v139, v162, v160
	v_fmamk_f32 v160, v135, 0xbc800000, v51
	v_fmamk_f32 v162, v135, 0xbc800000, v49
	v_add_f32_e32 v138, v138, v139
	v_fmamk_f32 v139, v135, 0xbc800000, v50
	v_fmamk_f32 v161, v135, 0xbc800000, v48
	v_mul_f32_e32 v162, v162, v162
	v_mul_f32_e32 v160, v160, v160
	v_fmac_f32_e32 v162, v161, v161
	v_fmac_f32_e32 v160, v139, v139
	v_add_f32_e32 v139, v162, v160
	v_fmamk_f32 v160, v135, 0xbc800000, v19
	v_fmamk_f32 v162, v135, 0xbc800000, v17
	v_add_f32_e32 v138, v139, v138
	v_fmamk_f32 v139, v135, 0xbc800000, v18
	v_fmamk_f32 v161, v135, 0xbc800000, v16
	v_mul_f32_e32 v162, v162, v162
	v_mul_f32_e32 v160, v160, v160
	v_fmac_f32_e32 v162, v161, v161
	v_fmac_f32_e32 v160, v139, v139
	v_add_f32_e32 v139, v162, v160
	v_add_f32_e32 v138, v139, v138
	ds_bpermute_b32 v139, v132, v138
	s_waitcnt lgkmcnt(0)
	v_add_f32_e32 v138, v138, v139
	ds_bpermute_b32 v139, v133, v138
	s_and_saveexec_b64 s[6:7], vcc
	s_cbranch_execz .LBB0_1308
	s_lshl_b32 s9, s47, 11
	s_add_i32 s9, s8, s9
	v_mul_f32_e32 v160, 0x3c800000, v135
	v_lshl_add_u32 v135, v178, 5, s9
	s_waitcnt lgkmcnt(0)
	v_add_f32_e32 v161, v138, v139
	ds_write_b64 v135, v[160:161] offset:1536
.LBB0_1308:
	s_or_b64 exec, exec, s[6:7]
	v_mov_b32_e32 v138, v117
	s_waitcnt lgkmcnt(0)
	v_mov_b32_e32 v139, v118
	v_mov_b32_e32 v160, v116
	v_mov_b32_e32 v161, v119
	v_add_f32_e64 v138, v138, v160
	v_add_f32_e64 v139, v139, v161
	v_mov_b32_e32 v160, v85
	v_mov_b32_e32 v161, v86
	v_mov_b32_e32 v162, v84
	v_mov_b32_e32 v163, v87
	v_add_f32_e64 v160, v160, v162
	v_add_f32_e64 v161, v161, v163
	v_add_f32_e32 v135, v138, v139
	v_add_f32_e64 v161, v160, v161
	v_add_f32_e64 v160, v160, v160
	v_add_f32_e32 v139, 0, v135
	v_add_f32_e32 v163, v52, v53
	v_add_f32_e32 v165, v54, v55
	v_mov_b32_e32 v162, v20
	v_mov_b32_e32 v164, v21
	v_mov_b32_e32 v160, v22
	v_mov_b32_e32 v138, v23
	v_add_f32_e64 v162, v162, v164
	v_add_f32_e64 v163, v163, v165
	v_add_f32_e64 v138, v160, v138
	v_add_f32_e64 v139, v161, v139
	s_nop 0
	v_add_f32_e64 v138, v162, v138
	v_add_f32_e64 v139, v163, v139
	s_nop 0
	v_add_f32_e32 v135, v138, v139
	ds_bpermute_b32 v138, v132, v135
	s_waitcnt lgkmcnt(0)
	v_add_f32_e32 v135, v135, v138
	ds_bpermute_b32 v138, v133, v135
	s_waitcnt lgkmcnt(0)
	v_add_f32_e32 v135, v135, v138
	v_fmamk_f32 v139, v135, 0xbc800000, v119
	v_fmamk_f32 v161, v135, 0xbc800000, v117
	v_fmamk_f32 v138, v135, 0xbc800000, v118
	v_fmamk_f32 v160, v135, 0xbc800000, v116
	v_mul_f32_e32 v161, v161, v161
	v_mul_f32_e32 v139, v139, v139
	v_fmac_f32_e32 v161, v160, v160
	v_fmac_f32_e32 v139, v138, v138
	v_fmamk_f32 v160, v135, 0xbc800000, v87
	v_fmamk_f32 v162, v135, 0xbc800000, v85
	v_add_f32_e32 v138, v161, v139
	v_fmamk_f32 v139, v135, 0xbc800000, v86
	v_fmamk_f32 v161, v135, 0xbc800000, v84
	v_mul_f32_e32 v162, v162, v162
	v_mul_f32_e32 v160, v160, v160
	v_fmac_f32_e32 v162, v161, v161
	v_fmac_f32_e32 v160, v139, v139
	v_add_f32_e32 v139, v162, v160
	v_fmamk_f32 v160, v135, 0xbc800000, v55
	v_fmamk_f32 v162, v135, 0xbc800000, v53
	v_add_f32_e32 v138, v138, v139
	v_fmamk_f32 v139, v135, 0xbc800000, v54
	v_fmamk_f32 v161, v135, 0xbc800000, v52
	v_mul_f32_e32 v162, v162, v162
	v_mul_f32_e32 v160, v160, v160
	v_fmac_f32_e32 v162, v161, v161
	v_fmac_f32_e32 v160, v139, v139
	v_add_f32_e32 v139, v162, v160
	v_fmamk_f32 v160, v135, 0xbc800000, v23
	v_fmamk_f32 v162, v135, 0xbc800000, v21
	v_add_f32_e32 v138, v139, v138
	v_fmamk_f32 v139, v135, 0xbc800000, v22
	v_fmamk_f32 v161, v135, 0xbc800000, v20
	v_mul_f32_e32 v162, v162, v162
	v_mul_f32_e32 v160, v160, v160
	v_fmac_f32_e32 v162, v161, v161
	v_fmac_f32_e32 v160, v139, v139
	v_add_f32_e32 v139, v162, v160
	v_add_f32_e32 v138, v139, v138
	ds_bpermute_b32 v139, v132, v138
	s_waitcnt lgkmcnt(0)
	v_add_f32_e32 v138, v138, v139
	ds_bpermute_b32 v139, v133, v138
	s_and_saveexec_b64 s[6:7], vcc
	s_cbranch_execz .LBB0_1310
	s_lshl_b32 s9, s47, 11
	s_add_i32 s9, s8, s9
	v_mul_f32_e32 v160, 0x3c800000, v135
	v_lshl_add_u32 v135, v178, 5, s9
	s_waitcnt lgkmcnt(0)
	v_add_f32_e32 v161, v138, v139
	ds_write_b64 v135, v[160:161] offset:4096
;     __device__ __forceinline__ bool run(const f32x4 (&v)[2][2][4][2], const Unit& u, int wr, int wc, int fr, int fq, PG8_LAS unsigned char* lds, int wid, int lane) const {
;     ...
;                 float s = 0.f;
; #pragma unroll
;                 for (int bj = 0; bj < 2; ++bj)
; #pragma unroll
;                     for (int n = 0; n < 2; ++n) { const f32x4 x = v[ai][bj][m][n]; s += (x[0] + x[1]) + (x[2] + x[3]); }
;                 s += __shfl_xor(s, 16); s += __shfl_xor(s, 32);
;                 const float mw = s * (1.0f / 64.0f); float q = 0.f;
; #pragma unroll
;                 for (int bj = 0; bj < 2; ++bj)
; #pragma unroll
;                     for (int n = 0; n < 2; ++n) { const f32x4 d = v[ai][bj][m][n] - mw; q += (d[0] * d[0] + d[1] * d[1]) + (d[2] * d[2] + d[3] * d[3]); }
;                 q += __shfl_xor(q, 16); q += __shfl_xor(q, 32);
;                 if (fq == 0) P[(ai * HALF + wr * 64 + m * 16 + fr) * 4 + wc] = (f32x2v){mw, q};
.LBB0_1310:
	s_or_b64 exec, exec, s[6:7]
	v_mov_b32_e32 v138, v121
	s_waitcnt lgkmcnt(0)
	v_mov_b32_e32 v139, v122
	v_mov_b32_e32 v160, v120
	v_mov_b32_e32 v161, v123
	v_add_f32_e64 v138, v138, v160
	v_add_f32_e64 v139, v139, v161
	v_mov_b32_e32 v160, v89
	v_mov_b32_e32 v161, v90
	v_mov_b32_e32 v162, v88
	v_mov_b32_e32 v163, v91
	v_add_f32_e64 v160, v160, v162
	v_add_f32_e64 v161, v161, v163
	v_add_f32_e32 v135, v138, v139
	v_add_f32_e64 v161, v160, v161
	v_add_f32_e64 v160, v160, v160
	v_add_f32_e32 v139, 0, v135
	v_add_f32_e32 v163, v56, v57
	v_add_f32_e32 v165, v58, v59
	v_mov_b32_e32 v162, v24
	v_mov_b32_e32 v164, v25
	v_mov_b32_e32 v160, v26
	v_mov_b32_e32 v138, v27
	v_add_f32_e64 v162, v162, v164
	v_add_f32_e64 v163, v163, v165
	v_add_f32_e64 v138, v160, v138
	v_add_f32_e64 v139, v161, v139
	s_nop 0
	v_add_f32_e64 v138, v162, v138
	v_add_f32_e64 v139, v163, v139
	s_nop 0
	v_add_f32_e32 v135, v138, v139
	ds_bpermute_b32 v138, v132, v135
	s_waitcnt lgkmcnt(0)
	v_add_f32_e32 v135, v135, v138
	ds_bpermute_b32 v138, v133, v135
	s_waitcnt lgkmcnt(0)
	v_add_f32_e32 v135, v135, v138
	v_fmamk_f32 v139, v135, 0xbc800000, v123
	v_fmamk_f32 v161, v135, 0xbc800000, v121
	v_fmamk_f32 v138, v135, 0xbc800000, v122
	v_fmamk_f32 v160, v135, 0xbc800000, v120
	v_mul_f32_e32 v161, v161, v161
	v_mul_f32_e32 v139, v139, v139
	v_fmac_f32_e32 v161, v160, v160
	v_fmac_f32_e32 v139, v138, v138
	v_fmamk_f32 v160, v135, 0xbc800000, v91
	v_fmamk_f32 v162, v135, 0xbc800000, v89
	v_add_f32_e32 v138, v161, v139
	v_fmamk_f32 v139, v135, 0xbc800000, v90
	v_fmamk_f32 v161, v135, 0xbc800000, v88
	v_mul_f32_e32 v162, v162, v162
	v_mul_f32_e32 v160, v160, v160
	v_fmac_f32_e32 v162, v161, v161
	v_fmac_f32_e32 v160, v139, v139
	v_add_f32_e32 v139, v162, v160
	v_fmamk_f32 v160, v135, 0xbc800000, v59
	v_fmamk_f32 v162, v135, 0xbc800000, v57
	v_add_f32_e32 v138, v138, v139
	v_fmamk_f32 v139, v135, 0xbc800000, v58
	v_fmamk_f32 v161, v135, 0xbc800000, v56
	v_mul_f32_e32 v162, v162, v162
	v_mul_f32_e32 v160, v160, v160
	v_fmac_f32_e32 v162, v161, v161
	v_fmac_f32_e32 v160, v139, v139
	v_add_f32_e32 v139, v162, v160
	v_fmamk_f32 v160, v135, 0xbc800000, v27
	v_fmamk_f32 v162, v135, 0xbc800000, v25
	v_add_f32_e32 v138, v139, v138
	v_fmamk_f32 v139, v135, 0xbc800000, v26
	v_fmamk_f32 v161, v135, 0xbc800000, v24
	v_mul_f32_e32 v162, v162, v162
	v_mul_f32_e32 v160, v160, v160
	v_fmac_f32_e32 v162, v161, v161
	v_fmac_f32_e32 v160, v139, v139
	v_add_f32_e32 v139, v162, v160
	v_add_f32_e32 v138, v139, v138
	ds_bpermute_b32 v139, v132, v138
	s_waitcnt lgkmcnt(0)
	v_add_f32_e32 v138, v138, v139
	ds_bpermute_b32 v139, v133, v138
	s_and_saveexec_b64 s[6:7], vcc
	s_cbranch_execz .LBB0_1312
	s_lshl_b32 s9, s47, 11
	s_add_i32 s9, s8, s9
	v_mul_f32_e32 v160, 0x3c800000, v135
	v_lshl_add_u32 v135, v178, 5, s9
	s_waitcnt lgkmcnt(0)
	v_add_f32_e32 v161, v138, v139
	ds_write_b64 v135, v[160:161] offset:4608
.LBB0_1312:
	s_or_b64 exec, exec, s[6:7]
	v_mov_b32_e32 v138, v125
	s_waitcnt lgkmcnt(0)
	v_mov_b32_e32 v139, v126
	v_mov_b32_e32 v160, v124
	v_mov_b32_e32 v161, v127
	v_add_f32_e64 v138, v138, v160
	v_add_f32_e64 v139, v139, v161
	v_mov_b32_e32 v160, v97
	v_mov_b32_e32 v161, v98
	v_mov_b32_e32 v162, v96
	v_mov_b32_e32 v163, v99
	v_add_f32_e64 v160, v160, v162
	v_add_f32_e64 v161, v161, v163
	v_add_f32_e32 v135, v138, v139
	v_add_f32_e64 v161, v160, v161
	v_add_f32_e64 v160, v160, v160
	v_add_f32_e32 v139, 0, v135
	v_add_f32_e32 v163, v60, v61
	v_add_f32_e32 v165, v62, v63
	v_mov_b32_e32 v162, v28
	v_mov_b32_e32 v164, v29
	v_mov_b32_e32 v160, v30
	v_mov_b32_e32 v138, v31
	v_add_f32_e64 v162, v162, v164
	v_add_f32_e64 v163, v163, v165
	v_add_f32_e64 v138, v160, v138
	v_add_f32_e64 v139, v161, v139
	s_nop 0
	v_add_f32_e64 v138, v162, v138
	v_add_f32_e64 v139, v163, v139
	s_nop 0
	v_add_f32_e32 v135, v138, v139
	ds_bpermute_b32 v138, v132, v135
	s_waitcnt lgkmcnt(0)
	v_add_f32_e32 v135, v135, v138
	ds_bpermute_b32 v138, v133, v135
	s_waitcnt lgkmcnt(0)
	v_add_f32_e32 v135, v135, v138
	v_fmamk_f32 v139, v135, 0xbc800000, v127
	v_fmamk_f32 v161, v135, 0xbc800000, v125
	v_fmamk_f32 v138, v135, 0xbc800000, v126
	v_fmamk_f32 v160, v135, 0xbc800000, v124
	v_mul_f32_e32 v161, v161, v161
	v_mul_f32_e32 v139, v139, v139
	v_fmac_f32_e32 v161, v160, v160
	v_fmac_f32_e32 v139, v138, v138
	v_fmamk_f32 v160, v135, 0xbc800000, v99
	v_fmamk_f32 v162, v135, 0xbc800000, v97
	v_add_f32_e32 v138, v161, v139
	v_fmamk_f32 v139, v135, 0xbc800000, v98
	v_fmamk_f32 v161, v135, 0xbc800000, v96
	v_mul_f32_e32 v162, v162, v162
	v_mul_f32_e32 v160, v160, v160
	v_fmac_f32_e32 v162, v161, v161
	v_fmac_f32_e32 v160, v139, v139
	v_add_f32_e32 v139, v162, v160
	v_fmamk_f32 v160, v135, 0xbc800000, v63
	v_fmamk_f32 v162, v135, 0xbc800000, v61
	v_add_f32_e32 v138, v138, v139
	v_fmamk_f32 v139, v135, 0xbc800000, v62
	v_fmamk_f32 v161, v135, 0xbc800000, v60
	v_mul_f32_e32 v162, v162, v162
	v_mul_f32_e32 v160, v160, v160
	v_fmac_f32_e32 v162, v161, v161
	v_fmac_f32_e32 v160, v139, v139
	v_add_f32_e32 v139, v162, v160
	v_fmamk_f32 v160, v135, 0xbc800000, v31
	v_fmamk_f32 v162, v135, 0xbc800000, v29
	v_add_f32_e32 v138, v139, v138
	v_fmamk_f32 v139, v135, 0xbc800000, v30
	v_fmamk_f32 v161, v135, 0xbc800000, v28
	v_mul_f32_e32 v162, v162, v162
	v_mul_f32_e32 v160, v160, v160
	v_fmac_f32_e32 v162, v161, v161
	v_fmac_f32_e32 v160, v139, v139
	v_add_f32_e32 v139, v162, v160
	v_add_f32_e32 v138, v139, v138
	ds_bpermute_b32 v139, v132, v138
	s_waitcnt lgkmcnt(0)
	v_add_f32_e32 v138, v138, v139
	ds_bpermute_b32 v139, v133, v138
	s_and_saveexec_b64 s[6:7], vcc
	s_cbranch_execz .LBB0_1314
	s_lshl_b32 s9, s47, 11
	s_add_i32 s9, s8, s9
	v_mul_f32_e32 v160, 0x3c800000, v135
	v_lshl_add_u32 v135, v178, 5, s9
	s_waitcnt lgkmcnt(0)
	v_add_f32_e32 v161, v138, v139
	ds_write_b64 v135, v[160:161] offset:5120
;     __device__ __forceinline__ bool run(const f32x4 (&v)[2][2][4][2], const Unit& u, int wr, int wc, int fr, int fq, PG8_LAS unsigned char* lds, int wid, int lane) const {
;     ...
;                 float s = 0.f;
; #pragma unroll
;                 for (int bj = 0; bj < 2; ++bj)
; #pragma unroll
;                     for (int n = 0; n < 2; ++n) { const f32x4 x = v[ai][bj][m][n]; s += (x[0] + x[1]) + (x[2] + x[3]); }
;                 s += __shfl_xor(s, 16); s += __shfl_xor(s, 32);
;                 const float mw = s * (1.0f / 64.0f); float q = 0.f;
; #pragma unroll
;                 for (int bj = 0; bj < 2; ++bj)
; #pragma unroll
;                     for (int n = 0; n < 2; ++n) { const f32x4 d = v[ai][bj][m][n] - mw; q += (d[0] * d[0] + d[1] * d[1]) + (d[2] * d[2] + d[3] * d[3]); }
;                 q += __shfl_xor(q, 16); q += __shfl_xor(q, 32);
;                 if (fq == 0) P[(ai * HALF + wr * 64 + m * 16 + fr) * 4 + wc] = (f32x2v){mw, q};
;             }
;         asm volatile("s_waitcnt lgkmcnt(0)" ::: "memory"); __builtin_amdgcn_s_barrier(); asm volatile("" ::: "memory");
;     ...
;         if (blockIdx.x >= 64) { const long long t0_ = clock64(); while (clock64() - t0_ < 60000) __builtin_amdgcn_s_sleep(8); }
;     ...
;         const int row = wid * 32 + (lane & 31);
;         if (lane < 32) {
;             const f32x2v a = P[row * 4 + 0], b = P[row * 4 + 1], c = P[row * 4 + 2], d = P[row * 4 + 3];
;             const float mt = (a.x + b.x + c.x + d.x) * 0.25f;
;             const float da = a.x - mt, db = b.x - mt, dc = c.x - mt, dd = d.x - mt;
;             const float m2 = (a.y + b.y) + (c.y + d.y) + 64.0f * ((da * da + db * db) + (dc * dc + dd * dd));
;             unsigned long long* slot = (unsigned long long*)xbuf + ((size_t)(u.pm * BM + row) * 4 + u.pn);
;             __hip_atomic_store(slot, ((unsigned long long)__float_as_uint(m2) << 32) | __float_as_uint(mt), __ATOMIC_RELAXED, __HIP_MEMORY_SCOPE_AGENT);
.LBB0_1314:
	s_or_b64 exec, exec, s[6:7]
	v_mov_b32_e32 v138, v129
	s_waitcnt lgkmcnt(0)
	v_mov_b32_e32 v139, v130
	v_mov_b32_e32 v160, v128
	v_mov_b32_e32 v161, v131
	v_add_f32_e64 v138, v138, v160
	v_add_f32_e64 v139, v139, v161
	v_mov_b32_e32 v160, v109
	v_mov_b32_e32 v161, v110
	v_mov_b32_e32 v162, v108
	v_mov_b32_e32 v163, v111
	v_add_f32_e64 v160, v160, v162
	v_add_f32_e64 v161, v161, v163
	v_add_f32_e32 v135, v138, v139
	v_add_f32_e64 v161, v160, v161
	v_add_f32_e64 v160, v160, v160
	v_add_f32_e32 v139, 0, v135
	v_add_f32_e32 v163, v76, v77
	v_add_f32_e32 v165, v78, v79
	v_mov_b32_e32 v162, v44
	v_mov_b32_e32 v164, v45
	v_mov_b32_e32 v160, v46
	v_mov_b32_e32 v138, v47
	v_add_f32_e64 v162, v162, v164
	v_add_f32_e64 v163, v163, v165
	v_add_f32_e64 v138, v160, v138
	v_add_f32_e64 v139, v161, v139
	s_nop 0
	v_add_f32_e64 v138, v162, v138
	v_add_f32_e64 v139, v163, v139
	s_nop 0
	v_add_f32_e32 v135, v138, v139
	ds_bpermute_b32 v138, v132, v135
	s_waitcnt lgkmcnt(0)
	v_add_f32_e32 v135, v135, v138
	ds_bpermute_b32 v138, v133, v135
	s_waitcnt lgkmcnt(0)
	v_add_f32_e32 v135, v135, v138
	v_fmamk_f32 v139, v135, 0xbc800000, v131
	v_fmamk_f32 v161, v135, 0xbc800000, v129
	v_fmamk_f32 v138, v135, 0xbc800000, v130
	v_fmamk_f32 v160, v135, 0xbc800000, v128
	v_mul_f32_e32 v161, v161, v161
	v_mul_f32_e32 v139, v139, v139
	v_fmac_f32_e32 v161, v160, v160
	v_fmac_f32_e32 v139, v138, v138
	v_fmamk_f32 v160, v135, 0xbc800000, v111
	v_fmamk_f32 v162, v135, 0xbc800000, v109
	v_add_f32_e32 v138, v161, v139
	v_fmamk_f32 v139, v135, 0xbc800000, v110
	v_fmamk_f32 v161, v135, 0xbc800000, v108
	v_mul_f32_e32 v162, v162, v162
	v_mul_f32_e32 v160, v160, v160
	v_fmac_f32_e32 v162, v161, v161
	v_fmac_f32_e32 v160, v139, v139
	v_add_f32_e32 v139, v162, v160
	v_fmamk_f32 v160, v135, 0xbc800000, v79
	v_fmamk_f32 v162, v135, 0xbc800000, v77
	v_add_f32_e32 v138, v138, v139
	v_fmamk_f32 v139, v135, 0xbc800000, v78
	v_fmamk_f32 v161, v135, 0xbc800000, v76
	v_mul_f32_e32 v162, v162, v162
	v_mul_f32_e32 v160, v160, v160
	v_fmac_f32_e32 v162, v161, v161
	v_fmac_f32_e32 v160, v139, v139
	v_add_f32_e32 v139, v162, v160
	v_fmamk_f32 v160, v135, 0xbc800000, v47
	v_fmamk_f32 v162, v135, 0xbc800000, v45
	v_add_f32_e32 v138, v139, v138
	v_fmamk_f32 v139, v135, 0xbc800000, v46
	v_fmamk_f32 v161, v135, 0xbc800000, v44
	v_mul_f32_e32 v162, v162, v162
	v_mul_f32_e32 v160, v160, v160
	v_fmac_f32_e32 v162, v161, v161
	v_fmac_f32_e32 v160, v139, v139
	v_add_f32_e32 v139, v162, v160
	v_add_f32_e32 v138, v139, v138
	ds_bpermute_b32 v132, v132, v138
	s_waitcnt lgkmcnt(0)
	v_add_f32_e32 v132, v138, v132
	ds_bpermute_b32 v133, v133, v132
	s_and_saveexec_b64 s[6:7], vcc
	s_cbranch_execz .LBB0_1316
	s_lshl_b32 s9, s47, 11
	s_add_i32 s8, s8, s9
	v_mul_f32_e32 v138, 0x3c800000, v135
	v_lshl_add_u32 v135, v178, 5, s8
	s_waitcnt lgkmcnt(0)
	v_add_f32_e32 v139, v132, v133
	ds_write_b64 v135, v[138:139] offset:5632
.LBB0_1316:
	s_or_b64 exec, exec, s[6:7]
	v_and_b32_e32 v132, 31, v177
	s_waitcnt lgkmcnt(0)
	s_barrier
	v_lshl_or_b32 v160, s15, 5, v132
	s_add_u32 s18, s12, 0x3780000
	v_add_u32_e32 v132, s20, v160
	s_addc_u32 s19, s13, 0
	v_cmp_gt_u32_e64 s[6:7], 32, v134
	s_waitcnt lgkmcnt(0)
	v_ashrrev_i32_e32 v133, 31, v132
	s_and_saveexec_b64 s[8:9], s[6:7]
	s_cbranch_execz .LBB0_1318
	v_lshl_add_u32 v135, v160, 5, 0
	ds_read_b128 v[162:165], v135
	ds_read_b128 v[166:169], v135 offset:16
	s_ashr_i32 s15, s14, 31
	s_waitcnt lgkmcnt(1)
	v_add_f32_e32 v135, v162, v164
	s_waitcnt lgkmcnt(0)
	v_add_f32_e32 v135, v135, v166
	v_add_f32_e32 v135, v135, v168
	v_fmamk_f32 v139, v135, 0xbe800000, v162
	v_fmac_f32_e32 v164, 0xbe800000, v135
	v_fmamk_f32 v161, v135, 0xbe800000, v166
	v_fmac_f32_e32 v168, 0xbe800000, v135
	v_mul_f32_e32 v171, v139, v139
	v_mul_f32_e32 v173, v164, v164
	v_mul_f32_e32 v175, v161, v161
	v_mul_f32_e32 v179, v168, v168
	v_mov_b32_e32 v170, v163
	v_mov_b32_e32 v172, v165
	v_mov_b32_e32 v174, v167
	v_mov_b32_e32 v178, v169
	v_add_f32_e64 v162, v170, v172
	v_add_f32_e64 v163, v171, v173
	v_add_f32_e64 v164, v174, v178
	v_add_f32_e64 v165, v175, v179
	v_mul_f32_e32 v138, 0x3e800000, v135
	v_add_f32_e64 v162, v162, v164
	v_add_f32_e64 v163, v163, v165
	s_nop 0
	v_fmamk_f32 v139, v163, 0x42800000, v162
	v_lshlrev_b64 v[162:163], 5, v[132:133]
	v_lshl_add_u64 v[162:163], s[18:19], 0, v[162:163]
	v_lshl_add_u64 v[162:163], s[14:15], 3, v[162:163]
	global_store_dwordx2 v[162:163], v[138:139], off sc1

; __device__ __forceinline__ unsigned cvt_pk_bf16(float lo, float hi) { unsigned r; asm volatile("v_cvt_pk_bf16_f32 %0, %1, %2" : "=v"(r) : "v"(lo), "v"(hi)); return r; }
;     __device__ __forceinline__ void fused(f32x4 (&acc)[2][2][4][2], const Unit& u, int wr, int wc, int fr, int fq, PG8_LAS unsigned char* lds, int wid, int lane) const {
;     ...
; #pragma unroll
;         for (int bj = 0; bj < 2; ++bj)
; #pragma unroll
;             for (int n = 0; n < 2; ++n) {
;                 const int col = col0 + bj * HALF + n * 16;
;                 const f32x4 lg = *(const f32x4*)(lng + col), lb = *(const f32x4*)(lnb + col);
;                 f32x4 sc1 = (f32x4){1.f, 1.f, 1.f, 1.f}, sh = (f32x4){0.f, 0.f, 0.f, 0.f};
;                 if (DO_U) { sc1 = *(const f32x4*)(msc + mo + col) + 1.0f; sh = *(const f32x4*)(msh + mo + col); }
; #pragma unroll
;                 for (int ai = 0; ai < 2; ++ai)
; #pragma unroll
;                     for (int m = 0; m < 4; ++m) { const int r = ai * HALF + wr * 64 + m * 16 + fr; const f32x2v sr = S[r]; const size_t off = (size_t)(u.pm * BM + r) * 1024 + col;
;                         f32x4 y = (acc[ai][bj][m][n] - sr.x) * sr.y * lg + lb; if (bad) y = (f32x4){qnan, qnan, qnan, qnan};
;                         *(f32x4*)(out + off) = y;
;                         if (DO_U) { const f32x4 uu = y * sc1 + sh; u32x2v w; w.x = cvt_pk_bf16(uu[0], uu[1]); w.y = cvt_pk_bf16(uu[2], uu[3]); *(u32x2v*)(U + off) = w; } }
.LBB0_1339:
	s_or_b64 exec, exec, s[8:9]
	s_mov_b64 s[6:7], 0x1000
	v_lshl_add_u64 v[162:163], v[0:1], 0, s[6:7]
	v_lshl_add_u64 v[160:161], v[2:3], 0, s[6:7]
	s_add_u32 s6, s12, 0xd600000
	s_addc_u32 s7, s13, 0
	s_add_u32 s8, s12, s16
	s_addc_u32 s9, s13, s17
	v_lshl_add_u64 v[172:173], s[8:9], 0, v[136:137]
	s_movk_i32 s3, 0x7000
	v_lshl_add_u64 v[0:1], v[162:163], 0, v[136:137]
	v_lshl_add_u64 v[132:133], v[160:161], 0, v[136:137]
	v_add_co_u32_e32 v136, vcc, s3, v172
	s_waitcnt lgkmcnt(0)
	s_barrier
	s_nop 0
	v_addc_co_u32_e32 v137, vcc, 0, v173, vcc
	s_movk_i32 s3, 0x6000
	global_load_dwordx4 v[0:3], v[0:1], off
	v_lshl_add_u32 v177, v176, 3, 0
	global_load_dwordx4 v[132:135], v[132:133], off
	ds_read_b64 v[166:167], v177 offset:8192
	global_load_dwordx4 v[178:181], v[136:137], off
	v_add_co_u32_e32 v136, vcc, s3, v172
	v_add_u32_e32 v174, s20, v176
	s_nop 0
	v_addc_co_u32_e32 v137, vcc, 0, v173, vcc
	global_load_dwordx4 v[136:139], v[136:137], off
	s_waitcnt lgkmcnt(0)
	v_sub_f32_e32 v95, v95, v166
	v_sub_f32_e32 v94, v94, v166
	v_sub_f32_e32 v93, v93, v166
	v_sub_f32_e32 v92, v92, v166
	v_ashrrev_i32_e32 v175, 31, v174
	v_mul_f32_e64 v92, v167, v92
	v_mul_f32_e64 v93, v167, v93
	v_mul_f32_e64 v94, v167, v94
	v_mul_f32_e64 v95, v167, v95
	v_mov_b32_e32 v176, 0x7fc00000
	v_lshlrev_b64 v[168:169], 10, v[174:175]
	v_cmp_eq_u32_e32 vcc, 0, v164
	v_lshl_add_u64 v[186:187], v[168:169], 0, v[140:141]
	v_lshl_add_u64 v[186:187], v[186:187], 1, s[6:7]
	v_add_u32_e32 v170, 16, v174
	v_ashrrev_i32_e32 v171, 31, v170
	v_add_u32_e32 v182, 32, v174
	v_ashrrev_i32_e32 v183, 31, v182
	v_add_u32_e32 v184, 48, v174
	v_ashrrev_i32_e32 v185, 31, v184
	s_mov_b64 s[8:9], 0x7000
	s_waitcnt vmcnt(0)
	v_fma_f32 v94, v2, v94, v134
	v_fma_f32 v95, v3, v95, v135
	v_fma_f32 v92, v0, v92, v132
	v_fma_f32 v93, v1, v93, v133
	v_cndmask_b32_e32 v167, v176, v95, vcc
	v_cndmask_b32_e32 v166, v176, v94, vcc
	v_cndmask_b32_e32 v165, v176, v93, vcc
	v_cndmask_b32_e32 v164, v176, v92, vcc
	v_add_f32_e64 v92, v178, 1.0
	v_add_f32_e64 v93, v179, 1.0
	global_store_dwordx4 v[142:143], v[164:167], off sc0 sc1
	v_add_f32_e64 v94, v180, 1.0
	v_add_f32_e64 v95, v181, 1.0
	s_nop 0
	v_fma_f32 v164, v92, v164, v136
	v_fma_f32 v165, v93, v165, v137
	v_fma_f32 v166, v94, v166, v138
	v_fma_f32 v167, v95, v167, v139
	v_cvt_pk_bf16_f32 v164, v164, v165
	s_nop 0
	v_cvt_pk_bf16_f32 v165, v166, v167
	global_store_dwordx2 v[186:187], v[164:165], off
	ds_read_b64 v[164:165], v177 offset:8320
	v_lshlrev_b64 v[166:167], 10, v[170:171]
	v_lshl_add_u64 v[170:171], v[166:167], 0, v[140:141]
	v_lshl_add_u64 v[170:171], v[170:171], 1, s[6:7]
	s_waitcnt lgkmcnt(0)
	v_sub_f32_e32 v103, v103, v164
	v_sub_f32_e32 v102, v102, v164
	v_sub_f32_e32 v101, v101, v164
	v_sub_f32_e32 v100, v100, v164
	v_mul_f32_e64 v100, v165, v100
	v_mul_f32_e64 v101, v165, v101
	v_mul_f32_e64 v102, v165, v102
	v_mul_f32_e64 v103, v165, v103
	v_fma_f32 v100, v0, v100, v132
	v_fma_f32 v101, v1, v101, v133
	v_fma_f32 v102, v2, v102, v134
	v_fma_f32 v103, v3, v103, v135
	v_cndmask_b32_e32 v101, v176, v101, vcc
	v_cndmask_b32_e32 v103, v176, v103, vcc
	v_cndmask_b32_e32 v102, v176, v102, vcc
	v_cndmask_b32_e32 v100, v176, v100, vcc
	global_store_dwordx4 v[146:147], v[100:103], off sc0 sc1
	v_lshlrev_b64 v[164:165], 10, v[182:183]
	s_nop 0
	v_fma_f32 v100, v92, v100, v136
	v_fma_f32 v101, v93, v101, v137
	v_fma_f32 v102, v94, v102, v138
	v_fma_f32 v103, v95, v103, v139
	v_cvt_pk_bf16_f32 v100, v100, v101
	s_nop 0
	v_cvt_pk_bf16_f32 v101, v102, v103
	global_store_dwordx2 v[170:171], v[100:101], off
	ds_read_b64 v[100:101], v177 offset:8448
	v_lshl_add_u64 v[102:103], v[164:165], 0, v[140:141]
	v_lshl_add_u64 v[170:171], v[102:103], 1, s[6:7]
	s_waitcnt lgkmcnt(0)
	v_sub_f32_e32 v103, v107, v100
	v_sub_f32_e32 v102, v106, v100
	v_sub_f32_e32 v105, v105, v100
	v_sub_f32_e32 v104, v104, v100
	v_mul_f32_e64 v104, v101, v104
	v_mul_f32_e64 v105, v101, v105
	v_mul_f32_e64 v100, v101, v102
	v_mul_f32_e64 v101, v101, v103
	v_fma_f32 v104, v0, v104, v132
	v_fma_f32 v105, v1, v105, v133
	v_fma_f32 v100, v2, v100, v134
	v_fma_f32 v101, v3, v101, v135
	s_nop 0
	v_cndmask_b32_e32 v103, v176, v101, vcc
	v_cndmask_b32_e32 v102, v176, v100, vcc
	v_cndmask_b32_e32 v101, v176, v105, vcc
	v_cndmask_b32_e32 v100, v176, v104, vcc
	global_store_dwordx4 v[148:149], v[100:103], off sc0 sc1
	v_lshlrev_b64 v[104:105], 10, v[184:185]
	v_lshl_add_u64 v[106:107], v[104:105], 0, v[140:141]
	v_fma_f32 v100, v92, v100, v136
	v_fma_f32 v101, v93, v101, v137
	v_fma_f32 v102, v94, v102, v138
	v_fma_f32 v103, v95, v103, v139
	v_cvt_pk_bf16_f32 v100, v100, v101
	s_nop 0
	v_cvt_pk_bf16_f32 v101, v102, v103
	global_store_dwordx2 v[170:171], v[100:101], off
	ds_read_b64 v[100:101], v177 offset:8576
	v_lshl_add_u64 v[170:171], v[172:173], 0, s[8:9]
	s_mov_b64 s[8:9], 0x6000
	s_waitcnt lgkmcnt(0)
	v_sub_f32_e32 v103, v115, v100
	v_sub_f32_e32 v102, v114, v100
	v_sub_f32_e32 v113, v113, v100
	v_sub_f32_e32 v112, v112, v100
	v_mul_f32_e64 v112, v101, v112
	v_mul_f32_e64 v113, v101, v113
	v_mul_f32_e64 v100, v101, v102
	v_mul_f32_e64 v101, v101, v103
	v_fma_f32 v112, v0, v112, v132
	v_fma_f32 v113, v1, v113, v133
	v_fma_f32 v100, v2, v100, v134
	v_fma_f32 v101, v3, v101, v135
	s_nop 0
	v_cndmask_b32_e32 v103, v176, v101, vcc
	v_cndmask_b32_e32 v102, v176, v100, vcc
	v_cndmask_b32_e32 v101, v176, v113, vcc
	v_cndmask_b32_e32 v100, v176, v112, vcc
	global_store_dwordx4 v[150:151], v[100:103], off sc0 sc1
	s_nop 1
	v_fma_f32 v102, v94, v102, v138
	v_fma_f32 v103, v95, v103, v139
	v_fma_f32 v100, v92, v100, v136
	v_fma_f32 v101, v93, v101, v137
	s_nop 0
	v_cvt_pk_bf16_f32 v100, v100, v101
	v_cvt_pk_bf16_f32 v101, v102, v103
	v_lshl_add_u64 v[102:103], v[106:107], 1, s[6:7]
	global_store_dwordx2 v[102:103], v[100:101], off
	ds_read_b64 v[100:101], v177 offset:9216
	v_add_u32_e32 v102, 0x80, v174
	v_ashrrev_i32_e32 v103, 31, v102
	v_lshlrev_b64 v[106:107], 10, v[102:103]
	v_lshl_add_u64 v[112:113], v[106:107], 0, v[140:141]
	s_waitcnt lgkmcnt(0)
; __device__ __forceinline__ unsigned cvt_pk_bf16(float lo, float hi) { unsigned r; asm volatile("v_cvt_pk_bf16_f32 %0, %1, %2" : "=v"(r) : "v"(lo), "v"(hi)); return r; }
;     __device__ __forceinline__ void fused(f32x4 (&acc)[2][2][4][2], const Unit& u, int wr, int wc, int fr, int fq, PG8_LAS unsigned char* lds, int wid, int lane) const {
;     ...
; #pragma unroll
;         for (int bj = 0; bj < 2; ++bj)
; #pragma unroll
;             for (int n = 0; n < 2; ++n) {
;                 const int col = col0 + bj * HALF + n * 16;
;                 const f32x4 lg = *(const f32x4*)(lng + col), lb = *(const f32x4*)(lnb + col);
;                 f32x4 sc1 = (f32x4){1.f, 1.f, 1.f, 1.f}, sh = (f32x4){0.f, 0.f, 0.f, 0.f};
;                 if (DO_U) { sc1 = *(const f32x4*)(msc + mo + col) + 1.0f; sh = *(const f32x4*)(msh + mo + col); }
; #pragma unroll
;                 for (int ai = 0; ai < 2; ++ai)
; #pragma unroll
;                     for (int m = 0; m < 4; ++m) { const int r = ai * HALF + wr * 64 + m * 16 + fr; const f32x2v sr = S[r]; const size_t off = (size_t)(u.pm * BM + r) * 1024 + col;
;                         f32x4 y = (acc[ai][bj][m][n] - sr.x) * sr.y * lg + lb; if (bad) y = (f32x4){qnan, qnan, qnan, qnan};
;                         *(f32x4*)(out + off) = y;
;                         if (DO_U) { const f32x4 uu = y * sc1 + sh; u32x2v w; w.x = cvt_pk_bf16(uu[0], uu[1]); w.y = cvt_pk_bf16(uu[2], uu[3]); *(u32x2v*)(U + off) = w; } }
	v_sub_f32_e32 v103, v119, v100
	v_sub_f32_e32 v102, v118, v100
	v_sub_f32_e32 v115, v117, v100
	v_sub_f32_e32 v114, v116, v100
	v_mul_f32_e64 v114, v101, v114
	v_mul_f32_e64 v115, v101, v115
	v_mul_f32_e64 v100, v101, v102
	v_mul_f32_e64 v101, v101, v103
	v_fma_f32 v114, v0, v114, v132
	v_fma_f32 v115, v1, v115, v133
	v_fma_f32 v100, v2, v100, v134
	v_fma_f32 v101, v3, v101, v135
	s_nop 0
	v_cndmask_b32_e32 v103, v176, v101, vcc
	v_cndmask_b32_e32 v102, v176, v100, vcc
	v_cndmask_b32_e32 v101, v176, v115, vcc
	v_cndmask_b32_e32 v100, v176, v114, vcc
	global_store_dwordx4 v[152:153], v[100:103], off sc0 sc1
	s_nop 1
	v_fma_f32 v102, v94, v102, v138
	v_fma_f32 v103, v95, v103, v139
	v_fma_f32 v100, v92, v100, v136
	v_fma_f32 v101, v93, v101, v137
	s_nop 0
	v_cvt_pk_bf16_f32 v100, v100, v101
	v_cvt_pk_bf16_f32 v101, v102, v103
	v_lshl_add_u64 v[102:103], v[112:113], 1, s[6:7]
	global_store_dwordx2 v[102:103], v[100:101], off
	ds_read_b64 v[100:101], v177 offset:9344
	v_add_u32_e32 v102, 0x90, v174
	v_ashrrev_i32_e32 v103, 31, v102
	v_lshlrev_b64 v[112:113], 10, v[102:103]
	v_lshl_add_u64 v[114:115], v[112:113], 0, v[140:141]
	s_waitcnt lgkmcnt(0)
	v_sub_f32_e32 v103, v123, v100
	v_sub_f32_e32 v102, v122, v100
	v_sub_f32_e32 v117, v121, v100
	v_sub_f32_e32 v116, v120, v100
	v_mul_f32_e64 v116, v101, v116
	v_mul_f32_e64 v117, v101, v117
	v_mul_f32_e64 v100, v101, v102
	v_mul_f32_e64 v101, v101, v103
	v_fma_f32 v116, v0, v116, v132
	v_fma_f32 v117, v1, v117, v133
	v_fma_f32 v100, v2, v100, v134
	v_fma_f32 v101, v3, v101, v135
	s_nop 0
	v_cndmask_b32_e32 v103, v176, v101, vcc
	v_cndmask_b32_e32 v102, v176, v100, vcc
	v_cndmask_b32_e32 v101, v176, v117, vcc
	v_cndmask_b32_e32 v100, v176, v116, vcc
	global_store_dwordx4 v[154:155], v[100:103], off sc0 sc1
	s_nop 1
	v_fma_f32 v102, v94, v102, v138
	v_fma_f32 v103, v95, v103, v139
	v_fma_f32 v100, v92, v100, v136
	v_fma_f32 v101, v93, v101, v137
	s_nop 0
	v_cvt_pk_bf16_f32 v100, v100, v101
	v_cvt_pk_bf16_f32 v101, v102, v103
	v_lshl_add_u64 v[102:103], v[114:115], 1, s[6:7]
	global_store_dwordx2 v[102:103], v[100:101], off
	ds_read_b64 v[100:101], v177 offset:9472
	v_add_u32_e32 v102, 0xa0, v174
	v_ashrrev_i32_e32 v103, 31, v102
	v_lshlrev_b64 v[114:115], 10, v[102:103]
	v_lshl_add_u64 v[116:117], v[114:115], 0, v[140:141]
	s_waitcnt lgkmcnt(0)
	v_sub_f32_e32 v103, v127, v100
	v_sub_f32_e32 v102, v126, v100
	v_sub_f32_e32 v119, v125, v100
	v_sub_f32_e32 v118, v124, v100
	v_mul_f32_e64 v118, v101, v118
	v_mul_f32_e64 v119, v101, v119
	v_mul_f32_e64 v100, v101, v102
	v_mul_f32_e64 v101, v101, v103
	v_fma_f32 v118, v0, v118, v132
	v_fma_f32 v119, v1, v119, v133
	v_fma_f32 v100, v2, v100, v134
	v_fma_f32 v101, v3, v101, v135
	s_nop 0
	v_cndmask_b32_e32 v103, v176, v101, vcc
	v_cndmask_b32_e32 v102, v176, v100, vcc
	v_cndmask_b32_e32 v101, v176, v119, vcc
	v_cndmask_b32_e32 v100, v176, v118, vcc
	global_store_dwordx4 v[156:157], v[100:103], off sc0 sc1
	s_nop 1
	v_fma_f32 v102, v94, v102, v138
	v_fma_f32 v103, v95, v103, v139
	v_fma_f32 v100, v92, v100, v136
	v_fma_f32 v101, v93, v101, v137
	s_nop 0
	v_cvt_pk_bf16_f32 v100, v100, v101
	v_cvt_pk_bf16_f32 v101, v102, v103
	v_lshl_add_u64 v[102:103], v[116:117], 1, s[6:7]
	global_store_dwordx2 v[102:103], v[100:101], off
	ds_read_b64 v[100:101], v177 offset:9600
	v_add_u32_e32 v102, 0xb0, v174
	v_ashrrev_i32_e32 v103, 31, v102
	v_lshlrev_b64 v[116:117], 10, v[102:103]
	v_lshl_add_u64 v[102:103], v[116:117], 0, v[140:141]
	s_waitcnt lgkmcnt(0)
	v_sub_f32_e32 v119, v131, v100
	v_sub_f32_e32 v118, v130, v100
	v_sub_f32_e32 v121, v129, v100
	v_sub_f32_e32 v120, v128, v100
	v_mul_f32_e64 v120, v101, v120
	v_mul_f32_e64 v121, v101, v121
	v_mul_f32_e64 v100, v101, v118
	v_mul_f32_e64 v101, v101, v119
	v_fma_f32 v0, v0, v120, v132
	v_fma_f32 v1, v1, v121, v133
	v_fma_f32 v2, v2, v100, v134
	v_fma_f32 v3, v3, v101, v135
	v_cndmask_b32_e32 v1, v176, v1, vcc
	v_cndmask_b32_e32 v3, v176, v3, vcc
	v_cndmask_b32_e32 v2, v176, v2, vcc
	v_cndmask_b32_e32 v0, v176, v0, vcc
	global_store_dwordx4 v[158:159], v[0:3], off sc0 sc1
	v_or_b32_e32 v120, 16, v140
	v_ashrrev_i32_e32 v121, 31, v120
	v_fma_f32 v2, v94, v2, v138
	v_fma_f32 v3, v95, v3, v139
	v_fma_f32 v0, v92, v0, v136
	v_fma_f32 v1, v93, v1, v137
	v_lshl_add_u64 v[118:119], v[172:173], 0, s[8:9]
	v_cvt_pk_bf16_f32 v0, v0, v1
	v_cvt_pk_bf16_f32 v1, v2, v3
	v_lshl_add_u64 v[2:3], v[102:103], 1, s[6:7]
	global_store_dwordx2 v[2:3], v[0:1], off
	v_lshlrev_b64 v[0:1], 2, v[120:121]
	v_lshl_add_u64 v[2:3], v[162:163], 0, v[0:1]
	v_lshl_add_u64 v[0:1], v[160:161], 0, v[0:1]
	global_load_dwordx4 v[92:95], v[2:3], off
	global_load_dwordx4 v[122:125], v[170:171], off offset:64
	global_load_dwordx4 v[100:103], v[0:1], off
	ds_read_b64 v[126:127], v177 offset:8192
	global_load_dwordx4 v[0:3], v[118:119], off offset:64
	v_lshl_add_u64 v[128:129], v[168:169], 0, v[120:121]
	s_waitcnt lgkmcnt(0)
	v_sub_f32_e32 v67, v67, v126
	v_sub_f32_e32 v66, v66, v126
	v_sub_f32_e32 v65, v65, v126
	v_sub_f32_e32 v64, v64, v126
	v_mul_f32_e64 v130, v127, v64
	v_mul_f32_e64 v131, v127, v65
	v_mul_f32_e64 v126, v127, v66
	v_mul_f32_e64 v127, v127, v67
	s_waitcnt vmcnt(0)
	v_add_f32_e64 v64, v122, 1.0
	v_add_f32_e64 v65, v123, 1.0
	v_fma_f32 v122, v94, v126, v102
	v_fma_f32 v123, v95, v127, v103
	v_fma_f32 v126, v92, v130, v100
	v_fma_f32 v127, v93, v131, v101
	v_add_f32_e64 v66, v124, 1.0
	v_add_f32_e64 v67, v125, 1.0
	v_cndmask_b32_e32 v125, v176, v123, vcc
	v_cndmask_b32_e32 v124, v176, v122, vcc
	v_cndmask_b32_e32 v123, v176, v127, vcc
	v_cndmask_b32_e32 v122, v176, v126, vcc
	global_store_dwordx4 v[142:143], v[122:125], off offset:64 sc0 sc1
	s_nop 1
	v_fma_f32 v124, v66, v124, v2
	v_fma_f32 v125, v67, v125, v3
	v_fma_f32 v122, v64, v122, v0
	v_fma_f32 v123, v65, v123, v1
	s_nop 0
	v_cvt_pk_bf16_f32 v122, v122, v123
	v_cvt_pk_bf16_f32 v123, v124, v125
	v_lshl_add_u64 v[124:125], v[128:129], 1, s[6:7]
	global_store_dwordx2 v[124:125], v[122:123], off
	ds_read_b64 v[122:123], v177 offset:8320
	v_lshl_add_u64 v[124:125], v[166:167], 0, v[120:121]
	s_waitcnt lgkmcnt(0)
; __device__ __forceinline__ unsigned cvt_pk_bf16(float lo, float hi) { unsigned r; asm volatile("v_cvt_pk_bf16_f32 %0, %1, %2" : "=v"(r) : "v"(lo), "v"(hi)); return r; }
;     __device__ __forceinline__ void fused(f32x4 (&acc)[2][2][4][2], const Unit& u, int wr, int wc, int fr, int fq, PG8_LAS unsigned char* lds, int wid, int lane) const {
;     ...
; #pragma unroll
;         for (int bj = 0; bj < 2; ++bj)
; #pragma unroll
;             for (int n = 0; n < 2; ++n) {
;                 const int col = col0 + bj * HALF + n * 16;
;                 const f32x4 lg = *(const f32x4*)(lng + col), lb = *(const f32x4*)(lnb + col);
;                 f32x4 sc1 = (f32x4){1.f, 1.f, 1.f, 1.f}, sh = (f32x4){0.f, 0.f, 0.f, 0.f};
;                 if (DO_U) { sc1 = *(const f32x4*)(msc + mo + col) + 1.0f; sh = *(const f32x4*)(msh + mo + col); }
; #pragma unroll
;                 for (int ai = 0; ai < 2; ++ai)
; #pragma unroll
;                     for (int m = 0; m < 4; ++m) { const int r = ai * HALF + wr * 64 + m * 16 + fr; const f32x2v sr = S[r]; const size_t off = (size_t)(u.pm * BM + r) * 1024 + col;
;                         f32x4 y = (acc[ai][bj][m][n] - sr.x) * sr.y * lg + lb; if (bad) y = (f32x4){qnan, qnan, qnan, qnan};
;                         *(f32x4*)(out + off) = y;
;                         if (DO_U) { const f32x4 uu = y * sc1 + sh; u32x2v w; w.x = cvt_pk_bf16(uu[0], uu[1]); w.y = cvt_pk_bf16(uu[2], uu[3]); *(u32x2v*)(U + off) = w; } }
	v_sub_f32_e32 v71, v71, v122
	v_sub_f32_e32 v70, v70, v122
	v_sub_f32_e32 v69, v69, v122
	v_sub_f32_e32 v68, v68, v122
	v_mul_f32_e64 v68, v123, v68
	v_mul_f32_e64 v69, v123, v69
	v_mul_f32_e64 v70, v123, v70
	v_mul_f32_e64 v71, v123, v71
	v_fma_f32 v68, v92, v68, v100
	v_fma_f32 v69, v93, v69, v101
	v_fma_f32 v70, v94, v70, v102
	v_fma_f32 v71, v95, v71, v103
	v_cndmask_b32_e32 v69, v176, v69, vcc
	v_cndmask_b32_e32 v71, v176, v71, vcc
	v_cndmask_b32_e32 v70, v176, v70, vcc
	v_cndmask_b32_e32 v68, v176, v68, vcc
	global_store_dwordx4 v[146:147], v[68:71], off offset:64 sc0 sc1
	v_lshl_add_u64 v[122:123], v[164:165], 0, v[120:121]
	s_nop 0
	v_fma_f32 v70, v66, v70, v2
	v_fma_f32 v71, v67, v71, v3
	v_fma_f32 v68, v64, v68, v0
	v_fma_f32 v69, v65, v69, v1
	s_nop 0
	v_cvt_pk_bf16_f32 v68, v68, v69
	v_cvt_pk_bf16_f32 v69, v70, v71
	v_lshl_add_u64 v[70:71], v[124:125], 1, s[6:7]
	global_store_dwordx2 v[70:71], v[68:69], off
	ds_read_b64 v[68:69], v177 offset:8448
	s_waitcnt lgkmcnt(0)
	v_sub_f32_e32 v71, v75, v68
	v_sub_f32_e32 v70, v74, v68
	v_sub_f32_e32 v73, v73, v68
	v_sub_f32_e32 v72, v72, v68
	v_mul_f32_e64 v72, v69, v72
	v_mul_f32_e64 v73, v69, v73
	v_mul_f32_e64 v68, v69, v70
	v_mul_f32_e64 v69, v69, v71
	v_fma_f32 v72, v92, v72, v100
	v_fma_f32 v73, v93, v73, v101
	v_fma_f32 v68, v94, v68, v102
	v_fma_f32 v69, v95, v69, v103
	s_nop 0
	v_cndmask_b32_e32 v71, v176, v69, vcc
	v_cndmask_b32_e32 v70, v176, v68, vcc
	v_cndmask_b32_e32 v69, v176, v73, vcc
	v_cndmask_b32_e32 v68, v176, v72, vcc
	global_store_dwordx4 v[148:149], v[68:71], off offset:64 sc0 sc1
	v_lshl_add_u64 v[72:73], v[104:105], 0, v[120:121]
	s_nop 0
	v_fma_f32 v70, v66, v70, v2
	v_fma_f32 v71, v67, v71, v3
	v_fma_f32 v68, v64, v68, v0
	v_fma_f32 v69, v65, v69, v1
	s_nop 0
	v_cvt_pk_bf16_f32 v68, v68, v69
	v_cvt_pk_bf16_f32 v69, v70, v71
	v_lshl_add_u64 v[70:71], v[122:123], 1, s[6:7]
	global_store_dwordx2 v[70:71], v[68:69], off
	ds_read_b64 v[68:69], v177 offset:8576
	s_waitcnt lgkmcnt(0)
	v_sub_f32_e32 v71, v83, v68
	v_sub_f32_e32 v70, v82, v68
	v_sub_f32_e32 v75, v81, v68
	v_sub_f32_e32 v74, v80, v68
	v_mul_f32_e64 v74, v69, v74
	v_mul_f32_e64 v75, v69, v75
	v_mul_f32_e64 v68, v69, v70
	v_mul_f32_e64 v69, v69, v71
	v_fma_f32 v74, v92, v74, v100
	v_fma_f32 v75, v93, v75, v101
	v_fma_f32 v68, v94, v68, v102
	v_fma_f32 v69, v95, v69, v103
	v_or_b32_e32 v80, 0x80, v140
	v_cndmask_b32_e32 v71, v176, v69, vcc
	v_cndmask_b32_e32 v70, v176, v68, vcc
	v_cndmask_b32_e32 v69, v176, v75, vcc
	v_cndmask_b32_e32 v68, v176, v74, vcc
	global_store_dwordx4 v[150:151], v[68:71], off offset:64 sc0 sc1
	v_ashrrev_i32_e32 v81, 31, v80
	s_nop 0
	v_fma_f32 v70, v66, v70, v2
	v_fma_f32 v71, v67, v71, v3
	v_fma_f32 v68, v64, v68, v0
	v_fma_f32 v69, v65, v69, v1
	s_nop 0
	v_cvt_pk_bf16_f32 v68, v68, v69
	v_cvt_pk_bf16_f32 v69, v70, v71
	v_lshl_add_u64 v[70:71], v[72:73], 1, s[6:7]
	global_store_dwordx2 v[70:71], v[68:69], off
	ds_read_b64 v[68:69], v177 offset:9216
	v_lshl_add_u64 v[72:73], v[106:107], 0, v[120:121]
	s_waitcnt lgkmcnt(0)
	v_sub_f32_e32 v71, v87, v68
	v_sub_f32_e32 v70, v86, v68
	v_sub_f32_e32 v75, v85, v68
	v_sub_f32_e32 v74, v84, v68
	v_mul_f32_e64 v74, v69, v74
	v_mul_f32_e64 v75, v69, v75
	v_mul_f32_e64 v68, v69, v70
	v_mul_f32_e64 v69, v69, v71
	v_fma_f32 v74, v92, v74, v100
	v_fma_f32 v75, v93, v75, v101
	v_fma_f32 v68, v94, v68, v102
	v_fma_f32 v69, v95, v69, v103
	v_lshl_add_u64 v[84:85], v[168:169], 0, v[80:81]
	v_cndmask_b32_e32 v71, v176, v69, vcc
	v_cndmask_b32_e32 v70, v176, v68, vcc
	v_cndmask_b32_e32 v69, v176, v75, vcc
	v_cndmask_b32_e32 v68, v176, v74, vcc
	global_store_dwordx4 v[152:153], v[68:71], off offset:64 sc0 sc1
	s_nop 1
	v_fma_f32 v70, v66, v70, v2
	v_fma_f32 v71, v67, v71, v3
	v_fma_f32 v68, v64, v68, v0
	v_fma_f32 v69, v65, v69, v1
	s_nop 0
	v_cvt_pk_bf16_f32 v68, v68, v69
	v_cvt_pk_bf16_f32 v69, v70, v71
	v_lshl_add_u64 v[70:71], v[72:73], 1, s[6:7]
	global_store_dwordx2 v[70:71], v[68:69], off
	ds_read_b64 v[68:69], v177 offset:9344
	v_lshl_add_u64 v[72:73], v[112:113], 0, v[120:121]
	s_waitcnt lgkmcnt(0)
	v_sub_f32_e32 v71, v91, v68
	v_sub_f32_e32 v70, v90, v68
	v_sub_f32_e32 v75, v89, v68
	v_sub_f32_e32 v74, v88, v68
	v_mul_f32_e64 v74, v69, v74
	v_mul_f32_e64 v75, v69, v75
	v_mul_f32_e64 v68, v69, v70
	v_mul_f32_e64 v69, v69, v71
	v_fma_f32 v74, v92, v74, v100
	v_fma_f32 v75, v93, v75, v101
	v_fma_f32 v68, v94, v68, v102
	v_fma_f32 v69, v95, v69, v103
	s_nop 0
	v_cndmask_b32_e32 v71, v176, v69, vcc
	v_cndmask_b32_e32 v70, v176, v68, vcc
	v_cndmask_b32_e32 v69, v176, v75, vcc
	v_cndmask_b32_e32 v68, v176, v74, vcc
	global_store_dwordx4 v[154:155], v[68:71], off offset:64 sc0 sc1
	s_nop 1
	v_fma_f32 v70, v66, v70, v2
	v_fma_f32 v71, v67, v71, v3
	v_fma_f32 v68, v64, v68, v0
	v_fma_f32 v69, v65, v69, v1
	s_nop 0
	v_cvt_pk_bf16_f32 v68, v68, v69
	v_cvt_pk_bf16_f32 v69, v70, v71
	v_lshl_add_u64 v[70:71], v[72:73], 1, s[6:7]
	global_store_dwordx2 v[70:71], v[68:69], off
	ds_read_b64 v[68:69], v177 offset:9472
	v_lshl_add_u64 v[72:73], v[114:115], 0, v[120:121]
	s_waitcnt lgkmcnt(0)
	v_sub_f32_e32 v71, v99, v68
	v_sub_f32_e32 v70, v98, v68
	v_sub_f32_e32 v75, v97, v68
	v_sub_f32_e32 v74, v96, v68
	v_mul_f32_e64 v74, v69, v74
	v_mul_f32_e64 v75, v69, v75
	v_mul_f32_e64 v68, v69, v70
	v_mul_f32_e64 v69, v69, v71
	v_fma_f32 v74, v92, v74, v100
	v_fma_f32 v75, v93, v75, v101
	v_fma_f32 v68, v94, v68, v102
	v_fma_f32 v69, v95, v69, v103
	s_nop 0
	v_cndmask_b32_e32 v71, v176, v69, vcc
	v_cndmask_b32_e32 v70, v176, v68, vcc
	v_cndmask_b32_e32 v69, v176, v75, vcc
	v_cndmask_b32_e32 v68, v176, v74, vcc
	global_store_dwordx4 v[156:157], v[68:71], off offset:64 sc0 sc1
	s_nop 1
	v_fma_f32 v70, v66, v70, v2
	v_fma_f32 v71, v67, v71, v3
	v_fma_f32 v68, v64, v68, v0
	v_fma_f32 v69, v65, v69, v1
	s_nop 0
	v_cvt_pk_bf16_f32 v68, v68, v69
	v_cvt_pk_bf16_f32 v69, v70, v71
	v_lshl_add_u64 v[70:71], v[72:73], 1, s[6:7]
	global_store_dwordx2 v[70:71], v[68:69], off
	ds_read_b64 v[68:69], v177 offset:9600
	v_lshl_add_u64 v[72:73], v[116:117], 0, v[120:121]
	s_waitcnt lgkmcnt(0)
; __device__ __forceinline__ unsigned cvt_pk_bf16(float lo, float hi) { unsigned r; asm volatile("v_cvt_pk_bf16_f32 %0, %1, %2" : "=v"(r) : "v"(lo), "v"(hi)); return r; }
;     __device__ __forceinline__ void fused(f32x4 (&acc)[2][2][4][2], const Unit& u, int wr, int wc, int fr, int fq, PG8_LAS unsigned char* lds, int wid, int lane) const {
;     ...
; #pragma unroll
;         for (int bj = 0; bj < 2; ++bj)
; #pragma unroll
;             for (int n = 0; n < 2; ++n) {
;                 const int col = col0 + bj * HALF + n * 16;
;                 const f32x4 lg = *(const f32x4*)(lng + col), lb = *(const f32x4*)(lnb + col);
;                 f32x4 sc1 = (f32x4){1.f, 1.f, 1.f, 1.f}, sh = (f32x4){0.f, 0.f, 0.f, 0.f};
;                 if (DO_U) { sc1 = *(const f32x4*)(msc + mo + col) + 1.0f; sh = *(const f32x4*)(msh + mo + col); }
; #pragma unroll
;                 for (int ai = 0; ai < 2; ++ai)
; #pragma unroll
;                     for (int m = 0; m < 4; ++m) { const int r = ai * HALF + wr * 64 + m * 16 + fr; const f32x2v sr = S[r]; const size_t off = (size_t)(u.pm * BM + r) * 1024 + col;
;                         f32x4 y = (acc[ai][bj][m][n] - sr.x) * sr.y * lg + lb; if (bad) y = (f32x4){qnan, qnan, qnan, qnan};
;                         *(f32x4*)(out + off) = y;
;                         if (DO_U) { const f32x4 uu = y * sc1 + sh; u32x2v w; w.x = cvt_pk_bf16(uu[0], uu[1]); w.y = cvt_pk_bf16(uu[2], uu[3]); *(u32x2v*)(U + off) = w; } }
	v_sub_f32_e32 v71, v111, v68
	v_sub_f32_e32 v70, v110, v68
	v_sub_f32_e32 v75, v109, v68
	v_sub_f32_e32 v74, v108, v68
	v_mul_f32_e64 v74, v69, v74
	v_mul_f32_e64 v75, v69, v75
	v_mul_f32_e64 v68, v69, v70
	v_mul_f32_e64 v69, v69, v71
	v_fma_f32 v74, v92, v74, v100
	v_fma_f32 v75, v93, v75, v101
	v_fma_f32 v68, v94, v68, v102
	v_fma_f32 v69, v95, v69, v103
	s_nop 0
	v_cndmask_b32_e32 v71, v176, v69, vcc
	v_cndmask_b32_e32 v70, v176, v68, vcc
	v_cndmask_b32_e32 v69, v176, v75, vcc
	v_cndmask_b32_e32 v68, v176, v74, vcc
	v_fma_f32 v2, v66, v70, v2
	v_fma_f32 v3, v67, v71, v3
	v_fma_f32 v0, v64, v68, v0
	v_fma_f32 v1, v65, v69, v1
	global_store_dwordx4 v[158:159], v[68:71], off offset:64 sc0 sc1
	v_cvt_pk_bf16_f32 v0, v0, v1
	v_cvt_pk_bf16_f32 v1, v2, v3
	v_lshl_add_u64 v[2:3], v[72:73], 1, s[6:7]
	global_store_dwordx2 v[2:3], v[0:1], off
	v_lshlrev_b64 v[0:1], 2, v[80:81]
	v_lshl_add_u64 v[2:3], v[162:163], 0, v[0:1]
	global_load_dwordx4 v[64:67], v[2:3], off
	v_lshl_add_u64 v[0:1], v[160:161], 0, v[0:1]
	global_load_dwordx4 v[72:75], v[170:171], off offset:512
	global_load_dwordx4 v[68:71], v[0:1], off
	s_nop 0
	global_load_dwordx4 v[0:3], v[118:119], off offset:512
	ds_read_b64 v[82:83], v177 offset:8192
	s_waitcnt lgkmcnt(0)
	v_sub_f32_e32 v35, v35, v82
	v_sub_f32_e32 v34, v34, v82
	v_sub_f32_e32 v33, v33, v82
	v_sub_f32_e32 v32, v32, v82
	v_mul_f32_e64 v32, v83, v32
	v_mul_f32_e64 v33, v83, v33
	v_mul_f32_e64 v34, v83, v34
	v_mul_f32_e64 v35, v83, v35
	v_lshl_add_u64 v[82:83], v[166:167], 0, v[80:81]
	s_waitcnt vmcnt(0)
	v_fma_f32 v34, v66, v34, v70
	v_fma_f32 v35, v67, v35, v71
	v_fma_f32 v32, v64, v32, v68
	v_fma_f32 v33, v65, v33, v69
	v_add_f32_e64 v74, v74, 1.0
	v_add_f32_e64 v75, v75, 1.0
	v_add_f32_e64 v72, v72, 1.0
	v_add_f32_e64 v73, v73, 1.0
	v_cndmask_b32_e32 v35, v176, v35, vcc
	v_cndmask_b32_e32 v34, v176, v34, vcc
	v_cndmask_b32_e32 v33, v176, v33, vcc
	v_cndmask_b32_e32 v32, v176, v32, vcc
	global_store_dwordx4 v[142:143], v[32:35], off offset:512 sc0 sc1
	s_nop 1
	v_fma_f32 v34, v74, v34, v2
	v_fma_f32 v35, v75, v35, v3
	v_fma_f32 v32, v72, v32, v0
	v_fma_f32 v33, v73, v33, v1
	s_nop 0
	v_cvt_pk_bf16_f32 v32, v32, v33
	v_cvt_pk_bf16_f32 v33, v34, v35
	v_lshl_add_u64 v[34:35], v[84:85], 1, s[6:7]
	global_store_dwordx2 v[34:35], v[32:33], off
	ds_read_b64 v[32:33], v177 offset:8320
	s_waitcnt lgkmcnt(0)
	v_sub_f32_e32 v35, v39, v32
	v_sub_f32_e32 v34, v38, v32
	v_sub_f32_e32 v37, v37, v32
	v_sub_f32_e32 v36, v36, v32
	v_mul_f32_e64 v36, v33, v36
	v_mul_f32_e64 v37, v33, v37
	v_mul_f32_e64 v32, v33, v34
	v_mul_f32_e64 v33, v33, v35
	v_fma_f32 v36, v64, v36, v68
	v_fma_f32 v37, v65, v37, v69
	v_fma_f32 v32, v66, v32, v70
	v_fma_f32 v33, v67, v33, v71
	s_nop 0
	v_cndmask_b32_e32 v35, v176, v33, vcc
	v_cndmask_b32_e32 v34, v176, v32, vcc
	v_cndmask_b32_e32 v33, v176, v37, vcc
	v_cndmask_b32_e32 v32, v176, v36, vcc
	global_store_dwordx4 v[146:147], v[32:35], off offset:512 sc0 sc1
	v_lshl_add_u64 v[36:37], v[164:165], 0, v[80:81]
	s_nop 0
	v_fma_f32 v34, v74, v34, v2
	v_fma_f32 v35, v75, v35, v3
	v_fma_f32 v32, v72, v32, v0
	v_fma_f32 v33, v73, v33, v1
	s_nop 0
	v_cvt_pk_bf16_f32 v32, v32, v33
	v_cvt_pk_bf16_f32 v33, v34, v35
	v_lshl_add_u64 v[34:35], v[82:83], 1, s[6:7]
	global_store_dwordx2 v[34:35], v[32:33], off
	ds_read_b64 v[32:33], v177 offset:8448
	s_waitcnt lgkmcnt(0)
	v_sub_f32_e32 v35, v43, v32
	v_sub_f32_e32 v34, v42, v32
	v_sub_f32_e32 v39, v41, v32
	v_sub_f32_e32 v38, v40, v32
	v_mul_f32_e64 v38, v33, v38
	v_mul_f32_e64 v39, v33, v39
	v_mul_f32_e64 v32, v33, v34
	v_mul_f32_e64 v33, v33, v35
	v_fma_f32 v38, v64, v38, v68
	v_fma_f32 v39, v65, v39, v69
	v_fma_f32 v32, v66, v32, v70
	v_fma_f32 v33, v67, v33, v71
	s_nop 0
	v_cndmask_b32_e32 v35, v176, v33, vcc
	v_cndmask_b32_e32 v34, v176, v32, vcc
	v_cndmask_b32_e32 v33, v176, v39, vcc
	v_cndmask_b32_e32 v32, v176, v38, vcc
	global_store_dwordx4 v[148:149], v[32:35], off offset:512 sc0 sc1
	s_nop 1
	v_fma_f32 v34, v74, v34, v2
	v_fma_f32 v35, v75, v35, v3
	v_fma_f32 v32, v72, v32, v0
	v_fma_f32 v33, v73, v33, v1
	s_nop 0
	v_cvt_pk_bf16_f32 v32, v32, v33
	v_cvt_pk_bf16_f32 v33, v34, v35
	v_lshl_add_u64 v[34:35], v[36:37], 1, s[6:7]
	global_store_dwordx2 v[34:35], v[32:33], off
	ds_read_b64 v[32:33], v177 offset:8576
	v_lshl_add_u64 v[36:37], v[104:105], 0, v[80:81]
	s_waitcnt lgkmcnt(0)
	v_sub_f32_e32 v35, v51, v32
	v_sub_f32_e32 v34, v50, v32
	v_sub_f32_e32 v39, v49, v32
	v_sub_f32_e32 v38, v48, v32
	v_mul_f32_e64 v38, v33, v38
	v_mul_f32_e64 v39, v33, v39
	v_mul_f32_e64 v32, v33, v34
	v_mul_f32_e64 v33, v33, v35
	v_fma_f32 v38, v64, v38, v68
	v_fma_f32 v39, v65, v39, v69
	v_fma_f32 v32, v66, v32, v70
	v_fma_f32 v33, v67, v33, v71
	v_or_b32_e32 v48, 0x90, v140
	v_cndmask_b32_e32 v35, v176, v33, vcc
	v_cndmask_b32_e32 v34, v176, v32, vcc
	v_cndmask_b32_e32 v33, v176, v39, vcc
	v_cndmask_b32_e32 v32, v176, v38, vcc
	global_store_dwordx4 v[150:151], v[32:35], off offset:512 sc0 sc1
	v_ashrrev_i32_e32 v49, 31, v48
	s_nop 0
	v_fma_f32 v34, v74, v34, v2
	v_fma_f32 v35, v75, v35, v3
	v_fma_f32 v32, v72, v32, v0
	v_fma_f32 v33, v73, v33, v1
	s_nop 0
	v_cvt_pk_bf16_f32 v32, v32, v33
	v_cvt_pk_bf16_f32 v33, v34, v35
	v_lshl_add_u64 v[34:35], v[36:37], 1, s[6:7]
	global_store_dwordx2 v[34:35], v[32:33], off
	ds_read_b64 v[32:33], v177 offset:9216
	v_lshl_add_u64 v[36:37], v[106:107], 0, v[80:81]
	s_waitcnt lgkmcnt(0)
; __device__ __forceinline__ unsigned cvt_pk_bf16(float lo, float hi) { unsigned r; asm volatile("v_cvt_pk_bf16_f32 %0, %1, %2" : "=v"(r) : "v"(lo), "v"(hi)); return r; }
;     __device__ __forceinline__ void fused(f32x4 (&acc)[2][2][4][2], const Unit& u, int wr, int wc, int fr, int fq, PG8_LAS unsigned char* lds, int wid, int lane) const {
;     ...
; #pragma unroll
;         for (int bj = 0; bj < 2; ++bj)
; #pragma unroll
;             for (int n = 0; n < 2; ++n) {
;                 const int col = col0 + bj * HALF + n * 16;
;                 const f32x4 lg = *(const f32x4*)(lng + col), lb = *(const f32x4*)(lnb + col);
;                 f32x4 sc1 = (f32x4){1.f, 1.f, 1.f, 1.f}, sh = (f32x4){0.f, 0.f, 0.f, 0.f};
;                 if (DO_U) { sc1 = *(const f32x4*)(msc + mo + col) + 1.0f; sh = *(const f32x4*)(msh + mo + col); }
; #pragma unroll
;                 for (int ai = 0; ai < 2; ++ai)
; #pragma unroll
;                     for (int m = 0; m < 4; ++m) { const int r = ai * HALF + wr * 64 + m * 16 + fr; const f32x2v sr = S[r]; const size_t off = (size_t)(u.pm * BM + r) * 1024 + col;
;                         f32x4 y = (acc[ai][bj][m][n] - sr.x) * sr.y * lg + lb; if (bad) y = (f32x4){qnan, qnan, qnan, qnan};
;                         *(f32x4*)(out + off) = y;
;                         if (DO_U) { const f32x4 uu = y * sc1 + sh; u32x2v w; w.x = cvt_pk_bf16(uu[0], uu[1]); w.y = cvt_pk_bf16(uu[2], uu[3]); *(u32x2v*)(U + off) = w; } }
	v_sub_f32_e32 v35, v55, v32
	v_sub_f32_e32 v34, v54, v32
	v_sub_f32_e32 v39, v53, v32
	v_sub_f32_e32 v38, v52, v32
	v_mul_f32_e64 v38, v33, v38
	v_mul_f32_e64 v39, v33, v39
	v_mul_f32_e64 v32, v33, v34
	v_mul_f32_e64 v33, v33, v35
	v_fma_f32 v38, v64, v38, v68
	v_fma_f32 v39, v65, v39, v69
	v_fma_f32 v32, v66, v32, v70
	v_fma_f32 v33, v67, v33, v71
	v_lshl_add_u64 v[52:53], v[168:169], 0, v[48:49]
	v_cndmask_b32_e32 v35, v176, v33, vcc
	v_cndmask_b32_e32 v34, v176, v32, vcc
	v_cndmask_b32_e32 v33, v176, v39, vcc
	v_cndmask_b32_e32 v32, v176, v38, vcc
	global_store_dwordx4 v[152:153], v[32:35], off offset:512 sc0 sc1
	s_nop 1
	v_fma_f32 v34, v74, v34, v2
	v_fma_f32 v35, v75, v35, v3
	v_fma_f32 v32, v72, v32, v0
	v_fma_f32 v33, v73, v33, v1
	s_nop 0
	v_cvt_pk_bf16_f32 v32, v32, v33
	v_cvt_pk_bf16_f32 v33, v34, v35
	v_lshl_add_u64 v[34:35], v[36:37], 1, s[6:7]
	global_store_dwordx2 v[34:35], v[32:33], off
	ds_read_b64 v[32:33], v177 offset:9344
	v_lshl_add_u64 v[36:37], v[112:113], 0, v[80:81]
	s_waitcnt lgkmcnt(0)
	v_sub_f32_e32 v35, v59, v32
	v_sub_f32_e32 v34, v58, v32
	v_sub_f32_e32 v39, v57, v32
	v_sub_f32_e32 v38, v56, v32
	v_mul_f32_e64 v38, v33, v38
	v_mul_f32_e64 v39, v33, v39
	v_mul_f32_e64 v32, v33, v34
	v_mul_f32_e64 v33, v33, v35
	v_fma_f32 v38, v64, v38, v68
	v_fma_f32 v39, v65, v39, v69
	v_fma_f32 v32, v66, v32, v70
	v_fma_f32 v33, v67, v33, v71
	s_nop 0
	v_cndmask_b32_e32 v35, v176, v33, vcc
	v_cndmask_b32_e32 v34, v176, v32, vcc
	v_cndmask_b32_e32 v33, v176, v39, vcc
	v_cndmask_b32_e32 v32, v176, v38, vcc
	global_store_dwordx4 v[154:155], v[32:35], off offset:512 sc0 sc1
	s_nop 1
	v_fma_f32 v34, v74, v34, v2
	v_fma_f32 v35, v75, v35, v3
	v_fma_f32 v32, v72, v32, v0
	v_fma_f32 v33, v73, v33, v1
	s_nop 0
	v_cvt_pk_bf16_f32 v32, v32, v33
	v_cvt_pk_bf16_f32 v33, v34, v35
	v_lshl_add_u64 v[34:35], v[36:37], 1, s[6:7]
	global_store_dwordx2 v[34:35], v[32:33], off
	ds_read_b64 v[32:33], v177 offset:9472
	v_lshl_add_u64 v[36:37], v[114:115], 0, v[80:81]
	s_waitcnt lgkmcnt(0)
	v_sub_f32_e32 v35, v63, v32
	v_sub_f32_e32 v34, v62, v32
	v_sub_f32_e32 v39, v61, v32
	v_sub_f32_e32 v38, v60, v32
	v_mul_f32_e64 v38, v33, v38
	v_mul_f32_e64 v39, v33, v39
	v_mul_f32_e64 v32, v33, v34
	v_mul_f32_e64 v33, v33, v35
	v_fma_f32 v38, v64, v38, v68
	v_fma_f32 v39, v65, v39, v69
	v_fma_f32 v32, v66, v32, v70
	v_fma_f32 v33, v67, v33, v71
	s_nop 0
	v_cndmask_b32_e32 v35, v176, v33, vcc
	v_cndmask_b32_e32 v34, v176, v32, vcc
	v_cndmask_b32_e32 v33, v176, v39, vcc
	v_cndmask_b32_e32 v32, v176, v38, vcc
	global_store_dwordx4 v[156:157], v[32:35], off offset:512 sc0 sc1
	s_nop 1
	v_fma_f32 v34, v74, v34, v2
	v_fma_f32 v35, v75, v35, v3
	v_fma_f32 v32, v72, v32, v0
	v_fma_f32 v33, v73, v33, v1
	s_nop 0
	v_cvt_pk_bf16_f32 v32, v32, v33
	v_cvt_pk_bf16_f32 v33, v34, v35
	v_lshl_add_u64 v[34:35], v[36:37], 1, s[6:7]
	global_store_dwordx2 v[34:35], v[32:33], off
	ds_read_b64 v[32:33], v177 offset:9600
	v_lshl_add_u64 v[36:37], v[116:117], 0, v[80:81]
	s_waitcnt lgkmcnt(0)
	v_sub_f32_e32 v35, v79, v32
	v_sub_f32_e32 v34, v78, v32
	v_sub_f32_e32 v39, v77, v32
	v_sub_f32_e32 v38, v76, v32
	v_mul_f32_e64 v38, v33, v38
	v_mul_f32_e64 v39, v33, v39
	v_mul_f32_e64 v32, v33, v34
	v_mul_f32_e64 v33, v33, v35
	v_fma_f32 v38, v64, v38, v68
	v_fma_f32 v39, v65, v39, v69
	v_fma_f32 v32, v66, v32, v70
	v_fma_f32 v33, v67, v33, v71
	s_nop 0
	v_cndmask_b32_e32 v35, v176, v33, vcc
	v_cndmask_b32_e32 v34, v176, v32, vcc
	v_cndmask_b32_e32 v33, v176, v39, vcc
	v_cndmask_b32_e32 v32, v176, v38, vcc
	v_fma_f32 v2, v74, v34, v2
	v_fma_f32 v3, v75, v35, v3
	v_fma_f32 v0, v72, v32, v0
	v_fma_f32 v1, v73, v33, v1
	global_store_dwordx4 v[158:159], v[32:35], off offset:512 sc0 sc1
	v_cvt_pk_bf16_f32 v0, v0, v1
	v_cvt_pk_bf16_f32 v1, v2, v3
	v_lshl_add_u64 v[2:3], v[36:37], 1, s[6:7]
	global_store_dwordx2 v[2:3], v[0:1], off
	v_lshlrev_b64 v[0:1], 2, v[48:49]
	v_lshl_add_u64 v[2:3], v[162:163], 0, v[0:1]
	global_load_dwordx4 v[32:35], v[2:3], off
	v_lshl_add_u64 v[50:51], v[160:161], 0, v[0:1]
	global_load_dwordx4 v[40:43], v[170:171], off offset:576
	global_load_dwordx4 v[36:39], v[50:51], off
	global_load_dwordx4 v[0:3], v[118:119], off offset:576
	ds_read_b64 v[50:51], v177 offset:8192
	s_waitcnt lgkmcnt(0)
	v_sub_f32_e32 v7, v7, v50
	v_sub_f32_e32 v6, v6, v50
	v_sub_f32_e32 v5, v5, v50
	v_sub_f32_e32 v4, v4, v50
	v_mul_f32_e64 v4, v51, v4
	v_mul_f32_e64 v5, v51, v5
	v_mul_f32_e64 v6, v51, v6
	v_mul_f32_e64 v7, v51, v7
	v_lshl_add_u64 v[50:51], v[166:167], 0, v[48:49]
	s_waitcnt vmcnt(0)
	v_fma_f32 v6, v34, v6, v38
	v_fma_f32 v7, v35, v7, v39
	v_fma_f32 v4, v32, v4, v36
	v_fma_f32 v5, v33, v5, v37
	v_add_f32_e64 v42, v42, 1.0
	v_add_f32_e64 v43, v43, 1.0
	v_add_f32_e64 v40, v40, 1.0
	v_add_f32_e64 v41, v41, 1.0
	v_cndmask_b32_e32 v7, v176, v7, vcc
	v_cndmask_b32_e32 v6, v176, v6, vcc
	v_cndmask_b32_e32 v5, v176, v5, vcc
	v_cndmask_b32_e32 v4, v176, v4, vcc
	global_store_dwordx4 v[142:143], v[4:7], off offset:576 sc0 sc1
	s_nop 1
	v_fma_f32 v6, v42, v6, v2
	v_fma_f32 v7, v43, v7, v3
	v_fma_f32 v4, v40, v4, v0
	v_fma_f32 v5, v41, v5, v1
	s_nop 0
	v_cvt_pk_bf16_f32 v4, v4, v5
	v_cvt_pk_bf16_f32 v5, v6, v7
	v_lshl_add_u64 v[6:7], v[52:53], 1, s[6:7]
	global_store_dwordx2 v[6:7], v[4:5], off
	ds_read_b64 v[4:5], v177 offset:8320
	s_waitcnt lgkmcnt(0)
; __device__ __forceinline__ unsigned cvt_pk_bf16(float lo, float hi) { unsigned r; asm volatile("v_cvt_pk_bf16_f32 %0, %1, %2" : "=v"(r) : "v"(lo), "v"(hi)); return r; }
;     __device__ __forceinline__ void fused(f32x4 (&acc)[2][2][4][2], const Unit& u, int wr, int wc, int fr, int fq, PG8_LAS unsigned char* lds, int wid, int lane) const {
;     ...
; #pragma unroll
;         for (int bj = 0; bj < 2; ++bj)
; #pragma unroll
;             for (int n = 0; n < 2; ++n) {
;                 const int col = col0 + bj * HALF + n * 16;
;                 const f32x4 lg = *(const f32x4*)(lng + col), lb = *(const f32x4*)(lnb + col);
;                 f32x4 sc1 = (f32x4){1.f, 1.f, 1.f, 1.f}, sh = (f32x4){0.f, 0.f, 0.f, 0.f};
;                 if (DO_U) { sc1 = *(const f32x4*)(msc + mo + col) + 1.0f; sh = *(const f32x4*)(msh + mo + col); }
; #pragma unroll
;                 for (int ai = 0; ai < 2; ++ai)
; #pragma unroll
;                     for (int m = 0; m < 4; ++m) { const int r = ai * HALF + wr * 64 + m * 16 + fr; const f32x2v sr = S[r]; const size_t off = (size_t)(u.pm * BM + r) * 1024 + col;
;                         f32x4 y = (acc[ai][bj][m][n] - sr.x) * sr.y * lg + lb; if (bad) y = (f32x4){qnan, qnan, qnan, qnan};
;                         *(f32x4*)(out + off) = y;
;                         if (DO_U) { const f32x4 uu = y * sc1 + sh; u32x2v w; w.x = cvt_pk_bf16(uu[0], uu[1]); w.y = cvt_pk_bf16(uu[2], uu[3]); *(u32x2v*)(U + off) = w; } }
	v_sub_f32_e32 v7, v11, v4
	v_sub_f32_e32 v6, v10, v4
	v_sub_f32_e32 v9, v9, v4
	v_sub_f32_e32 v8, v8, v4
	v_mul_f32_e64 v8, v5, v8
	v_mul_f32_e64 v9, v5, v9
	v_mul_f32_e64 v4, v5, v6
	v_mul_f32_e64 v5, v5, v7
	v_fma_f32 v8, v32, v8, v36
	v_fma_f32 v9, v33, v9, v37
	v_fma_f32 v4, v34, v4, v38
	v_fma_f32 v5, v35, v5, v39
	s_nop 0
	v_cndmask_b32_e32 v7, v176, v5, vcc
	v_cndmask_b32_e32 v6, v176, v4, vcc
	v_cndmask_b32_e32 v5, v176, v9, vcc
	v_cndmask_b32_e32 v4, v176, v8, vcc
	global_store_dwordx4 v[146:147], v[4:7], off offset:576 sc0 sc1
	v_lshl_add_u64 v[8:9], v[164:165], 0, v[48:49]
	s_nop 0
	v_fma_f32 v6, v42, v6, v2
	v_fma_f32 v7, v43, v7, v3
	v_fma_f32 v4, v40, v4, v0
	v_fma_f32 v5, v41, v5, v1
	s_nop 0
	v_cvt_pk_bf16_f32 v4, v4, v5
	v_cvt_pk_bf16_f32 v5, v6, v7
	v_lshl_add_u64 v[6:7], v[50:51], 1, s[6:7]
	global_store_dwordx2 v[6:7], v[4:5], off
	ds_read_b64 v[4:5], v177 offset:8448
	s_waitcnt lgkmcnt(0)
	v_sub_f32_e32 v7, v15, v4
	v_sub_f32_e32 v6, v14, v4
	v_sub_f32_e32 v11, v13, v4
	v_sub_f32_e32 v10, v12, v4
	v_mul_f32_e64 v10, v5, v10
	v_mul_f32_e64 v11, v5, v11
	v_mul_f32_e64 v4, v5, v6
	v_mul_f32_e64 v5, v5, v7
	v_fma_f32 v10, v32, v10, v36
	v_fma_f32 v11, v33, v11, v37
	v_fma_f32 v4, v34, v4, v38
	v_fma_f32 v5, v35, v5, v39
	s_nop 0
	v_cndmask_b32_e32 v7, v176, v5, vcc
	v_cndmask_b32_e32 v6, v176, v4, vcc
	v_cndmask_b32_e32 v5, v176, v11, vcc
	v_cndmask_b32_e32 v4, v176, v10, vcc
	global_store_dwordx4 v[148:149], v[4:7], off offset:576 sc0 sc1
	s_nop 1
	v_fma_f32 v6, v42, v6, v2
	v_fma_f32 v7, v43, v7, v3
	v_fma_f32 v4, v40, v4, v0
	v_fma_f32 v5, v41, v5, v1
	s_nop 0
	v_cvt_pk_bf16_f32 v4, v4, v5
	v_cvt_pk_bf16_f32 v5, v6, v7
	v_lshl_add_u64 v[6:7], v[8:9], 1, s[6:7]
	global_store_dwordx2 v[6:7], v[4:5], off
	ds_read_b64 v[4:5], v177 offset:8576
	v_lshl_add_u64 v[8:9], v[104:105], 0, v[48:49]
	s_waitcnt lgkmcnt(0)
	v_sub_f32_e32 v7, v19, v4
	v_sub_f32_e32 v6, v18, v4
	v_sub_f32_e32 v11, v17, v4
	v_sub_f32_e32 v10, v16, v4
	v_mul_f32_e64 v10, v5, v10
	v_mul_f32_e64 v11, v5, v11
	v_mul_f32_e64 v4, v5, v6
	v_mul_f32_e64 v5, v5, v7
	v_fma_f32 v10, v32, v10, v36
	v_fma_f32 v11, v33, v11, v37
	v_fma_f32 v4, v34, v4, v38
	v_fma_f32 v5, v35, v5, v39
	s_nop 0
	v_cndmask_b32_e32 v7, v176, v5, vcc
	v_cndmask_b32_e32 v6, v176, v4, vcc
	v_cndmask_b32_e32 v5, v176, v11, vcc
	v_cndmask_b32_e32 v4, v176, v10, vcc
	global_store_dwordx4 v[150:151], v[4:7], off offset:576 sc0 sc1
	s_nop 1
	v_fma_f32 v6, v42, v6, v2
	v_fma_f32 v7, v43, v7, v3
	v_fma_f32 v4, v40, v4, v0
	v_fma_f32 v5, v41, v5, v1
	s_nop 0
	v_cvt_pk_bf16_f32 v4, v4, v5
	v_cvt_pk_bf16_f32 v5, v6, v7
	v_lshl_add_u64 v[6:7], v[8:9], 1, s[6:7]
	global_store_dwordx2 v[6:7], v[4:5], off
	ds_read_b64 v[4:5], v177 offset:9216
	v_lshl_add_u64 v[8:9], v[106:107], 0, v[48:49]
	s_waitcnt lgkmcnt(0)
	v_sub_f32_e32 v7, v23, v4
	v_sub_f32_e32 v6, v22, v4
	v_sub_f32_e32 v11, v21, v4
	v_sub_f32_e32 v10, v20, v4
	v_mul_f32_e64 v10, v5, v10
	v_mul_f32_e64 v11, v5, v11
	v_mul_f32_e64 v4, v5, v6
	v_mul_f32_e64 v5, v5, v7
	v_fma_f32 v10, v32, v10, v36
	v_fma_f32 v11, v33, v11, v37
	v_fma_f32 v4, v34, v4, v38
	v_fma_f32 v5, v35, v5, v39
	s_nop 0
	v_cndmask_b32_e32 v7, v176, v5, vcc
	v_cndmask_b32_e32 v6, v176, v4, vcc
	v_cndmask_b32_e32 v5, v176, v11, vcc
	v_cndmask_b32_e32 v4, v176, v10, vcc
	global_store_dwordx4 v[152:153], v[4:7], off offset:576 sc0 sc1
	s_nop 1
	v_fma_f32 v6, v42, v6, v2
	v_fma_f32 v7, v43, v7, v3
	v_fma_f32 v4, v40, v4, v0
	v_fma_f32 v5, v41, v5, v1
	s_nop 0
	v_cvt_pk_bf16_f32 v4, v4, v5
	v_cvt_pk_bf16_f32 v5, v6, v7
	v_lshl_add_u64 v[6:7], v[8:9], 1, s[6:7]
	global_store_dwordx2 v[6:7], v[4:5], off
	ds_read_b64 v[4:5], v177 offset:9344
	v_lshl_add_u64 v[8:9], v[112:113], 0, v[48:49]
	s_waitcnt lgkmcnt(0)
	v_sub_f32_e32 v7, v27, v4
	v_sub_f32_e32 v6, v26, v4
	v_sub_f32_e32 v11, v25, v4
	v_sub_f32_e32 v10, v24, v4
	v_mul_f32_e64 v10, v5, v10
	v_mul_f32_e64 v11, v5, v11
	v_mul_f32_e64 v4, v5, v6
	v_mul_f32_e64 v5, v5, v7
	v_fma_f32 v10, v32, v10, v36
	v_fma_f32 v11, v33, v11, v37
	v_fma_f32 v4, v34, v4, v38
	v_fma_f32 v5, v35, v5, v39
	s_nop 0
	v_cndmask_b32_e32 v7, v176, v5, vcc
	v_cndmask_b32_e32 v6, v176, v4, vcc
	v_cndmask_b32_e32 v5, v176, v11, vcc
	v_cndmask_b32_e32 v4, v176, v10, vcc
	global_store_dwordx4 v[154:155], v[4:7], off offset:576 sc0 sc1
	s_nop 1
	v_fma_f32 v6, v42, v6, v2
	v_fma_f32 v7, v43, v7, v3
	v_fma_f32 v4, v40, v4, v0
	v_fma_f32 v5, v41, v5, v1
	s_nop 0
	v_cvt_pk_bf16_f32 v4, v4, v5
	v_cvt_pk_bf16_f32 v5, v6, v7
	v_lshl_add_u64 v[6:7], v[8:9], 1, s[6:7]
	global_store_dwordx2 v[6:7], v[4:5], off
	ds_read_b64 v[4:5], v177 offset:9472
	v_lshl_add_u64 v[8:9], v[114:115], 0, v[48:49]
	s_waitcnt lgkmcnt(0)
	v_sub_f32_e32 v7, v31, v4
	v_sub_f32_e32 v6, v30, v4
	v_sub_f32_e32 v11, v29, v4
	v_sub_f32_e32 v10, v28, v4
	v_mul_f32_e64 v10, v5, v10
	v_mul_f32_e64 v11, v5, v11
	v_mul_f32_e64 v4, v5, v6
	v_mul_f32_e64 v5, v5, v7
	v_fma_f32 v10, v32, v10, v36
	v_fma_f32 v11, v33, v11, v37
	v_fma_f32 v4, v34, v4, v38
	v_fma_f32 v5, v35, v5, v39
	s_nop 0
	v_cndmask_b32_e32 v7, v176, v5, vcc
	v_cndmask_b32_e32 v6, v176, v4, vcc
	v_cndmask_b32_e32 v5, v176, v11, vcc
	v_cndmask_b32_e32 v4, v176, v10, vcc
	global_store_dwordx4 v[156:157], v[4:7], off offset:576 sc0 sc1
	s_nop 1
	v_fma_f32 v6, v42, v6, v2
	v_fma_f32 v7, v43, v7, v3
	v_fma_f32 v4, v40, v4, v0
	v_fma_f32 v5, v41, v5, v1
	s_nop 0
	v_cvt_pk_bf16_f32 v4, v4, v5
	v_cvt_pk_bf16_f32 v5, v6, v7
	v_lshl_add_u64 v[6:7], v[8:9], 1, s[6:7]
	global_store_dwordx2 v[6:7], v[4:5], off
	ds_read_b64 v[4:5], v177 offset:9600
	v_lshl_add_u64 v[8:9], v[116:117], 0, v[48:49]
	s_waitcnt lgkmcnt(0)
	v_sub_f32_e32 v7, v47, v4
	v_sub_f32_e32 v6, v46, v4
	v_sub_f32_e32 v11, v45, v4
	v_sub_f32_e32 v10, v44, v4
	v_mul_f32_e64 v10, v5, v10
	v_mul_f32_e64 v11, v5, v11
	v_mul_f32_e64 v4, v5, v6
	v_mul_f32_e64 v5, v5, v7
	v_fma_f32 v10, v32, v10, v36
	v_fma_f32 v11, v33, v11, v37
	v_fma_f32 v4, v34, v4, v38
	v_fma_f32 v5, v35, v5, v39
	s_nop 0
	v_cndmask_b32_e32 v7, v176, v5, vcc
	v_cndmask_b32_e32 v6, v176, v4, vcc
	v_cndmask_b32_e32 v5, v176, v11, vcc
	v_cndmask_b32_e32 v4, v176, v10, vcc
	v_fma_f32 v2, v42, v6, v2
	v_fma_f32 v3, v43, v7, v3
	v_fma_f32 v0, v40, v4, v0
	v_fma_f32 v1, v41, v5, v1
	global_store_dwordx4 v[158:159], v[4:7], off offset:576 sc0 sc1
	v_cvt_pk_bf16_f32 v0, v0, v1
	v_cvt_pk_bf16_f32 v1, v2, v3
	v_lshl_add_u64 v[2:3], v[8:9], 1, s[6:7]
	global_store_dwordx2 v[2:3], v[0:1], off

;     __device__ __forceinline__ void fused(f32x4 (&acc)[2][2][4][2], const Unit& u, int wr, int wc, int fr, int fq, PG8_LAS unsigned char* lds, int wid, int lane) const {
;     ...
;         const int col0 = u.pn * BM + wc * 32 + 4 * fq; const int b = (u.pm * BM) >> 13; const size_t mo = (size_t)b * 9216;
; #pragma unroll
;         for (int bj = 0; bj < 2; ++bj)
; #pragma unroll
;             for (int n = 0; n < 2; ++n) { const f32x4 gv = (*(const f32x4*)(gate + mo + col0 + bj * HALF + n * 16) + 1.0f) * coef;
; #pragma unroll
;                 for (int ai = 0; ai < 2; ++ai)
; #pragma unroll
;                     for (int m = 0; m < 4; ++m) acc[ai][bj][m][n] = acc[ai][bj][m][n] * gv; }
; #pragma unroll
;         for (int ai = 0; ai < 2; ++ai)
; #pragma unroll
;             for (int m = 0; m < 4; ++m) { const size_t off = (size_t)(u.pm * BM + ai * HALF + wr * 64 + m * 16 + fr) * 1024 + col0;
; #pragma unroll
;                 for (int bj = 0; bj < 2; ++bj)
; #pragma unroll
;                     for (int n = 0; n < 2; ++n) { const f32x4 xv = *(const f32x4*)(xin + off + bj * HALF + n * 16); acc[ai][bj][m][n] = xv * ALPHA_ + acc[ai][bj][m][n]; }
;                 asm volatile("" : "+v"(acc[ai][0][m][0]), "+v"(acc[ai][0][m][1]), "+v"(acc[ai][1][m][0]), "+v"(acc[ai][1][m][1]));
;                 if (m & 1) asm volatile("" ::: "memory"); }
.LBB0_1491:
	s_lshl_b32 s0, s42, 5
	s_lshl_b32 s1, s10, 8
	s_or_b32 s0, s1, s0
	v_lshrrev_b32_e32 v4, 2, v144
	v_and_or_b32 v138, v4, 12, s0
	s_ashr_i32 s0, s41, 5
	s_mul_hi_i32 s1, s0, 0x9000
	s_mul_i32 s0, s0, 0x9000
	v_ashrrev_i32_e32 v139, 31, v138
	s_add_u32 s0, s8, s0
	s_addc_u32 s1, s9, s1
	v_lshlrev_b64 v[140:141], 2, v[138:139]
	v_lshl_add_u64 v[142:143], s[0:1], 0, v[140:141]
	s_mov_b32 s2, 0x8000
	s_mov_b64 s[0:1], 0x8000
	v_add_co_u32_e32 v4, vcc, s2, v142
	s_lshl_b32 s16, s41, 8
	s_nop 0
	v_addc_co_u32_e32 v5, vcc, 0, v143, vcc
	v_lshl_add_u64 v[142:143], v[142:143], 0, s[0:1]
	s_add_i32 s0, s16, s53
	v_or_b32_e32 v160, s0, v163
	v_ashrrev_i32_e32 v161, 31, v160
	s_barrier
	global_load_dwordx4 v[4:7], v[4:5], off
	s_nop 0
	global_load_dwordx4 v[146:149], v[142:143], off offset:64
	global_load_dwordx4 v[150:153], v[142:143], off offset:512
	global_load_dwordx4 v[154:157], v[142:143], off offset:576
	v_lshlrev_b64 v[142:143], 12, v[160:161]
	s_waitcnt vmcnt(0) lgkmcnt(0)
	v_lshl_add_u64 v[142:143], v[136:137], 0, v[142:143]
	v_lshl_add_u64 v[142:143], v[142:143], 0, v[140:141]
	global_load_dwordx4 v[164:167], v[142:143], off
	global_load_dwordx4 v[168:171], v[142:143], off offset:64
	global_load_dwordx4 v[172:175], v[142:143], off offset:512
	global_load_dwordx4 v[176:179], v[142:143], off offset:576
	v_or_b32_e32 v142, 16, v160
	v_ashrrev_i32_e32 v143, 31, v142
	v_lshlrev_b64 v[142:143], 12, v[142:143]
	s_mov_b32 s0, 0x3f9837f0
	v_lshl_add_u64 v[142:143], v[136:137], 0, v[142:143]
	v_lshl_add_u64 v[180:181], v[142:143], 0, v[140:141]
	v_add_f32_e64 v148, v148, 1.0
	v_add_f32_e64 v149, v149, 1.0
	v_add_f32_e64 v6, v6, 1.0
	v_add_f32_e64 v7, v7, 1.0
	v_add_f32_e64 v4, v4, 1.0
	v_add_f32_e64 v5, v5, 1.0
	v_add_f32_e64 v158, v146, 1.0
	v_add_f32_e64 v159, v147, 1.0
	v_add_f32_e64 v152, v152, 1.0
	v_add_f32_e64 v153, v153, 1.0
	v_add_f32_e64 v182, v150, 1.0
	v_add_f32_e64 v183, v151, 1.0
	v_add_f32_e64 v156, v156, 1.0
	v_add_f32_e64 v157, v157, 1.0
	v_add_f32_e64 v184, v154, 1.0
	v_add_f32_e64 v185, v155, 1.0
	v_mul_f32_e64 v142, v6, 0.5
	v_mul_f32_e64 v143, v7, 0.5
	v_mul_f32_e64 v146, v4, 0.5
	v_mul_f32_e64 v147, v5, 0.5
	v_mul_f32_e64 v148, v148, 0.5
	v_mul_f32_e64 v149, v149, 0.5
	v_mul_f32_e64 v150, v158, 0.5
	v_mul_f32_e64 v151, v159, 0.5
	v_mul_f32_e64 v152, v152, 0.5
	v_mul_f32_e64 v153, v153, 0.5
	v_mul_f32_e64 v154, v182, 0.5
	v_mul_f32_e64 v155, v183, 0.5
	v_mul_f32_e64 v156, v156, 0.5
	v_mul_f32_e64 v157, v157, 0.5
	v_mul_f32_e64 v158, v184, 0.5
	v_mul_f32_e64 v159, v185, 0.5
	s_waitcnt vmcnt(0) lgkmcnt(0)
	v_mul_f32_e64 v4, v166, s0
	v_mul_f32_e64 v5, v167, s0
	v_mul_f32_e64 v6, v164, s0
	v_mul_f32_e64 v7, v165, s0
	v_mul_f32_e64 v164, v170, s0
	v_mul_f32_e64 v165, v171, s0
	v_mul_f32_e64 v166, v168, s0
	v_mul_f32_e64 v167, v169, s0
	v_mul_f32_e64 v168, v174, s0
	v_mul_f32_e64 v169, v175, s0
	v_mul_f32_e64 v170, v172, s0
	v_mul_f32_e64 v171, v173, s0
	v_mul_f32_e64 v172, v178, s0
	v_mul_f32_e64 v173, v179, s0
	v_mul_f32_e64 v174, v176, s0
	v_mul_f32_e64 v175, v177, s0
	v_fma_f32 v82, v82, v142, v4
	v_fma_f32 v83, v83, v143, v5
	v_fma_f32 v80, v80, v146, v6
	v_fma_f32 v81, v81, v147, v7
	v_fma_f32 v46, v46, v148, v164
	v_fma_f32 v47, v47, v149, v165
	v_fma_f32 v44, v44, v150, v166
	v_fma_f32 v45, v45, v151, v167
	v_fma_f32 v22, v22, v152, v168
	v_fma_f32 v23, v23, v153, v169
	v_fma_f32 v20, v20, v154, v170
	v_fma_f32 v21, v21, v155, v171
	v_fma_f32 v6, v134, v156, v172
	v_fma_f32 v7, v135, v157, v173
	v_fma_f32 v4, v132, v158, v174
	v_fma_f32 v5, v133, v159, v175
	v_or_b32_e32 v176, 32, v160
	global_load_dwordx4 v[132:135], v[180:181], off
	global_load_dwordx4 v[164:167], v[180:181], off offset:64
	global_load_dwordx4 v[168:171], v[180:181], off offset:512
	global_load_dwordx4 v[172:175], v[180:181], off offset:576
	v_ashrrev_i32_e32 v177, 31, v176
	v_lshlrev_b64 v[176:177], 12, v[176:177]
	v_lshl_add_u64 v[176:177], v[136:137], 0, v[176:177]
	v_lshl_add_u64 v[176:177], v[176:177], 0, v[140:141]
	v_mov_b32_e32 v161, v82
	v_mov_b32_e32 v180, v80
	v_mov_b32_e32 v181, v83
	v_mov_b32_e32 v182, v45
	v_mov_b32_e32 v183, v46
	v_mov_b32_e32 v184, v44
	v_mov_b32_e32 v185, v47
	v_add_f32_e32 v187, v22, v23
	v_mov_b32_e32 v186, v5
	v_mov_b32_e32 v188, v7
	s_waitcnt vmcnt(0) lgkmcnt(0)
	v_mul_f32_e64 v134, v134, s0
	v_mul_f32_e64 v135, v135, s0
	v_mul_f32_e64 v132, v132, s0
	v_mul_f32_e64 v133, v133, s0
	v_mul_f32_e64 v166, v166, s0
	v_mul_f32_e64 v167, v167, s0
	v_mul_f32_e64 v164, v164, s0
	v_mul_f32_e64 v165, v165, s0
	v_mul_f32_e64 v170, v170, s0
	v_mul_f32_e64 v171, v171, s0
	v_mul_f32_e64 v168, v168, s0
	v_mul_f32_e64 v169, v169, s0
	v_mul_f32_e64 v174, v174, s0
	v_mul_f32_e64 v175, v175, s0
	v_mul_f32_e64 v172, v172, s0
	v_mul_f32_e64 v173, v173, s0
	v_fma_f32 v90, v90, v142, v134
	v_fma_f32 v91, v91, v143, v135
	v_fma_f32 v88, v88, v146, v132
	v_fma_f32 v89, v89, v147, v133
	v_fma_f32 v58, v58, v148, v166
	v_fma_f32 v59, v59, v149, v167
	v_fma_f32 v56, v56, v150, v164
	v_fma_f32 v57, v57, v151, v165
	v_fma_f32 v30, v30, v152, v170
	v_fma_f32 v31, v31, v153, v171
	v_fma_f32 v28, v28, v154, v168
	v_fma_f32 v29, v29, v155, v169
	v_fma_f32 v10, v10, v156, v174
	v_fma_f32 v11, v11, v157, v175
	v_fma_f32 v8, v8, v158, v172
	v_fma_f32 v9, v9, v159, v173
	s_nop 0
	global_load_dwordx4 v[132:135], v[176:177], off
	global_load_dwordx4 v[164:167], v[176:177], off offset:64
	global_load_dwordx4 v[168:171], v[176:177], off offset:512
	global_load_dwordx4 v[172:175], v[176:177], off offset:576
	v_or_b32_e32 v176, 48, v160
	v_ashrrev_i32_e32 v177, 31, v176
	v_lshlrev_b64 v[176:177], 12, v[176:177]
	v_lshl_add_u64 v[176:177], v[136:137], 0, v[176:177]
	v_lshl_add_u64 v[176:177], v[176:177], 0, v[140:141]
	s_waitcnt vmcnt(0) lgkmcnt(0)
;     __device__ __forceinline__ bool run(const f32x4 (&v)[2][2][4][2], const Unit& u, int wr, int wc, int fr, int fq, PG8_LAS unsigned char* lds, int wid, int lane) const {
;     ...
;                 float s = 0.f;
; #pragma unroll
;                 for (int bj = 0; bj < 2; ++bj)
; #pragma unroll
;                     for (int n = 0; n < 2; ++n) { const f32x4 x = v[ai][bj][m][n]; s += (x[0] + x[1]) + (x[2] + x[3]); }
;                 s += __shfl_xor(s, 16); s += __shfl_xor(s, 32);
;     __device__ __forceinline__ void fused(f32x4 (&acc)[2][2][4][2], const Unit& u, int wr, int wc, int fr, int fq, PG8_LAS unsigned char* lds, int wid, int lane) const {
;     ...
;         for (int ai = 0; ai < 2; ++ai)
; #pragma unroll
;             for (int m = 0; m < 4; ++m) { const size_t off = (size_t)(u.pm * BM + ai * HALF + wr * 64 + m * 16 + fr) * 1024 + col0;
; #pragma unroll
;                 for (int bj = 0; bj < 2; ++bj)
; #pragma unroll
;                     for (int n = 0; n < 2; ++n) { const f32x4 xv = *(const f32x4*)(xin + off + bj * HALF + n * 16); acc[ai][bj][m][n] = xv * ALPHA_ + acc[ai][bj][m][n]; }
;                 asm volatile("" : "+v"(acc[ai][0][m][0]), "+v"(acc[ai][0][m][1]), "+v"(acc[ai][1][m][0]), "+v"(acc[ai][1][m][1]));
;                 if (m & 1) asm volatile("" ::: "memory"); }
	v_mul_f32_e64 v134, v134, s0
	v_mul_f32_e64 v135, v135, s0
	v_mul_f32_e64 v132, v132, s0
	v_mul_f32_e64 v133, v133, s0
	v_mul_f32_e64 v166, v166, s0
	v_mul_f32_e64 v167, v167, s0
	v_mul_f32_e64 v164, v164, s0
	v_mul_f32_e64 v165, v165, s0
	v_mul_f32_e64 v170, v170, s0
	v_mul_f32_e64 v171, v171, s0
	v_mul_f32_e64 v168, v168, s0
	v_mul_f32_e64 v169, v169, s0
	v_mul_f32_e64 v174, v174, s0
	v_mul_f32_e64 v175, v175, s0
	v_mul_f32_e64 v172, v172, s0
	v_mul_f32_e64 v173, v173, s0
	v_fma_f32 v102, v102, v142, v134
	v_fma_f32 v103, v103, v143, v135
	v_fma_f32 v100, v100, v146, v132
	v_fma_f32 v101, v101, v147, v133
	v_fma_f32 v70, v70, v148, v166
	v_fma_f32 v71, v71, v149, v167
	v_fma_f32 v68, v68, v150, v164
	v_fma_f32 v69, v69, v151, v165
	v_fma_f32 v38, v38, v152, v170
	v_fma_f32 v39, v39, v153, v171
	v_fma_f32 v36, v36, v154, v168
	v_fma_f32 v37, v37, v155, v169
	v_fma_f32 v14, v14, v156, v174
	v_fma_f32 v15, v15, v157, v175
	v_fma_f32 v12, v12, v158, v172
	v_fma_f32 v13, v13, v159, v173
	s_nop 0
	global_load_dwordx4 v[132:135], v[176:177], off
	global_load_dwordx4 v[164:167], v[176:177], off offset:64
	global_load_dwordx4 v[168:171], v[176:177], off offset:512
	global_load_dwordx4 v[172:175], v[176:177], off offset:576
	v_add_u32_e32 v176, 0x80, v160
	v_ashrrev_i32_e32 v177, 31, v176
	v_lshlrev_b64 v[176:177], 12, v[176:177]
	v_lshl_add_u64 v[176:177], v[136:137], 0, v[176:177]
	v_lshl_add_u64 v[176:177], v[176:177], 0, v[140:141]
	s_waitcnt vmcnt(0) lgkmcnt(0)
	v_mul_f32_e64 v134, v134, s0
	v_mul_f32_e64 v135, v135, s0
	v_mul_f32_e64 v132, v132, s0
	v_mul_f32_e64 v133, v133, s0
	v_mul_f32_e64 v166, v166, s0
	v_mul_f32_e64 v167, v167, s0
	v_mul_f32_e64 v164, v164, s0
	v_mul_f32_e64 v165, v165, s0
	v_mul_f32_e64 v170, v170, s0
	v_mul_f32_e64 v171, v171, s0
	v_mul_f32_e64 v168, v168, s0
	v_mul_f32_e64 v169, v169, s0
	v_mul_f32_e64 v174, v174, s0
	v_mul_f32_e64 v175, v175, s0
	v_mul_f32_e64 v172, v172, s0
	v_mul_f32_e64 v173, v173, s0
	v_fma_f32 v106, v106, v142, v134
	v_fma_f32 v107, v107, v143, v135
	v_fma_f32 v104, v104, v146, v132
	v_fma_f32 v105, v105, v147, v133
	v_fma_f32 v74, v74, v148, v166
	v_fma_f32 v75, v75, v149, v167
	v_fma_f32 v72, v72, v150, v164
	v_fma_f32 v73, v73, v151, v165
	v_fma_f32 v42, v42, v152, v170
	v_fma_f32 v43, v43, v153, v171
	v_fma_f32 v40, v40, v154, v168
	v_fma_f32 v41, v41, v155, v169
	v_fma_f32 v18, v18, v156, v174
	v_fma_f32 v19, v19, v157, v175
	v_fma_f32 v16, v16, v158, v172
	v_fma_f32 v17, v17, v159, v173
	s_nop 0
	global_load_dwordx4 v[132:135], v[176:177], off
	global_load_dwordx4 v[164:167], v[176:177], off offset:64
	global_load_dwordx4 v[168:171], v[176:177], off offset:512
	global_load_dwordx4 v[172:175], v[176:177], off offset:576
	v_add_u32_e32 v176, 0x90, v160
	v_ashrrev_i32_e32 v177, 31, v176
	v_lshlrev_b64 v[176:177], 12, v[176:177]
	v_lshl_add_u64 v[176:177], v[136:137], 0, v[176:177]
	v_lshl_add_u64 v[176:177], v[176:177], 0, v[140:141]
	s_waitcnt vmcnt(0) lgkmcnt(0)
	v_mul_f32_e64 v134, v134, s0
	v_mul_f32_e64 v135, v135, s0
	v_mul_f32_e64 v132, v132, s0
	v_mul_f32_e64 v133, v133, s0
	v_mul_f32_e64 v166, v166, s0
	v_mul_f32_e64 v167, v167, s0
	v_mul_f32_e64 v164, v164, s0
	v_mul_f32_e64 v165, v165, s0
	v_mul_f32_e64 v170, v170, s0
	v_mul_f32_e64 v171, v171, s0
	v_mul_f32_e64 v168, v168, s0
	v_mul_f32_e64 v169, v169, s0
	v_mul_f32_e64 v174, v174, s0
	v_mul_f32_e64 v175, v175, s0
	v_mul_f32_e64 v172, v172, s0
	v_mul_f32_e64 v173, v173, s0
	v_fma_f32 v114, v114, v142, v134
	v_fma_f32 v115, v115, v143, v135
	v_fma_f32 v112, v112, v146, v132
	v_fma_f32 v113, v113, v147, v133
	v_fma_f32 v86, v86, v148, v166
	v_fma_f32 v87, v87, v149, v167
	v_fma_f32 v84, v84, v150, v164
	v_fma_f32 v85, v85, v151, v165
	v_fma_f32 v54, v54, v152, v170
	v_fma_f32 v55, v55, v153, v171
	v_fma_f32 v52, v52, v154, v168
	v_fma_f32 v53, v53, v155, v169
	v_fma_f32 v26, v26, v156, v174
	v_fma_f32 v27, v27, v157, v175
	v_fma_f32 v24, v24, v158, v172
	v_fma_f32 v25, v25, v159, v173
	s_nop 0
	global_load_dwordx4 v[132:135], v[176:177], off
	global_load_dwordx4 v[164:167], v[176:177], off offset:64
	global_load_dwordx4 v[168:171], v[176:177], off offset:512
	global_load_dwordx4 v[172:175], v[176:177], off offset:576
	v_add_u32_e32 v176, 0xa0, v160
	v_ashrrev_i32_e32 v177, 31, v176
	v_lshlrev_b64 v[176:177], 12, v[176:177]
	v_lshl_add_u64 v[176:177], v[136:137], 0, v[176:177]
	v_lshl_add_u64 v[176:177], v[176:177], 0, v[140:141]
	s_waitcnt vmcnt(0) lgkmcnt(0)
	v_mul_f32_e64 v134, v134, s0
	v_mul_f32_e64 v135, v135, s0
	v_mul_f32_e64 v132, v132, s0
	v_mul_f32_e64 v133, v133, s0
	v_mul_f32_e64 v166, v166, s0
	v_mul_f32_e64 v167, v167, s0
	v_mul_f32_e64 v164, v164, s0
	v_mul_f32_e64 v165, v165, s0
	v_mul_f32_e64 v170, v170, s0
	v_mul_f32_e64 v171, v171, s0
	v_mul_f32_e64 v168, v168, s0
	v_mul_f32_e64 v169, v169, s0
	v_mul_f32_e64 v174, v174, s0
	v_mul_f32_e64 v175, v175, s0
	v_mul_f32_e64 v172, v172, s0
	v_mul_f32_e64 v173, v173, s0
	v_fma_f32 v122, v122, v142, v134
	v_fma_f32 v123, v123, v143, v135
	v_fma_f32 v120, v120, v146, v132
	v_fma_f32 v121, v121, v147, v133
	v_fma_f32 v98, v98, v148, v166
	v_fma_f32 v99, v99, v149, v167
	v_fma_f32 v96, v96, v150, v164
	v_fma_f32 v97, v97, v151, v165
	v_fma_f32 v62, v62, v152, v170
	v_fma_f32 v63, v63, v153, v171
	v_fma_f32 v60, v60, v154, v168
	v_fma_f32 v61, v61, v155, v169
	v_fma_f32 v34, v34, v156, v174
	v_fma_f32 v35, v35, v157, v175
	v_fma_f32 v32, v32, v158, v172
	v_fma_f32 v33, v33, v159, v173
	v_mbcnt_hi_u32_b32 v133, -1, v145
	global_load_dwordx4 v[164:167], v[176:177], off
	global_load_dwordx4 v[168:171], v[176:177], off offset:64
	global_load_dwordx4 v[172:175], v[176:177], off offset:512
	s_nop 0
	global_load_dwordx4 v[176:179], v[176:177], off offset:576
	v_and_b32_e32 v134, 64, v133
	v_add_u32_e32 v139, 64, v134
	v_add_u32_e32 v134, 0xb0, v160
	v_ashrrev_i32_e32 v135, 31, v134
	v_lshlrev_b64 v[134:135], 12, v[134:135]
	v_lshl_add_u64 v[134:135], v[136:137], 0, v[134:135]
	v_lshl_add_u64 v[134:135], v[134:135], 0, v[140:141]
	v_mov_b32_e32 v160, v81
	v_add_f32_e64 v160, v160, v180
	v_add_f32_e64 v161, v161, v181
	v_add_f32_e64 v180, v182, v184
	v_add_f32_e64 v181, v183, v185
	v_add_f32_e32 v145, v160, v161
	v_add_f32_e64 v160, v180, v180
	v_add_f32_e64 v161, v180, v181
	v_xor_b32_e32 v132, 16, v133
	v_add_f32_e32 v189, 0, v145
	v_mov_b32_e32 v160, v6
	v_cmp_lt_i32_e32 vcc, v132, v139
	v_add_f32_e64 v160, v160, v188
	v_add_f32_e64 v161, v161, v189
	v_xor_b32_e32 v145, 32, v133
	v_cndmask_b32_e32 v132, v133, v132, vcc
	v_lshlrev_b32_e32 v132, 2, v132
	v_cmp_lt_i32_e32 vcc, v145, v139
	s_waitcnt vmcnt(0) lgkmcnt(0)
;     __device__ __forceinline__ bool run(const f32x4 (&v)[2][2][4][2], const Unit& u, int wr, int wc, int fr, int fq, PG8_LAS unsigned char* lds, int wid, int lane) const {
;     ...
;                 float s = 0.f;
; #pragma unroll
;                 for (int bj = 0; bj < 2; ++bj)
; #pragma unroll
;                     for (int n = 0; n < 2; ++n) { const f32x4 x = v[ai][bj][m][n]; s += (x[0] + x[1]) + (x[2] + x[3]); }
;                 s += __shfl_xor(s, 16); s += __shfl_xor(s, 32);
;                 const float mw = s * (1.0f / 64.0f); float q = 0.f;
; #pragma unroll
;                 for (int bj = 0; bj < 2; ++bj)
; #pragma unroll
;                     for (int n = 0; n < 2; ++n) { const f32x4 d = v[ai][bj][m][n] - mw; q += (d[0] * d[0] + d[1] * d[1]) + (d[2] * d[2] + d[3] * d[3]); }
;                 q += __shfl_xor(q, 16); q += __shfl_xor(q, 32);
;                 if (fq == 0) P[(ai * HALF + wr * 64 + m * 16 + fr) * 4 + wc] = (f32x2v){mw, q};
;     __device__ __forceinline__ void fused(f32x4 (&acc)[2][2][4][2], const Unit& u, int wr, int wc, int fr, int fq, PG8_LAS unsigned char* lds, int wid, int lane) const {
;     ...
;         for (int ai = 0; ai < 2; ++ai)
; #pragma unroll
;             for (int m = 0; m < 4; ++m) { const size_t off = (size_t)(u.pm * BM + ai * HALF + wr * 64 + m * 16 + fr) * 1024 + col0;
; #pragma unroll
;                 for (int bj = 0; bj < 2; ++bj)
; #pragma unroll
;                     for (int n = 0; n < 2; ++n) { const f32x4 xv = *(const f32x4*)(xin + off + bj * HALF + n * 16); acc[ai][bj][m][n] = xv * ALPHA_ + acc[ai][bj][m][n]; }
;                 asm volatile("" : "+v"(acc[ai][0][m][0]), "+v"(acc[ai][0][m][1]), "+v"(acc[ai][1][m][0]), "+v"(acc[ai][1][m][1]));
;                 if (m & 1) asm volatile("" ::: "memory"); }
	v_mul_f32_e64 v166, v166, s0
	v_mul_f32_e64 v167, v167, s0
	v_mul_f32_e64 v164, v164, s0
	v_mul_f32_e64 v165, v165, s0
	v_mul_f32_e64 v170, v170, s0
	v_mul_f32_e64 v171, v171, s0
	v_mul_f32_e64 v168, v168, s0
	v_mul_f32_e64 v169, v169, s0
	v_mul_f32_e64 v174, v174, s0
	v_mul_f32_e64 v175, v175, s0
	v_mul_f32_e64 v172, v172, s0
	v_mul_f32_e64 v173, v173, s0
	v_mul_f32_e64 v178, v178, s0
	v_mul_f32_e64 v179, v179, s0
	v_mul_f32_e64 v176, v176, s0
	v_mul_f32_e64 v177, v177, s0
	v_fma_f32 v130, v130, v142, v166
	v_fma_f32 v131, v131, v143, v167
	v_fma_f32 v128, v128, v146, v164
	v_fma_f32 v129, v129, v147, v165
	v_fma_f32 v110, v110, v148, v170
	v_fma_f32 v111, v111, v149, v171
	v_fma_f32 v108, v108, v150, v168
	v_fma_f32 v109, v109, v151, v169
	v_fma_f32 v78, v78, v152, v174
	v_fma_f32 v79, v79, v153, v175
	v_fma_f32 v76, v76, v154, v172
	v_fma_f32 v77, v77, v155, v173
	v_fma_f32 v50, v50, v156, v178
	v_fma_f32 v51, v51, v157, v179
	v_fma_f32 v48, v48, v158, v176
	v_fma_f32 v49, v49, v159, v177
	v_cndmask_b32_e32 v133, v133, v145, vcc
	global_load_dwordx4 v[164:167], v[134:135], off
	global_load_dwordx4 v[168:171], v[134:135], off offset:64
	global_load_dwordx4 v[172:175], v[134:135], off offset:512
	global_load_dwordx4 v[176:179], v[134:135], off offset:576
	v_add_f32_e32 v135, v20, v21
	v_mov_b32_e32 v134, v4
	v_add_f32_e64 v134, v134, v186
	v_add_f32_e64 v135, v135, v187
	v_lshlrev_b32_e32 v133, 2, v133
	v_add_f32_e64 v134, v134, v160
	v_add_f32_e64 v135, v135, v161
	s_waitcnt vmcnt(0) lgkmcnt(0)
	v_mul_f32_e64 v164, v164, s0
	v_mul_f32_e64 v165, v165, s0
	v_add_f32_e32 v134, v134, v135
	ds_bpermute_b32 v135, v132, v134
	v_mul_f32_e64 v168, v168, s0
	v_mul_f32_e64 v169, v169, s0
	v_mul_f32_e64 v172, v172, s0
	v_mul_f32_e64 v173, v173, s0
	v_mul_f32_e64 v176, v176, s0
	v_mul_f32_e64 v177, v177, s0
	v_fma_f32 v124, v124, v146, v164
	v_fma_f32 v125, v125, v147, v165
	s_waitcnt lgkmcnt(0)
	v_add_f32_e32 v134, v134, v135
	ds_bpermute_b32 v135, v133, v134
	v_fma_f32 v116, v116, v150, v168
	v_fma_f32 v117, v117, v151, v169
	v_fma_f32 v92, v92, v154, v172
	v_fma_f32 v93, v93, v155, v173
	v_fma_f32 v64, v64, v158, v176
	v_fma_f32 v65, v65, v159, v177
	s_waitcnt lgkmcnt(0)
	v_add_f32_e32 v135, v134, v135
	v_fmamk_f32 v139, v135, 0xbc800000, v83
	v_fmamk_f32 v160, v135, 0xbc800000, v81
	v_fmamk_f32 v180, v135, 0xbc800000, v47
	v_fmamk_f32 v182, v135, 0xbc800000, v45
	v_fmamk_f32 v134, v135, 0xbc800000, v82
	v_fmamk_f32 v145, v135, 0xbc800000, v80
	v_fmamk_f32 v161, v135, 0xbc800000, v46
	v_fmamk_f32 v181, v135, 0xbc800000, v44
	v_fmamk_f32 v184, v135, 0xbc800000, v23
	v_fmamk_f32 v186, v135, 0xbc800000, v21
	v_mul_f32_e32 v160, v160, v160
	v_mul_f32_e32 v139, v139, v139
	v_mul_f32_e32 v182, v182, v182
	v_mul_f32_e32 v180, v180, v180
	v_fmamk_f32 v183, v135, 0xbc800000, v22
	v_fmamk_f32 v185, v135, 0xbc800000, v20
	v_fmamk_f32 v188, v135, 0xbc800000, v7
	v_fmamk_f32 v190, v135, 0xbc800000, v5
	v_mul_f32_e32 v186, v186, v186
	v_mul_f32_e32 v184, v184, v184
	v_fmac_f32_e32 v160, v145, v145
	v_fmac_f32_e32 v139, v134, v134
	v_fmac_f32_e32 v182, v181, v181
	v_fmac_f32_e32 v180, v161, v161
	v_fmamk_f32 v187, v135, 0xbc800000, v6
	v_fmamk_f32 v189, v135, 0xbc800000, v4
	v_mul_f32_e32 v190, v190, v190
	v_mul_f32_e32 v188, v188, v188
	v_fmac_f32_e32 v186, v185, v185
	v_fmac_f32_e32 v184, v183, v183
	v_add_f32_e32 v134, v160, v139
	v_add_f32_e32 v139, v182, v180
	v_fmac_f32_e32 v190, v189, v189
	v_fmac_f32_e32 v188, v187, v187
	v_add_f32_e32 v145, v186, v184
	v_add_f32_e32 v134, v134, v139
	v_add_f32_e32 v160, v190, v188
	v_add_f32_e32 v134, v145, v134
	v_add_f32_e32 v139, v160, v134
	ds_bpermute_b32 v145, v132, v139
	v_mul_f32_e64 v160, v166, s0
	v_mul_f32_e64 v161, v167, s0
	v_mul_f32_e64 v166, v170, s0
	v_mul_f32_e64 v167, v171, s0
	v_mul_f32_e64 v170, v174, s0
	v_mul_f32_e64 v171, v175, s0
	v_mul_f32_e64 v174, v178, s0
	v_mul_f32_e64 v175, v179, s0
	s_waitcnt lgkmcnt(0)
	v_add_f32_e32 v139, v139, v145
	ds_bpermute_b32 v145, v133, v139
	v_fma_f32 v126, v126, v142, v160
	v_fma_f32 v127, v127, v143, v161
	v_fma_f32 v118, v118, v148, v166
	v_fma_f32 v119, v119, v149, v167
	v_fma_f32 v94, v94, v152, v170
	v_fma_f32 v95, v95, v153, v171
	v_fma_f32 v66, v66, v156, v174
	v_fma_f32 v67, v67, v157, v175
	v_and_b32_e32 v134, 63, v144
	s_lshl_b32 s0, s42, 3
	v_cmp_gt_u32_e32 vcc, 16, v134
	s_add_i32 s2, s0, 0
	s_and_saveexec_b64 s[0:1], vcc
	s_cbranch_execz .LBB0_1493
	s_lshl_b32 s4, s3, 11
	s_add_i32 s4, s2, s4
	v_mul_f32_e32 v142, 0x3c800000, v135
	v_lshl_add_u32 v135, v163, 5, s4
	s_waitcnt lgkmcnt(0)
	v_add_f32_e32 v143, v139, v145
	ds_write_b64 v135, v[142:143]
;     __device__ __forceinline__ bool run(const f32x4 (&v)[2][2][4][2], const Unit& u, int wr, int wc, int fr, int fq, PG8_LAS unsigned char* lds, int wid, int lane) const {
;     ...
;                 float s = 0.f;
; #pragma unroll
;                 for (int bj = 0; bj < 2; ++bj)
; #pragma unroll
;                     for (int n = 0; n < 2; ++n) { const f32x4 x = v[ai][bj][m][n]; s += (x[0] + x[1]) + (x[2] + x[3]); }
;                 s += __shfl_xor(s, 16); s += __shfl_xor(s, 32);
;                 const float mw = s * (1.0f / 64.0f); float q = 0.f;
; #pragma unroll
;                 for (int bj = 0; bj < 2; ++bj)
; #pragma unroll
;                     for (int n = 0; n < 2; ++n) { const f32x4 d = v[ai][bj][m][n] - mw; q += (d[0] * d[0] + d[1] * d[1]) + (d[2] * d[2] + d[3] * d[3]); }
;                 q += __shfl_xor(q, 16); q += __shfl_xor(q, 32);
;                 if (fq == 0) P[(ai * HALF + wr * 64 + m * 16 + fr) * 4 + wc] = (f32x2v){mw, q};
.LBB0_1493:
	s_or_b64 exec, exec, s[0:1]
	v_mov_b32_e32 v142, v89
	v_mov_b32_e32 v143, v90
	v_mov_b32_e32 v146, v88
	v_mov_b32_e32 v147, v91
	v_add_f32_e64 v142, v142, v146
	v_add_f32_e64 v143, v143, v147
	v_mov_b32_e32 v146, v57
	v_mov_b32_e32 v147, v58
	v_mov_b32_e32 v148, v56
	v_mov_b32_e32 v149, v59
	v_add_f32_e64 v146, v146, v148
	v_add_f32_e64 v147, v147, v149
	v_add_f32_e32 v135, v142, v143
	v_add_f32_e64 v147, v146, v147
	v_add_f32_e64 v146, v146, v146
	v_add_f32_e32 v143, 0, v135
	v_add_f32_e32 v149, v28, v29
	v_add_f32_e32 v151, v30, v31
	v_mov_b32_e32 v148, v8
	v_mov_b32_e32 v150, v9
	v_mov_b32_e32 v146, v10
	v_mov_b32_e32 v142, v11
	v_add_f32_e64 v148, v148, v150
	v_add_f32_e64 v149, v149, v151
	v_add_f32_e64 v142, v146, v142
	v_add_f32_e64 v143, v147, v143
	s_nop 0
	v_add_f32_e64 v142, v148, v142
	v_add_f32_e64 v143, v149, v143
	s_nop 0
	v_add_f32_e32 v135, v142, v143
	ds_bpermute_b32 v139, v132, v135
	s_waitcnt lgkmcnt(0)
	v_add_f32_e32 v135, v135, v139
	ds_bpermute_b32 v139, v133, v135
	s_waitcnt lgkmcnt(0)
	v_add_f32_e32 v135, v135, v139
	v_fmamk_f32 v142, v135, 0xbc800000, v91
	v_fmamk_f32 v145, v135, 0xbc800000, v89
	v_fmamk_f32 v139, v135, 0xbc800000, v90
	v_fmamk_f32 v143, v135, 0xbc800000, v88
	v_mul_f32_e32 v145, v145, v145
	v_mul_f32_e32 v142, v142, v142
	v_fmac_f32_e32 v145, v143, v143
	v_fmac_f32_e32 v142, v139, v139
	v_fmamk_f32 v143, v135, 0xbc800000, v59
	v_fmamk_f32 v146, v135, 0xbc800000, v57
	v_add_f32_e32 v139, v145, v142
	v_fmamk_f32 v142, v135, 0xbc800000, v58
	v_fmamk_f32 v145, v135, 0xbc800000, v56
	v_mul_f32_e32 v146, v146, v146
	v_mul_f32_e32 v143, v143, v143
	v_fmac_f32_e32 v146, v145, v145
	v_fmac_f32_e32 v143, v142, v142
	v_add_f32_e32 v142, v146, v143
	v_fmamk_f32 v143, v135, 0xbc800000, v31
	v_fmamk_f32 v146, v135, 0xbc800000, v29
	v_add_f32_e32 v139, v139, v142
	v_fmamk_f32 v142, v135, 0xbc800000, v30
	v_fmamk_f32 v145, v135, 0xbc800000, v28
	v_mul_f32_e32 v146, v146, v146
	v_mul_f32_e32 v143, v143, v143
	v_fmac_f32_e32 v146, v145, v145
	v_fmac_f32_e32 v143, v142, v142
	v_add_f32_e32 v142, v146, v143
	v_fmamk_f32 v143, v135, 0xbc800000, v11
	v_fmamk_f32 v146, v135, 0xbc800000, v9
	v_add_f32_e32 v139, v142, v139
	v_fmamk_f32 v142, v135, 0xbc800000, v10
	v_fmamk_f32 v145, v135, 0xbc800000, v8
	v_mul_f32_e32 v146, v146, v146
	v_mul_f32_e32 v143, v143, v143
	v_fmac_f32_e32 v146, v145, v145
	v_fmac_f32_e32 v143, v142, v142
	v_add_f32_e32 v142, v146, v143
	v_add_f32_e32 v139, v142, v139
	ds_bpermute_b32 v142, v132, v139
	s_waitcnt lgkmcnt(0)
	v_add_f32_e32 v139, v139, v142
	ds_bpermute_b32 v142, v133, v139
	s_and_saveexec_b64 s[0:1], vcc
	s_cbranch_execz .LBB0_1495
	s_lshl_b32 s4, s3, 11
	s_add_i32 s4, s2, s4
	v_mul_f32_e32 v146, 0x3c800000, v135
	v_lshl_add_u32 v135, v163, 5, s4
	s_waitcnt lgkmcnt(0)
	v_add_f32_e32 v147, v139, v142
	ds_write_b64 v135, v[146:147] offset:512
.LBB0_1495:
	s_or_b64 exec, exec, s[0:1]
	s_waitcnt lgkmcnt(0)
	v_mov_b32_e32 v142, v101
	v_mov_b32_e32 v143, v102
	v_mov_b32_e32 v146, v100
	v_mov_b32_e32 v147, v103
	v_add_f32_e64 v142, v142, v146
	v_add_f32_e64 v143, v143, v147
	v_mov_b32_e32 v146, v69
	v_mov_b32_e32 v147, v70
	v_mov_b32_e32 v148, v68
	v_mov_b32_e32 v149, v71
	v_add_f32_e64 v146, v146, v148
	v_add_f32_e64 v147, v147, v149
	v_add_f32_e32 v135, v142, v143
	v_add_f32_e64 v147, v146, v147
	v_add_f32_e64 v146, v146, v146
	v_add_f32_e32 v143, 0, v135
	v_add_f32_e32 v149, v36, v37
	v_add_f32_e32 v151, v38, v39
	v_mov_b32_e32 v148, v12
	v_mov_b32_e32 v150, v13
	v_mov_b32_e32 v146, v14
	v_mov_b32_e32 v142, v15
	v_add_f32_e64 v148, v148, v150
	v_add_f32_e64 v149, v149, v151
	v_add_f32_e64 v142, v146, v142
	v_add_f32_e64 v143, v147, v143
	s_nop 0
	v_add_f32_e64 v142, v148, v142
	v_add_f32_e64 v143, v149, v143
	s_nop 0
	v_add_f32_e32 v135, v142, v143
	ds_bpermute_b32 v139, v132, v135
	s_waitcnt lgkmcnt(0)
	v_add_f32_e32 v135, v135, v139
	ds_bpermute_b32 v139, v133, v135
	s_waitcnt lgkmcnt(0)
	v_add_f32_e32 v135, v135, v139
	v_fmamk_f32 v142, v135, 0xbc800000, v103
	v_fmamk_f32 v145, v135, 0xbc800000, v101
	v_fmamk_f32 v139, v135, 0xbc800000, v102
	v_fmamk_f32 v143, v135, 0xbc800000, v100
	v_mul_f32_e32 v145, v145, v145
	v_mul_f32_e32 v142, v142, v142
	v_fmac_f32_e32 v145, v143, v143
	v_fmac_f32_e32 v142, v139, v139
	v_fmamk_f32 v143, v135, 0xbc800000, v71
	v_fmamk_f32 v146, v135, 0xbc800000, v69
	v_add_f32_e32 v139, v145, v142
	v_fmamk_f32 v142, v135, 0xbc800000, v70
	v_fmamk_f32 v145, v135, 0xbc800000, v68
	v_mul_f32_e32 v146, v146, v146
	v_mul_f32_e32 v143, v143, v143
	v_fmac_f32_e32 v146, v145, v145
	v_fmac_f32_e32 v143, v142, v142
	v_add_f32_e32 v142, v146, v143
	v_fmamk_f32 v143, v135, 0xbc800000, v39
	v_fmamk_f32 v146, v135, 0xbc800000, v37
	v_add_f32_e32 v139, v139, v142
	v_fmamk_f32 v142, v135, 0xbc800000, v38
	v_fmamk_f32 v145, v135, 0xbc800000, v36
	v_mul_f32_e32 v146, v146, v146
	v_mul_f32_e32 v143, v143, v143
	v_fmac_f32_e32 v146, v145, v145
	v_fmac_f32_e32 v143, v142, v142
	v_add_f32_e32 v142, v146, v143
	v_fmamk_f32 v143, v135, 0xbc800000, v15
	v_fmamk_f32 v146, v135, 0xbc800000, v13
	v_add_f32_e32 v139, v142, v139
	v_fmamk_f32 v142, v135, 0xbc800000, v14
	v_fmamk_f32 v145, v135, 0xbc800000, v12
	v_mul_f32_e32 v146, v146, v146
	v_mul_f32_e32 v143, v143, v143
	v_fmac_f32_e32 v146, v145, v145
	v_fmac_f32_e32 v143, v142, v142
	v_add_f32_e32 v142, v146, v143
	v_add_f32_e32 v139, v142, v139
	ds_bpermute_b32 v142, v132, v139
	s_waitcnt lgkmcnt(0)
	v_add_f32_e32 v139, v139, v142
	ds_bpermute_b32 v142, v133, v139
	s_and_saveexec_b64 s[0:1], vcc
	s_cbranch_execz .LBB0_1497
	s_lshl_b32 s4, s3, 11
	s_add_i32 s4, s2, s4
	v_mul_f32_e32 v146, 0x3c800000, v135
	v_lshl_add_u32 v135, v163, 5, s4
	s_waitcnt lgkmcnt(0)
	v_add_f32_e32 v147, v139, v142
	ds_write_b64 v135, v[146:147] offset:1024
;     __device__ __forceinline__ bool run(const f32x4 (&v)[2][2][4][2], const Unit& u, int wr, int wc, int fr, int fq, PG8_LAS unsigned char* lds, int wid, int lane) const {
;     ...
;                 float s = 0.f;
; #pragma unroll
;                 for (int bj = 0; bj < 2; ++bj)
; #pragma unroll
;                     for (int n = 0; n < 2; ++n) { const f32x4 x = v[ai][bj][m][n]; s += (x[0] + x[1]) + (x[2] + x[3]); }
;                 s += __shfl_xor(s, 16); s += __shfl_xor(s, 32);
;                 const float mw = s * (1.0f / 64.0f); float q = 0.f;
; #pragma unroll
;                 for (int bj = 0; bj < 2; ++bj)
; #pragma unroll
;                     for (int n = 0; n < 2; ++n) { const f32x4 d = v[ai][bj][m][n] - mw; q += (d[0] * d[0] + d[1] * d[1]) + (d[2] * d[2] + d[3] * d[3]); }
;                 q += __shfl_xor(q, 16); q += __shfl_xor(q, 32);
;                 if (fq == 0) P[(ai * HALF + wr * 64 + m * 16 + fr) * 4 + wc] = (f32x2v){mw, q};
.LBB0_1497:
	s_or_b64 exec, exec, s[0:1]
	s_waitcnt lgkmcnt(0)
	v_mov_b32_e32 v142, v105
	v_mov_b32_e32 v143, v106
	v_mov_b32_e32 v146, v104
	v_mov_b32_e32 v147, v107
	v_add_f32_e64 v142, v142, v146
	v_add_f32_e64 v143, v143, v147
	v_mov_b32_e32 v146, v73
	v_mov_b32_e32 v147, v74
	v_mov_b32_e32 v148, v72
	v_mov_b32_e32 v149, v75
	v_add_f32_e64 v146, v146, v148
	v_add_f32_e64 v147, v147, v149
	v_add_f32_e32 v135, v142, v143
	v_add_f32_e64 v147, v146, v147
	v_add_f32_e64 v146, v146, v146
	v_add_f32_e32 v143, 0, v135
	v_add_f32_e32 v149, v40, v41
	v_add_f32_e32 v151, v42, v43
	v_mov_b32_e32 v148, v16
	v_mov_b32_e32 v150, v17
	v_mov_b32_e32 v146, v18
	v_mov_b32_e32 v142, v19
	v_add_f32_e64 v148, v148, v150
	v_add_f32_e64 v149, v149, v151
	v_add_f32_e64 v142, v146, v142
	v_add_f32_e64 v143, v147, v143
	s_nop 0
	v_add_f32_e64 v142, v148, v142
	v_add_f32_e64 v143, v149, v143
	s_nop 0
	v_add_f32_e32 v135, v142, v143
	ds_bpermute_b32 v139, v132, v135
	s_waitcnt lgkmcnt(0)
	v_add_f32_e32 v135, v135, v139
	ds_bpermute_b32 v139, v133, v135
	s_waitcnt lgkmcnt(0)
	v_add_f32_e32 v135, v135, v139
	v_fmamk_f32 v142, v135, 0xbc800000, v107
	v_fmamk_f32 v145, v135, 0xbc800000, v105
	v_fmamk_f32 v139, v135, 0xbc800000, v106
	v_fmamk_f32 v143, v135, 0xbc800000, v104
	v_mul_f32_e32 v145, v145, v145
	v_mul_f32_e32 v142, v142, v142
	v_fmac_f32_e32 v145, v143, v143
	v_fmac_f32_e32 v142, v139, v139
	v_fmamk_f32 v143, v135, 0xbc800000, v75
	v_fmamk_f32 v146, v135, 0xbc800000, v73
	v_add_f32_e32 v139, v145, v142
	v_fmamk_f32 v142, v135, 0xbc800000, v74
	v_fmamk_f32 v145, v135, 0xbc800000, v72
	v_mul_f32_e32 v146, v146, v146
	v_mul_f32_e32 v143, v143, v143
	v_fmac_f32_e32 v146, v145, v145
	v_fmac_f32_e32 v143, v142, v142
	v_add_f32_e32 v142, v146, v143
	v_fmamk_f32 v143, v135, 0xbc800000, v43
	v_fmamk_f32 v146, v135, 0xbc800000, v41
	v_add_f32_e32 v139, v139, v142
	v_fmamk_f32 v142, v135, 0xbc800000, v42
	v_fmamk_f32 v145, v135, 0xbc800000, v40
	v_mul_f32_e32 v146, v146, v146
	v_mul_f32_e32 v143, v143, v143
	v_fmac_f32_e32 v146, v145, v145
	v_fmac_f32_e32 v143, v142, v142
	v_add_f32_e32 v142, v146, v143
	v_fmamk_f32 v143, v135, 0xbc800000, v19
	v_fmamk_f32 v146, v135, 0xbc800000, v17
	v_add_f32_e32 v139, v142, v139
	v_fmamk_f32 v142, v135, 0xbc800000, v18
	v_fmamk_f32 v145, v135, 0xbc800000, v16
	v_mul_f32_e32 v146, v146, v146
	v_mul_f32_e32 v143, v143, v143
	v_fmac_f32_e32 v146, v145, v145
	v_fmac_f32_e32 v143, v142, v142
	v_add_f32_e32 v142, v146, v143
	v_add_f32_e32 v139, v142, v139
	ds_bpermute_b32 v142, v132, v139
	s_waitcnt lgkmcnt(0)
	v_add_f32_e32 v139, v139, v142
	ds_bpermute_b32 v142, v133, v139
	s_and_saveexec_b64 s[0:1], vcc
	s_cbranch_execz .LBB0_1499
	s_lshl_b32 s4, s3, 11
	s_add_i32 s4, s2, s4
	v_mul_f32_e32 v146, 0x3c800000, v135
	v_lshl_add_u32 v135, v163, 5, s4
	s_waitcnt lgkmcnt(0)
	v_add_f32_e32 v147, v139, v142
	ds_write_b64 v135, v[146:147] offset:1536
.LBB0_1499:
	s_or_b64 exec, exec, s[0:1]
	s_waitcnt lgkmcnt(0)
	v_mov_b32_e32 v142, v113
	v_mov_b32_e32 v143, v114
	v_mov_b32_e32 v146, v112
	v_mov_b32_e32 v147, v115
	v_add_f32_e64 v142, v142, v146
	v_add_f32_e64 v143, v143, v147
	v_mov_b32_e32 v146, v85
	v_mov_b32_e32 v147, v86
	v_mov_b32_e32 v148, v84
	v_mov_b32_e32 v149, v87
	v_add_f32_e64 v146, v146, v148
	v_add_f32_e64 v147, v147, v149
	v_add_f32_e32 v135, v142, v143
	v_add_f32_e64 v147, v146, v147
	v_add_f32_e64 v146, v146, v146
	v_add_f32_e32 v143, 0, v135
	v_add_f32_e32 v149, v52, v53
	v_add_f32_e32 v151, v54, v55
	v_mov_b32_e32 v148, v24
	v_mov_b32_e32 v150, v25
	v_mov_b32_e32 v146, v26
	v_mov_b32_e32 v142, v27
	v_add_f32_e64 v148, v148, v150
	v_add_f32_e64 v149, v149, v151
	v_add_f32_e64 v142, v146, v142
	v_add_f32_e64 v143, v147, v143
	s_nop 0
	v_add_f32_e64 v142, v148, v142
	v_add_f32_e64 v143, v149, v143
	s_nop 0
	v_add_f32_e32 v135, v142, v143
	ds_bpermute_b32 v139, v132, v135
	s_waitcnt lgkmcnt(0)
	v_add_f32_e32 v135, v135, v139
	ds_bpermute_b32 v139, v133, v135
	s_waitcnt lgkmcnt(0)
	v_add_f32_e32 v135, v135, v139
	v_fmamk_f32 v142, v135, 0xbc800000, v115
	v_fmamk_f32 v145, v135, 0xbc800000, v113
	v_fmamk_f32 v139, v135, 0xbc800000, v114
	v_fmamk_f32 v143, v135, 0xbc800000, v112
	v_mul_f32_e32 v145, v145, v145
	v_mul_f32_e32 v142, v142, v142
	v_fmac_f32_e32 v145, v143, v143
	v_fmac_f32_e32 v142, v139, v139
	v_fmamk_f32 v143, v135, 0xbc800000, v87
	v_fmamk_f32 v146, v135, 0xbc800000, v85
	v_add_f32_e32 v139, v145, v142
	v_fmamk_f32 v142, v135, 0xbc800000, v86
	v_fmamk_f32 v145, v135, 0xbc800000, v84
	v_mul_f32_e32 v146, v146, v146
	v_mul_f32_e32 v143, v143, v143
	v_fmac_f32_e32 v146, v145, v145
	v_fmac_f32_e32 v143, v142, v142
	v_add_f32_e32 v142, v146, v143
	v_fmamk_f32 v143, v135, 0xbc800000, v55
	v_fmamk_f32 v146, v135, 0xbc800000, v53
	v_add_f32_e32 v139, v139, v142
	v_fmamk_f32 v142, v135, 0xbc800000, v54
	v_fmamk_f32 v145, v135, 0xbc800000, v52
	v_mul_f32_e32 v146, v146, v146
	v_mul_f32_e32 v143, v143, v143
	v_fmac_f32_e32 v146, v145, v145
	v_fmac_f32_e32 v143, v142, v142
	v_add_f32_e32 v142, v146, v143
	v_fmamk_f32 v143, v135, 0xbc800000, v27
	v_fmamk_f32 v146, v135, 0xbc800000, v25
	v_add_f32_e32 v139, v142, v139
	v_fmamk_f32 v142, v135, 0xbc800000, v26
	v_fmamk_f32 v145, v135, 0xbc800000, v24
	v_mul_f32_e32 v146, v146, v146
	v_mul_f32_e32 v143, v143, v143
	v_fmac_f32_e32 v146, v145, v145
	v_fmac_f32_e32 v143, v142, v142
	v_add_f32_e32 v142, v146, v143
	v_add_f32_e32 v139, v142, v139
	ds_bpermute_b32 v142, v132, v139
	s_waitcnt lgkmcnt(0)
	v_add_f32_e32 v139, v139, v142
	ds_bpermute_b32 v142, v133, v139
	s_and_saveexec_b64 s[0:1], vcc
	s_cbranch_execz .LBB0_1501
	s_lshl_b32 s4, s3, 11
	s_add_i32 s4, s2, s4
	v_mul_f32_e32 v146, 0x3c800000, v135
	v_lshl_add_u32 v135, v163, 5, s4
	s_waitcnt lgkmcnt(0)
	v_add_f32_e32 v147, v139, v142
	ds_write_b64 v135, v[146:147] offset:4096
;     __device__ __forceinline__ bool run(const f32x4 (&v)[2][2][4][2], const Unit& u, int wr, int wc, int fr, int fq, PG8_LAS unsigned char* lds, int wid, int lane) const {
;     ...
;                 float s = 0.f;
; #pragma unroll
;                 for (int bj = 0; bj < 2; ++bj)
; #pragma unroll
;                     for (int n = 0; n < 2; ++n) { const f32x4 x = v[ai][bj][m][n]; s += (x[0] + x[1]) + (x[2] + x[3]); }
;                 s += __shfl_xor(s, 16); s += __shfl_xor(s, 32);
;                 const float mw = s * (1.0f / 64.0f); float q = 0.f;
; #pragma unroll
;                 for (int bj = 0; bj < 2; ++bj)
; #pragma unroll
;                     for (int n = 0; n < 2; ++n) { const f32x4 d = v[ai][bj][m][n] - mw; q += (d[0] * d[0] + d[1] * d[1]) + (d[2] * d[2] + d[3] * d[3]); }
;                 q += __shfl_xor(q, 16); q += __shfl_xor(q, 32);
;                 if (fq == 0) P[(ai * HALF + wr * 64 + m * 16 + fr) * 4 + wc] = (f32x2v){mw, q};
.LBB0_1501:
	s_or_b64 exec, exec, s[0:1]
	s_waitcnt lgkmcnt(0)
	v_mov_b32_e32 v142, v121
	v_mov_b32_e32 v143, v122
	v_mov_b32_e32 v146, v120
	v_mov_b32_e32 v147, v123
	v_add_f32_e64 v142, v142, v146
	v_add_f32_e64 v143, v143, v147
	v_mov_b32_e32 v146, v97
	v_mov_b32_e32 v147, v98
	v_mov_b32_e32 v148, v96
	v_mov_b32_e32 v149, v99
	v_add_f32_e64 v146, v146, v148
	v_add_f32_e64 v147, v147, v149
	v_add_f32_e32 v135, v142, v143
	v_add_f32_e64 v147, v146, v147
	v_add_f32_e64 v146, v146, v146
	v_add_f32_e32 v143, 0, v135
	v_add_f32_e32 v149, v60, v61
	v_add_f32_e32 v151, v62, v63
	v_mov_b32_e32 v148, v32
	v_mov_b32_e32 v150, v33
	v_mov_b32_e32 v146, v34
	v_mov_b32_e32 v142, v35
	v_add_f32_e64 v148, v148, v150
	v_add_f32_e64 v149, v149, v151
	v_add_f32_e64 v142, v146, v142
	v_add_f32_e64 v143, v147, v143
	s_nop 0
	v_add_f32_e64 v142, v148, v142
	v_add_f32_e64 v143, v149, v143
	s_nop 0
	v_add_f32_e32 v135, v142, v143
	ds_bpermute_b32 v139, v132, v135
	s_waitcnt lgkmcnt(0)
	v_add_f32_e32 v135, v135, v139
	ds_bpermute_b32 v139, v133, v135
	s_waitcnt lgkmcnt(0)
	v_add_f32_e32 v135, v135, v139
	v_fmamk_f32 v142, v135, 0xbc800000, v123
	v_fmamk_f32 v145, v135, 0xbc800000, v121
	v_fmamk_f32 v139, v135, 0xbc800000, v122
	v_fmamk_f32 v143, v135, 0xbc800000, v120
	v_mul_f32_e32 v145, v145, v145
	v_mul_f32_e32 v142, v142, v142
	v_fmac_f32_e32 v145, v143, v143
	v_fmac_f32_e32 v142, v139, v139
	v_fmamk_f32 v143, v135, 0xbc800000, v99
	v_fmamk_f32 v146, v135, 0xbc800000, v97
	v_add_f32_e32 v139, v145, v142
	v_fmamk_f32 v142, v135, 0xbc800000, v98
	v_fmamk_f32 v145, v135, 0xbc800000, v96
	v_mul_f32_e32 v146, v146, v146
	v_mul_f32_e32 v143, v143, v143
	v_fmac_f32_e32 v146, v145, v145
	v_fmac_f32_e32 v143, v142, v142
	v_add_f32_e32 v142, v146, v143
	v_fmamk_f32 v143, v135, 0xbc800000, v63
	v_fmamk_f32 v146, v135, 0xbc800000, v61
	v_add_f32_e32 v139, v139, v142
	v_fmamk_f32 v142, v135, 0xbc800000, v62
	v_fmamk_f32 v145, v135, 0xbc800000, v60
	v_mul_f32_e32 v146, v146, v146
	v_mul_f32_e32 v143, v143, v143
	v_fmac_f32_e32 v146, v145, v145
	v_fmac_f32_e32 v143, v142, v142
	v_add_f32_e32 v142, v146, v143
	v_fmamk_f32 v143, v135, 0xbc800000, v35
	v_fmamk_f32 v146, v135, 0xbc800000, v33
	v_add_f32_e32 v139, v142, v139
	v_fmamk_f32 v142, v135, 0xbc800000, v34
	v_fmamk_f32 v145, v135, 0xbc800000, v32
	v_mul_f32_e32 v146, v146, v146
	v_mul_f32_e32 v143, v143, v143
	v_fmac_f32_e32 v146, v145, v145
	v_fmac_f32_e32 v143, v142, v142
	v_add_f32_e32 v142, v146, v143
	v_add_f32_e32 v139, v142, v139
	ds_bpermute_b32 v142, v132, v139
	s_waitcnt lgkmcnt(0)
	v_add_f32_e32 v139, v139, v142
	ds_bpermute_b32 v142, v133, v139
	s_and_saveexec_b64 s[0:1], vcc
	s_cbranch_execz .LBB0_1503
	s_lshl_b32 s4, s3, 11
	s_add_i32 s4, s2, s4
	v_mul_f32_e32 v146, 0x3c800000, v135
	v_lshl_add_u32 v135, v163, 5, s4
	s_waitcnt lgkmcnt(0)
	v_add_f32_e32 v147, v139, v142
	ds_write_b64 v135, v[146:147] offset:4608
.LBB0_1503:
	s_or_b64 exec, exec, s[0:1]
	s_waitcnt lgkmcnt(0)
	v_mov_b32_e32 v142, v129
	v_mov_b32_e32 v143, v130
	v_mov_b32_e32 v146, v128
	v_mov_b32_e32 v147, v131
	v_add_f32_e64 v142, v142, v146
	v_add_f32_e64 v143, v143, v147
	v_mov_b32_e32 v146, v109
	v_mov_b32_e32 v147, v110
	v_mov_b32_e32 v148, v108
	v_mov_b32_e32 v149, v111
	v_add_f32_e64 v146, v146, v148
	v_add_f32_e64 v147, v147, v149
	v_add_f32_e32 v135, v142, v143
	v_add_f32_e64 v147, v146, v147
	v_add_f32_e64 v146, v146, v146
	v_add_f32_e32 v143, 0, v135
	v_add_f32_e32 v149, v76, v77
	v_add_f32_e32 v151, v78, v79
	v_mov_b32_e32 v148, v48
	v_mov_b32_e32 v150, v49
	v_mov_b32_e32 v146, v50
	v_mov_b32_e32 v142, v51
	v_add_f32_e64 v148, v148, v150
	v_add_f32_e64 v149, v149, v151
	v_add_f32_e64 v142, v146, v142
	v_add_f32_e64 v143, v147, v143
	s_nop 0
	v_add_f32_e64 v142, v148, v142
	v_add_f32_e64 v143, v149, v143
	s_nop 0
	v_add_f32_e32 v135, v142, v143
	ds_bpermute_b32 v139, v132, v135
	s_waitcnt lgkmcnt(0)
	v_add_f32_e32 v135, v135, v139
	ds_bpermute_b32 v139, v133, v135
	s_waitcnt lgkmcnt(0)
	v_add_f32_e32 v135, v135, v139
	v_fmamk_f32 v142, v135, 0xbc800000, v131
	v_fmamk_f32 v145, v135, 0xbc800000, v129
	v_fmamk_f32 v139, v135, 0xbc800000, v130
	v_fmamk_f32 v143, v135, 0xbc800000, v128
	v_mul_f32_e32 v145, v145, v145
	v_mul_f32_e32 v142, v142, v142
	v_fmac_f32_e32 v145, v143, v143
	v_fmac_f32_e32 v142, v139, v139
	v_fmamk_f32 v143, v135, 0xbc800000, v111
	v_fmamk_f32 v146, v135, 0xbc800000, v109
	v_add_f32_e32 v139, v145, v142
	v_fmamk_f32 v142, v135, 0xbc800000, v110
	v_fmamk_f32 v145, v135, 0xbc800000, v108
	v_mul_f32_e32 v146, v146, v146
	v_mul_f32_e32 v143, v143, v143
	v_fmac_f32_e32 v146, v145, v145
	v_fmac_f32_e32 v143, v142, v142
	v_add_f32_e32 v142, v146, v143
	v_fmamk_f32 v143, v135, 0xbc800000, v79
	v_fmamk_f32 v146, v135, 0xbc800000, v77
	v_add_f32_e32 v139, v139, v142
	v_fmamk_f32 v142, v135, 0xbc800000, v78
	v_fmamk_f32 v145, v135, 0xbc800000, v76
	v_mul_f32_e32 v146, v146, v146
	v_mul_f32_e32 v143, v143, v143
	v_fmac_f32_e32 v146, v145, v145
	v_fmac_f32_e32 v143, v142, v142
	v_add_f32_e32 v142, v146, v143
	v_fmamk_f32 v143, v135, 0xbc800000, v51
	v_fmamk_f32 v146, v135, 0xbc800000, v49
	v_add_f32_e32 v139, v142, v139
	v_fmamk_f32 v142, v135, 0xbc800000, v50
	v_fmamk_f32 v145, v135, 0xbc800000, v48
	v_mul_f32_e32 v146, v146, v146
	v_mul_f32_e32 v143, v143, v143
	v_fmac_f32_e32 v146, v145, v145
	v_fmac_f32_e32 v143, v142, v142
	v_add_f32_e32 v142, v146, v143
	v_add_f32_e32 v139, v142, v139
	ds_bpermute_b32 v142, v132, v139
	s_waitcnt lgkmcnt(0)
	v_add_f32_e32 v139, v139, v142
	ds_bpermute_b32 v142, v133, v139
	s_and_saveexec_b64 s[0:1], vcc
	s_cbranch_execz .LBB0_1505
	s_lshl_b32 s4, s3, 11
	s_add_i32 s4, s2, s4
	v_mul_f32_e32 v146, 0x3c800000, v135
	v_lshl_add_u32 v135, v163, 5, s4
	s_waitcnt lgkmcnt(0)
	v_add_f32_e32 v147, v139, v142
	ds_write_b64 v135, v[146:147] offset:5120
;     __device__ __forceinline__ bool run(const f32x4 (&v)[2][2][4][2], const Unit& u, int wr, int wc, int fr, int fq, PG8_LAS unsigned char* lds, int wid, int lane) const {
;     ...
;                 float s = 0.f;
; #pragma unroll
;                 for (int bj = 0; bj < 2; ++bj)
; #pragma unroll
;                     for (int n = 0; n < 2; ++n) { const f32x4 x = v[ai][bj][m][n]; s += (x[0] + x[1]) + (x[2] + x[3]); }
;                 s += __shfl_xor(s, 16); s += __shfl_xor(s, 32);
;                 const float mw = s * (1.0f / 64.0f); float q = 0.f;
; #pragma unroll
;                 for (int bj = 0; bj < 2; ++bj)
; #pragma unroll
;                     for (int n = 0; n < 2; ++n) { const f32x4 d = v[ai][bj][m][n] - mw; q += (d[0] * d[0] + d[1] * d[1]) + (d[2] * d[2] + d[3] * d[3]); }
;                 q += __shfl_xor(q, 16); q += __shfl_xor(q, 32);
;                 if (fq == 0) P[(ai * HALF + wr * 64 + m * 16 + fr) * 4 + wc] = (f32x2v){mw, q};
;     ...
;         const int row = wid * 32 + (lane & 31);
;         if (lane < 32) {
;             const f32x2v a = P[row * 4 + 0], b = P[row * 4 + 1], c = P[row * 4 + 2], d = P[row * 4 + 3];
;             const float mt = (a.x + b.x + c.x + d.x) * 0.25f;
;             const float da = a.x - mt, db = b.x - mt, dc = c.x - mt, dd = d.x - mt;
;             const float m2 = (a.y + b.y) + (c.y + d.y) + 64.0f * ((da * da + db * db) + (dc * dc + dd * dd));
;             unsigned long long* slot = (unsigned long long*)xbuf + ((size_t)(u.pm * BM + row) * 4 + u.pn);
;             __hip_atomic_store(slot, ((unsigned long long)__float_as_uint(m2) << 32) | __float_as_uint(mt), __ATOMIC_RELAXED, __HIP_MEMORY_SCOPE_AGENT);
.LBB0_1505:
	s_or_b64 exec, exec, s[0:1]
	s_waitcnt lgkmcnt(0)
	v_mov_b32_e32 v142, v125
	v_mov_b32_e32 v143, v126
	v_mov_b32_e32 v146, v124
	v_mov_b32_e32 v147, v127
	v_add_f32_e64 v142, v142, v146
	v_add_f32_e64 v143, v143, v147
	v_mov_b32_e32 v146, v117
	v_mov_b32_e32 v147, v118
	v_mov_b32_e32 v148, v116
	v_mov_b32_e32 v149, v119
	v_add_f32_e64 v146, v146, v148
	v_add_f32_e64 v147, v147, v149
	v_add_f32_e32 v135, v142, v143
	v_add_f32_e64 v147, v146, v147
	v_add_f32_e64 v146, v146, v146
	v_add_f32_e32 v143, 0, v135
	v_add_f32_e32 v149, v92, v93
	v_add_f32_e32 v151, v94, v95
	v_mov_b32_e32 v148, v64
	v_mov_b32_e32 v150, v65
	v_mov_b32_e32 v146, v66
	v_mov_b32_e32 v142, v67
	v_add_f32_e64 v148, v148, v150
	v_add_f32_e64 v149, v149, v151
	v_add_f32_e64 v142, v146, v142
	v_add_f32_e64 v143, v147, v143
	s_nop 0
	v_add_f32_e64 v142, v148, v142
	v_add_f32_e64 v143, v149, v143
	s_nop 0
	v_add_f32_e32 v135, v142, v143
	ds_bpermute_b32 v139, v132, v135
	s_waitcnt lgkmcnt(0)
	v_add_f32_e32 v135, v135, v139
	ds_bpermute_b32 v139, v133, v135
	s_waitcnt lgkmcnt(0)
	v_add_f32_e32 v135, v135, v139
	v_fmamk_f32 v142, v135, 0xbc800000, v127
	v_fmamk_f32 v145, v135, 0xbc800000, v125
	v_fmamk_f32 v139, v135, 0xbc800000, v126
	v_fmamk_f32 v143, v135, 0xbc800000, v124
	v_mul_f32_e32 v145, v145, v145
	v_mul_f32_e32 v142, v142, v142
	v_fmac_f32_e32 v145, v143, v143
	v_fmac_f32_e32 v142, v139, v139
	v_fmamk_f32 v143, v135, 0xbc800000, v119
	v_fmamk_f32 v146, v135, 0xbc800000, v117
	v_add_f32_e32 v139, v145, v142
	v_fmamk_f32 v142, v135, 0xbc800000, v118
	v_fmamk_f32 v145, v135, 0xbc800000, v116
	v_mul_f32_e32 v146, v146, v146
	v_mul_f32_e32 v143, v143, v143
	v_fmac_f32_e32 v146, v145, v145
	v_fmac_f32_e32 v143, v142, v142
	v_add_f32_e32 v142, v146, v143
	v_fmamk_f32 v143, v135, 0xbc800000, v95
	v_fmamk_f32 v146, v135, 0xbc800000, v93
	v_add_f32_e32 v139, v139, v142
	v_fmamk_f32 v142, v135, 0xbc800000, v94
	v_fmamk_f32 v145, v135, 0xbc800000, v92
	v_mul_f32_e32 v146, v146, v146
	v_mul_f32_e32 v143, v143, v143
	v_fmac_f32_e32 v146, v145, v145
	v_fmac_f32_e32 v143, v142, v142
	v_add_f32_e32 v142, v146, v143
	v_fmamk_f32 v143, v135, 0xbc800000, v67
	v_fmamk_f32 v146, v135, 0xbc800000, v65
	v_add_f32_e32 v139, v142, v139
	v_fmamk_f32 v142, v135, 0xbc800000, v66
	v_fmamk_f32 v145, v135, 0xbc800000, v64
	v_mul_f32_e32 v146, v146, v146
	v_mul_f32_e32 v143, v143, v143
	v_fmac_f32_e32 v146, v145, v145
	v_fmac_f32_e32 v143, v142, v142
	v_add_f32_e32 v142, v146, v143
	v_add_f32_e32 v139, v142, v139
	ds_bpermute_b32 v132, v132, v139
	s_waitcnt lgkmcnt(0)
	v_add_f32_e32 v132, v139, v132
	ds_bpermute_b32 v133, v133, v132
	s_and_saveexec_b64 s[0:1], vcc
	s_cbranch_execz .LBB0_1507
	s_lshl_b32 s3, s3, 11
	s_add_i32 s2, s2, s3
	v_mul_f32_e32 v142, 0x3c800000, v135
	v_lshl_add_u32 v135, v163, 5, s2
	s_waitcnt lgkmcnt(0)
	v_add_f32_e32 v143, v132, v133
	ds_write_b64 v135, v[142:143] offset:5632
.LBB0_1507:
	s_or_b64 exec, exec, s[0:1]
	v_and_b32_e32 v132, 31, v144
	s_waitcnt lgkmcnt(0)
	s_barrier
	v_lshl_or_b32 v139, s11, 5, v132
	s_add_u32 s2, s8, 0x3780000
	v_add_u32_e32 v132, s16, v139
	s_addc_u32 s3, s9, 0
	v_cmp_gt_u32_e64 s[0:1], 32, v134
	s_waitcnt lgkmcnt(0)
	v_ashrrev_i32_e32 v133, 31, v132
	s_and_saveexec_b64 s[4:5], s[0:1]
	s_cbranch_execz .LBB0_1509
	v_lshl_add_u32 v135, v139, 5, 0
	ds_read_b128 v[142:145], v135
	ds_read_b128 v[146:149], v135 offset:16
	s_ashr_i32 s11, s10, 31
	s_waitcnt lgkmcnt(1)
	v_add_f32_e32 v135, v142, v144
	s_waitcnt lgkmcnt(0)
	v_add_f32_e32 v135, v135, v146
	v_add_f32_e32 v135, v135, v148
	v_fmamk_f32 v142, v135, 0xbe800000, v142
	v_fmac_f32_e32 v144, 0xbe800000, v135
	v_fmamk_f32 v146, v135, 0xbe800000, v146
	v_fmac_f32_e32 v148, 0xbe800000, v135
	v_mul_f32_e32 v153, v142, v142
	v_mul_f32_e32 v155, v144, v144
	v_mul_f32_e32 v157, v146, v146
	v_mul_f32_e32 v159, v148, v148
	v_mov_b32_e32 v152, v143
	v_mov_b32_e32 v154, v145
	v_mov_b32_e32 v156, v147
	v_mov_b32_e32 v158, v149
	v_add_f32_e64 v142, v152, v154
	v_add_f32_e64 v143, v153, v155
	v_add_f32_e64 v144, v156, v158
	v_add_f32_e64 v145, v157, v159
	v_mul_f32_e32 v150, 0x3e800000, v135
	v_add_f32_e64 v142, v142, v144
	v_add_f32_e64 v143, v143, v145
	s_nop 0
	v_fmamk_f32 v151, v143, 0x42800000, v142
	v_lshlrev_b64 v[142:143], 5, v[132:133]
	v_lshl_add_u64 v[142:143], s[2:3], 0, v[142:143]
	v_lshl_add_u64 v[142:143], s[10:11], 3, v[142:143]
	global_store_dwordx2 v[142:143], v[150:151], off sc1

; __device__ __forceinline__ unsigned cvt_pk_bf16(float lo, float hi) { unsigned r; asm volatile("v_cvt_pk_bf16_f32 %0, %1, %2" : "=v"(r) : "v"(lo), "v"(hi)); return r; }
;     __device__ __forceinline__ void fused(f32x4 (&acc)[2][2][4][2], const Unit& u, int wr, int wc, int fr, int fq, PG8_LAS unsigned char* lds, int wid, int lane) const {
;     ...
;         const float qnan = __builtin_nanf("");
; #pragma unroll
;         for (int bj = 0; bj < 2; ++bj)
; #pragma unroll
;             for (int n = 0; n < 2; ++n) {
;                 const int col = col0 + bj * HALF + n * 16;
;                 const f32x4 lg = *(const f32x4*)(lng + col), lb = *(const f32x4*)(lnb + col);
;                 f32x4 sc1 = (f32x4){1.f, 1.f, 1.f, 1.f}, sh = (f32x4){0.f, 0.f, 0.f, 0.f};
;                 if (DO_U) { sc1 = *(const f32x4*)(msc + mo + col) + 1.0f; sh = *(const f32x4*)(msh + mo + col); }
; #pragma unroll
;                 for (int ai = 0; ai < 2; ++ai)
; #pragma unroll
;                     for (int m = 0; m < 4; ++m) { const int r = ai * HALF + wr * 64 + m * 16 + fr; const f32x2v sr = S[r]; const size_t off = (size_t)(u.pm * BM + r) * 1024 + col;
;                         f32x4 y = (acc[ai][bj][m][n] - sr.x) * sr.y * lg + lb; if (bad) y = (f32x4){qnan, qnan, qnan, qnan};
;                         *(f32x4*)(out + off) = y;
;                         if (DO_U) { const f32x4 uu = y * sc1 + sh; u32x2v w; w.x = cvt_pk_bf16(uu[0], uu[1]); w.y = cvt_pk_bf16(uu[2], uu[3]); *(u32x2v*)(U + off) = w; } }
.LBB0_1530:
	s_or_b64 exec, exec, s[4:5]
	s_mov_b64 s[0:1], 0x2000
	v_lshl_add_u64 v[144:145], v[0:1], 0, s[0:1]
	v_lshl_add_u64 v[142:143], v[2:3], 0, s[0:1]
	s_waitcnt lgkmcnt(0)
	s_barrier
	v_lshl_add_u64 v[0:1], v[144:145], 0, v[140:141]
	v_lshl_add_u64 v[132:133], v[142:143], 0, v[140:141]
	global_load_dwordx4 v[0:3], v[0:1], off
	v_lshl_add_u32 v139, v162, 3, 0
	global_load_dwordx4 v[132:135], v[132:133], off
	ds_read_b64 v[154:155], v139 offset:8192
	v_add_u32_e32 v150, s16, v162
	v_ashrrev_i32_e32 v151, 31, v150
	v_lshlrev_b64 v[148:149], 12, v[150:151]
	v_mov_b32_e32 v152, 0x7fc00000
	s_waitcnt lgkmcnt(0)
	v_sub_f32_e32 v83, v83, v154
	v_sub_f32_e32 v82, v82, v154
	v_sub_f32_e32 v81, v81, v154
	v_sub_f32_e32 v80, v80, v154
	v_mul_f32_e64 v80, v155, v80
	v_mul_f32_e64 v81, v155, v81
	v_mul_f32_e64 v82, v155, v82
	v_mul_f32_e64 v83, v155, v83
	v_lshl_add_u64 v[148:149], v[136:137], 0, v[148:149]
	v_cmp_eq_u32_e32 vcc, 0, v146
	v_lshl_add_u64 v[148:149], v[148:149], 0, v[140:141]
	v_add_u32_e32 v156, 16, v150
	v_ashrrev_i32_e32 v157, 31, v156
	v_add_u32_e32 v158, 32, v150
	v_ashrrev_i32_e32 v159, 31, v158
	v_add_u32_e32 v160, 48, v150
	v_ashrrev_i32_e32 v161, 31, v160
	v_add_u32_e32 v162, 0x80, v150
	v_ashrrev_i32_e32 v163, 31, v162
	v_add_u32_e32 v164, 0x90, v150
	v_ashrrev_i32_e32 v165, 31, v164
	s_waitcnt vmcnt(0)
	v_fma_f32 v82, v2, v82, v134
	v_fma_f32 v83, v3, v83, v135
	v_fma_f32 v80, v0, v80, v132
	v_fma_f32 v81, v1, v81, v133
	v_cndmask_b32_e32 v83, v152, v83, vcc
	v_cndmask_b32_e32 v82, v152, v82, vcc
	v_cndmask_b32_e32 v81, v152, v81, vcc
	v_cndmask_b32_e32 v80, v152, v80, vcc
	global_store_dwordx4 v[148:149], v[80:83], off sc0 sc1 nt
	ds_read_b64 v[80:81], v139 offset:8320
	s_waitcnt lgkmcnt(0)
	v_sub_f32_e32 v89, v89, v80
	v_lshlrev_b64 v[82:83], 12, v[156:157]
	v_lshl_add_u64 v[82:83], v[136:137], 0, v[82:83]
	v_lshl_add_u64 v[146:147], v[82:83], 0, v[140:141]
	v_sub_f32_e32 v83, v91, v80
	v_sub_f32_e32 v82, v90, v80
	v_sub_f32_e32 v88, v88, v80
	v_mul_f32_e64 v88, v81, v88
	v_mul_f32_e64 v89, v81, v89
	v_mul_f32_e64 v80, v81, v82
	v_mul_f32_e64 v81, v81, v83
	v_fma_f32 v88, v0, v88, v132
	v_fma_f32 v89, v1, v89, v133
	v_fma_f32 v80, v2, v80, v134
	v_fma_f32 v81, v3, v81, v135
	s_nop 0
	v_cndmask_b32_e32 v83, v152, v81, vcc
	v_cndmask_b32_e32 v82, v152, v80, vcc
	v_cndmask_b32_e32 v81, v152, v89, vcc
	v_cndmask_b32_e32 v80, v152, v88, vcc
	global_store_dwordx4 v[146:147], v[80:83], off sc0 sc1 nt
	ds_read_b64 v[80:81], v139 offset:8448
	s_waitcnt lgkmcnt(0)
	v_sub_f32_e32 v91, v101, v80
	v_lshlrev_b64 v[82:83], 12, v[158:159]
	v_lshl_add_u64 v[82:83], v[136:137], 0, v[82:83]
	v_lshl_add_u64 v[88:89], v[82:83], 0, v[140:141]
	v_sub_f32_e32 v83, v103, v80
	v_sub_f32_e32 v82, v102, v80
	v_sub_f32_e32 v90, v100, v80
	v_mul_f32_e64 v90, v81, v90
	v_mul_f32_e64 v91, v81, v91
	v_mul_f32_e64 v80, v81, v82
	v_mul_f32_e64 v81, v81, v83
	v_fma_f32 v90, v0, v90, v132
	v_fma_f32 v91, v1, v91, v133
	v_fma_f32 v80, v2, v80, v134
	v_fma_f32 v81, v3, v81, v135
	s_nop 0
	v_cndmask_b32_e32 v83, v152, v81, vcc
	v_cndmask_b32_e32 v82, v152, v80, vcc
	v_cndmask_b32_e32 v81, v152, v91, vcc
	v_cndmask_b32_e32 v80, v152, v90, vcc
	global_store_dwordx4 v[88:89], v[80:83], off sc0 sc1 nt
	ds_read_b64 v[80:81], v139 offset:8576
	s_waitcnt lgkmcnt(0)
	v_sub_f32_e32 v91, v107, v80
	v_sub_f32_e32 v90, v106, v80
	v_sub_f32_e32 v101, v105, v80
	v_sub_f32_e32 v100, v104, v80
	v_lshlrev_b64 v[82:83], 12, v[160:161]
	v_mul_f32_e64 v100, v81, v100
	v_mul_f32_e64 v101, v81, v101
	v_mul_f32_e64 v80, v81, v90
	v_mul_f32_e64 v81, v81, v91
	v_lshl_add_u64 v[82:83], v[136:137], 0, v[82:83]
	v_fma_f32 v80, v2, v80, v134
	v_fma_f32 v81, v3, v81, v135
	v_fma_f32 v90, v0, v100, v132
	v_fma_f32 v91, v1, v101, v133
	v_lshl_add_u64 v[82:83], v[82:83], 0, v[140:141]
	v_cndmask_b32_e32 v103, v152, v81, vcc
	v_cndmask_b32_e32 v102, v152, v80, vcc
	v_cndmask_b32_e32 v101, v152, v91, vcc
	v_cndmask_b32_e32 v100, v152, v90, vcc
	global_store_dwordx4 v[82:83], v[100:103], off sc0 sc1 nt
	ds_read_b64 v[90:91], v139 offset:9216
	v_lshlrev_b64 v[80:81], 12, v[162:163]
	v_lshl_add_u64 v[80:81], v[136:137], 0, v[80:81]
	v_lshl_add_u64 v[80:81], v[80:81], 0, v[140:141]
	s_waitcnt lgkmcnt(0)
	v_sub_f32_e32 v101, v115, v90
	v_sub_f32_e32 v100, v114, v90
	v_sub_f32_e32 v103, v113, v90
	v_sub_f32_e32 v102, v112, v90
	v_mul_f32_e64 v102, v91, v102
	v_mul_f32_e64 v103, v91, v103
	v_mul_f32_e64 v90, v91, v100
	v_mul_f32_e64 v91, v91, v101
	v_fma_f32 v100, v0, v102, v132
	v_fma_f32 v101, v1, v103, v133
	v_fma_f32 v90, v2, v90, v134
	v_fma_f32 v91, v3, v91, v135
	v_cndmask_b32_e32 v101, v152, v101, vcc
	v_cndmask_b32_e32 v103, v152, v91, vcc
	v_cndmask_b32_e32 v102, v152, v90, vcc
	v_cndmask_b32_e32 v100, v152, v100, vcc
	global_store_dwordx4 v[80:81], v[100:103], off sc0 sc1 nt
	ds_read_b64 v[100:101], v139 offset:9344
	v_lshlrev_b64 v[90:91], 12, v[164:165]
	v_lshl_add_u64 v[90:91], v[136:137], 0, v[90:91]
	v_lshl_add_u64 v[90:91], v[90:91], 0, v[140:141]
	s_waitcnt lgkmcnt(0)
	v_sub_f32_e32 v103, v123, v100
	v_sub_f32_e32 v102, v122, v100
	v_sub_f32_e32 v105, v121, v100
	v_sub_f32_e32 v104, v120, v100
	v_mul_f32_e64 v104, v101, v104
	v_mul_f32_e64 v105, v101, v105
	v_mul_f32_e64 v100, v101, v102
	v_mul_f32_e64 v101, v101, v103
	v_fma_f32 v104, v0, v104, v132
	v_fma_f32 v105, v1, v105, v133
	v_fma_f32 v100, v2, v100, v134
	v_fma_f32 v101, v3, v101, v135
	s_nop 0
	v_cndmask_b32_e32 v103, v152, v101, vcc
	v_cndmask_b32_e32 v102, v152, v100, vcc
	v_cndmask_b32_e32 v101, v152, v105, vcc
	v_cndmask_b32_e32 v100, v152, v104, vcc
	global_store_dwordx4 v[90:91], v[100:103], off sc0 sc1 nt
	ds_read_b64 v[100:101], v139 offset:9472
	s_waitcnt lgkmcnt(0)
; __device__ __forceinline__ unsigned cvt_pk_bf16(float lo, float hi) { unsigned r; asm volatile("v_cvt_pk_bf16_f32 %0, %1, %2" : "=v"(r) : "v"(lo), "v"(hi)); return r; }
;     __device__ __forceinline__ void fused(f32x4 (&acc)[2][2][4][2], const Unit& u, int wr, int wc, int fr, int fq, PG8_LAS unsigned char* lds, int wid, int lane) const {
;     ...
;         const float qnan = __builtin_nanf("");
; #pragma unroll
;         for (int bj = 0; bj < 2; ++bj)
; #pragma unroll
;             for (int n = 0; n < 2; ++n) {
;                 const int col = col0 + bj * HALF + n * 16;
;                 const f32x4 lg = *(const f32x4*)(lng + col), lb = *(const f32x4*)(lnb + col);
;                 f32x4 sc1 = (f32x4){1.f, 1.f, 1.f, 1.f}, sh = (f32x4){0.f, 0.f, 0.f, 0.f};
;                 if (DO_U) { sc1 = *(const f32x4*)(msc + mo + col) + 1.0f; sh = *(const f32x4*)(msh + mo + col); }
; #pragma unroll
;                 for (int ai = 0; ai < 2; ++ai)
; #pragma unroll
;                     for (int m = 0; m < 4; ++m) { const int r = ai * HALF + wr * 64 + m * 16 + fr; const f32x2v sr = S[r]; const size_t off = (size_t)(u.pm * BM + r) * 1024 + col;
;                         f32x4 y = (acc[ai][bj][m][n] - sr.x) * sr.y * lg + lb; if (bad) y = (f32x4){qnan, qnan, qnan, qnan};
;                         *(f32x4*)(out + off) = y;
;                         if (DO_U) { const f32x4 uu = y * sc1 + sh; u32x2v w; w.x = cvt_pk_bf16(uu[0], uu[1]); w.y = cvt_pk_bf16(uu[2], uu[3]); *(u32x2v*)(U + off) = w; } }
	v_sub_f32_e32 v105, v129, v100
	v_add_u32_e32 v102, 0xa0, v150
	v_ashrrev_i32_e32 v103, 31, v102
	v_lshlrev_b64 v[102:103], 12, v[102:103]
	v_lshl_add_u64 v[106:107], v[136:137], 0, v[102:103]
	v_sub_f32_e32 v103, v131, v100
	v_sub_f32_e32 v102, v130, v100
	v_sub_f32_e32 v104, v128, v100
	v_mul_f32_e64 v104, v101, v104
	v_mul_f32_e64 v105, v101, v105
	v_mul_f32_e64 v100, v101, v102
	v_mul_f32_e64 v101, v101, v103
	v_fma_f32 v102, v0, v104, v132
	v_fma_f32 v103, v1, v105, v133
	v_fma_f32 v100, v2, v100, v134
	v_fma_f32 v101, v3, v101, v135
	v_cndmask_b32_e32 v103, v152, v103, vcc
	v_cndmask_b32_e32 v105, v152, v101, vcc
	v_cndmask_b32_e32 v104, v152, v100, vcc
	v_cndmask_b32_e32 v102, v152, v102, vcc
	v_lshl_add_u64 v[100:101], v[106:107], 0, v[140:141]
	global_store_dwordx4 v[100:101], v[102:105], off sc0 sc1 nt
	ds_read_b64 v[102:103], v139 offset:9600
	v_add_u32_e32 v106, 0xb0, v150
	v_ashrrev_i32_e32 v107, 31, v106
	s_waitcnt lgkmcnt(0)
	v_sub_f32_e32 v105, v127, v102
	v_sub_f32_e32 v104, v126, v102
	v_sub_f32_e32 v113, v125, v102
	v_sub_f32_e32 v112, v124, v102
	v_mul_f32_e64 v112, v103, v112
	v_mul_f32_e64 v113, v103, v113
	v_mul_f32_e64 v102, v103, v104
	v_mul_f32_e64 v103, v103, v105
	v_fma_f32 v0, v0, v112, v132
	v_fma_f32 v1, v1, v113, v133
	v_fma_f32 v2, v2, v102, v134
	v_fma_f32 v3, v3, v103, v135
	v_cndmask_b32_e32 v103, v152, v1, vcc
	v_cndmask_b32_e32 v104, v152, v2, vcc
	v_cndmask_b32_e32 v102, v152, v0, vcc
	v_lshlrev_b64 v[0:1], 12, v[106:107]
	v_or_b32_e32 v2, 16, v138
	v_cndmask_b32_e32 v105, v152, v3, vcc
	v_lshl_add_u64 v[0:1], v[136:137], 0, v[0:1]
	v_ashrrev_i32_e32 v3, 31, v2
	v_lshl_add_u64 v[0:1], v[0:1], 0, v[140:141]
	v_lshlrev_b64 v[2:3], 2, v[2:3]
	global_store_dwordx4 v[0:1], v[102:105], off sc0 sc1 nt
	s_nop 1
	v_lshl_add_u64 v[102:103], v[144:145], 0, v[2:3]
	v_lshl_add_u64 v[2:3], v[142:143], 0, v[2:3]
	global_load_dwordx4 v[102:105], v[102:103], off
	s_nop 0
	global_load_dwordx4 v[112:115], v[2:3], off
	ds_read_b64 v[2:3], v139 offset:8192
	s_waitcnt lgkmcnt(0)
	v_sub_f32_e32 v47, v47, v2
	v_sub_f32_e32 v46, v46, v2
	v_sub_f32_e32 v45, v45, v2
	v_sub_f32_e32 v44, v44, v2
	v_mul_f32_e64 v44, v3, v44
	v_mul_f32_e64 v45, v3, v45
	v_mul_f32_e64 v2, v3, v46
	v_mul_f32_e64 v3, v3, v47
	s_waitcnt vmcnt(0)
	v_fma_f32 v44, v102, v44, v112
	v_fma_f32 v45, v103, v45, v113
	v_fma_f32 v2, v104, v2, v114
	v_fma_f32 v3, v105, v3, v115
	v_cndmask_b32_e32 v45, v152, v45, vcc
	v_cndmask_b32_e32 v47, v152, v3, vcc
	v_cndmask_b32_e32 v46, v152, v2, vcc
	v_cndmask_b32_e32 v44, v152, v44, vcc
	global_store_dwordx4 v[148:149], v[44:47], off offset:64 sc0 sc1 nt
	ds_read_b64 v[2:3], v139 offset:8320
	s_waitcnt lgkmcnt(0)
	v_sub_f32_e32 v45, v59, v2
	v_sub_f32_e32 v44, v58, v2
	v_sub_f32_e32 v47, v57, v2
	v_sub_f32_e32 v46, v56, v2
	v_mul_f32_e64 v46, v3, v46
	v_mul_f32_e64 v47, v3, v47
	v_mul_f32_e64 v2, v3, v44
	v_mul_f32_e64 v3, v3, v45
	v_fma_f32 v44, v102, v46, v112
	v_fma_f32 v45, v103, v47, v113
	v_fma_f32 v2, v104, v2, v114
	v_fma_f32 v3, v105, v3, v115
	v_cndmask_b32_e32 v45, v152, v45, vcc
	v_cndmask_b32_e32 v47, v152, v3, vcc
	v_cndmask_b32_e32 v46, v152, v2, vcc
	v_cndmask_b32_e32 v44, v152, v44, vcc
	global_store_dwordx4 v[146:147], v[44:47], off offset:64 sc0 sc1 nt
	ds_read_b64 v[2:3], v139 offset:8448
	v_or_b32_e32 v56, 0x80, v138
	v_ashrrev_i32_e32 v57, 31, v56
	s_waitcnt lgkmcnt(0)
	v_sub_f32_e32 v45, v71, v2
	v_sub_f32_e32 v44, v70, v2
	v_sub_f32_e32 v47, v69, v2
	v_sub_f32_e32 v46, v68, v2
	v_mul_f32_e64 v46, v3, v46
	v_mul_f32_e64 v47, v3, v47
	v_mul_f32_e64 v2, v3, v44
	v_mul_f32_e64 v3, v3, v45
	v_fma_f32 v44, v102, v46, v112
	v_fma_f32 v45, v103, v47, v113
	v_fma_f32 v2, v104, v2, v114
	v_fma_f32 v3, v105, v3, v115
	v_cndmask_b32_e32 v45, v152, v45, vcc
	v_cndmask_b32_e32 v47, v152, v3, vcc
	v_cndmask_b32_e32 v46, v152, v2, vcc
	v_cndmask_b32_e32 v44, v152, v44, vcc
	global_store_dwordx4 v[88:89], v[44:47], off offset:64 sc0 sc1 nt
	ds_read_b64 v[2:3], v139 offset:8576
	s_waitcnt lgkmcnt(0)
	v_sub_f32_e32 v45, v75, v2
	v_sub_f32_e32 v44, v74, v2
	v_sub_f32_e32 v47, v73, v2
	v_sub_f32_e32 v46, v72, v2
	v_mul_f32_e64 v46, v3, v46
	v_mul_f32_e64 v47, v3, v47
	v_mul_f32_e64 v2, v3, v44
	v_mul_f32_e64 v3, v3, v45
	v_fma_f32 v44, v102, v46, v112
	v_fma_f32 v45, v103, v47, v113
	v_fma_f32 v2, v104, v2, v114
	v_fma_f32 v3, v105, v3, v115
	v_cndmask_b32_e32 v45, v152, v45, vcc
	v_cndmask_b32_e32 v47, v152, v3, vcc
	v_cndmask_b32_e32 v46, v152, v2, vcc
	v_cndmask_b32_e32 v44, v152, v44, vcc
	global_store_dwordx4 v[82:83], v[44:47], off offset:64 sc0 sc1 nt
	ds_read_b64 v[2:3], v139 offset:9216
	s_waitcnt lgkmcnt(0)
	v_sub_f32_e32 v45, v87, v2
	v_sub_f32_e32 v44, v86, v2
	v_sub_f32_e32 v47, v85, v2
	v_sub_f32_e32 v46, v84, v2
	v_mul_f32_e64 v46, v3, v46
	v_mul_f32_e64 v47, v3, v47
	v_mul_f32_e64 v2, v3, v44
	v_mul_f32_e64 v3, v3, v45
	v_fma_f32 v44, v102, v46, v112
	v_fma_f32 v45, v103, v47, v113
	v_fma_f32 v2, v104, v2, v114
	v_fma_f32 v3, v105, v3, v115
	v_cndmask_b32_e32 v45, v152, v45, vcc
	v_cndmask_b32_e32 v47, v152, v3, vcc
	v_cndmask_b32_e32 v46, v152, v2, vcc
	v_cndmask_b32_e32 v44, v152, v44, vcc
	global_store_dwordx4 v[80:81], v[44:47], off offset:64 sc0 sc1 nt
	ds_read_b64 v[2:3], v139 offset:9344
	s_waitcnt lgkmcnt(0)
	v_sub_f32_e32 v45, v99, v2
	v_sub_f32_e32 v44, v98, v2
	v_sub_f32_e32 v47, v97, v2
	v_sub_f32_e32 v46, v96, v2
	v_mul_f32_e64 v46, v3, v46
	v_mul_f32_e64 v47, v3, v47
	v_mul_f32_e64 v2, v3, v44
	v_mul_f32_e64 v3, v3, v45
	v_fma_f32 v44, v102, v46, v112
	v_fma_f32 v45, v103, v47, v113
	v_fma_f32 v2, v104, v2, v114
	v_fma_f32 v3, v105, v3, v115
	v_cndmask_b32_e32 v45, v152, v45, vcc
	v_cndmask_b32_e32 v47, v152, v3, vcc
	v_cndmask_b32_e32 v46, v152, v2, vcc
	v_cndmask_b32_e32 v44, v152, v44, vcc
	global_store_dwordx4 v[90:91], v[44:47], off offset:64 sc0 sc1 nt
	ds_read_b64 v[2:3], v139 offset:9472
	s_waitcnt lgkmcnt(0)
; __device__ __forceinline__ unsigned cvt_pk_bf16(float lo, float hi) { unsigned r; asm volatile("v_cvt_pk_bf16_f32 %0, %1, %2" : "=v"(r) : "v"(lo), "v"(hi)); return r; }
;     __device__ __forceinline__ void fused(f32x4 (&acc)[2][2][4][2], const Unit& u, int wr, int wc, int fr, int fq, PG8_LAS unsigned char* lds, int wid, int lane) const {
;     ...
;         const float qnan = __builtin_nanf("");
; #pragma unroll
;         for (int bj = 0; bj < 2; ++bj)
; #pragma unroll
;             for (int n = 0; n < 2; ++n) {
;                 const int col = col0 + bj * HALF + n * 16;
;                 const f32x4 lg = *(const f32x4*)(lng + col), lb = *(const f32x4*)(lnb + col);
;                 f32x4 sc1 = (f32x4){1.f, 1.f, 1.f, 1.f}, sh = (f32x4){0.f, 0.f, 0.f, 0.f};
;                 if (DO_U) { sc1 = *(const f32x4*)(msc + mo + col) + 1.0f; sh = *(const f32x4*)(msh + mo + col); }
; #pragma unroll
;                 for (int ai = 0; ai < 2; ++ai)
; #pragma unroll
;                     for (int m = 0; m < 4; ++m) { const int r = ai * HALF + wr * 64 + m * 16 + fr; const f32x2v sr = S[r]; const size_t off = (size_t)(u.pm * BM + r) * 1024 + col;
;                         f32x4 y = (acc[ai][bj][m][n] - sr.x) * sr.y * lg + lb; if (bad) y = (f32x4){qnan, qnan, qnan, qnan};
;                         *(f32x4*)(out + off) = y;
;                         if (DO_U) { const f32x4 uu = y * sc1 + sh; u32x2v w; w.x = cvt_pk_bf16(uu[0], uu[1]); w.y = cvt_pk_bf16(uu[2], uu[3]); *(u32x2v*)(U + off) = w; } }
	v_sub_f32_e32 v45, v111, v2
	v_sub_f32_e32 v44, v110, v2
	v_sub_f32_e32 v47, v109, v2
	v_sub_f32_e32 v46, v108, v2
	v_mul_f32_e64 v46, v3, v46
	v_mul_f32_e64 v47, v3, v47
	v_mul_f32_e64 v2, v3, v44
	v_mul_f32_e64 v3, v3, v45
	v_fma_f32 v44, v102, v46, v112
	v_fma_f32 v45, v103, v47, v113
	v_fma_f32 v2, v104, v2, v114
	v_fma_f32 v3, v105, v3, v115
	v_cndmask_b32_e32 v45, v152, v45, vcc
	v_cndmask_b32_e32 v47, v152, v3, vcc
	v_cndmask_b32_e32 v46, v152, v2, vcc
	v_cndmask_b32_e32 v44, v152, v44, vcc
	global_store_dwordx4 v[100:101], v[44:47], off offset:64 sc0 sc1 nt
	ds_read_b64 v[2:3], v139 offset:9600
	s_nop 0
	v_lshlrev_b64 v[44:45], 2, v[56:57]
	v_lshl_add_u64 v[56:57], v[144:145], 0, v[44:45]
	v_lshl_add_u64 v[58:59], v[142:143], 0, v[44:45]
	s_waitcnt lgkmcnt(0)
	v_sub_f32_e32 v45, v119, v2
	v_sub_f32_e32 v44, v118, v2
	v_sub_f32_e32 v47, v117, v2
	v_sub_f32_e32 v46, v116, v2
	v_mul_f32_e64 v46, v3, v46
	v_mul_f32_e64 v47, v3, v47
	v_mul_f32_e64 v2, v3, v44
	v_mul_f32_e64 v3, v3, v45
	v_fma_f32 v44, v102, v46, v112
	v_fma_f32 v45, v103, v47, v113
	v_fma_f32 v2, v104, v2, v114
	v_fma_f32 v3, v105, v3, v115
	v_cndmask_b32_e32 v45, v152, v45, vcc
	v_cndmask_b32_e32 v47, v152, v3, vcc
	v_cndmask_b32_e32 v46, v152, v2, vcc
	v_cndmask_b32_e32 v44, v152, v44, vcc
	global_store_dwordx4 v[0:1], v[44:47], off offset:64 sc0 sc1 nt
	global_load_dwordx4 v[44:47], v[56:57], off
	s_nop 0
	global_load_dwordx4 v[56:59], v[58:59], off
	ds_read_b64 v[2:3], v139 offset:8192
	s_waitcnt lgkmcnt(0)
	v_sub_f32_e32 v23, v23, v2
	v_sub_f32_e32 v22, v22, v2
	v_sub_f32_e32 v21, v21, v2
	v_sub_f32_e32 v20, v20, v2
	v_mul_f32_e64 v20, v3, v20
	v_mul_f32_e64 v21, v3, v21
	v_mul_f32_e64 v2, v3, v22
	v_mul_f32_e64 v3, v3, v23
	s_waitcnt vmcnt(0)
	v_fma_f32 v20, v44, v20, v56
	v_fma_f32 v21, v45, v21, v57
	v_fma_f32 v2, v46, v2, v58
	v_fma_f32 v3, v47, v3, v59
	v_cndmask_b32_e32 v21, v152, v21, vcc
	v_cndmask_b32_e32 v23, v152, v3, vcc
	v_cndmask_b32_e32 v22, v152, v2, vcc
	v_cndmask_b32_e32 v20, v152, v20, vcc
	global_store_dwordx4 v[148:149], v[20:23], off offset:512 sc0 sc1 nt
	ds_read_b64 v[2:3], v139 offset:8320
	s_waitcnt lgkmcnt(0)
	v_sub_f32_e32 v21, v31, v2
	v_sub_f32_e32 v20, v30, v2
	v_sub_f32_e32 v23, v29, v2
	v_sub_f32_e32 v22, v28, v2
	v_mul_f32_e64 v22, v3, v22
	v_mul_f32_e64 v23, v3, v23
	v_mul_f32_e64 v2, v3, v20
	v_mul_f32_e64 v3, v3, v21
	v_fma_f32 v20, v44, v22, v56
	v_fma_f32 v21, v45, v23, v57
	v_fma_f32 v2, v46, v2, v58
	v_fma_f32 v3, v47, v3, v59
	v_cndmask_b32_e32 v21, v152, v21, vcc
	v_cndmask_b32_e32 v23, v152, v3, vcc
	v_cndmask_b32_e32 v22, v152, v2, vcc
	v_cndmask_b32_e32 v20, v152, v20, vcc
	global_store_dwordx4 v[146:147], v[20:23], off offset:512 sc0 sc1 nt
	ds_read_b64 v[2:3], v139 offset:8448
	v_or_b32_e32 v28, 0x90, v138
	v_ashrrev_i32_e32 v29, 31, v28
	s_waitcnt lgkmcnt(0)
	v_sub_f32_e32 v21, v39, v2
	v_sub_f32_e32 v20, v38, v2
	v_sub_f32_e32 v23, v37, v2
	v_sub_f32_e32 v22, v36, v2
	v_mul_f32_e64 v22, v3, v22
	v_mul_f32_e64 v23, v3, v23
	v_mul_f32_e64 v2, v3, v20
	v_mul_f32_e64 v3, v3, v21
	v_fma_f32 v20, v44, v22, v56
	v_fma_f32 v21, v45, v23, v57
	v_fma_f32 v2, v46, v2, v58
	v_fma_f32 v3, v47, v3, v59
	v_cndmask_b32_e32 v21, v152, v21, vcc
	v_cndmask_b32_e32 v23, v152, v3, vcc
	v_cndmask_b32_e32 v22, v152, v2, vcc
	v_cndmask_b32_e32 v20, v152, v20, vcc
	global_store_dwordx4 v[88:89], v[20:23], off offset:512 sc0 sc1 nt
	ds_read_b64 v[2:3], v139 offset:8576
	s_waitcnt lgkmcnt(0)
	v_sub_f32_e32 v21, v43, v2
	v_sub_f32_e32 v20, v42, v2
	v_sub_f32_e32 v23, v41, v2
	v_sub_f32_e32 v22, v40, v2
	v_mul_f32_e64 v22, v3, v22
	v_mul_f32_e64 v23, v3, v23
	v_mul_f32_e64 v2, v3, v20
	v_mul_f32_e64 v3, v3, v21
	v_fma_f32 v20, v44, v22, v56
	v_fma_f32 v21, v45, v23, v57
	v_fma_f32 v2, v46, v2, v58
	v_fma_f32 v3, v47, v3, v59
	v_cndmask_b32_e32 v21, v152, v21, vcc
	v_cndmask_b32_e32 v23, v152, v3, vcc
	v_cndmask_b32_e32 v22, v152, v2, vcc
	v_cndmask_b32_e32 v20, v152, v20, vcc
	global_store_dwordx4 v[82:83], v[20:23], off offset:512 sc0 sc1 nt
	ds_read_b64 v[2:3], v139 offset:9216
	s_waitcnt lgkmcnt(0)
	v_sub_f32_e32 v21, v55, v2
	v_sub_f32_e32 v20, v54, v2
	v_sub_f32_e32 v23, v53, v2
	v_sub_f32_e32 v22, v52, v2
	v_mul_f32_e64 v22, v3, v22
	v_mul_f32_e64 v23, v3, v23
	v_mul_f32_e64 v2, v3, v20
	v_mul_f32_e64 v3, v3, v21
	v_fma_f32 v20, v44, v22, v56
	v_fma_f32 v21, v45, v23, v57
	v_fma_f32 v2, v46, v2, v58
	v_fma_f32 v3, v47, v3, v59
	v_cndmask_b32_e32 v21, v152, v21, vcc
	v_cndmask_b32_e32 v23, v152, v3, vcc
	v_cndmask_b32_e32 v22, v152, v2, vcc
	v_cndmask_b32_e32 v20, v152, v20, vcc
	global_store_dwordx4 v[80:81], v[20:23], off offset:512 sc0 sc1 nt
	ds_read_b64 v[2:3], v139 offset:9344
	s_waitcnt lgkmcnt(0)
	v_sub_f32_e32 v21, v63, v2
	v_sub_f32_e32 v20, v62, v2
	v_sub_f32_e32 v23, v61, v2
	v_sub_f32_e32 v22, v60, v2
	v_mul_f32_e64 v22, v3, v22
	v_mul_f32_e64 v23, v3, v23
	v_mul_f32_e64 v2, v3, v20
	v_mul_f32_e64 v3, v3, v21
	v_fma_f32 v20, v44, v22, v56
	v_fma_f32 v21, v45, v23, v57
	v_fma_f32 v2, v46, v2, v58
	v_fma_f32 v3, v47, v3, v59
	v_cndmask_b32_e32 v21, v152, v21, vcc
	v_cndmask_b32_e32 v23, v152, v3, vcc
	v_cndmask_b32_e32 v22, v152, v2, vcc
	v_cndmask_b32_e32 v20, v152, v20, vcc
	global_store_dwordx4 v[90:91], v[20:23], off offset:512 sc0 sc1 nt
	ds_read_b64 v[2:3], v139 offset:9472
	s_waitcnt lgkmcnt(0)
; __device__ __forceinline__ unsigned cvt_pk_bf16(float lo, float hi) { unsigned r; asm volatile("v_cvt_pk_bf16_f32 %0, %1, %2" : "=v"(r) : "v"(lo), "v"(hi)); return r; }
;     __device__ __forceinline__ void fused(f32x4 (&acc)[2][2][4][2], const Unit& u, int wr, int wc, int fr, int fq, PG8_LAS unsigned char* lds, int wid, int lane) const {
;     ...
;         const float qnan = __builtin_nanf("");
; #pragma unroll
;         for (int bj = 0; bj < 2; ++bj)
; #pragma unroll
;             for (int n = 0; n < 2; ++n) {
;                 const int col = col0 + bj * HALF + n * 16;
;                 const f32x4 lg = *(const f32x4*)(lng + col), lb = *(const f32x4*)(lnb + col);
;                 f32x4 sc1 = (f32x4){1.f, 1.f, 1.f, 1.f}, sh = (f32x4){0.f, 0.f, 0.f, 0.f};
;                 if (DO_U) { sc1 = *(const f32x4*)(msc + mo + col) + 1.0f; sh = *(const f32x4*)(msh + mo + col); }
; #pragma unroll
;                 for (int ai = 0; ai < 2; ++ai)
; #pragma unroll
;                     for (int m = 0; m < 4; ++m) { const int r = ai * HALF + wr * 64 + m * 16 + fr; const f32x2v sr = S[r]; const size_t off = (size_t)(u.pm * BM + r) * 1024 + col;
;                         f32x4 y = (acc[ai][bj][m][n] - sr.x) * sr.y * lg + lb; if (bad) y = (f32x4){qnan, qnan, qnan, qnan};
;                         *(f32x4*)(out + off) = y;
;                         if (DO_U) { const f32x4 uu = y * sc1 + sh; u32x2v w; w.x = cvt_pk_bf16(uu[0], uu[1]); w.y = cvt_pk_bf16(uu[2], uu[3]); *(u32x2v*)(U + off) = w; } }
	v_sub_f32_e32 v21, v79, v2
	v_sub_f32_e32 v20, v78, v2
	v_sub_f32_e32 v23, v77, v2
	v_sub_f32_e32 v22, v76, v2
	v_mul_f32_e64 v22, v3, v22
	v_mul_f32_e64 v23, v3, v23
	v_mul_f32_e64 v2, v3, v20
	v_mul_f32_e64 v3, v3, v21
	v_fma_f32 v20, v44, v22, v56
	v_fma_f32 v21, v45, v23, v57
	v_fma_f32 v2, v46, v2, v58
	v_fma_f32 v3, v47, v3, v59
	v_cndmask_b32_e32 v21, v152, v21, vcc
	v_cndmask_b32_e32 v23, v152, v3, vcc
	v_cndmask_b32_e32 v22, v152, v2, vcc
	v_cndmask_b32_e32 v20, v152, v20, vcc
	global_store_dwordx4 v[100:101], v[20:23], off offset:512 sc0 sc1 nt
	ds_read_b64 v[2:3], v139 offset:9600
	s_nop 0
	v_lshlrev_b64 v[20:21], 2, v[28:29]
	v_lshl_add_u64 v[36:37], v[144:145], 0, v[20:21]
	v_lshl_add_u64 v[38:39], v[142:143], 0, v[20:21]
	s_waitcnt lgkmcnt(0)
	v_sub_f32_e32 v21, v95, v2
	v_sub_f32_e32 v20, v94, v2
	v_sub_f32_e32 v23, v93, v2
	v_sub_f32_e32 v22, v92, v2
	v_mul_f32_e64 v22, v3, v22
	v_mul_f32_e64 v23, v3, v23
	v_mul_f32_e64 v2, v3, v20
	v_mul_f32_e64 v3, v3, v21
	v_fma_f32 v20, v44, v22, v56
	v_fma_f32 v21, v45, v23, v57
	v_fma_f32 v2, v46, v2, v58
	v_fma_f32 v3, v47, v3, v59
	v_cndmask_b32_e32 v21, v152, v21, vcc
	v_cndmask_b32_e32 v23, v152, v3, vcc
	v_cndmask_b32_e32 v22, v152, v2, vcc
	v_cndmask_b32_e32 v20, v152, v20, vcc
	global_store_dwordx4 v[0:1], v[20:23], off offset:512 sc0 sc1 nt
	global_load_dwordx4 v[20:23], v[36:37], off
	s_nop 0
	global_load_dwordx4 v[28:31], v[38:39], off
	ds_read_b64 v[2:3], v139 offset:8192
	s_waitcnt lgkmcnt(0)
	v_sub_f32_e32 v7, v7, v2
	v_sub_f32_e32 v6, v6, v2
	v_sub_f32_e32 v5, v5, v2
	v_sub_f32_e32 v4, v4, v2
	v_mul_f32_e64 v4, v3, v4
	v_mul_f32_e64 v5, v3, v5
	v_mul_f32_e64 v2, v3, v6
	v_mul_f32_e64 v3, v3, v7
	s_waitcnt vmcnt(0)
	v_fma_f32 v6, v20, v4, v28
	v_fma_f32 v7, v21, v5, v29
	v_fma_f32 v2, v22, v2, v30
	v_fma_f32 v3, v23, v3, v31
	s_nop 0
	v_cndmask_b32_e32 v5, v152, v3, vcc
	v_cndmask_b32_e32 v4, v152, v2, vcc
	v_cndmask_b32_e32 v3, v152, v7, vcc
	v_cndmask_b32_e32 v2, v152, v6, vcc
	global_store_dwordx4 v[148:149], v[2:5], off offset:576 sc0 sc1 nt
	ds_read_b64 v[2:3], v139 offset:8320
	s_waitcnt lgkmcnt(0)
	v_sub_f32_e32 v7, v9, v2
	v_sub_f32_e32 v5, v11, v2
	v_sub_f32_e32 v4, v10, v2
	v_sub_f32_e32 v6, v8, v2
	v_mul_f32_e64 v6, v3, v6
	v_mul_f32_e64 v7, v3, v7
	v_mul_f32_e64 v2, v3, v4
	v_mul_f32_e64 v3, v3, v5
	v_fma_f32 v6, v20, v6, v28
	v_fma_f32 v7, v21, v7, v29
	v_fma_f32 v2, v22, v2, v30
	v_fma_f32 v3, v23, v3, v31
	s_nop 0
	v_cndmask_b32_e32 v5, v152, v3, vcc
	v_cndmask_b32_e32 v4, v152, v2, vcc
	v_cndmask_b32_e32 v3, v152, v7, vcc
	v_cndmask_b32_e32 v2, v152, v6, vcc
	global_store_dwordx4 v[146:147], v[2:5], off offset:576 sc0 sc1 nt
	ds_read_b64 v[2:3], v139 offset:8448
	s_waitcnt lgkmcnt(0)
	v_sub_f32_e32 v7, v13, v2
	v_sub_f32_e32 v5, v15, v2
	v_sub_f32_e32 v4, v14, v2
	v_sub_f32_e32 v6, v12, v2
	v_mul_f32_e64 v6, v3, v6
	v_mul_f32_e64 v7, v3, v7
	v_mul_f32_e64 v2, v3, v4
	v_mul_f32_e64 v3, v3, v5
	v_fma_f32 v6, v20, v6, v28
	v_fma_f32 v7, v21, v7, v29
	v_fma_f32 v2, v22, v2, v30
	v_fma_f32 v3, v23, v3, v31
	s_nop 0
	v_cndmask_b32_e32 v5, v152, v3, vcc
	v_cndmask_b32_e32 v4, v152, v2, vcc
	v_cndmask_b32_e32 v3, v152, v7, vcc
	v_cndmask_b32_e32 v2, v152, v6, vcc
	global_store_dwordx4 v[88:89], v[2:5], off offset:576 sc0 sc1 nt
	ds_read_b64 v[2:3], v139 offset:8576
	s_waitcnt lgkmcnt(0)
	v_sub_f32_e32 v7, v17, v2
	v_sub_f32_e32 v5, v19, v2
	v_sub_f32_e32 v4, v18, v2
	v_sub_f32_e32 v6, v16, v2
	v_mul_f32_e64 v6, v3, v6
	v_mul_f32_e64 v7, v3, v7
	v_mul_f32_e64 v2, v3, v4
	v_mul_f32_e64 v3, v3, v5
	v_fma_f32 v6, v20, v6, v28
	v_fma_f32 v7, v21, v7, v29
	v_fma_f32 v2, v22, v2, v30
	v_fma_f32 v3, v23, v3, v31
	s_nop 0
	v_cndmask_b32_e32 v5, v152, v3, vcc
	v_cndmask_b32_e32 v4, v152, v2, vcc
	v_cndmask_b32_e32 v3, v152, v7, vcc
	v_cndmask_b32_e32 v2, v152, v6, vcc
	global_store_dwordx4 v[82:83], v[2:5], off offset:576 sc0 sc1 nt
	ds_read_b64 v[2:3], v139 offset:9216
	s_waitcnt lgkmcnt(0)
	v_sub_f32_e32 v7, v25, v2
	v_sub_f32_e32 v5, v27, v2
	v_sub_f32_e32 v4, v26, v2
	v_sub_f32_e32 v6, v24, v2
	v_mul_f32_e64 v6, v3, v6
	v_mul_f32_e64 v7, v3, v7
	v_mul_f32_e64 v2, v3, v4
	v_mul_f32_e64 v3, v3, v5
	v_fma_f32 v6, v20, v6, v28
	v_fma_f32 v7, v21, v7, v29
	v_fma_f32 v2, v22, v2, v30
	v_fma_f32 v3, v23, v3, v31
	s_nop 0
	v_cndmask_b32_e32 v5, v152, v3, vcc
	v_cndmask_b32_e32 v4, v152, v2, vcc
	v_cndmask_b32_e32 v3, v152, v7, vcc
	v_cndmask_b32_e32 v2, v152, v6, vcc
	global_store_dwordx4 v[80:81], v[2:5], off offset:576 sc0 sc1 nt
	ds_read_b64 v[2:3], v139 offset:9344
	s_waitcnt lgkmcnt(0)
	v_sub_f32_e32 v7, v33, v2
	v_sub_f32_e32 v5, v35, v2
	v_sub_f32_e32 v4, v34, v2
	v_sub_f32_e32 v6, v32, v2
	v_mul_f32_e64 v6, v3, v6
	v_mul_f32_e64 v7, v3, v7
	v_mul_f32_e64 v2, v3, v4
	v_mul_f32_e64 v3, v3, v5
	v_fma_f32 v6, v20, v6, v28
	v_fma_f32 v7, v21, v7, v29
	v_fma_f32 v2, v22, v2, v30
	v_fma_f32 v3, v23, v3, v31
	s_nop 0
	v_cndmask_b32_e32 v5, v152, v3, vcc
	v_cndmask_b32_e32 v4, v152, v2, vcc
	v_cndmask_b32_e32 v3, v152, v7, vcc
	v_cndmask_b32_e32 v2, v152, v6, vcc
	global_store_dwordx4 v[90:91], v[2:5], off offset:576 sc0 sc1 nt
	ds_read_b64 v[2:3], v139 offset:9472
	s_waitcnt lgkmcnt(0)
	v_sub_f32_e32 v7, v49, v2
	v_sub_f32_e32 v5, v51, v2
	v_sub_f32_e32 v4, v50, v2
	v_sub_f32_e32 v6, v48, v2
	v_mul_f32_e64 v6, v3, v6
	v_mul_f32_e64 v7, v3, v7
	v_mul_f32_e64 v2, v3, v4
	v_mul_f32_e64 v3, v3, v5
	v_fma_f32 v6, v20, v6, v28
	v_fma_f32 v7, v21, v7, v29
	v_fma_f32 v2, v22, v2, v30
	v_fma_f32 v3, v23, v3, v31
	s_nop 0
	v_cndmask_b32_e32 v5, v152, v3, vcc
	v_cndmask_b32_e32 v4, v152, v2, vcc
	v_cndmask_b32_e32 v3, v152, v7, vcc
	v_cndmask_b32_e32 v2, v152, v6, vcc
	global_store_dwordx4 v[100:101], v[2:5], off offset:576 sc0 sc1 nt
	ds_read_b64 v[2:3], v139 offset:9600
	s_waitcnt lgkmcnt(0)
	v_sub_f32_e32 v7, v65, v2
	v_sub_f32_e32 v5, v67, v2
	v_sub_f32_e32 v4, v66, v2
	v_sub_f32_e32 v6, v64, v2
	v_mul_f32_e64 v6, v3, v6
	v_mul_f32_e64 v7, v3, v7
	v_mul_f32_e64 v2, v3, v4
	v_mul_f32_e64 v3, v3, v5
	v_fma_f32 v6, v20, v6, v28
	v_fma_f32 v7, v21, v7, v29
	v_fma_f32 v2, v22, v2, v30
	v_fma_f32 v3, v23, v3, v31
	s_nop 0
	v_cndmask_b32_e32 v5, v152, v3, vcc
	v_cndmask_b32_e32 v4, v152, v2, vcc
	v_cndmask_b32_e32 v3, v152, v7, vcc
	v_cndmask_b32_e32 v2, v152, v6, vcc
	global_store_dwordx4 v[0:1], v[2:5], off offset:576 sc0 sc1 nt
